# all 16-byte global stores write-through (sc1): the seam's L2 write-back finds little dirty data
# baseline (speedup 1.0000x reference)
; __device__ __forceinline__ unsigned cvt_pk_bf16(float lo, float hi) { unsigned r; asm volatile("v_cvt_pk_bf16_f32 %0, %1, %2" : "=v"(r) : "v"(lo), "v"(hi)); return r; }
; #define LAS __attribute__((address_space(3)))
; __device__ __forceinline__ void tr_store(const TrDesc& d, float (&v)[32], LAS float* scr, int lane) {
;     if (d.gain) {
; #pragma unroll
;         for (int i = 0; i < 32; ++i) v[i] *= d.gain[d.k0 + 2 * i + (lane >> 5)]; }
; #pragma unroll
;     for (int i = 0; i < 32; ++i) { const int kk = 2 * i + (lane >> 5); scr[kk * 33 + (lane & 31)] = v[i]; }
;     asm volatile("s_waitcnt lgkmcnt(0)" ::: "memory");
;     const int c = lane & 7;
; #pragma unroll
;     for (int j = 0; j < 4; ++j) { const int n = (lane >> 3) + 8 * j; const LAS float* s = scr + (8 * c) * 33 + n;
;         u32x4 o; o.x = cvt_pk_bf16(s[0 * 33], s[1 * 33]); o.y = cvt_pk_bf16(s[2 * 33], s[3 * 33]); o.z = cvt_pk_bf16(s[4 * 33], s[5 * 33]); o.w = cvt_pk_bf16(s[6 * 33], s[7 * 33]);
;         *(u32x4*)(d.WT + (size_t)(d.drow0 + n) * d.K + d.k0 + 8 * c) = o; }
;     asm volatile("s_waitcnt lgkmcnt(0)" ::: "memory");
; }
; __global__ void __launch_bounds__(NTHREADS, 2) mega_fwd(Args a) {
;     ...
;             for (int it = gw; it < NITEMS; it += NGW) {
;                 TrDesc dn = dc; float vn[32];
;                 const bool more = it + NGW < NITEMS;
;                 if (more) { P0_DESC(it + NGW, dn); tr_load(dn, vn, lane); }
;                 tr_store(dc, vc, scr, lane);
;                 if (more) { dc = dn;
; #pragma unroll
;                     for (int i = 0; i < 32; ++i) vc[i] = vn[i]; }
;             }
.LBB0_106:
	v_add_u32_e32 v67, 0x400, v71
	s_waitcnt vmcnt(30)
	ds_write2_b32 v71, v0, v1 offset1:66
	s_waitcnt vmcnt(28)
	ds_write2_b32 v71, v2, v3 offset0:132 offset1:198
	s_waitcnt vmcnt(26)
	ds_write2_b32 v67, v4, v5 offset0:8 offset1:74
	s_waitcnt vmcnt(24)
	ds_write2_b32 v67, v6, v7 offset0:140 offset1:206
	v_add_u32_e32 v67, 0x800, v71
	s_waitcnt vmcnt(22)
	ds_write2_b32 v67, v8, v9 offset0:16 offset1:82
	s_waitcnt vmcnt(20)
	ds_write2_b32 v67, v10, v11 offset0:148 offset1:214
	v_add_u32_e32 v67, 0xc00, v71
	s_waitcnt vmcnt(18)
	ds_write2_b32 v67, v12, v13 offset0:24 offset1:90
	s_waitcnt vmcnt(16)
	ds_write2_b32 v67, v14, v15 offset0:156 offset1:222
	v_add_u32_e32 v67, 0x1000, v71
	s_waitcnt vmcnt(14)
	ds_write2_b32 v67, v16, v17 offset0:32 offset1:98
	s_waitcnt vmcnt(12)
	ds_write2_b32 v67, v18, v19 offset0:164 offset1:230
	v_add_u32_e32 v67, 0x1400, v71
	s_waitcnt vmcnt(10)
	ds_write2_b32 v67, v20, v21 offset0:40 offset1:106
	s_waitcnt vmcnt(8)
	ds_write2_b32 v67, v22, v23 offset0:172 offset1:238
	v_add_u32_e32 v67, 0x1800, v71
	s_waitcnt vmcnt(6)
	ds_write2_b32 v67, v24, v25 offset0:48 offset1:114
	s_waitcnt vmcnt(4)
	ds_write2_b32 v67, v26, v27 offset0:180 offset1:246
	v_add_u32_e32 v67, 0x1c00, v71
	s_waitcnt vmcnt(2)
	ds_write2_b32 v67, v28, v29 offset0:56 offset1:122
	s_waitcnt vmcnt(0)
	ds_write2_b32 v67, v30, v31 offset0:188 offset1:254
	s_waitcnt lgkmcnt(0)
	ds_read2_b32 v[76:77], v70 offset1:33
	s_waitcnt lgkmcnt(0)
	v_cvt_pk_bf16_f32 v76, v76, v77
	ds_read2_b32 v[78:79], v70 offset0:66 offset1:99
	s_waitcnt lgkmcnt(0)
	v_cvt_pk_bf16_f32 v77, v78, v79
	ds_read2_b32 v[78:79], v70 offset0:132 offset1:165
	s_waitcnt lgkmcnt(0)
	v_cvt_pk_bf16_f32 v78, v78, v79
	ds_read2_b32 v[80:81], v70 offset0:198 offset1:231
	v_add_u32_e32 v67, s64, v69
	s_waitcnt lgkmcnt(0)
	v_cvt_pk_bf16_f32 v79, v80, v81
	v_mad_u64_u32 v[80:81], s[52:53], v67, s3, 0
	v_ashrrev_i32_e32 v75, 31, v67
	v_mov_b32_e32 v82, v81
	v_mad_u64_u32 v[82:83], s[52:53], v75, s3, v[82:83]
	v_mov_b32_e32 v81, v82
	s_ashr_i32 s5, s4, 31
	v_lshl_add_u64 v[80:81], v[80:81], 1, s[0:1]
	s_lshl_b64 s[52:53], s[4:5], 1
	v_lshl_add_u64 v[80:81], v[80:81], 0, s[52:53]
	v_lshl_add_u64 v[80:81], v[80:81], 0, v[64:65]
	ds_read2_b32 v[82:83], v70 offset0:8 offset1:41
	global_store_dwordx4 v[80:81], v[76:79], off sc1
	v_add_u32_e32 v67, s64, v72
	v_ashrrev_i32_e32 v75, 31, v67
	s_waitcnt lgkmcnt(0)
	v_cvt_pk_bf16_f32 v76, v82, v83
	ds_read2_b32 v[78:79], v70 offset0:74 offset1:107
	s_waitcnt lgkmcnt(0)
	v_cvt_pk_bf16_f32 v77, v78, v79
	ds_read2_b32 v[78:79], v70 offset0:140 offset1:173
	s_waitcnt lgkmcnt(0)
	v_cvt_pk_bf16_f32 v78, v78, v79
	ds_read2_b32 v[80:81], v70 offset0:206 offset1:239
	s_waitcnt lgkmcnt(0)
	v_cvt_pk_bf16_f32 v79, v80, v81
	v_mad_u64_u32 v[80:81], s[54:55], v67, s3, 0
	v_mov_b32_e32 v82, v81
	v_mad_u64_u32 v[82:83], s[54:55], v75, s3, v[82:83]
	v_mov_b32_e32 v81, v82
	v_lshl_add_u64 v[80:81], v[80:81], 1, s[0:1]
	v_lshl_add_u64 v[80:81], v[80:81], 0, s[52:53]
	v_lshl_add_u64 v[80:81], v[80:81], 0, v[64:65]
	ds_read2_b32 v[82:83], v70 offset0:16 offset1:49
	global_store_dwordx4 v[80:81], v[76:79], off sc1
	v_add_u32_e32 v67, s64, v73
	v_ashrrev_i32_e32 v75, 31, v67
	s_waitcnt lgkmcnt(0)
	v_cvt_pk_bf16_f32 v76, v82, v83
	ds_read2_b32 v[78:79], v70 offset0:82 offset1:115
	s_waitcnt lgkmcnt(0)
	v_cvt_pk_bf16_f32 v77, v78, v79
	ds_read2_b32 v[78:79], v70 offset0:148 offset1:181
	s_waitcnt lgkmcnt(0)
	v_cvt_pk_bf16_f32 v78, v78, v79
	ds_read2_b32 v[80:81], v70 offset0:214 offset1:247
	s_waitcnt lgkmcnt(0)
	v_cvt_pk_bf16_f32 v79, v80, v81
	v_mad_u64_u32 v[80:81], s[54:55], v67, s3, 0
	v_mov_b32_e32 v82, v81
	v_mad_u64_u32 v[82:83], s[54:55], v75, s3, v[82:83]
	v_mov_b32_e32 v81, v82
	v_lshl_add_u64 v[80:81], v[80:81], 1, s[0:1]
	v_lshl_add_u64 v[80:81], v[80:81], 0, s[52:53]
	v_lshl_add_u64 v[80:81], v[80:81], 0, v[64:65]
	ds_read2_b32 v[82:83], v70 offset0:24 offset1:57
	global_store_dwordx4 v[80:81], v[76:79], off sc1
	v_add_u32_e32 v67, s64, v74
	v_ashrrev_i32_e32 v75, 31, v67
	s_waitcnt lgkmcnt(0)
	v_cvt_pk_bf16_f32 v76, v82, v83
	ds_read2_b32 v[78:79], v70 offset0:90 offset1:123
	s_waitcnt lgkmcnt(0)
	v_cvt_pk_bf16_f32 v77, v78, v79
	ds_read2_b32 v[78:79], v70 offset0:156 offset1:189
	s_waitcnt lgkmcnt(0)
	v_cvt_pk_bf16_f32 v78, v78, v79
	ds_read2_b32 v[80:81], v70 offset0:222 offset1:255
	s_waitcnt lgkmcnt(0)
	v_cvt_pk_bf16_f32 v79, v80, v81
	v_mad_u64_u32 v[80:81], s[54:55], v67, s3, 0
	v_mov_b32_e32 v82, v81
	v_mad_u64_u32 v[82:83], s[54:55], v75, s3, v[82:83]
	v_mov_b32_e32 v81, v82
	v_lshl_add_u64 v[80:81], v[80:81], 1, s[0:1]
	v_lshl_add_u64 v[80:81], v[80:81], 0, s[52:53]
	v_lshl_add_u64 v[80:81], v[80:81], 0, v[64:65]
	global_store_dwordx4 v[80:81], v[76:79], off sc1
	s_waitcnt lgkmcnt(0)
	s_andn2_b64 vcc, exec, s[34:35]
	s_cbranch_vccnz .LBB0_62
	v_mov_b64_e32 v[0:1], v[32:33]
	s_mov_b64 s[84:85], s[6:7]
	s_mov_b64 s[0:1], s[92:93]
	s_mov_b32 s3, s17
	s_mov_b32 s64, s86
	s_mov_b32 s4, s16
	v_mov_b64_e32 v[2:3], v[34:35]
	v_mov_b64_e32 v[4:5], v[36:37]
	v_mov_b64_e32 v[6:7], v[38:39]
	v_mov_b64_e32 v[8:9], v[40:41]
	v_mov_b64_e32 v[10:11], v[42:43]
	v_mov_b64_e32 v[12:13], v[44:45]
	v_mov_b64_e32 v[14:15], v[46:47]
	v_mov_b64_e32 v[16:17], v[48:49]
	v_mov_b64_e32 v[18:19], v[50:51]
	v_mov_b64_e32 v[20:21], v[52:53]
	v_mov_b64_e32 v[22:23], v[54:55]
	v_mov_b64_e32 v[24:25], v[56:57]
	v_mov_b64_e32 v[26:27], v[58:59]
	v_mov_b64_e32 v[28:29], v[60:61]
	v_mov_b64_e32 v[30:31], v[62:63]
	s_branch .LBB0_62

; __device__ __forceinline__ void ssm_tables(int idx, const float* a_re, const float* a_im, const float* b_re, const float* b_im, const float* log_dt, float* ABAR, bf16_t* BBH, bf16_t* BBL) {
;     const int g = idx >> 6, p = idx & 63;
;     const float dt = expf(log_dt[g]), are = a_re[idx], aim = a_im[idx];
;     const float mag = expf(dt * are), ang = dt * aim, ar = mag * cosf(ang), ai = mag * sinf(ang);
;     ABAR[2 * idx] = ar; ABAR[2 * idx + 1] = ai;
;     const float den = are * are + aim * aim, nr = ar - 1.f, ni = ai;
;     const float qr = (nr * are + ni * aim) / den, qi = (ni * are - nr * aim) / den;
;     const float* pbr = b_re + (size_t)idx * 16; const float* pbi = b_im + (size_t)idx * 16;
; #pragma unroll
;     for (int h8 = 0; h8 < 2; ++h8) { float vr[8], vi[8];
; #pragma unroll
;         for (int e = 0; e < 8; ++e) { const float r = pbr[8 * h8 + e], i = pbi[8 * h8 + e]; vr[e] = qr * r - qi * i; vi[e] = qr * i + qi * r; }
.LBB0_118:
	s_or_b64 exec, exec, s[0:1]
	s_waitcnt vmcnt(0)
	v_mul_f32_e32 v5, v6, v2
	s_mov_b32 s0, 0x3fb8aa3b
	v_mul_f32_e32 v6, 0x3fb8aa3b, v5
	v_fma_f32 v11, v5, s0, -v6
	v_rndne_f32_e32 v13, v6
	v_fmamk_f32 v11, v5, 0x32a5705f, v11
	v_sub_f32_e32 v6, v6, v13
	v_add_f32_e32 v6, v6, v11
	v_exp_f32_e32 v6, v6
	v_cvt_i32_f32_e32 v11, v13
	s_mov_b32 s0, 0xc2ce8ed0
	v_cmp_ngt_f32_e32 vcc, s0, v5
	s_mov_b32 s0, 0x42b17218
	v_ldexp_f32 v6, v6, v11
	v_cndmask_b32_e32 v6, 0, v6, vcc
	v_cmp_nlt_f32_e32 vcc, s0, v5
	v_lshlrev_b32_e32 v5, 30, v10
	v_mov_b32_e32 v11, 0x7f800000
	v_and_b32_e32 v15, 0x80000000, v5
	v_mul_f32_e32 v5, v7, v7
	v_mov_b32_e32 v17, 0x3c0881c4
	v_cndmask_b32_e32 v14, v11, v6, vcc
	v_fmamk_f32 v6, v5, 0xb94c1982, v17
	v_mov_b32_e32 v21, 0xbab64f3b
	v_fmaak_f32 v11, v5, v6, 0xbe2aaa9d
	v_fmamk_f32 v6, v5, 0x37d75334, v21
	v_and_b32_e32 v19, 1, v10
	v_fmaak_f32 v10, v5, v6, 0x3d2aabf7
	v_fmaak_f32 v10, v5, v10, 0xbf000004
	v_fma_f32 v23, v5, v10, 1.0
	v_lshlrev_b32_e32 v10, 30, v12
	v_and_b32_e32 v10, 0x80000000, v10
	v_xor_b32_e32 v9, v9, v8
	v_xor_b32_e32 v9, v9, v10
	v_mov_b32_e32 v10, v4
	v_pk_mul_f32 v[10:11], v[4:5], v[10:11]
	v_mov_b32_e32 v22, 0x3d2aabf7
	v_fmac_f32_e32 v21, 0x37d75334, v10
	v_mov_b32_e32 v20, 0xbe2aaa9d
	v_mov_b32_e32 v6, 0xbf000004
	v_fmac_f32_e32 v22, v10, v21
	v_fmac_f32_e32 v17, 0xb94c1982, v10
	v_and_b32_e32 v18, 1, v12
	v_mov_b32_e32 v16, 1.0
	v_fmac_f32_e32 v6, v10, v22
	v_fmac_f32_e32 v20, v10, v17
	v_mov_b32_e32 v17, v7
	v_mul_f32_e32 v5, v10, v20
	v_pk_fma_f32 v[6:7], v[10:11], v[6:7], v[16:17]
	v_cmp_eq_u32_e32 vcc, 0, v18
	v_fmac_f32_e32 v4, v4, v5
	s_movk_i32 s0, 0x1f8
	v_cndmask_b32_e32 v5, v23, v7, vcc
	v_cmp_eq_u32_e32 vcc, 0, v19
	v_lshlrev_b32_e32 v12, 1, v0
	v_ashrrev_i32_e32 v13, 31, v12
	v_cndmask_b32_e64 v4, -v4, v6, vcc
	v_xor_b32_e32 v5, v9, v5
	v_xor_b32_e32 v4, v15, v4
	v_mov_b32_e32 v6, 0x7fc00000
	v_cmp_class_f32_e64 vcc, v8, s0
	v_lshl_add_u64 v[12:13], v[12:13], 2, s[28:29]
	s_mov_b32 s0, 0x100000
	v_cndmask_b32_e32 v5, v6, v5, vcc
	v_cndmask_b32_e32 v4, v6, v4, vcc
	v_pk_mul_f32 v[20:21], v[14:15], v[4:5] op_sel_hi:[0,1]
	v_add_co_u32_e32 v4, vcc, s0, v12
	v_readlane_b32 s48, v249, 2
	s_nop 0
	v_addc_co_u32_e32 v5, vcc, 0, v13, vcc
	global_store_dwordx2 v[4:5], v[20:21], off
	v_lshlrev_b64 v[4:5], 6, v[0:1]
	v_readlane_b32 s60, v249, 14
	v_readlane_b32 s61, v249, 15
	v_readlane_b32 s58, v249, 12
	v_readlane_b32 s59, v249, 13
	v_lshl_add_u64 v[24:25], s[60:61], 0, v[4:5]
	v_add_f32_e32 v29, -1.0, v20
	v_lshl_add_u64 v[22:23], s[58:59], 0, v[4:5]
	global_load_dwordx4 v[4:7], v[24:25], off
	global_load_dwordx4 v[8:11], v[22:23], off
	global_load_dwordx4 v[12:15], v[24:25], off offset:16
	global_load_dwordx4 v[16:19], v[22:23], off offset:16
	v_mov_b32_e32 v32, v3
	v_mov_b32_e32 v34, v29
	v_mov_b32_e32 v35, v21
	v_pk_mul_f32 v[26:27], v[2:3], v[2:3]
	v_mov_b32_e32 v28, v21
	v_pk_mul_f32 v[32:33], v[32:33], v[34:35] op_sel_hi:[0,1]
	v_pk_fma_f32 v[28:29], v[2:3], v[28:29], v[32:33] op_sel_hi:[0,1,1]
	v_pk_add_f32 v[26:27], v[26:27], v[26:27] op_sel:[0,1] op_sel_hi:[0,1]
	v_div_scale_f32 v1, s[6:7], v27, v27, v29
	v_rcp_f32_e32 v28, v1
	v_pk_fma_f32 v[2:3], v[2:3], v[20:21], v[32:33] op_sel:[0,1,0] op_sel_hi:[1,0,1] neg_lo:[0,0,1] neg_hi:[0,0,1]
	s_add_u32 s0, s28, 0x110000
	v_lshl_or_b32 v30, s92, 7, v196
	v_fma_f32 v3, -v1, v28, 1.0
	v_fmac_f32_e32 v28, v3, v28
	v_div_scale_f32 v3, vcc, v29, v27, v29
	v_mul_f32_e32 v20, v3, v28
	v_fma_f32 v21, -v1, v20, v3
	v_fmac_f32_e32 v20, v21, v28
	v_fma_f32 v1, -v1, v20, v3
	v_div_scale_f32 v3, s[6:7], v26, v26, v2
	v_rcp_f32_e32 v32, v3
	v_div_fmas_f32 v1, v1, v28, v20
	v_div_fixup_f32 v21, v1, v27, v29
	s_addc_u32 s1, s29, 0
	v_fma_f32 v1, -v3, v32, 1.0
	v_fmac_f32_e32 v32, v1, v32
	v_div_scale_f32 v1, vcc, v2, v26, v2
	v_mul_f32_e32 v20, v1, v32
	v_fma_f32 v27, -v3, v20, v1
	v_fmac_f32_e32 v20, v27, v32
	v_fma_f32 v1, -v3, v20, v1
	v_div_fmas_f32 v1, v1, v32, v20
	v_div_fixup_f32 v20, v1, v26, v2
	v_ashrrev_i32_e32 v31, 31, v30
	s_add_u32 s4, s28, 0x140000
	v_or_b32_e32 v34, 64, v30
	s_addc_u32 s5, s29, 0
	v_ashrrev_i32_e32 v35, 31, v34
	v_readlane_b32 s49, v249, 3
	v_readlane_b32 s50, v249, 4
	v_readlane_b32 s51, v249, 5
	v_readlane_b32 s52, v249, 6
	v_readlane_b32 s53, v249, 7
	v_readlane_b32 s54, v249, 8
	v_readlane_b32 s55, v249, 9
	v_readlane_b32 s56, v249, 10
	v_readlane_b32 s57, v249, 11
	v_readlane_b32 s62, v249, 16
	v_readlane_b32 s63, v249, 17
	s_waitcnt vmcnt(3)
	v_mov_b32_e32 v2, v4
	s_waitcnt vmcnt(2)
	v_mov_b32_e32 v3, v8
	v_pk_mul_f32 v[2:3], v[2:3], v[20:21]
	s_nop 0
	v_sub_f32_e32 v1, v3, v2
	v_mov_b32_e32 v2, v8
	v_mov_b32_e32 v3, v4
	v_pk_mul_f32 v[2:3], v[2:3], v[20:21]
	v_mov_b32_e32 v8, v5
	v_add_f32_e32 v26, v2, v3
	v_pk_mul_f32 v[2:3], v[8:9], v[20:21]
	v_mov_b32_e32 v4, v9
	v_sub_f32_e32 v8, v3, v2
	v_pk_mul_f32 v[2:3], v[4:5], v[20:21]
	s_nop 0
	v_add_f32_e32 v4, v2, v3
	v_mov_b32_e32 v2, v6
	v_mov_b32_e32 v3, v10
	v_pk_mul_f32 v[2:3], v[2:3], v[20:21]
	s_nop 0
	v_sub_f32_e32 v5, v3, v2
	v_mov_b32_e32 v2, v10
	v_mov_b32_e32 v3, v6
	v_pk_mul_f32 v[2:3], v[2:3], v[20:21]
	v_mov_b32_e32 v10, v7
	v_add_f32_e32 v9, v2, v3
	v_pk_mul_f32 v[2:3], v[10:11], v[20:21]
	v_mov_b32_e32 v6, v11
	v_sub_f32_e32 v27, v3, v2
	v_pk_mul_f32 v[2:3], v[6:7], v[20:21]
	s_nop 0
	v_add_f32_e32 v28, v2, v3
	s_waitcnt vmcnt(1)
	v_mov_b32_e32 v2, v12
	s_waitcnt vmcnt(0)
; __device__ __forceinline__ unsigned cvt_pk_bf16(float lo, float hi) { unsigned r; asm volatile("v_cvt_pk_bf16_f32 %0, %1, %2" : "=v"(r) : "v"(lo), "v"(hi)); return r; }
; __device__ __forceinline__ void ssm_tables(int idx, const float* a_re, const float* a_im, const float* b_re, const float* b_im, const float* log_dt, float* ABAR, bf16_t* BBH, bf16_t* BBL) {
;     ...
;         for (int e = 0; e < 8; ++e) { const float r = pbr[8 * h8 + e], i = pbi[8 * h8 + e]; vr[e] = qr * r - qi * i; vi[e] = qr * i + qi * r; }
;         u32x4 hr, lr, hi, li;
; #pragma unroll
;         for (int e = 0; e < 4; ++e) { const unsigned a = cvt_pk_bf16(vr[2 * e], vr[2 * e + 1]); hr[e] = a; lr[e] = cvt_pk_bf16(vr[2 * e] - bf_lo(a), vr[2 * e + 1] - bf_hi(a));
;             const unsigned c = cvt_pk_bf16(vi[2 * e], vi[2 * e + 1]); hi[e] = c; li[e] = cvt_pk_bf16(vi[2 * e] - bf_lo(c), vi[2 * e + 1] - bf_hi(c)); }
;         *(u32x4*)(BBH + ((size_t)(g * 128 + p) * 16 + 8 * h8)) = hr; *(u32x4*)(BBL + ((size_t)(g * 128 + p) * 16 + 8 * h8)) = lr;
;         *(u32x4*)(BBH + ((size_t)(g * 128 + 64 + p) * 16 + 8 * h8)) = hi; *(u32x4*)(BBL + ((size_t)(g * 128 + 64 + p) * 16 + 8 * h8)) = li; }
	v_mov_b32_e32 v3, v16
	v_pk_mul_f32 v[2:3], v[2:3], v[20:21]
	s_nop 0
	v_sub_f32_e32 v29, v3, v2
	v_mov_b32_e32 v2, v16
	v_mov_b32_e32 v3, v12
	v_pk_mul_f32 v[2:3], v[2:3], v[20:21]
	v_mov_b32_e32 v16, v13
	v_add_f32_e32 v32, v2, v3
	v_pk_mul_f32 v[2:3], v[20:21], v[16:17]
	v_mov_b32_e32 v12, v17
	v_sub_f32_e32 v16, v3, v2
	v_pk_mul_f32 v[2:3], v[20:21], v[12:13]
	s_nop 0
	v_add_f32_e32 v13, v2, v3
	v_mov_b32_e32 v2, v14
	v_mov_b32_e32 v3, v18
	v_pk_mul_f32 v[2:3], v[20:21], v[2:3]
	s_nop 0
	v_sub_f32_e32 v17, v3, v2
	v_mov_b32_e32 v2, v18
	v_mov_b32_e32 v3, v14
	v_pk_mul_f32 v[2:3], v[20:21], v[2:3]
	v_mov_b32_e32 v18, v15
	v_add_f32_e32 v33, v2, v3
	v_pk_mul_f32 v[2:3], v[20:21], v[18:19]
	v_mov_b32_e32 v14, v19
	v_sub_f32_e32 v18, v3, v2
	v_pk_mul_f32 v[2:3], v[20:21], v[14:15]
	s_nop 0
	v_add_f32_e32 v19, v2, v3
	v_cvt_pk_bf16_f32 v2, v1, v8
	s_nop 0
	v_lshlrev_b32_e32 v3, 16, v2
	v_sub_f32_e32 v1, v1, v3
	v_and_b32_e32 v3, 0xffff0000, v2
	v_sub_f32_e32 v3, v8, v3
	v_cvt_pk_bf16_f32 v6, v1, v3
	v_cvt_pk_bf16_f32 v10, v26, v4
	s_nop 0
	v_and_b32_e32 v3, 0xffff0000, v10
	v_lshlrev_b32_e32 v1, 16, v10
	v_sub_f32_e32 v3, v4, v3
	v_sub_f32_e32 v1, v26, v1
	v_cvt_pk_bf16_f32 v14, v1, v3
	v_cvt_pk_bf16_f32 v3, v5, v27
	s_nop 0
	v_and_b32_e32 v4, 0xffff0000, v3
	v_lshlrev_b32_e32 v1, 16, v3
	v_sub_f32_e32 v4, v27, v4
	v_sub_f32_e32 v1, v5, v1
	v_cvt_pk_bf16_f32 v7, v1, v4
	v_cvt_pk_bf16_f32 v11, v9, v28
	s_nop 0
	v_and_b32_e32 v4, 0xffff0000, v11
	v_lshlrev_b32_e32 v1, 16, v11
	v_sub_f32_e32 v4, v28, v4
	v_sub_f32_e32 v1, v9, v1
	v_cvt_pk_bf16_f32 v15, v1, v4
	v_cvt_pk_bf16_f32 v4, v29, v16
	s_nop 0
	v_and_b32_e32 v5, 0xffff0000, v4
	v_lshlrev_b32_e32 v1, 16, v4
	v_sub_f32_e32 v5, v16, v5
	v_sub_f32_e32 v1, v29, v1
	v_cvt_pk_bf16_f32 v8, v1, v5
	v_cvt_pk_bf16_f32 v12, v32, v13
	s_nop 0
	v_and_b32_e32 v5, 0xffff0000, v12
	v_lshlrev_b32_e32 v1, 16, v12
	v_sub_f32_e32 v5, v13, v5
	v_sub_f32_e32 v1, v32, v1
	v_cvt_pk_bf16_f32 v16, v1, v5
	v_cvt_pk_bf16_f32 v5, v17, v18
	s_nop 0
	v_and_b32_e32 v9, 0xffff0000, v5
	v_lshlrev_b32_e32 v1, 16, v5
	v_sub_f32_e32 v9, v18, v9
	v_sub_f32_e32 v1, v17, v1
	v_cvt_pk_bf16_f32 v9, v1, v9
	v_cvt_pk_bf16_f32 v13, v33, v19
	s_nop 0
	v_and_b32_e32 v17, 0xffff0000, v13
	v_sub_f32_e32 v17, v19, v17
	v_lshlrev_b64 v[18:19], 5, v[30:31]
	v_lshlrev_b32_e32 v1, 16, v13
	v_lshl_add_u64 v[26:27], s[0:1], 0, v[18:19]
	v_sub_f32_e32 v1, v33, v1
	v_cvt_pk_bf16_f32 v17, v1, v17
	global_store_dwordx4 v[26:27], v[2:5], off sc1
	v_lshlrev_b64 v[26:27], 5, v[34:35]
	s_nop 0
	v_lshl_add_u64 v[2:3], s[4:5], 0, v[18:19]
	global_store_dwordx4 v[2:3], v[6:9], off sc1
	v_lshl_add_u64 v[2:3], s[0:1], 0, v[26:27]
	global_store_dwordx4 v[2:3], v[10:13], off sc1
	v_lshl_add_u64 v[2:3], s[4:5], 0, v[26:27]
	global_store_dwordx4 v[2:3], v[14:17], off sc1
	global_load_dwordx4 v[2:5], v[24:25], off offset:32
	s_nop 0
	global_load_dwordx4 v[6:9], v[22:23], off offset:32
	global_load_dwordx4 v[10:13], v[24:25], off offset:48
	global_load_dwordx4 v[14:17], v[22:23], off offset:48
	v_or_b32_e32 v18, 16, v18
	v_or_b32_e32 v26, 16, v26
	s_waitcnt vmcnt(3)
	v_mov_b32_e32 v22, v2
	s_waitcnt vmcnt(2)
	v_mov_b32_e32 v23, v6
	v_pk_mul_f32 v[22:23], v[20:21], v[22:23]
	s_nop 0
	v_sub_f32_e32 v1, v23, v22
	v_mov_b32_e32 v22, v6
	v_mov_b32_e32 v23, v2
	v_mov_b32_e32 v2, v7
	v_pk_mul_f32 v[22:23], v[20:21], v[22:23]
	v_mov_b32_e32 v6, v3
	v_pk_mul_f32 v[2:3], v[20:21], v[2:3]
	v_add_f32_e32 v24, v22, v23
	v_pk_mul_f32 v[22:23], v[20:21], v[6:7]
	v_add_f32_e32 v7, v2, v3
	v_mov_b32_e32 v2, v4
	v_mov_b32_e32 v3, v8
	v_pk_mul_f32 v[2:3], v[20:21], v[2:3]
	v_sub_f32_e32 v6, v23, v22
	v_sub_f32_e32 v22, v3, v2
	v_mov_b32_e32 v2, v8
	v_mov_b32_e32 v3, v4
	v_pk_mul_f32 v[2:3], v[20:21], v[2:3]
	v_mov_b32_e32 v8, v5
	v_add_f32_e32 v23, v2, v3
	v_pk_mul_f32 v[2:3], v[20:21], v[8:9]
	v_mov_b32_e32 v4, v9
	v_sub_f32_e32 v8, v3, v2
	v_pk_mul_f32 v[2:3], v[20:21], v[4:5]
	s_nop 0
	v_add_f32_e32 v4, v2, v3
	s_waitcnt vmcnt(1)
	v_mov_b32_e32 v2, v10
	s_waitcnt vmcnt(0)
	v_mov_b32_e32 v3, v14
	v_pk_mul_f32 v[2:3], v[20:21], v[2:3]
	s_nop 0
	v_sub_f32_e32 v5, v3, v2
	v_mov_b32_e32 v2, v14
	v_mov_b32_e32 v3, v10
	v_pk_mul_f32 v[2:3], v[20:21], v[2:3]
	v_mov_b32_e32 v14, v11
	v_add_f32_e32 v9, v2, v3
	v_pk_mul_f32 v[2:3], v[20:21], v[14:15]
	v_mov_b32_e32 v10, v15
	v_sub_f32_e32 v25, v3, v2
	v_pk_mul_f32 v[2:3], v[20:21], v[10:11]
	s_nop 0
	v_add_f32_e32 v28, v2, v3
	v_mov_b32_e32 v2, v12
	v_mov_b32_e32 v3, v16
	v_pk_mul_f32 v[2:3], v[20:21], v[2:3]
	s_nop 0
	v_sub_f32_e32 v29, v3, v2
	v_mov_b32_e32 v2, v16
	v_mov_b32_e32 v3, v12
	v_pk_mul_f32 v[2:3], v[20:21], v[2:3]
	v_mov_b32_e32 v16, v13
	v_add_f32_e32 v30, v2, v3
	v_pk_mul_f32 v[2:3], v[20:21], v[16:17]
	v_mov_b32_e32 v12, v17
	v_sub_f32_e32 v31, v3, v2
	v_pk_mul_f32 v[2:3], v[20:21], v[12:13]
	s_nop 0
	v_add_f32_e32 v17, v2, v3
	v_cvt_pk_bf16_f32 v2, v1, v6
	s_nop 0
	v_lshlrev_b32_e32 v3, 16, v2
	v_sub_f32_e32 v1, v1, v3
	v_and_b32_e32 v3, 0xffff0000, v2
	v_sub_f32_e32 v3, v6, v3
	v_cvt_pk_bf16_f32 v6, v1, v3
	v_cvt_pk_bf16_f32 v10, v24, v7
	s_nop 0
	v_lshlrev_b32_e32 v1, 16, v10
	v_and_b32_e32 v3, 0xffff0000, v10
	v_sub_f32_e32 v1, v24, v1
	v_sub_f32_e32 v3, v7, v3
	v_cvt_pk_bf16_f32 v14, v1, v3
	v_cvt_pk_bf16_f32 v3, v22, v8
	s_nop 0
	v_lshlrev_b32_e32 v1, 16, v3
	v_and_b32_e32 v7, 0xffff0000, v3
	v_sub_f32_e32 v1, v22, v1
	v_sub_f32_e32 v7, v8, v7
	v_cvt_pk_bf16_f32 v7, v1, v7
	v_cvt_pk_bf16_f32 v11, v23, v4
	s_nop 0
	v_lshlrev_b32_e32 v1, 16, v11
	v_and_b32_e32 v8, 0xffff0000, v11
	v_sub_f32_e32 v1, v23, v1
	v_sub_f32_e32 v4, v4, v8
	v_cvt_pk_bf16_f32 v15, v1, v4
	v_cvt_pk_bf16_f32 v4, v5, v25
	s_nop 0
	v_lshlrev_b32_e32 v1, 16, v4
	v_sub_f32_e32 v1, v5, v1
	v_and_b32_e32 v5, 0xffff0000, v4
	v_sub_f32_e32 v5, v25, v5
	v_cvt_pk_bf16_f32 v8, v1, v5
	v_cvt_pk_bf16_f32 v12, v9, v28
	s_nop 0
	v_and_b32_e32 v5, 0xffff0000, v12
	v_lshlrev_b32_e32 v1, 16, v12
	v_sub_f32_e32 v5, v28, v5
	v_sub_f32_e32 v1, v9, v1
	v_cvt_pk_bf16_f32 v16, v1, v5
	v_cvt_pk_bf16_f32 v5, v29, v31
	s_nop 0
	v_and_b32_e32 v9, 0xffff0000, v5
	v_lshlrev_b32_e32 v1, 16, v5
	v_sub_f32_e32 v9, v31, v9
	v_sub_f32_e32 v1, v29, v1
	v_cvt_pk_bf16_f32 v9, v1, v9
	v_cvt_pk_bf16_f32 v13, v30, v17
	s_nop 0
	v_and_b32_e32 v20, 0xffff0000, v13
	v_lshlrev_b32_e32 v1, 16, v13
	v_sub_f32_e32 v17, v17, v20
	v_lshl_add_u64 v[20:21], s[0:1], 0, v[18:19]
	v_sub_f32_e32 v1, v30, v1
	v_cvt_pk_bf16_f32 v17, v1, v17
	global_store_dwordx4 v[20:21], v[2:5], off sc1
	s_nop 1
	v_lshl_add_u64 v[2:3], s[4:5], 0, v[18:19]
	global_store_dwordx4 v[2:3], v[6:9], off sc1
	v_lshl_add_u64 v[2:3], s[0:1], 0, v[26:27]
	global_store_dwordx4 v[2:3], v[10:13], off sc1
	v_lshl_add_u64 v[2:3], s[4:5], 0, v[26:27]
	global_store_dwordx4 v[2:3], v[14:17], off sc1
; __device__ __forceinline__ unsigned cvt_pk_bf16(float lo, float hi) { unsigned r; asm volatile("v_cvt_pk_bf16_f32 %0, %1, %2" : "=v"(r) : "v"(lo), "v"(hi)); return r; }
; __device__ __forceinline__ void ssm_ctable(int idx, const float* c_re, const float* c_im, bf16_t* CMH, bf16_t* CML) {
;     const int gh = idx >> 4, c8 = idx & 15; const float* src = (c8 < 8 ? c_re : c_im) + (size_t)gh * NS + (c8 & 7) * 8; const float sg = c8 < 8 ? 1.f : -1.f;
;     const f32x4 a = *(const f32x4*)src * sg, b = *(const f32x4*)(src + 4) * sg;
;     u32x4 h, l;
;     h.x = cvt_pk_bf16(a[0], a[1]); h.y = cvt_pk_bf16(a[2], a[3]); h.z = cvt_pk_bf16(b[0], b[1]); h.w = cvt_pk_bf16(b[2], b[3]);
;     l.x = cvt_pk_bf16(a[0] - bf_lo(h.x), a[1] - bf_hi(h.x)); l.y = cvt_pk_bf16(a[2] - bf_lo(h.y), a[3] - bf_hi(h.y)); l.z = cvt_pk_bf16(b[0] - bf_lo(h.z), b[1] - bf_hi(h.z)); l.w = cvt_pk_bf16(b[2] - bf_lo(h.w), b[3] - bf_hi(h.w));
;     *(u32x4*)(CMH + (size_t)gh * 128 + c8 * 8) = h; *(u32x4*)(CML + (size_t)gh * 128 + c8 * 8) = l;
; }
.LBB0_119:
	s_or_b64 exec, exec, s[10:11]
	s_movk_i32 s0, 0x2000
	v_cmp_gt_i32_e32 vcc, s0, v0
	s_and_saveexec_b64 s[0:1], vcc
	v_readlane_b32 s94, v249, 22
	v_readlane_b32 s95, v249, 23
	v_readlane_b32 s93, v249, 21
	v_readlane_b32 s96, v249, 20
	v_readlane_b32 s97, v249, 19
	s_cbranch_execz .LBB0_121
	v_readlane_b32 s48, v249, 2
	v_and_b32_e32 v1, 15, v197
	v_readlane_b32 s63, v249, 17
	v_mov_b32_e32 v3, s37
	v_readlane_b32 s62, v249, 16
	v_mov_b32_e32 v4, s63
	v_cmp_gt_u32_e32 vcc, 8, v1
	v_ashrrev_i32_e32 v2, 4, v0
	v_mov_b32_e32 v13, 0
	v_cndmask_b32_e32 v5, v3, v4, vcc
	v_mov_b32_e32 v3, s36
	v_mov_b32_e32 v4, s62
	v_cndmask_b32_e32 v4, v3, v4, vcc
	v_ashrrev_i32_e32 v3, 31, v2
	v_lshlrev_b64 v[10:11], 8, v[2:3]
	v_lshl_add_u64 v[2:3], v[4:5], 0, v[10:11]
	v_lshlrev_b32_e32 v4, 5, v197
	v_and_b32_e32 v12, 0xe0, v4
	v_lshl_add_u64 v[14:15], v[2:3], 0, v[12:13]
	global_load_dwordx4 v[2:5], v[14:15], off
	global_load_dwordx4 v[6:9], v[14:15], off offset:16
	v_lshl_add_u64 v[10:11], s[28:29], 0, v[10:11]
	v_lshlrev_b32_e32 v12, 4, v1
	v_lshl_add_u64 v[10:11], v[10:11], 0, v[12:13]
	v_cndmask_b32_e64 v14, -1.0, 1.0, vcc
	v_add_co_u32_e32 v12, vcc, 0x160000, v10
	v_readlane_b32 s49, v249, 3
	s_nop 0
	v_addc_co_u32_e32 v13, vcc, 0, v11, vcc
	v_add_co_u32_e32 v10, vcc, 0x190000, v10
	v_readlane_b32 s50, v249, 4
	s_nop 0
	v_addc_co_u32_e32 v11, vcc, 0, v11, vcc
	v_readlane_b32 s51, v249, 5
	v_readlane_b32 s52, v249, 6
	v_readlane_b32 s53, v249, 7
	v_readlane_b32 s54, v249, 8
	v_readlane_b32 s55, v249, 9
	v_readlane_b32 s56, v249, 10
	v_readlane_b32 s57, v249, 11
	v_readlane_b32 s58, v249, 12
	v_readlane_b32 s59, v249, 13
	v_readlane_b32 s60, v249, 14
	v_readlane_b32 s61, v249, 15
	s_waitcnt vmcnt(1)
	v_pk_mul_f32 v[16:17], v[14:15], v[4:5] op_sel_hi:[0,1]
	v_pk_mul_f32 v[18:19], v[14:15], v[2:3] op_sel_hi:[0,1]
	s_waitcnt vmcnt(0)
	v_pk_mul_f32 v[8:9], v[14:15], v[8:9] op_sel_hi:[0,1]
	v_pk_mul_f32 v[6:7], v[14:15], v[6:7] op_sel_hi:[0,1]
	v_cvt_pk_bf16_f32 v2, v18, v19
	v_cvt_pk_bf16_f32 v3, v16, v17
	v_cvt_pk_bf16_f32 v4, v6, v7
	v_cvt_pk_bf16_f32 v5, v8, v9
	s_nop 0
	v_and_b32_e32 v24, 0xffff0000, v5
	v_lshlrev_b32_e32 v1, 16, v2
	v_and_b32_e32 v14, 0xffff0000, v2
	v_lshlrev_b32_e32 v15, 16, v3
	v_and_b32_e32 v20, 0xffff0000, v3
	v_lshlrev_b32_e32 v21, 16, v4
	v_and_b32_e32 v22, 0xffff0000, v4
	v_lshlrev_b32_e32 v23, 16, v5
	v_sub_f32_e32 v9, v9, v24
	v_sub_f32_e32 v1, v18, v1
	v_sub_f32_e32 v14, v19, v14
	v_sub_f32_e32 v15, v16, v15
	v_sub_f32_e32 v16, v17, v20
	v_sub_f32_e32 v17, v6, v21
	v_sub_f32_e32 v18, v7, v22
	v_sub_f32_e32 v19, v8, v23
	v_cvt_pk_bf16_f32 v6, v1, v14
	v_cvt_pk_bf16_f32 v7, v15, v16
	v_cvt_pk_bf16_f32 v8, v17, v18
	v_cvt_pk_bf16_f32 v9, v19, v9
	global_store_dwordx4 v[12:13], v[2:5], off sc1
	global_store_dwordx4 v[10:11], v[6:9], off sc1

; #define LAS __attribute__((address_space(3)))
; __device__ __forceinline__ unsigned cvt_pk2(float lo, float hi) { f32x2c v = {lo, hi}; bf16x2c q = __builtin_convertvector(v, bf16x2c); return __builtin_bit_cast(unsigned, q); }
;     __device__ __forceinline__ void operator()(const f32x4 (&acc)[2][2][4][2], const pg8::Unit& u, int wr, int wc, int fr, int fq) const {
;         const int row0 = u.pm * 256 + wr * 64 + fr, col0 = u.pn * 128 + wc * 32 + 8 * fq;
;         const LAS float* rt = rt_.of(u.pm) + wr * 64 + fr;
; #pragma unroll
;         for (int ai = 0; ai < 2; ++ai)
; #pragma unroll
;             for (int m = 0; m < 4; ++m) { bf16_t* rowp = O + (size_t)(row0 + ai * 128 + m * 16) * FF + col0; const float r = rt[ai * 128 + m * 16];
;                 const float rl = -r * LOG2E, r2 = r * r; unsigned w[4];
; #pragma unroll
;                 for (int n = 0; n < 2; ++n)
; #pragma unroll
;                     for (int h = 0; h < 2; ++h) { const f32x2v g = {acc[ai][0][m][n][2 * h], acc[ai][0][m][n][2 * h + 1]}, uu = {acc[ai][1][m][n][2 * h], acc[ai][1][m][n][2 * h + 1]};
;                         const f32x2v t = g * rl; f32x2v d = {__builtin_amdgcn_exp2f(t.x), __builtin_amdgcn_exp2f(t.y)}; d = d + 1.0f;
;                         const f32x2v q = {__builtin_amdgcn_rcpf(d.x), __builtin_amdgcn_rcpf(d.y)}; const f32x2v o = ((g * uu) * r2) * q;
;                         w[2 * n + h] = cvt_pk2(o.x, o.y); }
;                 u32x4 wv; wv.x = w[0]; wv.y = w[1]; wv.z = w[2]; wv.w = w[3];
;                 *(u32x4*)rowp = wv; }
.LBB0_227:
	s_cmp_eq_u32 s34, s51
	s_cselect_b32 s13, s65, 0x300
	s_cmp_lg_u32 s34, s52
	s_cselect_b32 s13, s13, 0x100
	s_cmp_lg_u32 s34, s50
	s_cselect_b32 s13, s13, 0
	v_lshl_add_u32 v154, s13, 2, v148
	ds_read2_b32 v[200:201], v154 offset1:16
	ds_read2_b32 v[202:203], v154 offset0:32 offset1:48
	ds_read2_b32 v[204:205], v154 offset0:128 offset1:144
	ds_read2_b32 v[206:207], v154 offset0:160 offset1:176
	v_lshl_add_u32 v153, s34, 8, v146
	v_lshl_or_b32 v158, s67, 7, v149
	v_mov_b64_e32 v[178:179], s[40:41]
	s_mov_b32 s98, 0x1600
	v_lshlrev_b32_e32 v158, 1, v158
	v_mov_b32_e32 v159, 0
	v_mad_i64_i32 v[178:179], s[20:21], v153, s98, v[178:179]
	s_mov_b32 s98, 0x16000
	s_mov_b32 s99, 0
	s_mov_b32 s100, 0x6e000
	s_mov_b32 s101, 0
	v_lshl_add_u64 v[178:179], v[178:179], 0, v[158:159]
	s_waitcnt lgkmcnt(0)
	v_mul_f32_e32 v208, 0xbfb8aa3b, v200
	v_mul_f32_e32 v228, v200, v200
	v_mul_f32_e32 v210, 0xbfb8aa3b, v201
	v_mul_f32_e32 v230, v201, v201
	v_mul_f32_e32 v212, 0xbfb8aa3b, v202
	v_mul_f32_e32 v232, v202, v202
	v_mul_f32_e32 v214, 0xbfb8aa3b, v203
	v_mul_f32_e32 v234, v203, v203
	v_mul_f32_e32 v216, 0xbfb8aa3b, v204
	v_mul_f32_e32 v236, v204, v204
	v_mul_f32_e32 v218, 0xbfb8aa3b, v205
	v_mul_f32_e32 v238, v205, v205
	v_mul_f32_e32 v220, 0xbfb8aa3b, v206
	v_mul_f32_e32 v240, v206, v206
	v_mul_f32_e32 v222, 0xbfb8aa3b, v207
	v_mul_f32_e32 v242, v207, v207
	v_rcp_f32_e32 v228, v228
	v_rcp_f32_e32 v230, v230
	v_rcp_f32_e32 v232, v232
	v_rcp_f32_e32 v234, v234
	v_rcp_f32_e32 v236, v236
	v_rcp_f32_e32 v238, v238
	v_rcp_f32_e32 v240, v240
	v_rcp_f32_e32 v242, v242
	v_pk_mul_f32 v[154:155], v[124:125], v[208:209] op_sel_hi:[1,0]
	v_pk_mul_f32 v[156:157], v[126:127], v[208:209] op_sel_hi:[1,0]
	v_pk_mul_f32 v[158:159], v[116:117], v[208:209] op_sel_hi:[1,0]
	v_pk_mul_f32 v[160:161], v[118:119], v[208:209] op_sel_hi:[1,0]
	v_exp_f32_e32 v154, v154
	v_exp_f32_e32 v155, v155
	v_exp_f32_e32 v156, v156
	v_exp_f32_e32 v157, v157
	v_exp_f32_e32 v158, v158
	v_exp_f32_e32 v159, v159
	v_exp_f32_e32 v160, v160
	v_exp_f32_e32 v161, v161
	v_pk_mul_f32 v[162:163], v[108:109], v[210:211] op_sel_hi:[1,0]
	v_pk_mul_f32 v[164:165], v[110:111], v[210:211] op_sel_hi:[1,0]
	v_pk_mul_f32 v[166:167], v[100:101], v[210:211] op_sel_hi:[1,0]
	v_pk_mul_f32 v[168:169], v[102:103], v[210:211] op_sel_hi:[1,0]
	v_exp_f32_e32 v162, v162
	v_exp_f32_e32 v163, v163
	v_exp_f32_e32 v164, v164
	v_exp_f32_e32 v165, v165
	v_exp_f32_e32 v166, v166
	v_exp_f32_e32 v167, v167
	v_exp_f32_e32 v168, v168
	v_exp_f32_e32 v169, v169
	v_pk_mul_f32 v[120:121], v[124:125], v[120:121]
	v_pk_mul_f32 v[122:123], v[126:127], v[122:123]
	v_pk_mul_f32 v[112:113], v[116:117], v[112:113]
	v_pk_mul_f32 v[114:115], v[118:119], v[114:115]
	v_pk_fma_f32 v[154:155], v[154:155], v[228:229], v[228:229] op_sel_hi:[1,0,0]
	v_pk_fma_f32 v[156:157], v[156:157], v[228:229], v[228:229] op_sel_hi:[1,0,0]
	v_pk_fma_f32 v[158:159], v[158:159], v[228:229], v[228:229] op_sel_hi:[1,0,0]
	v_pk_fma_f32 v[160:161], v[160:161], v[228:229], v[228:229] op_sel_hi:[1,0,0]
	v_rcp_f32_e32 v154, v154
	v_rcp_f32_e32 v155, v155
	v_rcp_f32_e32 v156, v156
	v_rcp_f32_e32 v157, v157
	v_rcp_f32_e32 v158, v158
	v_rcp_f32_e32 v159, v159
	v_rcp_f32_e32 v160, v160
	v_rcp_f32_e32 v161, v161
	v_pk_mul_f32 v[170:171], v[92:93], v[212:213] op_sel_hi:[1,0]
	v_pk_mul_f32 v[172:173], v[94:95], v[212:213] op_sel_hi:[1,0]
	v_pk_mul_f32 v[174:175], v[84:85], v[212:213] op_sel_hi:[1,0]
	v_pk_mul_f32 v[176:177], v[86:87], v[212:213] op_sel_hi:[1,0]
	v_exp_f32_e32 v170, v170
	v_exp_f32_e32 v171, v171
	v_exp_f32_e32 v172, v172
	v_exp_f32_e32 v173, v173
	v_exp_f32_e32 v174, v174
	v_exp_f32_e32 v175, v175
	v_exp_f32_e32 v176, v176
	v_exp_f32_e32 v177, v177
	v_pk_mul_f32 v[104:105], v[108:109], v[104:105]
	v_pk_mul_f32 v[106:107], v[110:111], v[106:107]
	v_pk_mul_f32 v[96:97], v[100:101], v[96:97]
	v_pk_mul_f32 v[98:99], v[102:103], v[98:99]
	v_pk_fma_f32 v[162:163], v[162:163], v[230:231], v[230:231] op_sel_hi:[1,0,0]
	v_pk_fma_f32 v[164:165], v[164:165], v[230:231], v[230:231] op_sel_hi:[1,0,0]
	v_pk_fma_f32 v[166:167], v[166:167], v[230:231], v[230:231] op_sel_hi:[1,0,0]
	v_pk_fma_f32 v[168:169], v[168:169], v[230:231], v[230:231] op_sel_hi:[1,0,0]
	v_rcp_f32_e32 v162, v162
	v_rcp_f32_e32 v163, v163
	v_rcp_f32_e32 v164, v164
	v_rcp_f32_e32 v165, v165
	v_rcp_f32_e32 v166, v166
	v_rcp_f32_e32 v167, v167
	v_rcp_f32_e32 v168, v168
	v_rcp_f32_e32 v169, v169
	v_pk_mul_f32 v[120:121], v[120:121], v[154:155]
	v_pk_mul_f32 v[122:123], v[122:123], v[156:157]
	v_pk_mul_f32 v[112:113], v[112:113], v[158:159]
	v_pk_mul_f32 v[114:115], v[114:115], v[160:161]
	v_cvt_pk_bf16_f32 v154, v120, v121
	v_cvt_pk_bf16_f32 v155, v122, v123
	v_cvt_pk_bf16_f32 v156, v112, v113
	v_cvt_pk_bf16_f32 v157, v114, v115
	global_store_dwordx4 v[178:179], v[154:157], off sc1
	v_lshl_add_u64 v[178:179], v[178:179], 0, s[98:99]
	s_nop 1
	v_pk_mul_f32 v[154:155], v[76:77], v[214:215] op_sel_hi:[1,0]
	v_pk_mul_f32 v[156:157], v[78:79], v[214:215] op_sel_hi:[1,0]
	v_pk_mul_f32 v[158:159], v[68:69], v[214:215] op_sel_hi:[1,0]
	v_pk_mul_f32 v[160:161], v[70:71], v[214:215] op_sel_hi:[1,0]
	v_exp_f32_e32 v154, v154
	v_exp_f32_e32 v155, v155
	v_exp_f32_e32 v156, v156
	v_exp_f32_e32 v157, v157
	v_exp_f32_e32 v158, v158
	v_exp_f32_e32 v159, v159
	v_exp_f32_e32 v160, v160
	v_exp_f32_e32 v161, v161
	v_pk_mul_f32 v[88:89], v[92:93], v[88:89]
	v_pk_mul_f32 v[90:91], v[94:95], v[90:91]
	v_pk_mul_f32 v[80:81], v[84:85], v[80:81]
	v_pk_mul_f32 v[82:83], v[86:87], v[82:83]
	v_pk_fma_f32 v[170:171], v[170:171], v[232:233], v[232:233] op_sel_hi:[1,0,0]
	v_pk_fma_f32 v[172:173], v[172:173], v[232:233], v[232:233] op_sel_hi:[1,0,0]
; __device__ __forceinline__ unsigned cvt_pk2(float lo, float hi) { f32x2c v = {lo, hi}; bf16x2c q = __builtin_convertvector(v, bf16x2c); return __builtin_bit_cast(unsigned, q); }
;     __device__ __forceinline__ void operator()(const f32x4 (&acc)[2][2][4][2], const pg8::Unit& u, int wr, int wc, int fr, int fq) const {
;     ...
;             for (int m = 0; m < 4; ++m) { bf16_t* rowp = O + (size_t)(row0 + ai * 128 + m * 16) * FF + col0; const float r = rt[ai * 128 + m * 16];
;                 const float rl = -r * LOG2E, r2 = r * r; unsigned w[4];
; #pragma unroll
;                 for (int n = 0; n < 2; ++n)
; #pragma unroll
;                     for (int h = 0; h < 2; ++h) { const f32x2v g = {acc[ai][0][m][n][2 * h], acc[ai][0][m][n][2 * h + 1]}, uu = {acc[ai][1][m][n][2 * h], acc[ai][1][m][n][2 * h + 1]};
;                         const f32x2v t = g * rl; f32x2v d = {__builtin_amdgcn_exp2f(t.x), __builtin_amdgcn_exp2f(t.y)}; d = d + 1.0f;
;                         const f32x2v q = {__builtin_amdgcn_rcpf(d.x), __builtin_amdgcn_rcpf(d.y)}; const f32x2v o = ((g * uu) * r2) * q;
;                         w[2 * n + h] = cvt_pk2(o.x, o.y); }
;                 u32x4 wv; wv.x = w[0]; wv.y = w[1]; wv.z = w[2]; wv.w = w[3];
;                 *(u32x4*)rowp = wv; }
	v_pk_fma_f32 v[174:175], v[174:175], v[232:233], v[232:233] op_sel_hi:[1,0,0]
	v_pk_fma_f32 v[176:177], v[176:177], v[232:233], v[232:233] op_sel_hi:[1,0,0]
	v_rcp_f32_e32 v170, v170
	v_rcp_f32_e32 v171, v171
	v_rcp_f32_e32 v172, v172
	v_rcp_f32_e32 v173, v173
	v_rcp_f32_e32 v174, v174
	v_rcp_f32_e32 v175, v175
	v_rcp_f32_e32 v176, v176
	v_rcp_f32_e32 v177, v177
	v_pk_mul_f32 v[104:105], v[104:105], v[162:163]
	v_pk_mul_f32 v[106:107], v[106:107], v[164:165]
	v_pk_mul_f32 v[96:97], v[96:97], v[166:167]
	v_pk_mul_f32 v[98:99], v[98:99], v[168:169]
	v_cvt_pk_bf16_f32 v162, v104, v105
	v_cvt_pk_bf16_f32 v163, v106, v107
	v_cvt_pk_bf16_f32 v164, v96, v97
	v_cvt_pk_bf16_f32 v165, v98, v99
	global_store_dwordx4 v[178:179], v[162:165], off sc1
	v_lshl_add_u64 v[178:179], v[178:179], 0, s[98:99]
	s_nop 1
	v_pk_mul_f32 v[162:163], v[60:61], v[216:217] op_sel_hi:[1,0]
	v_pk_mul_f32 v[164:165], v[62:63], v[216:217] op_sel_hi:[1,0]
	v_pk_mul_f32 v[166:167], v[52:53], v[216:217] op_sel_hi:[1,0]
	v_pk_mul_f32 v[168:169], v[54:55], v[216:217] op_sel_hi:[1,0]
	v_exp_f32_e32 v162, v162
	v_exp_f32_e32 v163, v163
	v_exp_f32_e32 v164, v164
	v_exp_f32_e32 v165, v165
	v_exp_f32_e32 v166, v166
	v_exp_f32_e32 v167, v167
	v_exp_f32_e32 v168, v168
	v_exp_f32_e32 v169, v169
	v_pk_mul_f32 v[72:73], v[76:77], v[72:73]
	v_pk_mul_f32 v[74:75], v[78:79], v[74:75]
	v_pk_mul_f32 v[64:65], v[68:69], v[64:65]
	v_pk_mul_f32 v[66:67], v[70:71], v[66:67]
	v_pk_fma_f32 v[154:155], v[154:155], v[234:235], v[234:235] op_sel_hi:[1,0,0]
	v_pk_fma_f32 v[156:157], v[156:157], v[234:235], v[234:235] op_sel_hi:[1,0,0]
	v_pk_fma_f32 v[158:159], v[158:159], v[234:235], v[234:235] op_sel_hi:[1,0,0]
	v_pk_fma_f32 v[160:161], v[160:161], v[234:235], v[234:235] op_sel_hi:[1,0,0]
	v_rcp_f32_e32 v154, v154
	v_rcp_f32_e32 v155, v155
	v_rcp_f32_e32 v156, v156
	v_rcp_f32_e32 v157, v157
	v_rcp_f32_e32 v158, v158
	v_rcp_f32_e32 v159, v159
	v_rcp_f32_e32 v160, v160
	v_rcp_f32_e32 v161, v161
	v_pk_mul_f32 v[88:89], v[88:89], v[170:171]
	v_pk_mul_f32 v[90:91], v[90:91], v[172:173]
	v_pk_mul_f32 v[80:81], v[80:81], v[174:175]
	v_pk_mul_f32 v[82:83], v[82:83], v[176:177]
	v_cvt_pk_bf16_f32 v170, v88, v89
	v_cvt_pk_bf16_f32 v171, v90, v91
	v_cvt_pk_bf16_f32 v172, v80, v81
	v_cvt_pk_bf16_f32 v173, v82, v83
	global_store_dwordx4 v[178:179], v[170:173], off sc1
	v_lshl_add_u64 v[178:179], v[178:179], 0, s[98:99]
	s_nop 1
	v_pk_mul_f32 v[170:171], v[44:45], v[218:219] op_sel_hi:[1,0]
	v_pk_mul_f32 v[172:173], v[46:47], v[218:219] op_sel_hi:[1,0]
	v_pk_mul_f32 v[174:175], v[36:37], v[218:219] op_sel_hi:[1,0]
	v_pk_mul_f32 v[176:177], v[38:39], v[218:219] op_sel_hi:[1,0]
	v_exp_f32_e32 v170, v170
	v_exp_f32_e32 v171, v171
	v_exp_f32_e32 v172, v172
	v_exp_f32_e32 v173, v173
	v_exp_f32_e32 v174, v174
	v_exp_f32_e32 v175, v175
	v_exp_f32_e32 v176, v176
	v_exp_f32_e32 v177, v177
	v_pk_mul_f32 v[56:57], v[60:61], v[56:57]
	v_pk_mul_f32 v[58:59], v[62:63], v[58:59]
	v_pk_mul_f32 v[48:49], v[52:53], v[48:49]
	v_pk_mul_f32 v[50:51], v[54:55], v[50:51]
	v_pk_fma_f32 v[162:163], v[162:163], v[236:237], v[236:237] op_sel_hi:[1,0,0]
	v_pk_fma_f32 v[164:165], v[164:165], v[236:237], v[236:237] op_sel_hi:[1,0,0]
	v_pk_fma_f32 v[166:167], v[166:167], v[236:237], v[236:237] op_sel_hi:[1,0,0]
	v_pk_fma_f32 v[168:169], v[168:169], v[236:237], v[236:237] op_sel_hi:[1,0,0]
	v_rcp_f32_e32 v162, v162
	v_rcp_f32_e32 v163, v163
	v_rcp_f32_e32 v164, v164
	v_rcp_f32_e32 v165, v165
	v_rcp_f32_e32 v166, v166
	v_rcp_f32_e32 v167, v167
	v_rcp_f32_e32 v168, v168
	v_rcp_f32_e32 v169, v169
	v_pk_mul_f32 v[72:73], v[72:73], v[154:155]
	v_pk_mul_f32 v[74:75], v[74:75], v[156:157]
	v_pk_mul_f32 v[64:65], v[64:65], v[158:159]
	v_pk_mul_f32 v[66:67], v[66:67], v[160:161]
	v_cvt_pk_bf16_f32 v154, v72, v73
	v_cvt_pk_bf16_f32 v155, v74, v75
	v_cvt_pk_bf16_f32 v156, v64, v65
	v_cvt_pk_bf16_f32 v157, v66, v67
	global_store_dwordx4 v[178:179], v[154:157], off sc1
	v_lshl_add_u64 v[178:179], v[178:179], 0, s[100:101]
	s_nop 1
	v_pk_mul_f32 v[154:155], v[28:29], v[220:221] op_sel_hi:[1,0]
	v_pk_mul_f32 v[156:157], v[30:31], v[220:221] op_sel_hi:[1,0]
	v_pk_mul_f32 v[158:159], v[20:21], v[220:221] op_sel_hi:[1,0]
	v_pk_mul_f32 v[160:161], v[22:23], v[220:221] op_sel_hi:[1,0]
	v_exp_f32_e32 v154, v154
	v_exp_f32_e32 v155, v155
	v_exp_f32_e32 v156, v156
	v_exp_f32_e32 v157, v157
	v_exp_f32_e32 v158, v158
	v_exp_f32_e32 v159, v159
; #define PG8_BAR __builtin_amdgcn_s_barrier()
; __device__ __forceinline__ unsigned cvt_pk2(float lo, float hi) { f32x2c v = {lo, hi}; bf16x2c q = __builtin_convertvector(v, bf16x2c); return __builtin_bit_cast(unsigned, q); }
; template <class Epi, class Sched, bool ALIGN_EPI = false, bool SP2 = false>
; __device__ __forceinline__ void gemm_phase(PG8_LAS unsigned char* lds, const Gemm g, const Sched& S, const Epi& E) {
;     ...
;         if (!has_next) break;
; #pragma unroll
;         for (int a = 0; a < 2; ++a)
; #pragma unroll
;             for (int b = 0; b < 2; ++b)
; #pragma unroll
;                 for (int m = 0; m < 4; ++m)
; #pragma unroll
;                     for (int n = 0; n < 2; ++n) acc[a][b][m][n] = (f32x4){0.f, 0.f, 0.f, 0.f};
;         cur = nxt; cA = nA; cB = nB; ++ui;
;         if constexpr (ALIGN_EPI) { if (wr == 1) PG8_BAR; }
;     __device__ __forceinline__ void operator()(const f32x4 (&acc)[2][2][4][2], const pg8::Unit& u, int wr, int wc, int fr, int fq) const {
;     ...
;             for (int m = 0; m < 4; ++m) { bf16_t* rowp = O + (size_t)(row0 + ai * 128 + m * 16) * FF + col0; const float r = rt[ai * 128 + m * 16];
;                 const float rl = -r * LOG2E, r2 = r * r; unsigned w[4];
; #pragma unroll
;                 for (int n = 0; n < 2; ++n)
; #pragma unroll
;                     for (int h = 0; h < 2; ++h) { const f32x2v g = {acc[ai][0][m][n][2 * h], acc[ai][0][m][n][2 * h + 1]}, uu = {acc[ai][1][m][n][2 * h], acc[ai][1][m][n][2 * h + 1]};
;                         const f32x2v t = g * rl; f32x2v d = {__builtin_amdgcn_exp2f(t.x), __builtin_amdgcn_exp2f(t.y)}; d = d + 1.0f;
;                         const f32x2v q = {__builtin_amdgcn_rcpf(d.x), __builtin_amdgcn_rcpf(d.y)}; const f32x2v o = ((g * uu) * r2) * q;
;                         w[2 * n + h] = cvt_pk2(o.x, o.y); }
;                 u32x4 wv; wv.x = w[0]; wv.y = w[1]; wv.z = w[2]; wv.w = w[3];
;                 *(u32x4*)rowp = wv; }
	v_exp_f32_e32 v160, v160
	v_exp_f32_e32 v161, v161
	v_pk_mul_f32 v[40:41], v[44:45], v[40:41]
	v_pk_mul_f32 v[42:43], v[46:47], v[42:43]
	v_pk_mul_f32 v[32:33], v[36:37], v[32:33]
	v_pk_mul_f32 v[34:35], v[38:39], v[34:35]
	v_pk_fma_f32 v[170:171], v[170:171], v[238:239], v[238:239] op_sel_hi:[1,0,0]
	v_pk_fma_f32 v[172:173], v[172:173], v[238:239], v[238:239] op_sel_hi:[1,0,0]
	v_pk_fma_f32 v[174:175], v[174:175], v[238:239], v[238:239] op_sel_hi:[1,0,0]
	v_pk_fma_f32 v[176:177], v[176:177], v[238:239], v[238:239] op_sel_hi:[1,0,0]
	v_rcp_f32_e32 v170, v170
	v_rcp_f32_e32 v171, v171
	v_rcp_f32_e32 v172, v172
	v_rcp_f32_e32 v173, v173
	v_rcp_f32_e32 v174, v174
	v_rcp_f32_e32 v175, v175
	v_rcp_f32_e32 v176, v176
	v_rcp_f32_e32 v177, v177
	v_pk_mul_f32 v[56:57], v[56:57], v[162:163]
	v_pk_mul_f32 v[58:59], v[58:59], v[164:165]
	v_pk_mul_f32 v[48:49], v[48:49], v[166:167]
	v_pk_mul_f32 v[50:51], v[50:51], v[168:169]
	v_cvt_pk_bf16_f32 v162, v56, v57
	v_cvt_pk_bf16_f32 v163, v58, v59
	v_cvt_pk_bf16_f32 v164, v48, v49
	v_cvt_pk_bf16_f32 v165, v50, v51
	global_store_dwordx4 v[178:179], v[162:165], off sc1
	v_lshl_add_u64 v[178:179], v[178:179], 0, s[98:99]
	s_nop 1
	v_pk_mul_f32 v[162:163], v[12:13], v[222:223] op_sel_hi:[1,0]
	v_pk_mul_f32 v[164:165], v[14:15], v[222:223] op_sel_hi:[1,0]
	v_pk_mul_f32 v[166:167], v[4:5], v[222:223] op_sel_hi:[1,0]
	v_pk_mul_f32 v[168:169], v[6:7], v[222:223] op_sel_hi:[1,0]
	v_exp_f32_e32 v162, v162
	v_exp_f32_e32 v163, v163
	v_exp_f32_e32 v164, v164
	v_exp_f32_e32 v165, v165
	v_exp_f32_e32 v166, v166
	v_exp_f32_e32 v167, v167
	v_exp_f32_e32 v168, v168
	v_exp_f32_e32 v169, v169
	v_pk_mul_f32 v[24:25], v[28:29], v[24:25]
	v_pk_mul_f32 v[26:27], v[30:31], v[26:27]
	v_pk_mul_f32 v[16:17], v[20:21], v[16:17]
	v_pk_mul_f32 v[18:19], v[22:23], v[18:19]
	v_pk_fma_f32 v[154:155], v[154:155], v[240:241], v[240:241] op_sel_hi:[1,0,0]
	v_pk_fma_f32 v[156:157], v[156:157], v[240:241], v[240:241] op_sel_hi:[1,0,0]
	v_pk_fma_f32 v[158:159], v[158:159], v[240:241], v[240:241] op_sel_hi:[1,0,0]
	v_pk_fma_f32 v[160:161], v[160:161], v[240:241], v[240:241] op_sel_hi:[1,0,0]
	v_rcp_f32_e32 v154, v154
	v_rcp_f32_e32 v155, v155
	v_rcp_f32_e32 v156, v156
	v_rcp_f32_e32 v157, v157
	v_rcp_f32_e32 v158, v158
	v_rcp_f32_e32 v159, v159
	v_rcp_f32_e32 v160, v160
	v_rcp_f32_e32 v161, v161
	v_pk_mul_f32 v[40:41], v[40:41], v[170:171]
	v_pk_mul_f32 v[42:43], v[42:43], v[172:173]
	v_pk_mul_f32 v[32:33], v[32:33], v[174:175]
	v_pk_mul_f32 v[34:35], v[34:35], v[176:177]
	v_cvt_pk_bf16_f32 v170, v40, v41
	v_cvt_pk_bf16_f32 v171, v42, v43
	v_cvt_pk_bf16_f32 v172, v32, v33
	v_cvt_pk_bf16_f32 v173, v34, v35
	global_store_dwordx4 v[178:179], v[170:173], off sc1
	v_lshl_add_u64 v[178:179], v[178:179], 0, s[98:99]
	s_nop 1
	v_pk_mul_f32 v[8:9], v[12:13], v[8:9]
	v_pk_mul_f32 v[10:11], v[14:15], v[10:11]
	v_pk_mul_f32 v[0:1], v[4:5], v[0:1]
	v_pk_mul_f32 v[2:3], v[6:7], v[2:3]
	v_pk_fma_f32 v[162:163], v[162:163], v[242:243], v[242:243] op_sel_hi:[1,0,0]
	v_pk_fma_f32 v[164:165], v[164:165], v[242:243], v[242:243] op_sel_hi:[1,0,0]
	v_pk_fma_f32 v[166:167], v[166:167], v[242:243], v[242:243] op_sel_hi:[1,0,0]
	v_pk_fma_f32 v[168:169], v[168:169], v[242:243], v[242:243] op_sel_hi:[1,0,0]
	v_rcp_f32_e32 v162, v162
	v_rcp_f32_e32 v163, v163
	v_rcp_f32_e32 v164, v164
	v_rcp_f32_e32 v165, v165
	v_rcp_f32_e32 v166, v166
	v_rcp_f32_e32 v167, v167
	v_rcp_f32_e32 v168, v168
	v_rcp_f32_e32 v169, v169
	v_pk_mul_f32 v[24:25], v[24:25], v[154:155]
	v_pk_mul_f32 v[26:27], v[26:27], v[156:157]
	v_pk_mul_f32 v[16:17], v[16:17], v[158:159]
	v_pk_mul_f32 v[18:19], v[18:19], v[160:161]
	v_cvt_pk_bf16_f32 v154, v24, v25
	v_cvt_pk_bf16_f32 v155, v26, v27
	v_cvt_pk_bf16_f32 v156, v16, v17
	v_cvt_pk_bf16_f32 v157, v18, v19
	global_store_dwordx4 v[178:179], v[154:157], off sc1
	v_lshl_add_u64 v[178:179], v[178:179], 0, s[98:99]
	s_nop 1
	v_pk_mul_f32 v[8:9], v[8:9], v[162:163]
	v_pk_mul_f32 v[10:11], v[10:11], v[164:165]
	v_pk_mul_f32 v[0:1], v[0:1], v[166:167]
	v_pk_mul_f32 v[2:3], v[2:3], v[168:169]
	v_cvt_pk_bf16_f32 v162, v8, v9
	v_cvt_pk_bf16_f32 v163, v10, v11
	v_cvt_pk_bf16_f32 v164, v0, v1
	v_cvt_pk_bf16_f32 v165, v2, v3
	global_store_dwordx4 v[178:179], v[162:165], off sc1
	s_andn2_b64 vcc, exec, s[4:5]
	s_mov_b64 s[4:5], -1
	s_cbranch_vccnz .LBB0_220
	s_andn2_b64 vcc, exec, s[0:1]
	s_cbranch_vccnz .LBB0_219
	s_barrier
	s_branch .LBB0_219

; __device__ __forceinline__ unsigned cvt_pk_bf16(float lo, float hi) { unsigned r; asm volatile("v_cvt_pk_bf16_f32 %0, %1, %2" : "=v"(r) : "v"(lo), "v"(hi)); return r; }
;     __device__ __forceinline__ void operator()(const f32x4 (&acc)[2][2][4][2], const pg8::Unit& u, int wr, int wc, int fr, int fq) const {
;         const int row0 = u.pm * 256 + wr * 64 + fr, col0 = u.pn * 256 + wc * 32 + 8 * fq;
;         u32x4 xin[2][4][2];
; #pragma unroll
;         for (int ai = 0; ai < 2; ++ai)
; #pragma unroll
;             for (int m = 0; m < 4; ++m)
; #pragma unroll
;                 for (int bj = 0; bj < 2; ++bj) xin[ai][m][bj] = *(const u32x4*)(XB + (size_t)(row0 + ai * 128 + m * 16) * D + col0 + bj * 128);
; #pragma unroll
;         for (int ai = 0; ai < 2; ++ai)
; #pragma unroll
;             for (int m = 0; m < 4; ++m) { const size_t ro = (size_t)(row0 + ai * 128 + m * 16) * D + col0; float sq = 0.f;
; #pragma unroll
;                 for (int bj = 0; bj < 2; ++bj) { const u32x4 xb = xin[ai][m][bj];
;                     const f32x4 x0 = (f32x4){bf_lo(xb.x), bf_hi(xb.x), bf_lo(xb.y), bf_hi(xb.y)} + acc[ai][bj][m][0] * s, x1 = (f32x4){bf_lo(xb.z), bf_hi(xb.z), bf_lo(xb.w), bf_hi(xb.w)} + acc[ai][bj][m][1] * s;
;                     sq += (x0[0] * x0[0] + x0[1] * x0[1]) + (x0[2] * x0[2] + x0[3] * x0[3]) + (x1[0] * x1[0] + x1[1] * x1[1]) + (x1[2] * x1[2] + x1[3] * x1[3]);
;                     u32x4 w; w.x = cvt_pk_bf16(x0[0], x0[1]); w.y = cvt_pk_bf16(x0[2], x0[3]); w.z = cvt_pk_bf16(x1[0], x1[1]); w.w = cvt_pk_bf16(x1[2], x1[3]);
;                     *(u32x4*)(XB + ro + bj * 128) = w; }
;                 sq += __shfl_xor(sq, 16); sq += __shfl_xor(sq, 32);
;                 if (fq == 0) SSo[(size_t)(u.pn * 4 + wc) * T + row0 + ai * 128 + m * 16] = sq; }
;     }
.LBB0_312:
	v_lshl_or_b32 v204, s71, 8, v222
	v_lshl_add_u32 v202, s72, 8, v220
	v_ashrrev_i32_e32 v205, 31, v204
	v_lshlrev_b64 v[236:237], 1, v[204:205]
	v_ashrrev_i32_e32 v203, 31, v202
	v_lshl_add_u64 v[96:97], s[36:37], 0, v[236:237]
	v_lshlrev_b64 v[238:239], 11, v[202:203]
	v_lshl_add_u64 v[98:99], v[96:97], 0, v[238:239]
	global_load_dwordx4 v[228:231], v[98:99], off
	global_load_dwordx4 v[232:235], v[98:99], off offset:256
	v_or_b32_e32 v98, 16, v202
	v_or_b32_e32 v108, 32, v202
	v_or_b32_e32 v110, 48, v202
	v_ashrrev_i32_e32 v99, 31, v98
	v_ashrrev_i32_e32 v109, 31, v108
	v_ashrrev_i32_e32 v111, 31, v110
	v_lshlrev_b64 v[218:219], 11, v[98:99]
	v_lshlrev_b64 v[216:217], 11, v[108:109]
	v_lshlrev_b64 v[214:215], 11, v[110:111]
	v_lshl_add_u64 v[212:213], v[238:239], 0, s[16:17]
	v_lshl_add_u64 v[210:211], v[238:239], 0, s[18:19]
	v_lshl_add_u64 v[208:209], v[238:239], 0, s[42:43]
	v_lshl_add_u64 v[206:207], v[238:239], 0, s[46:47]
	v_lshl_add_u64 v[98:99], v[96:97], 0, v[218:219]
	v_lshl_add_u64 v[108:109], v[96:97], 0, v[216:217]
	v_lshl_add_u64 v[110:111], v[96:97], 0, v[214:215]
	v_lshl_add_u64 v[120:121], v[96:97], 0, v[212:213]
	v_lshl_add_u64 v[122:123], v[96:97], 0, v[210:211]
	v_lshl_add_u64 v[240:241], v[96:97], 0, v[208:209]
	v_lshl_add_u64 v[96:97], v[96:97], 0, v[206:207]
	global_load_dwordx4 v[180:183], v[98:99], off
	global_load_dwordx4 v[176:179], v[98:99], off offset:256
	global_load_dwordx4 v[172:175], v[108:109], off
	global_load_dwordx4 v[168:171], v[108:109], off offset:256
	global_load_dwordx4 v[164:167], v[110:111], off
	global_load_dwordx4 v[160:163], v[110:111], off offset:256
	global_load_dwordx4 v[156:159], v[120:121], off
	global_load_dwordx4 v[152:155], v[120:121], off offset:256
	global_load_dwordx4 v[148:151], v[122:123], off
	global_load_dwordx4 v[144:147], v[122:123], off offset:256
	global_load_dwordx4 v[128:131], v[240:241], off
	s_nop 0
	global_load_dwordx4 v[120:123], v[240:241], off offset:256
	global_load_dwordx4 v[108:111], v[96:97], off
	s_nop 0
	global_load_dwordx4 v[96:99], v[96:97], off offset:256
	s_lshl_b32 s20, s71, 2
	s_or_b32 s20, s20, s61
	s_ashr_i32 s21, s20, 31
	s_lshl_b64 s[20:21], s[20:21], 17
	s_waitcnt vmcnt(0)
	v_lshlrev_b32_e32 v240, 16, v228
	v_and_b32_e32 v241, 0xffff0000, v228
	v_lshlrev_b32_e32 v228, 16, v229
	v_and_b32_e32 v229, 0xffff0000, v229
	v_lshlrev_b32_e32 v242, 16, v230
	v_and_b32_e32 v243, 0xffff0000, v230
	v_lshlrev_b32_e32 v244, 16, v232
	v_and_b32_e32 v245, 0xffff0000, v232
	v_lshlrev_b32_e32 v232, 16, v233
	v_and_b32_e32 v233, 0xffff0000, v233
	v_lshlrev_b32_e32 v246, 16, v234
	v_and_b32_e32 v247, 0xffff0000, v234
	v_lshlrev_b32_e32 v234, 16, v235
	v_and_b32_e32 v235, 0xffff0000, v235
	v_pk_fma_f32 v[142:143], v[142:143], 0.5, v[228:229] op_sel_hi:[1,0,1]
	v_pk_fma_f32 v[140:141], v[140:141], 0.5, v[240:241] op_sel_hi:[1,0,1]
	v_lshlrev_b32_e32 v230, 16, v231
	v_and_b32_e32 v231, 0xffff0000, v231
	v_pk_fma_f32 v[136:137], v[136:137], 0.5, v[242:243] op_sel_hi:[1,0,1]
	v_pk_fma_f32 v[228:229], v[134:135], 0.5, v[232:233] op_sel_hi:[1,0,1]
	v_pk_fma_f32 v[232:233], v[126:127], 0.5, v[234:235] op_sel_hi:[1,0,1]
	v_pk_fma_f32 v[234:235], v[124:125], 0.5, v[246:247] op_sel_hi:[1,0,1]
	v_mul_f32_e32 v124, v141, v141
	v_mul_f32_e32 v125, v143, v143
	v_pk_fma_f32 v[138:139], v[138:139], 0.5, v[230:231] op_sel_hi:[1,0,1]
	v_pk_fma_f32 v[230:231], v[132:133], 0.5, v[244:245] op_sel_hi:[1,0,1]
	v_mul_f32_e32 v126, v137, v137
	v_fmac_f32_e32 v124, v140, v140
	v_fmac_f32_e32 v125, v142, v142
	v_mul_f32_e32 v127, v139, v139
	v_cvt_pk_bf16_f32 v132, v140, v141
	v_cvt_pk_bf16_f32 v133, v142, v143
	v_cvt_pk_bf16_f32 v134, v136, v137
	v_cvt_pk_bf16_f32 v135, v138, v139
	v_mul_f32_e32 v137, v231, v231
	v_mul_f32_e32 v139, v229, v229
	v_fmac_f32_e32 v126, v136, v136
	v_add_f32_e32 v124, v124, v125
	v_fmac_f32_e32 v137, v230, v230
	v_fmac_f32_e32 v139, v228, v228
	v_add_f32_e32 v124, v126, v124
	v_mul_f32_e32 v126, v235, v235
	v_add_f32_e32 v125, v137, v139
	v_fmac_f32_e32 v126, v234, v234
	v_add_f32_e32 v125, v126, v125
	v_mul_f32_e32 v126, v233, v233
	v_fmac_f32_e32 v127, v138, v138
	v_fmac_f32_e32 v126, v232, v232
	v_add_f32_e32 v124, v127, v124
	v_add_f32_e32 v125, v126, v125
	v_and_b32_e32 v126, 64, v226
	v_add_f32_e32 v125, v124, v125
	v_add_u32_e32 v138, 64, v126
	v_lshl_add_u64 v[126:127], s[36:37], 0, v[238:239]
	v_lshl_add_u64 v[136:137], v[126:127], 0, v[236:237]
	v_mov_b32_e32 v139, v125
	s_nop 1
	v_permlane16_swap_b32_e32 v139, v125
	global_store_dwordx4 v[136:137], v[132:135], off sc1
	s_waitcnt lgkmcnt(0)
	v_add_f32_e32 v126, v125, v139
	v_cvt_pk_bf16_f32 v132, v230, v231
	v_cvt_pk_bf16_f32 v133, v228, v229
	v_cvt_pk_bf16_f32 v134, v234, v235
	v_cvt_pk_bf16_f32 v135, v232, v233
	global_store_dwordx4 v[136:137], v[132:135], off offset:256 sc1
	s_nop 0
	v_mov_b32_e32 v127, v126
	s_nop 1
	v_permlane32_swap_b32_e32 v127, v126
	s_and_saveexec_b64 s[34:35], s[4:5]
	s_cbranch_execz .LBB0_314
	s_add_u32 s50, s59, s20
	s_addc_u32 s51, s60, s21
	v_lshl_add_u64 v[132:133], v[202:203], 2, s[50:51]
	s_waitcnt lgkmcnt(0)
	v_add_f32_e32 v126, v126, v127
	global_store_dword v[132:133], v126, off
; __device__ __forceinline__ unsigned cvt_pk_bf16(float lo, float hi) { unsigned r; asm volatile("v_cvt_pk_bf16_f32 %0, %1, %2" : "=v"(r) : "v"(lo), "v"(hi)); return r; }
;     __device__ __forceinline__ void operator()(const f32x4 (&acc)[2][2][4][2], const pg8::Unit& u, int wr, int wc, int fr, int fq) const {
;     ...
;             for (int m = 0; m < 4; ++m) { const size_t ro = (size_t)(row0 + ai * 128 + m * 16) * D + col0; float sq = 0.f;
; #pragma unroll
;                 for (int bj = 0; bj < 2; ++bj) { const u32x4 xb = xin[ai][m][bj];
;                     const f32x4 x0 = (f32x4){bf_lo(xb.x), bf_hi(xb.x), bf_lo(xb.y), bf_hi(xb.y)} + acc[ai][bj][m][0] * s, x1 = (f32x4){bf_lo(xb.z), bf_hi(xb.z), bf_lo(xb.w), bf_hi(xb.w)} + acc[ai][bj][m][1] * s;
;                     sq += (x0[0] * x0[0] + x0[1] * x0[1]) + (x0[2] * x0[2] + x0[3] * x0[3]) + (x1[0] * x1[0] + x1[1] * x1[1]) + (x1[2] * x1[2] + x1[3] * x1[3]);
;                     u32x4 w; w.x = cvt_pk_bf16(x0[0], x0[1]); w.y = cvt_pk_bf16(x0[2], x0[3]); w.z = cvt_pk_bf16(x1[0], x1[1]); w.w = cvt_pk_bf16(x1[2], x1[3]);
;                     *(u32x4*)(XB + ro + bj * 128) = w; }
;                 sq += __shfl_xor(sq, 16); sq += __shfl_xor(sq, 32);
;                 if (fq == 0) SSo[(size_t)(u.pn * 4 + wc) * T + row0 + ai * 128 + m * 16] = sq; }
.LBB0_314:
	s_or_b64 exec, exec, s[34:35]
	v_lshlrev_b32_e32 v126, 16, v180
	s_waitcnt lgkmcnt(0)
	v_and_b32_e32 v127, 0xffff0000, v180
	v_lshlrev_b32_e32 v132, 16, v181
	v_and_b32_e32 v133, 0xffff0000, v181
	v_pk_fma_f32 v[118:119], v[118:119], 0.5, v[132:133] op_sel_hi:[1,0,1]
	v_pk_fma_f32 v[116:117], v[116:117], 0.5, v[126:127] op_sel_hi:[1,0,1]
	v_lshlrev_b32_e32 v126, 16, v182
	v_and_b32_e32 v127, 0xffff0000, v182
	v_lshlrev_b32_e32 v132, 16, v183
	v_and_b32_e32 v133, 0xffff0000, v183
	v_pk_fma_f32 v[132:133], v[114:115], 0.5, v[132:133] op_sel_hi:[1,0,1]
	v_pk_fma_f32 v[114:115], v[112:113], 0.5, v[126:127] op_sel_hi:[1,0,1]
	v_mul_f32_e32 v112, v117, v117
	v_mul_f32_e32 v113, v119, v119
	v_fmac_f32_e32 v112, v116, v116
	v_fmac_f32_e32 v113, v118, v118
	v_add_f32_e32 v112, v112, v113
	v_mul_f32_e32 v113, v115, v115
	v_fmac_f32_e32 v113, v114, v114
	v_add_f32_e32 v112, v113, v112
	v_mul_f32_e32 v113, v133, v133
	v_fmac_f32_e32 v113, v132, v132
	v_add_f32_e32 v126, v113, v112
	v_cvt_pk_bf16_f32 v112, v116, v117
	v_cvt_pk_bf16_f32 v113, v118, v119
	v_lshlrev_b32_e32 v116, 16, v176
	v_and_b32_e32 v117, 0xffff0000, v176
	v_lshlrev_b32_e32 v118, 16, v177
	v_and_b32_e32 v119, 0xffff0000, v177
	v_pk_fma_f32 v[106:107], v[106:107], 0.5, v[118:119] op_sel_hi:[1,0,1]
	v_pk_fma_f32 v[104:105], v[104:105], 0.5, v[116:117] op_sel_hi:[1,0,1]
	v_lshlrev_b32_e32 v116, 16, v178
	v_and_b32_e32 v117, 0xffff0000, v178
	v_pk_fma_f32 v[116:117], v[100:101], 0.5, v[116:117] op_sel_hi:[1,0,1]
	v_mul_f32_e32 v100, v105, v105
	v_mul_f32_e32 v101, v107, v107
	v_fmac_f32_e32 v100, v104, v104
	v_fmac_f32_e32 v101, v106, v106
	v_lshlrev_b32_e32 v118, 16, v179
	v_and_b32_e32 v119, 0xffff0000, v179
	v_add_f32_e32 v100, v100, v101
	v_mul_f32_e32 v101, v117, v117
	v_pk_fma_f32 v[118:119], v[102:103], 0.5, v[118:119] op_sel_hi:[1,0,1]
	v_fmac_f32_e32 v101, v116, v116
	v_add_f32_e32 v100, v101, v100
	v_mul_f32_e32 v101, v119, v119
	v_fmac_f32_e32 v101, v118, v118
	v_add_f32_e32 v100, v101, v100
	v_add_f32_e32 v103, v126, v100
	v_cvt_pk_bf16_f32 v114, v114, v115
	v_cvt_pk_bf16_f32 v115, v132, v133
	v_mov_b32_e32 v132, v103
	s_nop 1
	v_permlane16_swap_b32_e32 v132, v103
	v_lshl_add_u64 v[100:101], s[36:37], 0, v[218:219]
	v_lshl_add_u64 v[126:127], v[204:205], 1, v[100:101]
	global_store_dwordx4 v[126:127], v[112:115], off sc1
	v_cvt_pk_bf16_f32 v102, v104, v105
	s_waitcnt lgkmcnt(0)
	v_add_f32_e32 v100, v103, v132
	v_mov_b32_e32 v101, v100
	s_nop 1
	v_permlane32_swap_b32_e32 v101, v100
	v_cvt_pk_bf16_f32 v103, v106, v107
	v_cvt_pk_bf16_f32 v104, v116, v117
	v_cvt_pk_bf16_f32 v105, v118, v119
	global_store_dwordx4 v[126:127], v[102:105], off offset:256 sc1
	s_and_saveexec_b64 s[34:35], s[4:5]
	s_cbranch_execz .LBB0_316
	s_add_u32 s50, s59, s20
	s_addc_u32 s51, s60, s21
	v_lshl_add_u64 v[102:103], v[202:203], 2, s[50:51]
	s_waitcnt lgkmcnt(0)
	v_add_f32_e32 v100, v100, v101
	global_store_dword v[102:103], v100, off offset:64
.LBB0_316:
	s_or_b64 exec, exec, s[34:35]
	v_lshlrev_b32_e32 v100, 16, v172
	s_waitcnt lgkmcnt(0)
	v_and_b32_e32 v101, 0xffff0000, v172
	v_lshlrev_b32_e32 v102, 16, v173
	v_and_b32_e32 v103, 0xffff0000, v173
	v_pk_fma_f32 v[94:95], v[94:95], 0.5, v[102:103] op_sel_hi:[1,0,1]
	v_pk_fma_f32 v[92:93], v[92:93], 0.5, v[100:101] op_sel_hi:[1,0,1]
	v_lshlrev_b32_e32 v100, 16, v174
	v_and_b32_e32 v101, 0xffff0000, v174
	v_lshlrev_b32_e32 v102, 16, v175
	v_and_b32_e32 v103, 0xffff0000, v175
	v_pk_fma_f32 v[102:103], v[90:91], 0.5, v[102:103] op_sel_hi:[1,0,1]
	v_pk_fma_f32 v[90:91], v[88:89], 0.5, v[100:101] op_sel_hi:[1,0,1]
	v_mul_f32_e32 v88, v93, v93
	v_mul_f32_e32 v89, v95, v95
	v_fmac_f32_e32 v88, v92, v92
	v_fmac_f32_e32 v89, v94, v94
	v_add_f32_e32 v88, v88, v89
	v_mul_f32_e32 v89, v91, v91
	v_fmac_f32_e32 v89, v90, v90
	v_add_f32_e32 v88, v89, v88
	v_mul_f32_e32 v89, v103, v103
	v_fmac_f32_e32 v89, v102, v102
	v_add_f32_e32 v100, v89, v88
	v_cvt_pk_bf16_f32 v88, v92, v93
	v_cvt_pk_bf16_f32 v89, v94, v95
	v_lshlrev_b32_e32 v92, 16, v168
	v_and_b32_e32 v93, 0xffff0000, v168
	v_lshlrev_b32_e32 v94, 16, v169
	v_and_b32_e32 v95, 0xffff0000, v169
	v_pk_fma_f32 v[86:87], v[86:87], 0.5, v[94:95] op_sel_hi:[1,0,1]
	v_pk_fma_f32 v[84:85], v[84:85], 0.5, v[92:93] op_sel_hi:[1,0,1]
	v_lshlrev_b32_e32 v92, 16, v170
	v_and_b32_e32 v93, 0xffff0000, v170
	v_pk_fma_f32 v[92:93], v[80:81], 0.5, v[92:93] op_sel_hi:[1,0,1]
	v_mul_f32_e32 v80, v85, v85
	v_mul_f32_e32 v81, v87, v87
	v_fmac_f32_e32 v80, v84, v84
	v_fmac_f32_e32 v81, v86, v86
	v_lshlrev_b32_e32 v94, 16, v171
	v_and_b32_e32 v95, 0xffff0000, v171
	v_add_f32_e32 v80, v80, v81
	v_mul_f32_e32 v81, v93, v93
	v_pk_fma_f32 v[94:95], v[82:83], 0.5, v[94:95] op_sel_hi:[1,0,1]
	v_fmac_f32_e32 v81, v92, v92
	v_add_f32_e32 v80, v81, v80
	v_mul_f32_e32 v81, v95, v95
	v_fmac_f32_e32 v81, v94, v94
	v_add_f32_e32 v80, v81, v80
	v_add_f32_e32 v83, v100, v80
	v_cvt_pk_bf16_f32 v90, v90, v91
	v_cvt_pk_bf16_f32 v91, v102, v103
	v_mov_b32_e32 v102, v83
	s_nop 1
	v_permlane16_swap_b32_e32 v102, v83
	v_lshl_add_u64 v[80:81], s[36:37], 0, v[216:217]
	v_lshl_add_u64 v[100:101], v[204:205], 1, v[80:81]
	global_store_dwordx4 v[100:101], v[88:91], off sc1
	v_cvt_pk_bf16_f32 v82, v84, v85
	s_waitcnt lgkmcnt(0)
	v_add_f32_e32 v80, v83, v102
	v_mov_b32_e32 v81, v80
	s_nop 1
	v_permlane32_swap_b32_e32 v81, v80
	v_cvt_pk_bf16_f32 v83, v86, v87
	v_cvt_pk_bf16_f32 v84, v92, v93
	v_cvt_pk_bf16_f32 v85, v94, v95
	global_store_dwordx4 v[100:101], v[82:85], off offset:256 sc1
	s_and_saveexec_b64 s[34:35], s[4:5]
	s_cbranch_execz .LBB0_318
	s_add_u32 s50, s59, s20
	s_addc_u32 s51, s60, s21
	v_lshl_add_u64 v[82:83], v[202:203], 2, s[50:51]
	s_waitcnt lgkmcnt(0)
	v_add_f32_e32 v80, v80, v81
	global_store_dword v[82:83], v80, off offset:128
; __device__ __forceinline__ unsigned cvt_pk_bf16(float lo, float hi) { unsigned r; asm volatile("v_cvt_pk_bf16_f32 %0, %1, %2" : "=v"(r) : "v"(lo), "v"(hi)); return r; }
;     __device__ __forceinline__ void operator()(const f32x4 (&acc)[2][2][4][2], const pg8::Unit& u, int wr, int wc, int fr, int fq) const {
;     ...
;             for (int m = 0; m < 4; ++m) { const size_t ro = (size_t)(row0 + ai * 128 + m * 16) * D + col0; float sq = 0.f;
; #pragma unroll
;                 for (int bj = 0; bj < 2; ++bj) { const u32x4 xb = xin[ai][m][bj];
;                     const f32x4 x0 = (f32x4){bf_lo(xb.x), bf_hi(xb.x), bf_lo(xb.y), bf_hi(xb.y)} + acc[ai][bj][m][0] * s, x1 = (f32x4){bf_lo(xb.z), bf_hi(xb.z), bf_lo(xb.w), bf_hi(xb.w)} + acc[ai][bj][m][1] * s;
;                     sq += (x0[0] * x0[0] + x0[1] * x0[1]) + (x0[2] * x0[2] + x0[3] * x0[3]) + (x1[0] * x1[0] + x1[1] * x1[1]) + (x1[2] * x1[2] + x1[3] * x1[3]);
;                     u32x4 w; w.x = cvt_pk_bf16(x0[0], x0[1]); w.y = cvt_pk_bf16(x0[2], x0[3]); w.z = cvt_pk_bf16(x1[0], x1[1]); w.w = cvt_pk_bf16(x1[2], x1[3]);
;                     *(u32x4*)(XB + ro + bj * 128) = w; }
;                 sq += __shfl_xor(sq, 16); sq += __shfl_xor(sq, 32);
;                 if (fq == 0) SSo[(size_t)(u.pn * 4 + wc) * T + row0 + ai * 128 + m * 16] = sq; }
.LBB0_318:
	s_or_b64 exec, exec, s[34:35]
	v_lshlrev_b32_e32 v80, 16, v164
	s_waitcnt lgkmcnt(0)
	v_and_b32_e32 v81, 0xffff0000, v164
	v_lshlrev_b32_e32 v82, 16, v165
	v_and_b32_e32 v83, 0xffff0000, v165
	v_pk_fma_f32 v[78:79], v[78:79], 0.5, v[82:83] op_sel_hi:[1,0,1]
	v_pk_fma_f32 v[76:77], v[76:77], 0.5, v[80:81] op_sel_hi:[1,0,1]
	v_lshlrev_b32_e32 v80, 16, v166
	v_and_b32_e32 v81, 0xffff0000, v166
	v_lshlrev_b32_e32 v82, 16, v167
	v_and_b32_e32 v83, 0xffff0000, v167
	v_pk_fma_f32 v[82:83], v[74:75], 0.5, v[82:83] op_sel_hi:[1,0,1]
	v_pk_fma_f32 v[74:75], v[72:73], 0.5, v[80:81] op_sel_hi:[1,0,1]
	v_mul_f32_e32 v72, v77, v77
	v_mul_f32_e32 v73, v79, v79
	v_fmac_f32_e32 v72, v76, v76
	v_fmac_f32_e32 v73, v78, v78
	v_add_f32_e32 v72, v72, v73
	v_mul_f32_e32 v73, v75, v75
	v_fmac_f32_e32 v73, v74, v74
	v_add_f32_e32 v72, v73, v72
	v_mul_f32_e32 v73, v83, v83
	v_fmac_f32_e32 v73, v82, v82
	v_add_f32_e32 v80, v73, v72
	v_cvt_pk_bf16_f32 v72, v76, v77
	v_cvt_pk_bf16_f32 v73, v78, v79
	v_lshlrev_b32_e32 v76, 16, v160
	v_and_b32_e32 v77, 0xffff0000, v160
	v_lshlrev_b32_e32 v78, 16, v161
	v_and_b32_e32 v79, 0xffff0000, v161
	v_pk_fma_f32 v[70:71], v[70:71], 0.5, v[78:79] op_sel_hi:[1,0,1]
	v_pk_fma_f32 v[68:69], v[68:69], 0.5, v[76:77] op_sel_hi:[1,0,1]
	v_lshlrev_b32_e32 v76, 16, v162
	v_and_b32_e32 v77, 0xffff0000, v162
	v_pk_fma_f32 v[76:77], v[64:65], 0.5, v[76:77] op_sel_hi:[1,0,1]
	v_mul_f32_e32 v64, v69, v69
	v_mul_f32_e32 v65, v71, v71
	v_fmac_f32_e32 v64, v68, v68
	v_fmac_f32_e32 v65, v70, v70
	v_lshlrev_b32_e32 v78, 16, v163
	v_and_b32_e32 v79, 0xffff0000, v163
	v_add_f32_e32 v64, v64, v65
	v_mul_f32_e32 v65, v77, v77
	v_pk_fma_f32 v[78:79], v[66:67], 0.5, v[78:79] op_sel_hi:[1,0,1]
	v_fmac_f32_e32 v65, v76, v76
	v_add_f32_e32 v64, v65, v64
	v_mul_f32_e32 v65, v79, v79
	v_fmac_f32_e32 v65, v78, v78
	v_add_f32_e32 v64, v65, v64
	v_add_f32_e32 v67, v80, v64
	v_cvt_pk_bf16_f32 v74, v74, v75
	v_cvt_pk_bf16_f32 v75, v82, v83
	v_mov_b32_e32 v82, v67
	s_nop 1
	v_permlane16_swap_b32_e32 v82, v67
	v_lshl_add_u64 v[64:65], s[36:37], 0, v[214:215]
	v_lshl_add_u64 v[80:81], v[204:205], 1, v[64:65]
	global_store_dwordx4 v[80:81], v[72:75], off sc1
	v_cvt_pk_bf16_f32 v66, v68, v69
	s_waitcnt lgkmcnt(0)
	v_add_f32_e32 v64, v67, v82
	v_mov_b32_e32 v65, v64
	s_nop 1
	v_permlane32_swap_b32_e32 v65, v64
	v_cvt_pk_bf16_f32 v67, v70, v71
	v_cvt_pk_bf16_f32 v68, v76, v77
	v_cvt_pk_bf16_f32 v69, v78, v79
	global_store_dwordx4 v[80:81], v[66:69], off offset:256 sc1
	s_and_saveexec_b64 s[34:35], s[4:5]
	s_cbranch_execz .LBB0_320
	s_add_u32 s50, s59, s20
	s_addc_u32 s51, s60, s21
	v_lshl_add_u64 v[66:67], v[202:203], 2, s[50:51]
	s_waitcnt lgkmcnt(0)
	v_add_f32_e32 v64, v64, v65
	global_store_dword v[66:67], v64, off offset:192
.LBB0_320:
	s_or_b64 exec, exec, s[34:35]
	v_lshlrev_b32_e32 v64, 16, v156
	s_waitcnt lgkmcnt(0)
	v_and_b32_e32 v65, 0xffff0000, v156
	v_lshlrev_b32_e32 v66, 16, v157
	v_and_b32_e32 v67, 0xffff0000, v157
	v_pk_fma_f32 v[62:63], v[62:63], 0.5, v[66:67] op_sel_hi:[1,0,1]
	v_pk_fma_f32 v[60:61], v[60:61], 0.5, v[64:65] op_sel_hi:[1,0,1]
	v_lshlrev_b32_e32 v64, 16, v158
	v_and_b32_e32 v65, 0xffff0000, v158
	v_lshlrev_b32_e32 v66, 16, v159
	v_and_b32_e32 v67, 0xffff0000, v159
	v_pk_fma_f32 v[66:67], v[58:59], 0.5, v[66:67] op_sel_hi:[1,0,1]
	v_pk_fma_f32 v[58:59], v[56:57], 0.5, v[64:65] op_sel_hi:[1,0,1]
	v_mul_f32_e32 v56, v61, v61
	v_mul_f32_e32 v57, v63, v63
	v_fmac_f32_e32 v56, v60, v60
	v_fmac_f32_e32 v57, v62, v62
	v_add_f32_e32 v56, v56, v57
	v_mul_f32_e32 v57, v59, v59
	v_fmac_f32_e32 v57, v58, v58
	v_add_f32_e32 v56, v57, v56
	v_mul_f32_e32 v57, v67, v67
	v_fmac_f32_e32 v57, v66, v66
	v_add_f32_e32 v64, v57, v56
	v_cvt_pk_bf16_f32 v56, v60, v61
	v_cvt_pk_bf16_f32 v57, v62, v63
	v_lshlrev_b32_e32 v60, 16, v152
	v_and_b32_e32 v61, 0xffff0000, v152
	v_lshlrev_b32_e32 v62, 16, v153
	v_and_b32_e32 v63, 0xffff0000, v153
	v_pk_fma_f32 v[54:55], v[54:55], 0.5, v[62:63] op_sel_hi:[1,0,1]
	v_pk_fma_f32 v[52:53], v[52:53], 0.5, v[60:61] op_sel_hi:[1,0,1]
	v_lshlrev_b32_e32 v60, 16, v154
	v_and_b32_e32 v61, 0xffff0000, v154
	v_pk_fma_f32 v[60:61], v[48:49], 0.5, v[60:61] op_sel_hi:[1,0,1]
	v_mul_f32_e32 v48, v53, v53
	v_mul_f32_e32 v49, v55, v55
	v_fmac_f32_e32 v48, v52, v52
	v_fmac_f32_e32 v49, v54, v54
	v_lshlrev_b32_e32 v62, 16, v155
	v_and_b32_e32 v63, 0xffff0000, v155
	v_add_f32_e32 v48, v48, v49
	v_mul_f32_e32 v49, v61, v61
	v_pk_fma_f32 v[62:63], v[50:51], 0.5, v[62:63] op_sel_hi:[1,0,1]
	v_fmac_f32_e32 v49, v60, v60
	v_add_f32_e32 v48, v49, v48
	v_mul_f32_e32 v49, v63, v63
	v_fmac_f32_e32 v49, v62, v62
	v_add_f32_e32 v48, v49, v48
	v_add_f32_e32 v51, v64, v48
	v_cvt_pk_bf16_f32 v58, v58, v59
	v_cvt_pk_bf16_f32 v59, v66, v67
	v_mov_b32_e32 v66, v51
	s_nop 1
	v_permlane16_swap_b32_e32 v66, v51
	v_lshl_add_u64 v[48:49], s[36:37], 0, v[212:213]
	v_lshl_add_u64 v[64:65], v[204:205], 1, v[48:49]
	global_store_dwordx4 v[64:65], v[56:59], off sc1
	v_cvt_pk_bf16_f32 v50, v52, v53
	s_waitcnt lgkmcnt(0)
	v_add_f32_e32 v48, v51, v66
	v_mov_b32_e32 v49, v48
	s_nop 1
	v_permlane32_swap_b32_e32 v49, v48
	v_cvt_pk_bf16_f32 v51, v54, v55
	v_cvt_pk_bf16_f32 v52, v60, v61
	v_cvt_pk_bf16_f32 v53, v62, v63
	global_store_dwordx4 v[64:65], v[50:53], off offset:256 sc1
	s_and_saveexec_b64 s[34:35], s[4:5]
	s_cbranch_execz .LBB0_322
	s_add_u32 s50, s59, s20
	s_addc_u32 s51, s60, s21
	v_lshl_add_u64 v[50:51], v[202:203], 2, s[50:51]
	s_waitcnt lgkmcnt(0)
	v_add_f32_e32 v48, v48, v49
	global_store_dword v[50:51], v48, off offset:512
; __device__ __forceinline__ unsigned cvt_pk_bf16(float lo, float hi) { unsigned r; asm volatile("v_cvt_pk_bf16_f32 %0, %1, %2" : "=v"(r) : "v"(lo), "v"(hi)); return r; }
;     __device__ __forceinline__ void operator()(const f32x4 (&acc)[2][2][4][2], const pg8::Unit& u, int wr, int wc, int fr, int fq) const {
;     ...
;             for (int m = 0; m < 4; ++m) { const size_t ro = (size_t)(row0 + ai * 128 + m * 16) * D + col0; float sq = 0.f;
; #pragma unroll
;                 for (int bj = 0; bj < 2; ++bj) { const u32x4 xb = xin[ai][m][bj];
;                     const f32x4 x0 = (f32x4){bf_lo(xb.x), bf_hi(xb.x), bf_lo(xb.y), bf_hi(xb.y)} + acc[ai][bj][m][0] * s, x1 = (f32x4){bf_lo(xb.z), bf_hi(xb.z), bf_lo(xb.w), bf_hi(xb.w)} + acc[ai][bj][m][1] * s;
;                     sq += (x0[0] * x0[0] + x0[1] * x0[1]) + (x0[2] * x0[2] + x0[3] * x0[3]) + (x1[0] * x1[0] + x1[1] * x1[1]) + (x1[2] * x1[2] + x1[3] * x1[3]);
;                     u32x4 w; w.x = cvt_pk_bf16(x0[0], x0[1]); w.y = cvt_pk_bf16(x0[2], x0[3]); w.z = cvt_pk_bf16(x1[0], x1[1]); w.w = cvt_pk_bf16(x1[2], x1[3]);
;                     *(u32x4*)(XB + ro + bj * 128) = w; }
;                 sq += __shfl_xor(sq, 16); sq += __shfl_xor(sq, 32);
;                 if (fq == 0) SSo[(size_t)(u.pn * 4 + wc) * T + row0 + ai * 128 + m * 16] = sq; }
.LBB0_322:
	s_or_b64 exec, exec, s[34:35]
	v_lshlrev_b32_e32 v48, 16, v148
	s_waitcnt lgkmcnt(0)
	v_and_b32_e32 v49, 0xffff0000, v148
	v_lshlrev_b32_e32 v50, 16, v149
	v_and_b32_e32 v51, 0xffff0000, v149
	v_pk_fma_f32 v[46:47], v[46:47], 0.5, v[50:51] op_sel_hi:[1,0,1]
	v_pk_fma_f32 v[44:45], v[44:45], 0.5, v[48:49] op_sel_hi:[1,0,1]
	v_lshlrev_b32_e32 v48, 16, v150
	v_and_b32_e32 v49, 0xffff0000, v150
	v_lshlrev_b32_e32 v50, 16, v151
	v_and_b32_e32 v51, 0xffff0000, v151
	v_pk_fma_f32 v[50:51], v[42:43], 0.5, v[50:51] op_sel_hi:[1,0,1]
	v_pk_fma_f32 v[42:43], v[40:41], 0.5, v[48:49] op_sel_hi:[1,0,1]
	v_mul_f32_e32 v40, v45, v45
	v_mul_f32_e32 v41, v47, v47
	v_fmac_f32_e32 v40, v44, v44
	v_fmac_f32_e32 v41, v46, v46
	v_add_f32_e32 v40, v40, v41
	v_mul_f32_e32 v41, v43, v43
	v_fmac_f32_e32 v41, v42, v42
	v_add_f32_e32 v40, v41, v40
	v_mul_f32_e32 v41, v51, v51
	v_fmac_f32_e32 v41, v50, v50
	v_add_f32_e32 v48, v41, v40
	v_cvt_pk_bf16_f32 v40, v44, v45
	v_cvt_pk_bf16_f32 v41, v46, v47
	v_lshlrev_b32_e32 v44, 16, v144
	v_and_b32_e32 v45, 0xffff0000, v144
	v_lshlrev_b32_e32 v46, 16, v145
	v_and_b32_e32 v47, 0xffff0000, v145
	v_pk_fma_f32 v[38:39], v[38:39], 0.5, v[46:47] op_sel_hi:[1,0,1]
	v_pk_fma_f32 v[36:37], v[36:37], 0.5, v[44:45] op_sel_hi:[1,0,1]
	v_lshlrev_b32_e32 v44, 16, v146
	v_and_b32_e32 v45, 0xffff0000, v146
	v_pk_fma_f32 v[44:45], v[32:33], 0.5, v[44:45] op_sel_hi:[1,0,1]
	v_mul_f32_e32 v32, v37, v37
	v_mul_f32_e32 v33, v39, v39
	v_fmac_f32_e32 v32, v36, v36
	v_fmac_f32_e32 v33, v38, v38
	v_lshlrev_b32_e32 v46, 16, v147
	v_and_b32_e32 v47, 0xffff0000, v147
	v_add_f32_e32 v32, v32, v33
	v_mul_f32_e32 v33, v45, v45
	v_pk_fma_f32 v[46:47], v[34:35], 0.5, v[46:47] op_sel_hi:[1,0,1]
	v_fmac_f32_e32 v33, v44, v44
	v_add_f32_e32 v32, v33, v32
	v_mul_f32_e32 v33, v47, v47
	v_fmac_f32_e32 v33, v46, v46
	v_add_f32_e32 v32, v33, v32
	v_add_f32_e32 v35, v48, v32
	v_cvt_pk_bf16_f32 v42, v42, v43
	v_cvt_pk_bf16_f32 v43, v50, v51
	v_mov_b32_e32 v50, v35
	s_nop 1
	v_permlane16_swap_b32_e32 v50, v35
	v_lshl_add_u64 v[32:33], s[36:37], 0, v[210:211]
	v_lshl_add_u64 v[48:49], v[204:205], 1, v[32:33]
	global_store_dwordx4 v[48:49], v[40:43], off sc1
	v_cvt_pk_bf16_f32 v34, v36, v37
	s_waitcnt lgkmcnt(0)
	v_add_f32_e32 v32, v35, v50
	v_mov_b32_e32 v33, v32
	s_nop 1
	v_permlane32_swap_b32_e32 v33, v32
	v_cvt_pk_bf16_f32 v35, v38, v39
	v_cvt_pk_bf16_f32 v36, v44, v45
	v_cvt_pk_bf16_f32 v37, v46, v47
	global_store_dwordx4 v[48:49], v[34:37], off offset:256 sc1
	s_and_saveexec_b64 s[34:35], s[4:5]
	s_cbranch_execz .LBB0_324
	s_add_u32 s50, s59, s20
	s_addc_u32 s51, s60, s21
	v_lshl_add_u64 v[34:35], v[202:203], 2, s[50:51]
	s_waitcnt lgkmcnt(0)
	v_add_f32_e32 v32, v32, v33
	global_store_dword v[34:35], v32, off offset:576
; __device__ __forceinline__ unsigned cvt_pk_bf16(float lo, float hi) { unsigned r; asm volatile("v_cvt_pk_bf16_f32 %0, %1, %2" : "=v"(r) : "v"(lo), "v"(hi)); return r; }
;     __device__ __forceinline__ void operator()(const f32x4 (&acc)[2][2][4][2], const pg8::Unit& u, int wr, int wc, int fr, int fq) const {
;     ...
;             for (int m = 0; m < 4; ++m) { const size_t ro = (size_t)(row0 + ai * 128 + m * 16) * D + col0; float sq = 0.f;
; #pragma unroll
;                 for (int bj = 0; bj < 2; ++bj) { const u32x4 xb = xin[ai][m][bj];
;                     const f32x4 x0 = (f32x4){bf_lo(xb.x), bf_hi(xb.x), bf_lo(xb.y), bf_hi(xb.y)} + acc[ai][bj][m][0] * s, x1 = (f32x4){bf_lo(xb.z), bf_hi(xb.z), bf_lo(xb.w), bf_hi(xb.w)} + acc[ai][bj][m][1] * s;
;                     sq += (x0[0] * x0[0] + x0[1] * x0[1]) + (x0[2] * x0[2] + x0[3] * x0[3]) + (x1[0] * x1[0] + x1[1] * x1[1]) + (x1[2] * x1[2] + x1[3] * x1[3]);
;                     u32x4 w; w.x = cvt_pk_bf16(x0[0], x0[1]); w.y = cvt_pk_bf16(x0[2], x0[3]); w.z = cvt_pk_bf16(x1[0], x1[1]); w.w = cvt_pk_bf16(x1[2], x1[3]);
;                     *(u32x4*)(XB + ro + bj * 128) = w; }
;                 sq += __shfl_xor(sq, 16); sq += __shfl_xor(sq, 32);
;                 if (fq == 0) SSo[(size_t)(u.pn * 4 + wc) * T + row0 + ai * 128 + m * 16] = sq; }
.LBB0_324:
	s_or_b64 exec, exec, s[34:35]
	v_lshlrev_b32_e32 v32, 16, v128
	s_waitcnt lgkmcnt(0)
	v_and_b32_e32 v33, 0xffff0000, v128
	v_lshlrev_b32_e32 v34, 16, v129
	v_and_b32_e32 v35, 0xffff0000, v129
	v_pk_fma_f32 v[30:31], v[30:31], 0.5, v[34:35] op_sel_hi:[1,0,1]
	v_pk_fma_f32 v[28:29], v[28:29], 0.5, v[32:33] op_sel_hi:[1,0,1]
	v_lshlrev_b32_e32 v32, 16, v130
	v_and_b32_e32 v33, 0xffff0000, v130
	v_lshlrev_b32_e32 v34, 16, v131
	v_and_b32_e32 v35, 0xffff0000, v131
	v_pk_fma_f32 v[34:35], v[26:27], 0.5, v[34:35] op_sel_hi:[1,0,1]
	v_pk_fma_f32 v[26:27], v[24:25], 0.5, v[32:33] op_sel_hi:[1,0,1]
	v_mul_f32_e32 v24, v29, v29
	v_mul_f32_e32 v25, v31, v31
	v_fmac_f32_e32 v24, v28, v28
	v_fmac_f32_e32 v25, v30, v30
	v_add_f32_e32 v24, v24, v25
	v_mul_f32_e32 v25, v27, v27
	v_fmac_f32_e32 v25, v26, v26
	v_add_f32_e32 v24, v25, v24
	v_mul_f32_e32 v25, v35, v35
	v_fmac_f32_e32 v25, v34, v34
	v_add_f32_e32 v32, v25, v24
	v_cvt_pk_bf16_f32 v24, v28, v29
	v_cvt_pk_bf16_f32 v25, v30, v31
	v_lshlrev_b32_e32 v28, 16, v120
	v_and_b32_e32 v29, 0xffff0000, v120
	v_lshlrev_b32_e32 v30, 16, v121
	v_and_b32_e32 v31, 0xffff0000, v121
	v_pk_fma_f32 v[22:23], v[22:23], 0.5, v[30:31] op_sel_hi:[1,0,1]
	v_pk_fma_f32 v[20:21], v[20:21], 0.5, v[28:29] op_sel_hi:[1,0,1]
	v_lshlrev_b32_e32 v28, 16, v122
	v_and_b32_e32 v29, 0xffff0000, v122
	v_pk_fma_f32 v[28:29], v[16:17], 0.5, v[28:29] op_sel_hi:[1,0,1]
	v_mul_f32_e32 v16, v21, v21
	v_mul_f32_e32 v17, v23, v23
	v_fmac_f32_e32 v16, v20, v20
	v_fmac_f32_e32 v17, v22, v22
	v_lshlrev_b32_e32 v30, 16, v123
	v_and_b32_e32 v31, 0xffff0000, v123
	v_add_f32_e32 v16, v16, v17
	v_mul_f32_e32 v17, v29, v29
	v_pk_fma_f32 v[30:31], v[18:19], 0.5, v[30:31] op_sel_hi:[1,0,1]
	v_fmac_f32_e32 v17, v28, v28
	v_add_f32_e32 v16, v17, v16
	v_mul_f32_e32 v17, v31, v31
	v_fmac_f32_e32 v17, v30, v30
	v_add_f32_e32 v16, v17, v16
	v_add_f32_e32 v19, v32, v16
	v_cvt_pk_bf16_f32 v26, v26, v27
	v_cvt_pk_bf16_f32 v27, v34, v35
	v_mov_b32_e32 v34, v19
	s_nop 1
	v_permlane16_swap_b32_e32 v34, v19
	v_lshl_add_u64 v[16:17], s[36:37], 0, v[208:209]
	v_lshl_add_u64 v[32:33], v[204:205], 1, v[16:17]
	global_store_dwordx4 v[32:33], v[24:27], off sc1
	v_cvt_pk_bf16_f32 v18, v20, v21
	s_waitcnt lgkmcnt(0)
	v_add_f32_e32 v16, v19, v34
	v_mov_b32_e32 v17, v16
	s_nop 1
	v_permlane32_swap_b32_e32 v17, v16
	v_cvt_pk_bf16_f32 v19, v22, v23
	v_cvt_pk_bf16_f32 v20, v28, v29
	v_cvt_pk_bf16_f32 v21, v30, v31
	global_store_dwordx4 v[32:33], v[18:21], off offset:256 sc1
	s_and_saveexec_b64 s[34:35], s[4:5]
	s_cbranch_execz .LBB0_326
	s_add_u32 s50, s59, s20
	s_addc_u32 s51, s60, s21
	v_lshl_add_u64 v[18:19], v[202:203], 2, s[50:51]
	s_waitcnt lgkmcnt(0)
	v_add_f32_e32 v16, v16, v17
	global_store_dword v[18:19], v16, off offset:640
.LBB0_326:
	s_or_b64 exec, exec, s[34:35]
	v_lshlrev_b32_e32 v16, 16, v108
	s_waitcnt lgkmcnt(0)
	v_and_b32_e32 v17, 0xffff0000, v108
	v_lshlrev_b32_e32 v18, 16, v109
	v_and_b32_e32 v19, 0xffff0000, v109
	v_pk_fma_f32 v[14:15], v[14:15], 0.5, v[18:19] op_sel_hi:[1,0,1]
	v_pk_fma_f32 v[12:13], v[12:13], 0.5, v[16:17] op_sel_hi:[1,0,1]
	v_lshlrev_b32_e32 v16, 16, v110
	v_and_b32_e32 v17, 0xffff0000, v110
	v_lshlrev_b32_e32 v18, 16, v111
	v_and_b32_e32 v19, 0xffff0000, v111
	v_pk_fma_f32 v[18:19], v[10:11], 0.5, v[18:19] op_sel_hi:[1,0,1]
	v_pk_fma_f32 v[10:11], v[8:9], 0.5, v[16:17] op_sel_hi:[1,0,1]
	v_mul_f32_e32 v8, v13, v13
	v_mul_f32_e32 v9, v15, v15
	v_fmac_f32_e32 v8, v12, v12
	v_fmac_f32_e32 v9, v14, v14
	v_add_f32_e32 v8, v8, v9
	v_mul_f32_e32 v9, v11, v11
	v_fmac_f32_e32 v9, v10, v10
	v_add_f32_e32 v8, v9, v8
	v_mul_f32_e32 v9, v19, v19
	v_fmac_f32_e32 v9, v18, v18
	v_add_f32_e32 v16, v9, v8
	v_cvt_pk_bf16_f32 v8, v12, v13
	v_cvt_pk_bf16_f32 v9, v14, v15
	v_lshlrev_b32_e32 v12, 16, v96
	v_and_b32_e32 v13, 0xffff0000, v96
	v_lshlrev_b32_e32 v14, 16, v97
	v_and_b32_e32 v15, 0xffff0000, v97
	v_pk_fma_f32 v[6:7], v[6:7], 0.5, v[14:15] op_sel_hi:[1,0,1]
	v_pk_fma_f32 v[4:5], v[4:5], 0.5, v[12:13] op_sel_hi:[1,0,1]
	v_lshlrev_b32_e32 v12, 16, v98
	v_and_b32_e32 v13, 0xffff0000, v98
	v_pk_fma_f32 v[12:13], v[0:1], 0.5, v[12:13] op_sel_hi:[1,0,1]
	v_mul_f32_e32 v0, v5, v5
	v_mul_f32_e32 v1, v7, v7
	v_fmac_f32_e32 v0, v4, v4
	v_fmac_f32_e32 v1, v6, v6
	v_lshlrev_b32_e32 v14, 16, v99
	v_and_b32_e32 v15, 0xffff0000, v99
	v_add_f32_e32 v0, v0, v1
	v_mul_f32_e32 v1, v13, v13
	v_pk_fma_f32 v[14:15], v[2:3], 0.5, v[14:15] op_sel_hi:[1,0,1]
	v_fmac_f32_e32 v1, v12, v12
	v_add_f32_e32 v0, v1, v0
	v_mul_f32_e32 v1, v15, v15
	v_fmac_f32_e32 v1, v14, v14
	v_add_f32_e32 v0, v1, v0
	v_add_f32_e32 v3, v16, v0
	v_cvt_pk_bf16_f32 v10, v10, v11
	v_cvt_pk_bf16_f32 v11, v18, v19
	v_mov_b32_e32 v18, v3
	s_nop 1
	v_permlane16_swap_b32_e32 v18, v3
	v_lshl_add_u64 v[0:1], s[36:37], 0, v[206:207]
	v_lshl_add_u64 v[16:17], v[204:205], 1, v[0:1]
	global_store_dwordx4 v[16:17], v[8:11], off sc1
	v_cvt_pk_bf16_f32 v2, v4, v5
	s_waitcnt lgkmcnt(0)
	v_add_f32_e32 v0, v3, v18
	v_mov_b32_e32 v1, v0
	s_nop 1
	v_permlane32_swap_b32_e32 v1, v0
	v_cvt_pk_bf16_f32 v3, v6, v7
	v_cvt_pk_bf16_f32 v4, v12, v13
	v_cvt_pk_bf16_f32 v5, v14, v15
	global_store_dwordx4 v[16:17], v[2:5], off offset:256 sc1
	s_and_saveexec_b64 s[34:35], s[4:5]
	s_cbranch_execz .LBB0_328
	s_add_u32 s20, s59, s20
	s_addc_u32 s21, s60, s21
	v_lshl_add_u64 v[2:3], v[202:203], 2, s[20:21]
	s_waitcnt lgkmcnt(0)
	v_add_f32_e32 v0, v0, v1
	global_store_dword v[2:3], v0, off offset:704

; __device__ __forceinline__ unsigned cvt_pk_bf16(float lo, float hi) { unsigned r; asm volatile("v_cvt_pk_bf16_f32 %0, %1, %2" : "=v"(r) : "v"(lo), "v"(hi)); return r; }
; #define LAS __attribute__((address_space(3)))
; __device__ __forceinline__ float fast_sigmoid(float x) { return __builtin_amdgcn_rcpf(1.f + __builtin_amdgcn_exp2f(-x * LOG2E)); }
;     __device__ __forceinline__ void operator()(const f32x4 (&acc)[2][2][4][2], const pg8::Unit& u, int wr, int wc, int fr, int fq) const {
;         const int row0 = u.pm * 256 + wr * 64 + fr; const LAS float* rt = rt_.of(u.pm) + wr * 64 + fr;
;         if (u.pn < 4) { const int col0 = u.pn * 128 + wc * 32 + 8 * fq;
; #pragma unroll
;             for (int ai = 0; ai < 2; ++ai)
; #pragma unroll
;                 for (int m = 0; m < 4; ++m) { bf16_t* rowp = VC + (size_t)(row0 + ai * 128 + m * 16) * CONVC + col0; const float r = rt[ai * 128 + m * 16];
;                     const f32x4 a0 = acc[ai][0][m][0] * r, a1 = acc[ai][0][m][1] * r, g0 = acc[ai][1][m][0] * r, g1 = acc[ai][1][m][1] * r;
;                     u32x4 w; w.x = cvt_pk_bf16(a0[0] * fast_sigmoid(g0[0]), a0[1] * fast_sigmoid(g0[1])); w.y = cvt_pk_bf16(a0[2] * fast_sigmoid(g0[2]), a0[3] * fast_sigmoid(g0[3]));
;                     w.z = cvt_pk_bf16(a1[0] * fast_sigmoid(g1[0]), a1[1] * fast_sigmoid(g1[1])); w.w = cvt_pk_bf16(a1[2] * fast_sigmoid(g1[2]), a1[3] * fast_sigmoid(g1[3]));
;                     *(u32x4*)rowp = w; }
;         } else { const int col0 = (u.pn - 4) * 256 + wc * 32 + 8 * fq;
; #pragma unroll
;             for (int ai = 0; ai < 2; ++ai)
; #pragma unroll
;                 for (int m = 0; m < 4; ++m) { bf16_t* rowp = US + (size_t)(row0 + ai * 128 + m * 16) * SSMW + col0; const float r = rt[ai * 128 + m * 16];
; #pragma unroll
;                     for (int bj = 0; bj < 2; ++bj) { const f32x4 v0 = acc[ai][bj][m][0] * r, v1 = acc[ai][bj][m][1] * r;
;                         u32x4 w; w.x = cvt_pk_bf16(v0[0], v0[1]); w.y = cvt_pk_bf16(v0[2], v0[3]); w.z = cvt_pk_bf16(v1[0], v1[1]); w.w = cvt_pk_bf16(v1[2], v1[3]);
;                         *(u32x4*)(rowp + bj * 128) = w; } }
.LBB0_417:
	s_cmp_eq_u32 s34, s59
	s_movk_i32 s19, 0x200
	s_cselect_b32 s19, s19, 0x300
	s_cmp_lg_u32 s34, s60
	s_cselect_b32 s19, s19, 0x100
	s_cmp_lg_u32 s34, s58
	s_cselect_b32 s19, s19, 0
	v_lshl_add_u32 v168, s19, 2, v164
	ds_read_b32 v154, v168
	v_lshl_add_u32 v146, s34, 8, v160
	v_ashrrev_i32_e32 v147, 31, v146
	s_cmp_gt_i32 s77, 3
	v_lshlrev_b64 v[148:149], 10, v[146:147]
	s_waitcnt lgkmcnt(0)
	v_mov_b32_e32 v155, v154
	v_pk_mul_f32 v[152:153], v[126:127], v[154:155] op_sel_hi:[1,0]
	v_pk_mul_f32 v[156:157], v[124:125], v[154:155] op_sel_hi:[1,0]
	v_pk_mul_f32 v[126:127], v[122:123], v[154:155] op_sel_hi:[1,0]
	v_pk_mul_f32 v[150:151], v[120:121], v[154:155] op_sel_hi:[1,0]
	v_or_b32_e32 v124, 16, v146
	v_or_b32_e32 v122, 32, v146
	v_or_b32_e32 v120, 48, v146
	s_mov_b64 s[20:21], -1
	v_pk_mul_f32 v[116:117], v[116:117], v[154:155]
	v_pk_mul_f32 v[112:113], v[112:113], v[154:155]
	v_ashrrev_i32_e32 v125, 31, v124
	v_ashrrev_i32_e32 v123, 31, v122
	v_ashrrev_i32_e32 v121, 31, v120
	s_cbranch_scc0 .LBB0_420
	v_lshl_add_u32 v136, s77, 8, v163
	v_lshl_add_u64 v[158:159], s[46:47], 0, v[148:149]
	v_lshlrev_b64 v[174:175], 1, v[136:137]
	v_lshl_add_u64 v[158:159], v[158:159], 0, v[174:175]
	v_cvt_pk_bf16_f32 v170, v156, v157
	v_cvt_pk_bf16_f32 v171, v152, v153
	v_cvt_pk_bf16_f32 v172, v150, v151
	v_cvt_pk_bf16_f32 v173, v126, v127
	v_mov_b32_e32 v155, v154
	global_store_dwordx4 v[158:159], v[170:173], off sc1
	v_pk_mul_f32 v[176:177], v[114:115], v[154:155]
	s_mov_b64 s[20:21], 0x20000
	v_pk_mul_f32 v[172:173], v[118:119], v[154:155]
	v_cvt_pk_bf16_f32 v170, v116, v117
	s_nop 0
	v_cvt_pk_bf16_f32 v171, v172, v173
	v_cvt_pk_bf16_f32 v172, v112, v113
	v_cvt_pk_bf16_f32 v173, v176, v177
	ds_read_b32 v136, v168 offset:64
	global_store_dwordx4 v[158:159], v[170:173], off offset:256 sc1
	s_waitcnt lgkmcnt(0)
	v_pk_mul_f32 v[178:179], v[106:107], v[136:137] op_sel_hi:[1,0]
	v_lshlrev_b64 v[170:171], 10, v[124:125]
	v_lshl_add_u64 v[170:171], s[46:47], 0, v[170:171]
	v_lshl_add_u64 v[176:177], v[170:171], 0, v[174:175]
	v_pk_mul_f32 v[172:173], v[110:111], v[136:137] op_sel_hi:[1,0]
	v_pk_mul_f32 v[170:171], v[108:109], v[136:137] op_sel_hi:[1,0]
	v_pk_mul_f32 v[180:181], v[104:105], v[136:137] op_sel_hi:[1,0]
	v_cvt_pk_bf16_f32 v170, v170, v171
	v_cvt_pk_bf16_f32 v171, v172, v173
	s_nop 0
	v_cvt_pk_bf16_f32 v172, v180, v181
	v_cvt_pk_bf16_f32 v173, v178, v179
	global_store_dwordx4 v[176:177], v[170:173], off sc1
	v_pk_mul_f32 v[178:179], v[98:99], v[136:137] op_sel_hi:[1,0]
	v_pk_mul_f32 v[180:181], v[96:97], v[136:137] op_sel_hi:[1,0]
	v_pk_mul_f32 v[172:173], v[102:103], v[136:137] op_sel_hi:[1,0]
	v_pk_mul_f32 v[170:171], v[100:101], v[136:137] op_sel_hi:[1,0]
	s_nop 0
	v_cvt_pk_bf16_f32 v170, v170, v171
	v_cvt_pk_bf16_f32 v171, v172, v173
	v_cvt_pk_bf16_f32 v172, v180, v181
	v_cvt_pk_bf16_f32 v173, v178, v179
	ds_read_b32 v136, v168 offset:128
	global_store_dwordx4 v[176:177], v[170:173], off offset:256 sc1
	s_waitcnt lgkmcnt(0)
	v_pk_mul_f32 v[178:179], v[90:91], v[136:137] op_sel_hi:[1,0]
	v_lshlrev_b64 v[170:171], 10, v[122:123]
	v_lshl_add_u64 v[170:171], s[46:47], 0, v[170:171]
	v_lshl_add_u64 v[176:177], v[170:171], 0, v[174:175]
	v_pk_mul_f32 v[172:173], v[94:95], v[136:137] op_sel_hi:[1,0]
	v_pk_mul_f32 v[170:171], v[92:93], v[136:137] op_sel_hi:[1,0]
	v_pk_mul_f32 v[180:181], v[88:89], v[136:137] op_sel_hi:[1,0]
	v_cvt_pk_bf16_f32 v170, v170, v171
	v_cvt_pk_bf16_f32 v171, v172, v173
	s_nop 0
	v_cvt_pk_bf16_f32 v172, v180, v181
	v_cvt_pk_bf16_f32 v173, v178, v179
	global_store_dwordx4 v[176:177], v[170:173], off sc1
	v_pk_mul_f32 v[178:179], v[82:83], v[136:137] op_sel_hi:[1,0]
	v_pk_mul_f32 v[180:181], v[80:81], v[136:137] op_sel_hi:[1,0]
	v_pk_mul_f32 v[172:173], v[86:87], v[136:137] op_sel_hi:[1,0]
	v_pk_mul_f32 v[170:171], v[84:85], v[136:137] op_sel_hi:[1,0]
	s_nop 0
	v_cvt_pk_bf16_f32 v170, v170, v171
	v_cvt_pk_bf16_f32 v171, v172, v173
	v_cvt_pk_bf16_f32 v172, v180, v181
	v_cvt_pk_bf16_f32 v173, v178, v179
	ds_read_b32 v136, v168 offset:192
	global_store_dwordx4 v[176:177], v[170:173], off offset:256 sc1
	s_waitcnt lgkmcnt(0)
	v_pk_mul_f32 v[176:177], v[74:75], v[136:137] op_sel_hi:[1,0]
	v_lshlrev_b64 v[170:171], 10, v[120:121]
	v_lshl_add_u64 v[170:171], s[46:47], 0, v[170:171]
	v_lshl_add_u64 v[174:175], v[170:171], 0, v[174:175]
	v_pk_mul_f32 v[172:173], v[78:79], v[136:137] op_sel_hi:[1,0]
	v_pk_mul_f32 v[170:171], v[76:77], v[136:137] op_sel_hi:[1,0]
	v_pk_mul_f32 v[178:179], v[72:73], v[136:137] op_sel_hi:[1,0]
	v_cvt_pk_bf16_f32 v170, v170, v171
	v_cvt_pk_bf16_f32 v171, v172, v173
	s_nop 0
	v_cvt_pk_bf16_f32 v172, v178, v179
	v_cvt_pk_bf16_f32 v173, v176, v177
	global_store_dwordx4 v[174:175], v[170:173], off sc1
	v_pk_mul_f32 v[176:177], v[66:67], v[136:137] op_sel_hi:[1,0]
	v_pk_mul_f32 v[178:179], v[64:65], v[136:137] op_sel_hi:[1,0]
	v_pk_mul_f32 v[172:173], v[70:71], v[136:137] op_sel_hi:[1,0]
	v_pk_mul_f32 v[170:171], v[68:69], v[136:137] op_sel_hi:[1,0]
	s_nop 0
	v_cvt_pk_bf16_f32 v170, v170, v171
	v_cvt_pk_bf16_f32 v171, v172, v173
	v_cvt_pk_bf16_f32 v172, v178, v179
	v_cvt_pk_bf16_f32 v173, v176, v177
	ds_read_b32 v136, v168 offset:512
	global_store_dwordx4 v[174:175], v[170:173], off offset:256 sc1
	s_waitcnt lgkmcnt(0)
; __device__ __forceinline__ unsigned cvt_pk_bf16(float lo, float hi) { unsigned r; asm volatile("v_cvt_pk_bf16_f32 %0, %1, %2" : "=v"(r) : "v"(lo), "v"(hi)); return r; }
;     __device__ __forceinline__ void operator()(const f32x4 (&acc)[2][2][4][2], const pg8::Unit& u, int wr, int wc, int fr, int fq) const {
;     ...
;                 for (int m = 0; m < 4; ++m) { bf16_t* rowp = US + (size_t)(row0 + ai * 128 + m * 16) * SSMW + col0; const float r = rt[ai * 128 + m * 16];
; #pragma unroll
;                     for (int bj = 0; bj < 2; ++bj) { const f32x4 v0 = acc[ai][bj][m][0] * r, v1 = acc[ai][bj][m][1] * r;
;                         u32x4 w; w.x = cvt_pk_bf16(v0[0], v0[1]); w.y = cvt_pk_bf16(v0[2], v0[3]); w.z = cvt_pk_bf16(v1[0], v1[1]); w.w = cvt_pk_bf16(v1[2], v1[3]);
;                         *(u32x4*)(rowp + bj * 128) = w; } }
	v_pk_mul_f32 v[174:175], v[58:59], v[136:137] op_sel_hi:[1,0]
	v_pk_mul_f32 v[172:173], v[62:63], v[136:137] op_sel_hi:[1,0]
	v_pk_mul_f32 v[170:171], v[60:61], v[136:137] op_sel_hi:[1,0]
	v_pk_mul_f32 v[176:177], v[56:57], v[136:137] op_sel_hi:[1,0]
	v_cvt_pk_bf16_f32 v170, v170, v171
	v_cvt_pk_bf16_f32 v171, v172, v173
	s_nop 0
	v_cvt_pk_bf16_f32 v172, v176, v177
	v_cvt_pk_bf16_f32 v173, v174, v175
	v_add_co_u32_e32 v174, vcc, s71, v158
	v_pk_mul_f32 v[176:177], v[48:49], v[136:137] op_sel_hi:[1,0]
	s_nop 0
	v_addc_co_u32_e32 v175, vcc, 0, v159, vcc
	global_store_dwordx4 v[174:175], v[170:173], off sc1
	v_pk_mul_f32 v[174:175], v[50:51], v[136:137] op_sel_hi:[1,0]
	s_nop 0
	v_pk_mul_f32 v[172:173], v[54:55], v[136:137] op_sel_hi:[1,0]
	v_pk_mul_f32 v[170:171], v[52:53], v[136:137] op_sel_hi:[1,0]
	s_nop 0
	v_cvt_pk_bf16_f32 v170, v170, v171
	v_cvt_pk_bf16_f32 v171, v172, v173
	v_cvt_pk_bf16_f32 v172, v176, v177
	v_cvt_pk_bf16_f32 v173, v174, v175
	ds_read_b32 v136, v168 offset:576
	v_lshl_add_u64 v[174:175], v[158:159], 0, s[20:21]
	global_store_dwordx4 v[174:175], v[170:173], off offset:256 sc1
	s_waitcnt lgkmcnt(0)
	v_pk_mul_f32 v[174:175], v[42:43], v[136:137] op_sel_hi:[1,0]
	v_pk_mul_f32 v[172:173], v[46:47], v[136:137] op_sel_hi:[1,0]
	v_pk_mul_f32 v[170:171], v[44:45], v[136:137] op_sel_hi:[1,0]
	v_pk_mul_f32 v[176:177], v[40:41], v[136:137] op_sel_hi:[1,0]
	v_cvt_pk_bf16_f32 v170, v170, v171
	v_cvt_pk_bf16_f32 v171, v172, v173
	s_nop 0
	v_cvt_pk_bf16_f32 v172, v176, v177
	v_cvt_pk_bf16_f32 v173, v174, v175
	v_add_co_u32_e32 v174, vcc, s74, v158
	v_pk_mul_f32 v[176:177], v[32:33], v[136:137] op_sel_hi:[1,0]
	s_nop 0
	v_addc_co_u32_e32 v175, vcc, 0, v159, vcc
	global_store_dwordx4 v[174:175], v[170:173], off sc1
	v_pk_mul_f32 v[174:175], v[34:35], v[136:137] op_sel_hi:[1,0]
	s_nop 0
	v_pk_mul_f32 v[172:173], v[38:39], v[136:137] op_sel_hi:[1,0]
	v_pk_mul_f32 v[170:171], v[36:37], v[136:137] op_sel_hi:[1,0]
	s_nop 0
	v_cvt_pk_bf16_f32 v170, v170, v171
	v_cvt_pk_bf16_f32 v171, v172, v173
	v_cvt_pk_bf16_f32 v172, v176, v177
	v_cvt_pk_bf16_f32 v173, v174, v175
	ds_read_b32 v136, v168 offset:640
	v_lshl_add_u64 v[174:175], v[158:159], 0, s[12:13]
	global_store_dwordx4 v[174:175], v[170:173], off offset:256 sc1
	s_waitcnt lgkmcnt(0)
	v_pk_mul_f32 v[174:175], v[26:27], v[136:137] op_sel_hi:[1,0]
	v_pk_mul_f32 v[172:173], v[30:31], v[136:137] op_sel_hi:[1,0]
	v_pk_mul_f32 v[170:171], v[28:29], v[136:137] op_sel_hi:[1,0]
	v_pk_mul_f32 v[176:177], v[24:25], v[136:137] op_sel_hi:[1,0]
	v_cvt_pk_bf16_f32 v170, v170, v171
	v_cvt_pk_bf16_f32 v171, v172, v173
	s_nop 0
	v_cvt_pk_bf16_f32 v172, v176, v177
	v_cvt_pk_bf16_f32 v173, v174, v175
	v_add_co_u32_e32 v174, vcc, s75, v158
	v_pk_mul_f32 v[176:177], v[16:17], v[136:137] op_sel_hi:[1,0]
	s_nop 0
	v_addc_co_u32_e32 v175, vcc, 0, v159, vcc
	global_store_dwordx4 v[174:175], v[170:173], off sc1
	v_pk_mul_f32 v[174:175], v[18:19], v[136:137] op_sel_hi:[1,0]
	s_nop 0
	v_pk_mul_f32 v[172:173], v[22:23], v[136:137] op_sel_hi:[1,0]
	v_pk_mul_f32 v[170:171], v[20:21], v[136:137] op_sel_hi:[1,0]
	s_nop 0
	v_cvt_pk_bf16_f32 v170, v170, v171
	v_cvt_pk_bf16_f32 v171, v172, v173
	v_cvt_pk_bf16_f32 v172, v176, v177
	v_cvt_pk_bf16_f32 v173, v174, v175
	ds_read_b32 v136, v168 offset:704
	v_lshl_add_u64 v[174:175], v[158:159], 0, s[14:15]
	global_store_dwordx4 v[174:175], v[170:173], off offset:256 sc1
	v_lshl_add_u64 v[174:175], v[158:159], 0, s[16:17]
	v_add_co_u32_e32 v158, vcc, s76, v158
	s_waitcnt lgkmcnt(0)
	v_pk_mul_f32 v[172:173], v[14:15], v[136:137] op_sel_hi:[1,0]
	v_pk_mul_f32 v[170:171], v[12:13], v[136:137] op_sel_hi:[1,0]
	v_pk_mul_f32 v[176:177], v[10:11], v[136:137] op_sel_hi:[1,0]
	v_pk_mul_f32 v[178:179], v[8:9], v[136:137] op_sel_hi:[1,0]
	v_cvt_pk_bf16_f32 v170, v170, v171
	v_cvt_pk_bf16_f32 v171, v172, v173
	v_addc_co_u32_e32 v159, vcc, 0, v159, vcc
	v_cvt_pk_bf16_f32 v172, v178, v179
	v_cvt_pk_bf16_f32 v173, v176, v177
	global_store_dwordx4 v[158:159], v[170:173], off sc1
	v_pk_mul_f32 v[158:159], v[6:7], v[136:137] op_sel_hi:[1,0]
	v_pk_mul_f32 v[176:177], v[2:3], v[136:137] op_sel_hi:[1,0]
	v_pk_mul_f32 v[170:171], v[4:5], v[136:137] op_sel_hi:[1,0]
	v_pk_mul_f32 v[172:173], v[0:1], v[136:137] op_sel_hi:[1,0]
	v_cvt_pk_bf16_f32 v170, v170, v171
	v_cvt_pk_bf16_f32 v171, v158, v159
	s_nop 0
	v_cvt_pk_bf16_f32 v172, v172, v173
	v_cvt_pk_bf16_f32 v173, v176, v177
	global_store_dwordx4 v[174:175], v[170:173], off offset:256 sc1
	s_cbranch_execz .LBB0_421

; __device__ __forceinline__ unsigned cvt_pk_bf16(float lo, float hi) { unsigned r; asm volatile("v_cvt_pk_bf16_f32 %0, %1, %2" : "=v"(r) : "v"(lo), "v"(hi)); return r; }
; __device__ __forceinline__ float fast_sigmoid(float x) { return __builtin_amdgcn_rcpf(1.f + __builtin_amdgcn_exp2f(-x * LOG2E)); }
;     __device__ __forceinline__ void operator()(const f32x4 (&acc)[2][2][4][2], const pg8::Unit& u, int wr, int wc, int fr, int fq) const {
;     ...
;         if (u.pn < 4) { const int col0 = u.pn * 128 + wc * 32 + 8 * fq;
; #pragma unroll
;             for (int ai = 0; ai < 2; ++ai)
; #pragma unroll
;                 for (int m = 0; m < 4; ++m) { bf16_t* rowp = VC + (size_t)(row0 + ai * 128 + m * 16) * CONVC + col0; const float r = rt[ai * 128 + m * 16];
;                     const f32x4 a0 = acc[ai][0][m][0] * r, a1 = acc[ai][0][m][1] * r, g0 = acc[ai][1][m][0] * r, g1 = acc[ai][1][m][1] * r;
;                     u32x4 w; w.x = cvt_pk_bf16(a0[0] * fast_sigmoid(g0[0]), a0[1] * fast_sigmoid(g0[1])); w.y = cvt_pk_bf16(a0[2] * fast_sigmoid(g0[2]), a0[3] * fast_sigmoid(g0[3]));
;                     w.z = cvt_pk_bf16(a1[0] * fast_sigmoid(g1[0]), a1[1] * fast_sigmoid(g1[1])); w.w = cvt_pk_bf16(a1[2] * fast_sigmoid(g1[2]), a1[3] * fast_sigmoid(g1[3]));
;                     *(u32x4*)rowp = w; }
.LBB0_421:
	v_mul_f32_e32 v116, 0xbfb8aa3b, v116
	v_exp_f32_e32 v136, v116
	v_mul_f32_e32 v116, 0xbfb8aa3b, v117
	v_exp_f32_e32 v169, v116
	v_mov_b32_e32 v155, v154
	v_pk_mul_f32 v[118:119], v[118:119], v[154:155]
	v_pk_mul_f32 v[116:117], v[114:115], v[154:155]
	v_add_f32_e32 v114, 1.0, v136
	v_add_f32_e32 v115, 1.0, v169
	v_rcp_f32_e32 v114, v114
	v_rcp_f32_e32 v115, v115
	v_mul_f32_e32 v118, 0xbfb8aa3b, v118
	v_exp_f32_e32 v118, v118
	v_mul_f32_e32 v114, v156, v114
	v_mul_f32_e32 v115, v157, v115
	v_cvt_pk_bf16_f32 v114, v114, v115
	v_add_f32_e32 v115, 1.0, v118
	v_mul_f32_e32 v118, 0xbfb8aa3b, v119
	v_exp_f32_e32 v118, v118
	v_mul_f32_e32 v112, 0xbfb8aa3b, v112
	v_mul_f32_e32 v113, 0xbfb8aa3b, v113
	v_mul_f32_e32 v116, 0xbfb8aa3b, v116
	v_add_f32_e32 v118, 1.0, v118
	v_rcp_f32_e32 v115, v115
	v_exp_f32_e32 v112, v112
	v_rcp_f32_e32 v118, v118
	v_exp_f32_e32 v113, v113
	v_exp_f32_e32 v116, v116
	v_mul_f32_e32 v117, 0xbfb8aa3b, v117
	v_exp_f32_e32 v117, v117
	v_mul_f32_e32 v115, v152, v115
	v_add_f32_e32 v112, 1.0, v112
	v_mul_f32_e32 v118, v153, v118
	v_add_f32_e32 v113, 1.0, v113
	v_add_f32_e32 v116, 1.0, v116
	v_rcp_f32_e32 v112, v112
	v_cvt_pk_bf16_f32 v115, v115, v118
	v_rcp_f32_e32 v113, v113
	v_rcp_f32_e32 v118, v116
	v_add_f32_e32 v116, 1.0, v117
	v_rcp_f32_e32 v117, v116
	v_mul_f32_e32 v112, v150, v112
	v_mul_f32_e32 v113, v151, v113
	v_cvt_pk_bf16_f32 v116, v112, v113
	v_mul_f32_e32 v112, v126, v118
	v_mul_f32_e32 v113, v127, v117
	v_cvt_pk_bf16_f32 v117, v112, v113
	ds_read_b32 v118, v168 offset:64
	v_lshl_or_b32 v158, s77, 7, v162
	v_ashrrev_i32_e32 v159, 31, v158
	v_lshl_add_u64 v[126:127], s[40:41], 0, v[148:149]
	v_lshlrev_b64 v[112:113], 1, v[158:159]
	s_waitcnt lgkmcnt(0)
	v_pk_mul_f32 v[100:101], v[100:101], v[118:119] op_sel_hi:[1,0]
	v_lshl_add_u64 v[126:127], v[126:127], 0, v[112:113]
	v_mul_f32_e32 v100, 0xbfb8aa3b, v100
	global_store_dwordx4 v[126:127], v[114:117], off sc1
	v_pk_mul_f32 v[102:103], v[102:103], v[118:119] op_sel_hi:[1,0]
	v_pk_mul_f32 v[108:109], v[108:109], v[118:119] op_sel_hi:[1,0]
	v_exp_f32_e32 v114, v100
	v_mul_f32_e32 v100, 0xbfb8aa3b, v101
	v_exp_f32_e32 v115, v100
	v_pk_mul_f32 v[100:101], v[96:97], v[118:119] op_sel_hi:[1,0]
	v_add_f32_e32 v96, 1.0, v114
	v_rcp_f32_e32 v96, v96
	v_add_f32_e32 v97, 1.0, v115
	v_rcp_f32_e32 v97, v97
	v_mul_f32_e32 v102, 0xbfb8aa3b, v102
	v_exp_f32_e32 v102, v102
	v_mul_f32_e32 v96, v108, v96
	v_mul_f32_e32 v97, v109, v97
	v_cvt_pk_bf16_f32 v96, v96, v97
	v_add_f32_e32 v97, 1.0, v102
	v_mul_f32_e32 v102, 0xbfb8aa3b, v103
	v_exp_f32_e32 v102, v102
	v_pk_mul_f32 v[98:99], v[98:99], v[118:119] op_sel_hi:[1,0]
	v_mul_f32_e32 v100, 0xbfb8aa3b, v100
	v_mul_f32_e32 v101, 0xbfb8aa3b, v101
	v_add_f32_e32 v102, 1.0, v102
	v_mul_f32_e32 v98, 0xbfb8aa3b, v98
	v_rcp_f32_e32 v97, v97
	v_exp_f32_e32 v100, v100
	v_rcp_f32_e32 v102, v102
	v_exp_f32_e32 v101, v101
	v_exp_f32_e32 v98, v98
	v_mul_f32_e32 v99, 0xbfb8aa3b, v99
	v_exp_f32_e32 v99, v99
	v_pk_mul_f32 v[110:111], v[110:111], v[118:119] op_sel_hi:[1,0]
	v_add_f32_e32 v100, 1.0, v100
	v_mul_f32_e32 v97, v110, v97
	v_mul_f32_e32 v102, v111, v102
	v_add_f32_e32 v101, 1.0, v101
	v_add_f32_e32 v98, 1.0, v98
	v_rcp_f32_e32 v100, v100
	v_cvt_pk_bf16_f32 v97, v97, v102
	v_rcp_f32_e32 v101, v101
	v_rcp_f32_e32 v102, v98
	v_add_f32_e32 v98, 1.0, v99
	v_rcp_f32_e32 v99, v98
	v_pk_mul_f32 v[104:105], v[104:105], v[118:119] op_sel_hi:[1,0]
	v_pk_mul_f32 v[106:107], v[106:107], v[118:119] op_sel_hi:[1,0]
	v_mul_f32_e32 v100, v104, v100
	v_mul_f32_e32 v98, v105, v101
	v_cvt_pk_bf16_f32 v98, v100, v98
	v_mul_f32_e32 v100, v106, v102
	v_mul_f32_e32 v99, v107, v99
	v_cvt_pk_bf16_f32 v99, v100, v99
	ds_read_b32 v100, v168 offset:128
	v_lshlrev_b64 v[102:103], 10, v[124:125]
	v_lshl_add_u64 v[102:103], s[40:41], 0, v[102:103]
	v_lshl_add_u64 v[102:103], v[102:103], 0, v[112:113]
	global_store_dwordx4 v[102:103], v[96:99], off sc1
	s_waitcnt lgkmcnt(0)
	v_pk_mul_f32 v[84:85], v[84:85], v[100:101] op_sel_hi:[1,0]
	v_pk_mul_f32 v[86:87], v[86:87], v[100:101] op_sel_hi:[1,0]
	v_mul_f32_e32 v84, 0xbfb8aa3b, v84
	v_exp_f32_e32 v96, v84
	v_mul_f32_e32 v84, 0xbfb8aa3b, v85
	v_exp_f32_e32 v97, v84
	v_pk_mul_f32 v[84:85], v[80:81], v[100:101] op_sel_hi:[1,0]
	v_add_f32_e32 v80, 1.0, v96
	v_rcp_f32_e32 v80, v80
	v_add_f32_e32 v81, 1.0, v97
	v_rcp_f32_e32 v81, v81
	v_mul_f32_e32 v86, 0xbfb8aa3b, v86
	v_exp_f32_e32 v86, v86
	v_pk_mul_f32 v[92:93], v[92:93], v[100:101] op_sel_hi:[1,0]
	v_pk_mul_f32 v[82:83], v[82:83], v[100:101] op_sel_hi:[1,0]
	v_mul_f32_e32 v80, v92, v80
	v_mul_f32_e32 v81, v93, v81
	v_cvt_pk_bf16_f32 v80, v80, v81
	v_add_f32_e32 v81, 1.0, v86
	v_mul_f32_e32 v86, 0xbfb8aa3b, v87
	v_exp_f32_e32 v86, v86
	v_mul_f32_e32 v84, 0xbfb8aa3b, v84
	v_mul_f32_e32 v85, 0xbfb8aa3b, v85
	v_mul_f32_e32 v82, 0xbfb8aa3b, v82
	v_add_f32_e32 v86, 1.0, v86
	v_rcp_f32_e32 v81, v81
	v_exp_f32_e32 v84, v84
	v_rcp_f32_e32 v86, v86
	v_exp_f32_e32 v85, v85
	v_exp_f32_e32 v82, v82
	v_mul_f32_e32 v83, 0xbfb8aa3b, v83
	v_exp_f32_e32 v83, v83
	v_pk_mul_f32 v[94:95], v[94:95], v[100:101] op_sel_hi:[1,0]
	v_add_f32_e32 v84, 1.0, v84
	v_mul_f32_e32 v81, v94, v81
	v_mul_f32_e32 v86, v95, v86
	v_add_f32_e32 v85, 1.0, v85
	v_add_f32_e32 v82, 1.0, v82
	v_rcp_f32_e32 v84, v84
	v_cvt_pk_bf16_f32 v81, v81, v86
	v_rcp_f32_e32 v85, v85
	v_rcp_f32_e32 v86, v82
	v_add_f32_e32 v82, 1.0, v83
	v_rcp_f32_e32 v83, v82
	v_pk_mul_f32 v[88:89], v[88:89], v[100:101] op_sel_hi:[1,0]
	v_pk_mul_f32 v[90:91], v[90:91], v[100:101] op_sel_hi:[1,0]
	v_mul_f32_e32 v84, v88, v84
	v_mul_f32_e32 v82, v89, v85
	v_cvt_pk_bf16_f32 v82, v84, v82
	v_mul_f32_e32 v84, v90, v86
	v_mul_f32_e32 v83, v91, v83
	v_cvt_pk_bf16_f32 v83, v84, v83
	ds_read_b32 v84, v168 offset:192
	v_lshlrev_b64 v[86:87], 10, v[122:123]
	v_lshl_add_u64 v[86:87], s[40:41], 0, v[86:87]
	v_lshl_add_u64 v[86:87], v[86:87], 0, v[112:113]
	global_store_dwordx4 v[86:87], v[80:83], off sc1
	s_waitcnt lgkmcnt(0)
; __device__ __forceinline__ unsigned cvt_pk_bf16(float lo, float hi) { unsigned r; asm volatile("v_cvt_pk_bf16_f32 %0, %1, %2" : "=v"(r) : "v"(lo), "v"(hi)); return r; }
; __device__ __forceinline__ float fast_sigmoid(float x) { return __builtin_amdgcn_rcpf(1.f + __builtin_amdgcn_exp2f(-x * LOG2E)); }
;     __device__ __forceinline__ void operator()(const f32x4 (&acc)[2][2][4][2], const pg8::Unit& u, int wr, int wc, int fr, int fq) const {
;     ...
;                 for (int m = 0; m < 4; ++m) { bf16_t* rowp = VC + (size_t)(row0 + ai * 128 + m * 16) * CONVC + col0; const float r = rt[ai * 128 + m * 16];
;                     const f32x4 a0 = acc[ai][0][m][0] * r, a1 = acc[ai][0][m][1] * r, g0 = acc[ai][1][m][0] * r, g1 = acc[ai][1][m][1] * r;
;                     u32x4 w; w.x = cvt_pk_bf16(a0[0] * fast_sigmoid(g0[0]), a0[1] * fast_sigmoid(g0[1])); w.y = cvt_pk_bf16(a0[2] * fast_sigmoid(g0[2]), a0[3] * fast_sigmoid(g0[3]));
;                     w.z = cvt_pk_bf16(a1[0] * fast_sigmoid(g1[0]), a1[1] * fast_sigmoid(g1[1])); w.w = cvt_pk_bf16(a1[2] * fast_sigmoid(g1[2]), a1[3] * fast_sigmoid(g1[3]));
;                     *(u32x4*)rowp = w; }
	v_pk_mul_f32 v[68:69], v[68:69], v[84:85] op_sel_hi:[1,0]
	v_pk_mul_f32 v[70:71], v[70:71], v[84:85] op_sel_hi:[1,0]
	v_mul_f32_e32 v68, 0xbfb8aa3b, v68
	v_exp_f32_e32 v80, v68
	v_mul_f32_e32 v68, 0xbfb8aa3b, v69
	v_exp_f32_e32 v81, v68
	v_pk_mul_f32 v[68:69], v[64:65], v[84:85] op_sel_hi:[1,0]
	v_add_f32_e32 v64, 1.0, v80
	v_rcp_f32_e32 v64, v64
	v_add_f32_e32 v65, 1.0, v81
	v_rcp_f32_e32 v65, v65
	v_mul_f32_e32 v70, 0xbfb8aa3b, v70
	v_exp_f32_e32 v70, v70
	v_pk_mul_f32 v[76:77], v[76:77], v[84:85] op_sel_hi:[1,0]
	v_pk_mul_f32 v[66:67], v[66:67], v[84:85] op_sel_hi:[1,0]
	v_mul_f32_e32 v64, v76, v64
	v_mul_f32_e32 v65, v77, v65
	v_cvt_pk_bf16_f32 v64, v64, v65
	v_add_f32_e32 v65, 1.0, v70
	v_mul_f32_e32 v70, 0xbfb8aa3b, v71
	v_exp_f32_e32 v70, v70
	v_mul_f32_e32 v68, 0xbfb8aa3b, v68
	v_mul_f32_e32 v69, 0xbfb8aa3b, v69
	v_mul_f32_e32 v66, 0xbfb8aa3b, v66
	v_add_f32_e32 v70, 1.0, v70
	v_rcp_f32_e32 v65, v65
	v_exp_f32_e32 v68, v68
	v_rcp_f32_e32 v70, v70
	v_exp_f32_e32 v69, v69
	v_exp_f32_e32 v66, v66
	v_mul_f32_e32 v67, 0xbfb8aa3b, v67
	v_exp_f32_e32 v67, v67
	v_pk_mul_f32 v[78:79], v[78:79], v[84:85] op_sel_hi:[1,0]
	v_add_f32_e32 v68, 1.0, v68
	v_mul_f32_e32 v65, v78, v65
	v_mul_f32_e32 v70, v79, v70
	v_add_f32_e32 v69, 1.0, v69
	v_add_f32_e32 v66, 1.0, v66
	v_rcp_f32_e32 v68, v68
	v_cvt_pk_bf16_f32 v65, v65, v70
	v_rcp_f32_e32 v69, v69
	v_rcp_f32_e32 v70, v66
	v_add_f32_e32 v66, 1.0, v67
	v_rcp_f32_e32 v67, v66
	v_pk_mul_f32 v[72:73], v[72:73], v[84:85] op_sel_hi:[1,0]
	v_pk_mul_f32 v[74:75], v[74:75], v[84:85] op_sel_hi:[1,0]
	v_mul_f32_e32 v68, v72, v68
	v_mul_f32_e32 v66, v73, v69
	v_cvt_pk_bf16_f32 v66, v68, v66
	v_mul_f32_e32 v68, v74, v70
	v_mul_f32_e32 v67, v75, v67
	v_cvt_pk_bf16_f32 v67, v68, v67
	ds_read_b32 v68, v168 offset:512
	v_lshlrev_b64 v[70:71], 10, v[120:121]
	v_lshl_add_u64 v[70:71], s[40:41], 0, v[70:71]
	v_lshl_add_u64 v[70:71], v[70:71], 0, v[112:113]
	global_store_dwordx4 v[70:71], v[64:67], off sc1
	s_waitcnt lgkmcnt(0)
	v_pk_mul_f32 v[52:53], v[52:53], v[68:69] op_sel_hi:[1,0]
	v_pk_mul_f32 v[54:55], v[54:55], v[68:69] op_sel_hi:[1,0]
	v_pk_mul_f32 v[64:65], v[50:51], v[68:69] op_sel_hi:[1,0]
	v_mul_f32_e32 v50, 0xbfb8aa3b, v52
	v_mul_f32_e32 v51, 0xbfb8aa3b, v53
	v_exp_f32_e32 v50, v50
	v_exp_f32_e32 v51, v51
	v_mul_f32_e32 v52, 0xbfb8aa3b, v54
	v_exp_f32_e32 v52, v52
	v_add_f32_e32 v50, 1.0, v50
	v_add_f32_e32 v51, 1.0, v51
	v_rcp_f32_e32 v50, v50
	v_rcp_f32_e32 v51, v51
	v_pk_mul_f32 v[60:61], v[60:61], v[68:69] op_sel_hi:[1,0]
	v_pk_mul_f32 v[62:63], v[62:63], v[68:69] op_sel_hi:[1,0]
	v_mul_f32_e32 v50, v60, v50
	v_mul_f32_e32 v51, v61, v51
	v_cvt_pk_bf16_f32 v50, v50, v51
	v_add_f32_e32 v51, 1.0, v52
	v_mul_f32_e32 v52, 0xbfb8aa3b, v55
	v_exp_f32_e32 v52, v52
	v_rcp_f32_e32 v51, v51
	v_pk_mul_f32 v[48:49], v[48:49], v[68:69] op_sel_hi:[1,0]
	v_mul_f32_e32 v53, 0xbfb8aa3b, v65
	v_add_f32_e32 v52, 1.0, v52
	v_rcp_f32_e32 v52, v52
	v_mul_f32_e32 v51, v62, v51
	v_mul_f32_e32 v48, 0xbfb8aa3b, v48
	v_mul_f32_e32 v49, 0xbfb8aa3b, v49
	v_mul_f32_e32 v52, v63, v52
	v_cvt_pk_bf16_f32 v51, v51, v52
	v_mul_f32_e32 v52, 0xbfb8aa3b, v64
	v_exp_f32_e32 v48, v48
	v_exp_f32_e32 v49, v49
	v_exp_f32_e32 v52, v52
	v_exp_f32_e32 v53, v53
	v_add_f32_e32 v48, 1.0, v48
	v_add_f32_e32 v49, 1.0, v49
	v_add_f32_e32 v52, 1.0, v52
	v_rcp_f32_e32 v48, v48
	v_rcp_f32_e32 v49, v49
	v_rcp_f32_e32 v54, v52
	v_add_f32_e32 v52, 1.0, v53
	v_rcp_f32_e32 v53, v52
	v_pk_mul_f32 v[56:57], v[56:57], v[68:69] op_sel_hi:[1,0]
	v_pk_mul_f32 v[58:59], v[58:59], v[68:69] op_sel_hi:[1,0]
	v_mul_f32_e32 v48, v56, v48
	v_mul_f32_e32 v49, v57, v49
	v_cvt_pk_bf16_f32 v52, v48, v49
	v_mul_f32_e32 v48, v58, v54
	v_mul_f32_e32 v49, v59, v53
	v_cvt_pk_bf16_f32 v53, v48, v49
	ds_read_b32 v54, v168 offset:576
	v_lshlrev_b64 v[48:49], 10, v[146:147]
	v_lshl_add_u64 v[48:49], s[40:41], 0, v[48:49]
	v_lshl_add_u64 v[48:49], v[48:49], 0, v[112:113]
	v_add_co_u32_e32 v56, vcc, s71, v48
	s_waitcnt lgkmcnt(0)
; __device__ __forceinline__ unsigned cvt_pk_bf16(float lo, float hi) { unsigned r; asm volatile("v_cvt_pk_bf16_f32 %0, %1, %2" : "=v"(r) : "v"(lo), "v"(hi)); return r; }
; __device__ __forceinline__ float fast_sigmoid(float x) { return __builtin_amdgcn_rcpf(1.f + __builtin_amdgcn_exp2f(-x * LOG2E)); }
;     __device__ __forceinline__ void operator()(const f32x4 (&acc)[2][2][4][2], const pg8::Unit& u, int wr, int wc, int fr, int fq) const {
;     ...
;         if (u.pn < 4) { const int col0 = u.pn * 128 + wc * 32 + 8 * fq;
; #pragma unroll
;             for (int ai = 0; ai < 2; ++ai)
; #pragma unroll
;                 for (int m = 0; m < 4; ++m) { bf16_t* rowp = VC + (size_t)(row0 + ai * 128 + m * 16) * CONVC + col0; const float r = rt[ai * 128 + m * 16];
;                     const f32x4 a0 = acc[ai][0][m][0] * r, a1 = acc[ai][0][m][1] * r, g0 = acc[ai][1][m][0] * r, g1 = acc[ai][1][m][1] * r;
;                     u32x4 w; w.x = cvt_pk_bf16(a0[0] * fast_sigmoid(g0[0]), a0[1] * fast_sigmoid(g0[1])); w.y = cvt_pk_bf16(a0[2] * fast_sigmoid(g0[2]), a0[3] * fast_sigmoid(g0[3]));
;                     w.z = cvt_pk_bf16(a1[0] * fast_sigmoid(g1[0]), a1[1] * fast_sigmoid(g1[1])); w.w = cvt_pk_bf16(a1[2] * fast_sigmoid(g1[2]), a1[3] * fast_sigmoid(g1[3]));
;                     *(u32x4*)rowp = w; }
	v_pk_mul_f32 v[36:37], v[36:37], v[54:55] op_sel_hi:[1,0]
	v_addc_co_u32_e32 v57, vcc, 0, v49, vcc
	v_mul_f32_e32 v36, 0xbfb8aa3b, v36
	global_store_dwordx4 v[56:57], v[50:53], off sc1
	v_pk_mul_f32 v[38:39], v[38:39], v[54:55] op_sel_hi:[1,0]
	v_pk_mul_f32 v[44:45], v[44:45], v[54:55] op_sel_hi:[1,0]
	v_exp_f32_e32 v50, v36
	v_mul_f32_e32 v36, 0xbfb8aa3b, v37
	v_exp_f32_e32 v51, v36
	v_pk_mul_f32 v[36:37], v[32:33], v[54:55] op_sel_hi:[1,0]
	v_add_f32_e32 v32, 1.0, v50
	v_rcp_f32_e32 v32, v32
	v_add_f32_e32 v33, 1.0, v51
	v_rcp_f32_e32 v33, v33
	v_mul_f32_e32 v38, 0xbfb8aa3b, v38
	v_exp_f32_e32 v38, v38
	v_mul_f32_e32 v32, v44, v32
	v_mul_f32_e32 v33, v45, v33
	v_cvt_pk_bf16_f32 v32, v32, v33
	v_add_f32_e32 v33, 1.0, v38
	v_mul_f32_e32 v38, 0xbfb8aa3b, v39
	v_exp_f32_e32 v38, v38
	v_pk_mul_f32 v[34:35], v[34:35], v[54:55] op_sel_hi:[1,0]
	v_mul_f32_e32 v36, 0xbfb8aa3b, v36
	v_mul_f32_e32 v37, 0xbfb8aa3b, v37
	v_add_f32_e32 v38, 1.0, v38
	v_mul_f32_e32 v34, 0xbfb8aa3b, v34
	v_rcp_f32_e32 v33, v33
	v_exp_f32_e32 v36, v36
	v_rcp_f32_e32 v38, v38
	v_exp_f32_e32 v37, v37
	v_exp_f32_e32 v34, v34
	v_mul_f32_e32 v35, 0xbfb8aa3b, v35
	v_exp_f32_e32 v35, v35
	v_pk_mul_f32 v[46:47], v[46:47], v[54:55] op_sel_hi:[1,0]
	v_add_f32_e32 v36, 1.0, v36
	v_mul_f32_e32 v33, v46, v33
	v_mul_f32_e32 v38, v47, v38
	v_add_f32_e32 v37, 1.0, v37
	v_add_f32_e32 v34, 1.0, v34
	v_rcp_f32_e32 v36, v36
	v_cvt_pk_bf16_f32 v33, v33, v38
	v_rcp_f32_e32 v37, v37
	v_rcp_f32_e32 v38, v34
	v_add_f32_e32 v34, 1.0, v35
	v_rcp_f32_e32 v35, v34
	v_pk_mul_f32 v[40:41], v[40:41], v[54:55] op_sel_hi:[1,0]
	v_pk_mul_f32 v[42:43], v[42:43], v[54:55] op_sel_hi:[1,0]
	v_mul_f32_e32 v36, v40, v36
	v_mul_f32_e32 v34, v41, v37
	v_cvt_pk_bf16_f32 v34, v36, v34
	v_mul_f32_e32 v36, v42, v38
	v_mul_f32_e32 v35, v43, v35
	v_cvt_pk_bf16_f32 v35, v36, v35
	ds_read_b32 v36, v168 offset:640
	v_add_co_u32_e32 v38, vcc, s74, v48
	s_waitcnt lgkmcnt(0)
	v_pk_mul_f32 v[20:21], v[20:21], v[36:37] op_sel_hi:[1,0]
	v_addc_co_u32_e32 v39, vcc, 0, v49, vcc
	v_mul_f32_e32 v20, 0xbfb8aa3b, v20
	global_store_dwordx4 v[38:39], v[32:35], off sc1
	v_pk_mul_f32 v[22:23], v[22:23], v[36:37] op_sel_hi:[1,0]
	v_pk_mul_f32 v[28:29], v[28:29], v[36:37] op_sel_hi:[1,0]
	v_exp_f32_e32 v32, v20
	v_mul_f32_e32 v20, 0xbfb8aa3b, v21
	v_exp_f32_e32 v33, v20
	v_pk_mul_f32 v[20:21], v[16:17], v[36:37] op_sel_hi:[1,0]
	v_add_f32_e32 v16, 1.0, v32
	v_rcp_f32_e32 v16, v16
	v_add_f32_e32 v17, 1.0, v33
	v_rcp_f32_e32 v17, v17
	v_mul_f32_e32 v22, 0xbfb8aa3b, v22
	v_exp_f32_e32 v22, v22
	v_mul_f32_e32 v16, v28, v16
	v_mul_f32_e32 v17, v29, v17
	v_cvt_pk_bf16_f32 v16, v16, v17
	v_add_f32_e32 v17, 1.0, v22
	v_mul_f32_e32 v22, 0xbfb8aa3b, v23
	v_exp_f32_e32 v22, v22
	v_pk_mul_f32 v[18:19], v[18:19], v[36:37] op_sel_hi:[1,0]
	v_mul_f32_e32 v20, 0xbfb8aa3b, v20
	v_mul_f32_e32 v21, 0xbfb8aa3b, v21
	v_add_f32_e32 v22, 1.0, v22
	v_mul_f32_e32 v18, 0xbfb8aa3b, v18
	v_rcp_f32_e32 v17, v17
	v_exp_f32_e32 v20, v20
	v_rcp_f32_e32 v22, v22
	v_exp_f32_e32 v21, v21
	v_exp_f32_e32 v18, v18
	v_mul_f32_e32 v19, 0xbfb8aa3b, v19
	v_exp_f32_e32 v19, v19
	v_pk_mul_f32 v[30:31], v[30:31], v[36:37] op_sel_hi:[1,0]
	v_add_f32_e32 v20, 1.0, v20
	v_mul_f32_e32 v17, v30, v17
	v_mul_f32_e32 v22, v31, v22
	v_add_f32_e32 v21, 1.0, v21
	v_add_f32_e32 v18, 1.0, v18
	v_rcp_f32_e32 v20, v20
	v_cvt_pk_bf16_f32 v17, v17, v22
	v_rcp_f32_e32 v21, v21
	v_rcp_f32_e32 v22, v18
	v_add_f32_e32 v18, 1.0, v19
	v_rcp_f32_e32 v19, v18
	v_pk_mul_f32 v[24:25], v[24:25], v[36:37] op_sel_hi:[1,0]
	v_pk_mul_f32 v[26:27], v[26:27], v[36:37] op_sel_hi:[1,0]
	v_mul_f32_e32 v20, v24, v20
	v_mul_f32_e32 v18, v25, v21
	v_cvt_pk_bf16_f32 v18, v20, v18
	v_mul_f32_e32 v20, v26, v22
	v_mul_f32_e32 v19, v27, v19
	v_cvt_pk_bf16_f32 v19, v20, v19
	ds_read_b32 v20, v168 offset:704
	v_add_co_u32_e32 v22, vcc, s75, v48
	s_waitcnt lgkmcnt(0)
	v_pk_mul_f32 v[4:5], v[4:5], v[20:21] op_sel_hi:[1,0]
	v_addc_co_u32_e32 v23, vcc, 0, v49, vcc
	v_mul_f32_e32 v4, 0xbfb8aa3b, v4
	global_store_dwordx4 v[22:23], v[16:19], off sc1
	v_pk_mul_f32 v[6:7], v[6:7], v[20:21] op_sel_hi:[1,0]
	v_pk_mul_f32 v[12:13], v[12:13], v[20:21] op_sel_hi:[1,0]
	v_exp_f32_e32 v16, v4
	v_mul_f32_e32 v4, 0xbfb8aa3b, v5
	v_exp_f32_e32 v17, v4
	v_pk_mul_f32 v[4:5], v[0:1], v[20:21] op_sel_hi:[1,0]
	v_add_f32_e32 v0, 1.0, v16
	v_rcp_f32_e32 v0, v0
	v_add_f32_e32 v1, 1.0, v17
	v_rcp_f32_e32 v1, v1
	v_mul_f32_e32 v6, 0xbfb8aa3b, v6
	v_exp_f32_e32 v6, v6
	v_mul_f32_e32 v0, v12, v0
	v_mul_f32_e32 v1, v13, v1
	v_cvt_pk_bf16_f32 v0, v0, v1
	v_add_f32_e32 v1, 1.0, v6
	v_mul_f32_e32 v6, 0xbfb8aa3b, v7
	v_exp_f32_e32 v6, v6
	v_pk_mul_f32 v[2:3], v[2:3], v[20:21] op_sel_hi:[1,0]
	v_mul_f32_e32 v4, 0xbfb8aa3b, v4
	v_mul_f32_e32 v5, 0xbfb8aa3b, v5
	v_add_f32_e32 v6, 1.0, v6
	v_mul_f32_e32 v2, 0xbfb8aa3b, v2
	v_rcp_f32_e32 v1, v1
	v_exp_f32_e32 v4, v4
	v_rcp_f32_e32 v6, v6
	v_exp_f32_e32 v5, v5
	v_exp_f32_e32 v2, v2
	v_mul_f32_e32 v3, 0xbfb8aa3b, v3
	v_exp_f32_e32 v3, v3
	v_pk_mul_f32 v[14:15], v[14:15], v[20:21] op_sel_hi:[1,0]
	v_add_f32_e32 v4, 1.0, v4
	v_mul_f32_e32 v1, v14, v1
	v_mul_f32_e32 v6, v15, v6
	v_add_f32_e32 v5, 1.0, v5
	v_add_f32_e32 v2, 1.0, v2
	v_rcp_f32_e32 v4, v4
	v_cvt_pk_bf16_f32 v1, v1, v6
	v_rcp_f32_e32 v5, v5
	v_rcp_f32_e32 v6, v2
	v_add_f32_e32 v2, 1.0, v3
	v_rcp_f32_e32 v3, v2
	v_pk_mul_f32 v[8:9], v[8:9], v[20:21] op_sel_hi:[1,0]
	v_pk_mul_f32 v[10:11], v[10:11], v[20:21] op_sel_hi:[1,0]
	v_mul_f32_e32 v4, v8, v4
	v_mul_f32_e32 v2, v9, v5
	v_cvt_pk_bf16_f32 v2, v4, v2
	v_mul_f32_e32 v4, v10, v6
	v_mul_f32_e32 v3, v11, v3
	v_cvt_pk_bf16_f32 v3, v4, v3
	v_add_co_u32_e32 v4, vcc, 0x2c000, v48
	s_nop 1
	v_addc_co_u32_e32 v5, vcc, 0, v49, vcc
	global_store_dwordx4 v[4:5], v[0:3], off sc1
	s_andn2_b64 vcc, exec, s[4:5]
	s_mov_b64 s[4:5], -1
	s_cbranch_vccnz .LBB0_410

; __device__ __forceinline__ void conv_phase(LAS unsigned char* lds, const bf16_t* VC, const float* cw, const float* cb, const float* lng, const float* lnb, bf16_t* CAT, int tid, int lane, int wave) {
;     ...
; #pragma unroll
;         for (int r = 0; r < 38; ++r) {
;             const unsigned v = (tb - 30 + r >= 0) ? vv[r] : 0u;
;             const f32x2v vf = {bf_lo(v), bf_hi(v)};
; #pragma unroll
;             for (int t = 0; t < 8; ++t) { const int k = r - t; if (k >= 0 && k < TAPS) av[t] = __builtin_elementwise_fma(wk[k], vf, av[t]); }
;         }
.LBB0_482:
	v_add_u32_e32 v0, s3, v98
	v_and_b32_e32 v174, 0x7f8, v0
	v_cmp_lt_u32_e32 vcc, 29, v174
	s_add_i32 s12, s14, s3
	s_ashr_i32 s13, s12, 31
	v_cndmask_b32_e32 v1, 0, v159, vcc
	v_cmp_lt_u32_e32 vcc, 28, v174
	v_lshlrev_b32_e32 v0, 16, v1
	v_and_b32_e32 v1, 0xffff0000, v1
	v_cndmask_b32_e32 v159, 0, v158, vcc
	v_cmp_lt_u32_e32 vcc, 27, v174
	v_pk_fma_f32 v[0:1], v[84:85], v[0:1], v[88:89]
	v_lshlrev_b32_e32 v158, 16, v159
	v_and_b32_e32 v159, 0xffff0000, v159
	v_cndmask_b32_e32 v156, 0, v156, vcc
	v_cmp_lt_u32_e32 vcc, 26, v174
	v_pk_fma_f32 v[0:1], v[86:87], v[158:159], v[0:1]
	v_pk_fma_f32 v[158:159], v[84:85], v[158:159], v[88:89]
	v_lshlrev_b32_e32 v162, 16, v156
	v_and_b32_e32 v163, 0xffff0000, v156
	v_cndmask_b32_e32 v155, 0, v155, vcc
	v_cmp_lt_u32_e32 vcc, 25, v174
	v_pk_fma_f32 v[0:1], v[26:27], v[162:163], v[0:1]
	v_pk_fma_f32 v[158:159], v[86:87], v[162:163], v[158:159]
	v_pk_fma_f32 v[162:163], v[84:85], v[162:163], v[88:89]
	v_lshlrev_b32_e32 v164, 16, v155
	v_and_b32_e32 v165, 0xffff0000, v155
	v_cndmask_b32_e32 v152, 0, v152, vcc
	v_cmp_lt_u32_e32 vcc, 24, v174
	v_pk_fma_f32 v[0:1], v[28:29], v[164:165], v[0:1]
	v_pk_fma_f32 v[158:159], v[26:27], v[164:165], v[158:159]
	v_pk_fma_f32 v[162:163], v[86:87], v[164:165], v[162:163]
	v_pk_fma_f32 v[164:165], v[84:85], v[164:165], v[88:89]
	v_lshlrev_b32_e32 v166, 16, v152
	v_and_b32_e32 v167, 0xffff0000, v152
	v_cndmask_b32_e32 v149, 0, v149, vcc
	v_cmp_lt_u32_e32 vcc, 23, v174
	v_pk_fma_f32 v[0:1], v[30:31], v[166:167], v[0:1]
	v_pk_fma_f32 v[158:159], v[28:29], v[166:167], v[158:159]
	v_pk_fma_f32 v[162:163], v[26:27], v[166:167], v[162:163]
	v_pk_fma_f32 v[164:165], v[86:87], v[166:167], v[164:165]
	v_pk_fma_f32 v[166:167], v[84:85], v[166:167], v[88:89]
	v_lshlrev_b32_e32 v168, 16, v149
	v_and_b32_e32 v169, 0xffff0000, v149
	v_cndmask_b32_e32 v147, 0, v147, vcc
	v_cmp_lt_u32_e32 vcc, 22, v174
	v_pk_fma_f32 v[0:1], v[32:33], v[168:169], v[0:1]
	v_pk_fma_f32 v[158:159], v[30:31], v[168:169], v[158:159]
	v_pk_fma_f32 v[162:163], v[28:29], v[168:169], v[162:163]
	v_pk_fma_f32 v[164:165], v[26:27], v[168:169], v[164:165]
	v_pk_fma_f32 v[166:167], v[86:87], v[168:169], v[166:167]
	v_pk_fma_f32 v[168:169], v[84:85], v[168:169], v[88:89]
	v_lshlrev_b32_e32 v170, 16, v147
	v_and_b32_e32 v171, 0xffff0000, v147
	v_cndmask_b32_e32 v23, 0, v23, vcc
	v_cmp_lt_u32_e32 vcc, 21, v174
	v_pk_fma_f32 v[0:1], v[34:35], v[170:171], v[0:1]
	v_pk_fma_f32 v[158:159], v[32:33], v[170:171], v[158:159]
	v_pk_fma_f32 v[162:163], v[30:31], v[170:171], v[162:163]
	v_pk_fma_f32 v[164:165], v[28:29], v[170:171], v[164:165]
	v_pk_fma_f32 v[166:167], v[26:27], v[170:171], v[166:167]
	v_pk_fma_f32 v[168:169], v[86:87], v[170:171], v[168:169]
	v_pk_fma_f32 v[170:171], v[84:85], v[170:171], v[88:89]
	v_lshlrev_b32_e32 v172, 16, v23
	v_and_b32_e32 v173, 0xffff0000, v23
	v_cndmask_b32_e32 v23, 0, v160, vcc
	v_cmp_lt_u32_e32 vcc, 20, v174
	v_pk_fma_f32 v[0:1], v[36:37], v[172:173], v[0:1]
	v_pk_fma_f32 v[158:159], v[34:35], v[172:173], v[158:159]
	v_pk_fma_f32 v[162:163], v[32:33], v[172:173], v[162:163]
	v_pk_fma_f32 v[164:165], v[30:31], v[172:173], v[164:165]
	v_pk_fma_f32 v[166:167], v[28:29], v[172:173], v[166:167]
	v_pk_fma_f32 v[168:169], v[26:27], v[172:173], v[168:169]
	v_pk_fma_f32 v[170:171], v[86:87], v[172:173], v[170:171]
	v_pk_fma_f32 v[172:173], v[84:85], v[172:173], v[88:89]
	v_lshlrev_b32_e32 v160, 16, v23
	v_and_b32_e32 v161, 0xffff0000, v23
	v_cndmask_b32_e32 v23, 0, v157, vcc
	v_cmp_lt_u32_e32 vcc, 19, v174
	v_pk_fma_f32 v[0:1], v[38:39], v[160:161], v[0:1]
	v_pk_fma_f32 v[158:159], v[36:37], v[160:161], v[158:159]
	v_pk_fma_f32 v[162:163], v[34:35], v[160:161], v[162:163]
	v_pk_fma_f32 v[164:165], v[32:33], v[160:161], v[164:165]
	v_pk_fma_f32 v[166:167], v[30:31], v[160:161], v[166:167]
	v_pk_fma_f32 v[168:169], v[28:29], v[160:161], v[168:169]
	v_pk_fma_f32 v[170:171], v[26:27], v[160:161], v[170:171]
	v_pk_fma_f32 v[160:161], v[86:87], v[160:161], v[172:173]
	v_lshlrev_b32_e32 v156, 16, v23
	v_and_b32_e32 v157, 0xffff0000, v23
	v_cndmask_b32_e32 v23, 0, v154, vcc
	v_cmp_lt_u32_e32 vcc, 18, v174
	v_pk_fma_f32 v[0:1], v[40:41], v[156:157], v[0:1]
	v_pk_fma_f32 v[158:159], v[38:39], v[156:157], v[158:159]
	v_pk_fma_f32 v[162:163], v[36:37], v[156:157], v[162:163]
	v_pk_fma_f32 v[164:165], v[34:35], v[156:157], v[164:165]
	v_pk_fma_f32 v[166:167], v[32:33], v[156:157], v[166:167]
	v_pk_fma_f32 v[168:169], v[30:31], v[156:157], v[168:169]
	v_pk_fma_f32 v[170:171], v[28:29], v[156:157], v[170:171]
	v_pk_fma_f32 v[156:157], v[26:27], v[156:157], v[160:161]
	v_lshlrev_b32_e32 v154, 16, v23
	v_and_b32_e32 v155, 0xffff0000, v23
	v_cndmask_b32_e32 v23, 0, v151, vcc
	v_cmp_lt_u32_e32 vcc, 17, v174
	v_pk_fma_f32 v[0:1], v[42:43], v[154:155], v[0:1]
	v_pk_fma_f32 v[158:159], v[40:41], v[154:155], v[158:159]
	v_pk_fma_f32 v[160:161], v[38:39], v[154:155], v[162:163]
	v_pk_fma_f32 v[162:163], v[36:37], v[154:155], v[164:165]
	v_pk_fma_f32 v[164:165], v[34:35], v[154:155], v[166:167]
	v_pk_fma_f32 v[166:167], v[32:33], v[154:155], v[168:169]
	v_pk_fma_f32 v[168:169], v[30:31], v[154:155], v[170:171]
	v_pk_fma_f32 v[154:155], v[28:29], v[154:155], v[156:157]
	v_lshlrev_b32_e32 v156, 16, v23
	v_and_b32_e32 v157, 0xffff0000, v23
	v_cndmask_b32_e32 v23, 0, v148, vcc
	v_cmp_lt_u32_e32 vcc, 16, v174
	v_pk_fma_f32 v[0:1], v[44:45], v[156:157], v[0:1]
	v_pk_fma_f32 v[158:159], v[42:43], v[156:157], v[158:159]
	v_pk_fma_f32 v[160:161], v[40:41], v[156:157], v[160:161]
	v_pk_fma_f32 v[162:163], v[38:39], v[156:157], v[162:163]
	v_pk_fma_f32 v[164:165], v[36:37], v[156:157], v[164:165]
; __device__ __forceinline__ void conv_phase(LAS unsigned char* lds, const bf16_t* VC, const float* cw, const float* cb, const float* lng, const float* lnb, bf16_t* CAT, int tid, int lane, int wave) {
;     ...
; #pragma unroll
;         for (int r = 0; r < 38; ++r) {
;             const unsigned v = (tb - 30 + r >= 0) ? vv[r] : 0u;
;             const f32x2v vf = {bf_lo(v), bf_hi(v)};
; #pragma unroll
;             for (int t = 0; t < 8; ++t) { const int k = r - t; if (k >= 0 && k < TAPS) av[t] = __builtin_elementwise_fma(wk[k], vf, av[t]); }
;         }
	v_pk_fma_f32 v[166:167], v[34:35], v[156:157], v[166:167]
	v_pk_fma_f32 v[168:169], v[32:33], v[156:157], v[168:169]
	v_pk_fma_f32 v[154:155], v[30:31], v[156:157], v[154:155]
	v_lshlrev_b32_e32 v148, 16, v23
	v_and_b32_e32 v149, 0xffff0000, v23
	v_cndmask_b32_e32 v23, 0, v22, vcc
	v_cmp_lt_u32_e32 vcc, 15, v174
	v_pk_fma_f32 v[0:1], v[46:47], v[148:149], v[0:1]
	v_pk_fma_f32 v[156:157], v[44:45], v[148:149], v[158:159]
	v_pk_fma_f32 v[158:159], v[42:43], v[148:149], v[160:161]
	v_pk_fma_f32 v[160:161], v[40:41], v[148:149], v[162:163]
	v_pk_fma_f32 v[162:163], v[38:39], v[148:149], v[164:165]
	v_pk_fma_f32 v[164:165], v[36:37], v[148:149], v[166:167]
	v_pk_fma_f32 v[166:167], v[34:35], v[148:149], v[168:169]
	v_pk_fma_f32 v[148:149], v[32:33], v[148:149], v[154:155]
	v_lshlrev_b32_e32 v22, 16, v23
	v_and_b32_e32 v23, 0xffff0000, v23
	v_cndmask_b32_e32 v19, 0, v19, vcc
	v_cmp_lt_u32_e32 vcc, 14, v174
	v_pk_fma_f32 v[0:1], v[48:49], v[22:23], v[0:1]
	v_pk_fma_f32 v[154:155], v[46:47], v[22:23], v[156:157]
	v_pk_fma_f32 v[156:157], v[44:45], v[22:23], v[158:159]
	v_pk_fma_f32 v[158:159], v[42:43], v[22:23], v[160:161]
	v_pk_fma_f32 v[160:161], v[40:41], v[22:23], v[162:163]
	v_pk_fma_f32 v[162:163], v[38:39], v[22:23], v[164:165]
	v_pk_fma_f32 v[164:165], v[36:37], v[22:23], v[166:167]
	v_pk_fma_f32 v[22:23], v[34:35], v[22:23], v[148:149]
	v_lshlrev_b32_e32 v148, 16, v19
	v_and_b32_e32 v149, 0xffff0000, v19
	v_cndmask_b32_e32 v15, 0, v15, vcc
	v_cmp_lt_u32_e32 vcc, 13, v174
	v_pk_fma_f32 v[0:1], v[50:51], v[148:149], v[0:1]
	v_pk_fma_f32 v[154:155], v[48:49], v[148:149], v[154:155]
	v_pk_fma_f32 v[156:157], v[46:47], v[148:149], v[156:157]
	v_pk_fma_f32 v[158:159], v[44:45], v[148:149], v[158:159]
	v_pk_fma_f32 v[160:161], v[42:43], v[148:149], v[160:161]
	v_pk_fma_f32 v[162:163], v[40:41], v[148:149], v[162:163]
	v_pk_fma_f32 v[164:165], v[38:39], v[148:149], v[164:165]
	v_pk_fma_f32 v[22:23], v[36:37], v[148:149], v[22:23]
	v_lshlrev_b32_e32 v148, 16, v15
	v_and_b32_e32 v149, 0xffff0000, v15
	v_cndmask_b32_e32 v15, 0, v153, vcc
	v_cmp_lt_u32_e32 vcc, 12, v174
	v_pk_fma_f32 v[0:1], v[52:53], v[148:149], v[0:1]
	v_pk_fma_f32 v[154:155], v[50:51], v[148:149], v[154:155]
	v_pk_fma_f32 v[156:157], v[48:49], v[148:149], v[156:157]
	v_pk_fma_f32 v[158:159], v[46:47], v[148:149], v[158:159]
	v_pk_fma_f32 v[160:161], v[44:45], v[148:149], v[160:161]
	v_pk_fma_f32 v[162:163], v[42:43], v[148:149], v[162:163]
	v_pk_fma_f32 v[164:165], v[40:41], v[148:149], v[164:165]
	v_pk_fma_f32 v[22:23], v[38:39], v[148:149], v[22:23]
	v_lshlrev_b32_e32 v148, 16, v15
	v_and_b32_e32 v149, 0xffff0000, v15
	v_cndmask_b32_e32 v15, 0, v150, vcc
	v_cmp_lt_u32_e32 vcc, 11, v174
	v_pk_fma_f32 v[0:1], v[54:55], v[148:149], v[0:1]
	v_pk_fma_f32 v[152:153], v[52:53], v[148:149], v[154:155]
	v_pk_fma_f32 v[154:155], v[50:51], v[148:149], v[156:157]
	v_pk_fma_f32 v[156:157], v[48:49], v[148:149], v[158:159]
	v_pk_fma_f32 v[158:159], v[46:47], v[148:149], v[160:161]
	v_pk_fma_f32 v[160:161], v[44:45], v[148:149], v[162:163]
	v_pk_fma_f32 v[162:163], v[42:43], v[148:149], v[164:165]
	v_pk_fma_f32 v[22:23], v[40:41], v[148:149], v[22:23]
	v_lshlrev_b32_e32 v148, 16, v15
	v_and_b32_e32 v149, 0xffff0000, v15
	v_cndmask_b32_e32 v15, 0, v146, vcc
	v_cmp_lt_u32_e32 vcc, 10, v174
	v_pk_fma_f32 v[0:1], v[56:57], v[148:149], v[0:1]
	v_pk_fma_f32 v[150:151], v[54:55], v[148:149], v[152:153]
	v_pk_fma_f32 v[152:153], v[52:53], v[148:149], v[154:155]
	v_pk_fma_f32 v[154:155], v[50:51], v[148:149], v[156:157]
	v_pk_fma_f32 v[156:157], v[48:49], v[148:149], v[158:159]
	v_pk_fma_f32 v[158:159], v[46:47], v[148:149], v[160:161]
	v_pk_fma_f32 v[160:161], v[44:45], v[148:149], v[162:163]
	v_pk_fma_f32 v[22:23], v[42:43], v[148:149], v[22:23]
	v_lshlrev_b32_e32 v146, 16, v15
	v_and_b32_e32 v147, 0xffff0000, v15
	v_cndmask_b32_e32 v15, 0, v21, vcc
	v_cmp_lt_u32_e32 vcc, 9, v174
	v_pk_fma_f32 v[0:1], v[58:59], v[146:147], v[0:1]
	v_pk_fma_f32 v[148:149], v[56:57], v[146:147], v[150:151]
	v_pk_fma_f32 v[150:151], v[54:55], v[146:147], v[152:153]
	v_pk_fma_f32 v[152:153], v[52:53], v[146:147], v[154:155]
	v_pk_fma_f32 v[154:155], v[50:51], v[146:147], v[156:157]
	v_pk_fma_f32 v[156:157], v[48:49], v[146:147], v[158:159]
	v_pk_fma_f32 v[158:159], v[46:47], v[146:147], v[160:161]
	v_pk_fma_f32 v[22:23], v[44:45], v[146:147], v[22:23]
	v_lshlrev_b32_e32 v146, 16, v15
	v_and_b32_e32 v147, 0xffff0000, v15
	v_cndmask_b32_e32 v15, 0, v17, vcc
	v_cmp_lt_u32_e32 vcc, 8, v174
	v_pk_fma_f32 v[0:1], v[60:61], v[146:147], v[0:1]
	v_pk_fma_f32 v[148:149], v[58:59], v[146:147], v[148:149]
	v_pk_fma_f32 v[150:151], v[56:57], v[146:147], v[150:151]
	v_pk_fma_f32 v[152:153], v[54:55], v[146:147], v[152:153]
	v_pk_fma_f32 v[154:155], v[52:53], v[146:147], v[154:155]
	v_pk_fma_f32 v[156:157], v[50:51], v[146:147], v[156:157]
	v_pk_fma_f32 v[158:159], v[48:49], v[146:147], v[158:159]
	v_pk_fma_f32 v[22:23], v[46:47], v[146:147], v[22:23]
	v_lshlrev_b32_e32 v146, 16, v15
	v_and_b32_e32 v147, 0xffff0000, v15
	v_cndmask_b32_e32 v15, 0, v14, vcc
	v_cmp_eq_u32_e32 vcc, 0, v174
	v_pk_fma_f32 v[0:1], v[62:63], v[146:147], v[0:1]
	v_pk_fma_f32 v[148:149], v[60:61], v[146:147], v[148:149]
	v_pk_fma_f32 v[150:151], v[58:59], v[146:147], v[150:151]
	v_pk_fma_f32 v[152:153], v[56:57], v[146:147], v[152:153]
	v_pk_fma_f32 v[154:155], v[54:55], v[146:147], v[154:155]
	v_pk_fma_f32 v[156:157], v[52:53], v[146:147], v[156:157]
	v_pk_fma_f32 v[158:159], v[50:51], v[146:147], v[158:159]
	v_pk_fma_f32 v[22:23], v[48:49], v[146:147], v[22:23]
	v_lshlrev_b32_e32 v14, 16, v15
	v_and_b32_e32 v15, 0xffff0000, v15
	v_cndmask_b32_e64 v10, v10, 0, vcc
; __device__ __forceinline__ void conv_phase(LAS unsigned char* lds, const bf16_t* VC, const float* cw, const float* cb, const float* lng, const float* lnb, bf16_t* CAT, int tid, int lane, int wave) {
;     ...
; #pragma unroll
;         for (int r = 0; r < 38; ++r) {
;             const unsigned v = (tb - 30 + r >= 0) ? vv[r] : 0u;
;             const f32x2v vf = {bf_lo(v), bf_hi(v)};
; #pragma unroll
;             for (int t = 0; t < 8; ++t) { const int k = r - t; if (k >= 0 && k < TAPS) av[t] = __builtin_elementwise_fma(wk[k], vf, av[t]); }
;         }
	v_pk_fma_f32 v[0:1], v[64:65], v[14:15], v[0:1]
	v_pk_fma_f32 v[146:147], v[62:63], v[14:15], v[148:149]
	v_pk_fma_f32 v[148:149], v[60:61], v[14:15], v[150:151]
	v_pk_fma_f32 v[150:151], v[58:59], v[14:15], v[152:153]
	v_pk_fma_f32 v[152:153], v[56:57], v[14:15], v[154:155]
	v_pk_fma_f32 v[154:155], v[54:55], v[14:15], v[156:157]
	v_pk_fma_f32 v[156:157], v[52:53], v[14:15], v[158:159]
	v_pk_fma_f32 v[14:15], v[50:51], v[14:15], v[22:23]
	v_lshlrev_b32_e32 v22, 16, v10
	v_and_b32_e32 v23, 0xffff0000, v10
	v_cndmask_b32_e64 v7, v7, 0, vcc
	v_pk_fma_f32 v[0:1], v[66:67], v[22:23], v[0:1]
	v_pk_fma_f32 v[146:147], v[64:65], v[22:23], v[146:147]
	v_pk_fma_f32 v[148:149], v[62:63], v[22:23], v[148:149]
	v_pk_fma_f32 v[150:151], v[60:61], v[22:23], v[150:151]
	v_pk_fma_f32 v[152:153], v[58:59], v[22:23], v[152:153]
	v_pk_fma_f32 v[154:155], v[56:57], v[22:23], v[154:155]
	v_pk_fma_f32 v[156:157], v[54:55], v[22:23], v[156:157]
	v_pk_fma_f32 v[14:15], v[52:53], v[22:23], v[14:15]
	v_lshlrev_b32_e32 v22, 16, v7
	v_and_b32_e32 v23, 0xffff0000, v7
	v_cndmask_b32_e64 v7, v145, 0, vcc
	v_pk_fma_f32 v[0:1], v[68:69], v[22:23], v[0:1]
	v_pk_fma_f32 v[146:147], v[66:67], v[22:23], v[146:147]
	v_pk_fma_f32 v[148:149], v[64:65], v[22:23], v[148:149]
	v_pk_fma_f32 v[150:151], v[62:63], v[22:23], v[150:151]
	v_pk_fma_f32 v[152:153], v[60:61], v[22:23], v[152:153]
	v_pk_fma_f32 v[154:155], v[58:59], v[22:23], v[154:155]
	v_pk_fma_f32 v[156:157], v[56:57], v[22:23], v[156:157]
	v_pk_fma_f32 v[14:15], v[54:55], v[22:23], v[14:15]
	v_lshlrev_b32_e32 v22, 16, v7
	v_and_b32_e32 v23, 0xffff0000, v7
	v_cndmask_b32_e64 v7, v20, 0, vcc
	v_pk_fma_f32 v[0:1], v[70:71], v[22:23], v[0:1]
	v_pk_fma_f32 v[146:147], v[68:69], v[22:23], v[146:147]
	v_pk_fma_f32 v[148:149], v[66:67], v[22:23], v[148:149]
	v_pk_fma_f32 v[150:151], v[64:65], v[22:23], v[150:151]
	v_pk_fma_f32 v[152:153], v[62:63], v[22:23], v[152:153]
	v_pk_fma_f32 v[154:155], v[60:61], v[22:23], v[154:155]
	v_pk_fma_f32 v[156:157], v[58:59], v[22:23], v[156:157]
	v_pk_fma_f32 v[14:15], v[56:57], v[22:23], v[14:15]
	v_lshlrev_b32_e32 v20, 16, v7
	v_and_b32_e32 v21, 0xffff0000, v7
	v_cndmask_b32_e64 v7, v18, 0, vcc
	v_pk_fma_f32 v[0:1], v[72:73], v[20:21], v[0:1]
	v_pk_fma_f32 v[22:23], v[70:71], v[20:21], v[146:147]
	v_pk_fma_f32 v[146:147], v[68:69], v[20:21], v[148:149]
	v_pk_fma_f32 v[148:149], v[66:67], v[20:21], v[150:151]
	v_pk_fma_f32 v[150:151], v[64:65], v[20:21], v[152:153]
	v_pk_fma_f32 v[152:153], v[62:63], v[20:21], v[154:155]
	v_pk_fma_f32 v[154:155], v[60:61], v[20:21], v[156:157]
	v_pk_fma_f32 v[14:15], v[58:59], v[20:21], v[14:15]
	v_lshlrev_b32_e32 v18, 16, v7
	v_and_b32_e32 v19, 0xffff0000, v7
	v_cndmask_b32_e64 v7, v16, 0, vcc
	v_pk_fma_f32 v[0:1], v[74:75], v[18:19], v[0:1]
	v_pk_fma_f32 v[20:21], v[72:73], v[18:19], v[22:23]
	v_pk_fma_f32 v[22:23], v[70:71], v[18:19], v[146:147]
	v_pk_fma_f32 v[146:147], v[68:69], v[18:19], v[148:149]
	v_pk_fma_f32 v[148:149], v[66:67], v[18:19], v[150:151]
	v_pk_fma_f32 v[150:151], v[64:65], v[18:19], v[152:153]
	v_pk_fma_f32 v[152:153], v[62:63], v[18:19], v[154:155]
	v_pk_fma_f32 v[14:15], v[60:61], v[18:19], v[14:15]
	v_lshlrev_b32_e32 v16, 16, v7
	v_and_b32_e32 v17, 0xffff0000, v7
	v_cndmask_b32_e64 v7, v12, 0, vcc
	v_pk_fma_f32 v[0:1], v[76:77], v[16:17], v[0:1]
	v_pk_fma_f32 v[18:19], v[74:75], v[16:17], v[20:21]
	v_pk_fma_f32 v[20:21], v[72:73], v[16:17], v[22:23]
	v_pk_fma_f32 v[22:23], v[70:71], v[16:17], v[146:147]
	v_pk_fma_f32 v[146:147], v[68:69], v[16:17], v[148:149]
	v_pk_fma_f32 v[148:149], v[66:67], v[16:17], v[150:151]
	v_pk_fma_f32 v[150:151], v[64:65], v[16:17], v[152:153]
	v_pk_fma_f32 v[14:15], v[62:63], v[16:17], v[14:15]
	v_lshlrev_b32_e32 v16, 16, v7
	v_and_b32_e32 v17, 0xffff0000, v7
	v_cndmask_b32_e64 v7, v8, 0, vcc
	v_pk_fma_f32 v[0:1], v[78:79], v[16:17], v[0:1]
	v_pk_fma_f32 v[18:19], v[76:77], v[16:17], v[18:19]
	v_pk_fma_f32 v[20:21], v[74:75], v[16:17], v[20:21]
	v_pk_fma_f32 v[22:23], v[72:73], v[16:17], v[22:23]
	v_pk_fma_f32 v[146:147], v[70:71], v[16:17], v[146:147]
	v_pk_fma_f32 v[148:149], v[68:69], v[16:17], v[148:149]
	v_pk_fma_f32 v[150:151], v[66:67], v[16:17], v[150:151]
	v_pk_fma_f32 v[14:15], v[64:65], v[16:17], v[14:15]
	v_lshlrev_b32_e32 v16, 16, v7
	v_and_b32_e32 v17, 0xffff0000, v7
	v_pk_fma_f32 v[0:1], v[80:81], v[16:17], v[0:1]
	v_pk_fma_f32 v[18:19], v[78:79], v[16:17], v[18:19]
	v_pk_fma_f32 v[20:21], v[76:77], v[16:17], v[20:21]
	v_pk_fma_f32 v[22:23], v[74:75], v[16:17], v[22:23]
	v_pk_fma_f32 v[146:147], v[72:73], v[16:17], v[146:147]
	v_pk_fma_f32 v[148:149], v[70:71], v[16:17], v[148:149]
	v_pk_fma_f32 v[150:151], v[68:69], v[16:17], v[150:151]
	v_pk_fma_f32 v[14:15], v[66:67], v[16:17], v[14:15]
	v_lshlrev_b32_e32 v16, 16, v3
	v_and_b32_e32 v17, 0xffff0000, v3
	v_pk_fma_f32 v[0:1], v[82:83], v[16:17], v[0:1]
	v_pk_fma_f32 v[18:19], v[80:81], v[16:17], v[18:19]
	v_pk_fma_f32 v[20:21], v[78:79], v[16:17], v[20:21]
	v_pk_fma_f32 v[22:23], v[76:77], v[16:17], v[22:23]
	v_pk_fma_f32 v[146:147], v[74:75], v[16:17], v[146:147]
	v_pk_fma_f32 v[148:149], v[72:73], v[16:17], v[148:149]
	v_pk_fma_f32 v[150:151], v[70:71], v[16:17], v[150:151]
	v_pk_fma_f32 v[14:15], v[68:69], v[16:17], v[14:15]
	v_lshlrev_b32_e32 v16, 16, v2
	v_and_b32_e32 v17, 0xffff0000, v2
	v_pk_fma_f32 v[2:3], v[82:83], v[16:17], v[18:19]
	v_pk_fma_f32 v[18:19], v[80:81], v[16:17], v[20:21]
	v_pk_fma_f32 v[20:21], v[78:79], v[16:17], v[22:23]
	v_pk_fma_f32 v[22:23], v[76:77], v[16:17], v[146:147]
	v_pk_fma_f32 v[146:147], v[74:75], v[16:17], v[148:149]
	v_pk_fma_f32 v[148:149], v[72:73], v[16:17], v[150:151]
; #define LAS __attribute__((address_space(3)))
; __device__ __forceinline__ void conv_phase(LAS unsigned char* lds, const bf16_t* VC, const float* cw, const float* cb, const float* lng, const float* lnb, bf16_t* CAT, int tid, int lane, int wave) {
;     ...
;             for (int t = 0; t < 8; ++t) { const int k = r - t; if (k >= 0 && k < TAPS) av[t] = __builtin_elementwise_fma(wk[k], vf, av[t]); }
;         }
; #pragma unroll
;         for (int t = 0; t < 8; ++t) *(LAS f32x2v*)(ybuf + (th * 8 + t) * CONVC + 2 * cp) = av[t];
;         __syncthreads();
;         {   f32x4 y0[2], y1[2]; float sm[2], sq[2];
; #pragma unroll
;             for (int q = 0; q < 2; ++q) { const LAS float* yr = ybuf + (wave * 2 + q) * CONVC + lane * 8; y0[q] = *(const LAS f32x4*)yr; y1[q] = *(const LAS f32x4*)(yr + 4);
;                 sm[q] = (y0[q].x + y0[q].y) + (y0[q].z + y0[q].w) + (y1[q].x + y1[q].y) + (y1[q].z + y1[q].w);
;                 sq[q] = (y0[q].x * y0[q].x + y0[q].y * y0[q].y) + (y0[q].z * y0[q].z + y0[q].w * y0[q].w) + (y1[q].x * y1[q].x + y1[q].y * y1[q].y) + (y1[q].z * y1[q].z + y1[q].w * y1[q].w); }
; #pragma unroll
;             for (int o = 1; o < 64; o <<= 1) { const float a0 = __shfl_xor(sm[0], o), a1 = __shfl_xor(sq[0], o), a2 = __shfl_xor(sm[1], o), a3 = __shfl_xor(sq[1], o); sm[0] += a0; sq[0] += a1; sm[1] += a2; sq[1] += a3; }
;             const f32x4 g0 = *(const f32x4*)(lng + lane * 8), g1 = *(const f32x4*)(lng + lane * 8 + 4), b0 = *(const f32x4*)(lnb + lane * 8), b1 = *(const f32x4*)(lnb + lane * 8 + 4);
; #pragma unroll
;             for (int q = 0; q < 2; ++q) { const float mu = sm[q] * (1.f / CONVC); const float var = fmaxf(sq[q] * (1.f / CONVC) - mu * mu, 0.f);
;                 const float rs = 1.0f / sqrtf(var + 1e-5f);
	v_pk_fma_f32 v[14:15], v[70:71], v[16:17], v[14:15]
	v_lshlrev_b32_e32 v12, 16, v13
	v_and_b32_e32 v13, 0xffff0000, v13
	v_pk_fma_f32 v[16:17], v[82:83], v[12:13], v[18:19]
	v_pk_fma_f32 v[18:19], v[80:81], v[12:13], v[20:21]
	v_pk_fma_f32 v[20:21], v[78:79], v[12:13], v[22:23]
	v_pk_fma_f32 v[22:23], v[76:77], v[12:13], v[146:147]
	v_pk_fma_f32 v[146:147], v[74:75], v[12:13], v[148:149]
	v_pk_fma_f32 v[12:13], v[72:73], v[12:13], v[14:15]
	v_lshlrev_b32_e32 v10, 16, v11
	v_and_b32_e32 v11, 0xffff0000, v11
	v_pk_fma_f32 v[14:15], v[82:83], v[10:11], v[18:19]
	v_pk_fma_f32 v[18:19], v[80:81], v[10:11], v[20:21]
	v_pk_fma_f32 v[20:21], v[78:79], v[10:11], v[22:23]
	v_pk_fma_f32 v[22:23], v[76:77], v[10:11], v[146:147]
	v_pk_fma_f32 v[10:11], v[74:75], v[10:11], v[12:13]
	v_lshlrev_b32_e32 v8, 16, v9
	v_and_b32_e32 v9, 0xffff0000, v9
	v_pk_fma_f32 v[12:13], v[82:83], v[8:9], v[18:19]
	v_pk_fma_f32 v[18:19], v[80:81], v[8:9], v[20:21]
	v_pk_fma_f32 v[20:21], v[78:79], v[8:9], v[22:23]
	v_pk_fma_f32 v[8:9], v[76:77], v[8:9], v[10:11]
	v_lshlrev_b32_e32 v10, 16, v6
	v_and_b32_e32 v11, 0xffff0000, v6
	v_pk_fma_f32 v[6:7], v[82:83], v[10:11], v[18:19]
	v_pk_fma_f32 v[18:19], v[80:81], v[10:11], v[20:21]
	v_pk_fma_f32 v[8:9], v[78:79], v[10:11], v[8:9]
	v_lshlrev_b32_e32 v10, 16, v5
	v_and_b32_e32 v11, 0xffff0000, v5
	v_pk_fma_f32 v[18:19], v[82:83], v[10:11], v[18:19]
	v_pk_fma_f32 v[8:9], v[80:81], v[10:11], v[8:9]
	v_lshlrev_b32_e32 v10, 16, v4
	v_and_b32_e32 v11, 0xffff0000, v4
	v_add_u32_e32 v145, s5, v24
	v_pk_fma_f32 v[4:5], v[82:83], v[10:11], v[8:9]
	ds_write2st64_b64 v105, v[0:1], v[2:3] offset1:4
	ds_write2st64_b64 v105, v[16:17], v[14:15] offset0:8 offset1:12
	ds_write2st64_b64 v105, v[12:13], v[6:7] offset0:16 offset1:20
	ds_write2st64_b64 v105, v[18:19], v[4:5] offset0:24 offset1:28
	s_waitcnt lgkmcnt(0)
	s_barrier
	ds_read_b128 v[146:149], v145
	ds_read_b128 v[150:153], v145 offset:16
	s_add_i32 s3, s3, s15
	s_waitcnt lgkmcnt(1)
	v_mul_f32_e32 v0, v146, v146
	v_mul_f32_e32 v2, v147, v147
	v_mul_f32_e32 v4, v148, v148
	v_mul_f32_e32 v6, v149, v149
	v_mov_b32_e32 v1, v146
	v_mov_b32_e32 v3, v147
	v_mov_b32_e32 v7, v148
	v_mov_b32_e32 v5, v149
	s_waitcnt lgkmcnt(0)
	v_mul_f32_e32 v8, v150, v150
	v_mul_f32_e32 v10, v151, v151
	v_pk_add_f32 v[0:1], v[0:1], v[2:3]
	v_pk_add_f32 v[2:3], v[6:7], v[4:5]
	v_mov_b32_e32 v9, v150
	v_mov_b32_e32 v11, v151
	v_mul_f32_e32 v12, v152, v152
	v_mul_f32_e32 v14, v153, v153
	v_pk_add_f32 v[0:1], v[0:1], v[2:3]
	v_pk_add_f32 v[2:3], v[8:9], v[10:11]
	v_mov_b32_e32 v13, v152
	v_mov_b32_e32 v15, v153
	v_pk_add_f32 v[0:1], v[0:1], v[2:3]
	v_pk_add_f32 v[2:3], v[12:13], v[14:15]
	global_load_dwordx4 v[8:11], v[92:93], off
	global_load_dwordx4 v[12:15], v[94:95], off
	v_pk_add_f32 v[0:1], v[2:3], v[0:1]
	ds_bpermute_b32 v3, v25, v1
	ds_bpermute_b32 v2, v25, v0
	s_waitcnt lgkmcnt(0)
	v_pk_add_f32 v[0:1], v[0:1], v[2:3]
	ds_bpermute_b32 v3, v99, v1
	ds_bpermute_b32 v2, v99, v0
	s_waitcnt lgkmcnt(0)
	v_pk_add_f32 v[16:17], v[0:1], v[2:3]
	ds_bpermute_b32 v19, v100, v17
	ds_bpermute_b32 v18, v100, v16
	global_load_dwordx4 v[0:3], v[92:93], off offset:16
	global_load_dwordx4 v[4:7], v[94:95], off offset:16
	ds_read_b128 v[20:23], v145 offset:2048
	s_waitcnt lgkmcnt(1)
	v_pk_add_f32 v[16:17], v[16:17], v[18:19]
	ds_bpermute_b32 v19, v101, v17
	ds_bpermute_b32 v18, v101, v16
	s_waitcnt lgkmcnt(0)
	v_pk_add_f32 v[16:17], v[16:17], v[18:19]
	ds_bpermute_b32 v19, v102, v17
	ds_bpermute_b32 v18, v102, v16
	s_waitcnt lgkmcnt(0)
	v_pk_add_f32 v[154:155], v[16:17], v[18:19]
	ds_bpermute_b32 v157, v103, v155
	ds_bpermute_b32 v156, v103, v154
	ds_read_b128 v[16:19], v145 offset:2064
	v_mul_f32_e32 v158, v20, v20
	v_mul_f32_e32 v160, v21, v21
	v_mul_f32_e32 v162, v22, v22
	s_waitcnt lgkmcnt(1)
	v_pk_add_f32 v[154:155], v[154:155], v[156:157]
	s_waitcnt lgkmcnt(0)
	v_mul_f32_e32 v156, v16, v16
	v_pk_mul_f32 v[154:155], v[154:155], s[4:5] op_sel_hi:[1,0]
	v_mul_f32_e32 v164, v17, v17
	v_fma_f32 v145, -v155, v155, v154
	v_max_f32_e32 v145, 0, v145
	v_add_f32_e32 v145, 0x3727c5ac, v145
	v_mul_f32_e32 v154, 0x4f800000, v145
	v_cmp_gt_f32_e32 vcc, s16, v145
	v_sub_f32_e32 v147, v147, v155
	v_sub_f32_e32 v146, v146, v155
	v_cndmask_b32_e32 v145, v145, v154, vcc
	v_sqrt_f32_e32 v157, v145
	v_sub_f32_e32 v149, v149, v155
	v_sub_f32_e32 v148, v148, v155
	v_sub_f32_e32 v153, v153, v155
	v_add_u32_e32 v159, -1, v157
	v_fma_f32 v161, -v159, v157, v145
	v_cmp_ge_f32_e64 s[0:1], 0, v161
	v_add_u32_e32 v161, 1, v157
	v_sub_f32_e32 v152, v152, v155
	v_cndmask_b32_e64 v159, v157, v159, s[0:1]
	v_fma_f32 v157, -v161, v157, v145
	v_cmp_lt_f32_e64 s[0:1], 0, v157
	v_sub_f32_e32 v151, v151, v155
	v_sub_f32_e32 v150, v150, v155
	v_cndmask_b32_e64 v157, v159, v161, s[0:1]
	v_mul_f32_e32 v159, 0x37800000, v157
	v_cndmask_b32_e32 v157, v157, v159, vcc
	v_cmp_class_f32_e32 vcc, v145, v106
	v_mul_f32_e32 v154, v23, v23
	v_mul_f32_e32 v166, v18, v18
	v_cndmask_b32_e32 v145, v157, v145, vcc
	v_div_scale_f32 v157, s[0:1], v145, v145, 1.0
	v_rcp_f32_e32 v159, v157
	v_mul_f32_e32 v168, v19, v19
	v_mov_b32_e32 v167, v18
	v_mov_b32_e32 v169, v19
	v_fma_f32 v161, -v157, v159, 1.0
	v_fmac_f32_e32 v159, v161, v159
	v_div_scale_f32 v161, vcc, 1.0, v145, 1.0
	v_mul_f32_e32 v163, v161, v159
	v_fma_f32 v165, -v157, v163, v161
	v_fmac_f32_e32 v163, v165, v159
	v_fma_f32 v157, -v157, v163, v161
	v_div_fmas_f32 v157, v157, v159, v163
	v_div_fixup_f32 v170, v157, v145, 1.0
	v_pk_mul_f32 v[146:147], v[146:147], v[170:171] op_sel_hi:[1,0]
	v_pk_mul_f32 v[148:149], v[148:149], v[170:171] op_sel_hi:[1,0]
	s_waitcnt vmcnt(2)
; __device__ __forceinline__ unsigned cvt_pk_bf16(float lo, float hi) { unsigned r; asm volatile("v_cvt_pk_bf16_f32 %0, %1, %2" : "=v"(r) : "v"(lo), "v"(hi)); return r; }
; __device__ __forceinline__ float fast_silu(float x) { return x * fast_sigmoid(x); }
; __device__ __forceinline__ void conv_phase(LAS unsigned char* lds, const bf16_t* VC, const float* cw, const float* cb, const float* lng, const float* lnb, bf16_t* CAT, int tid, int lane, int wave) {
;     ...
;                 sm[q] = (y0[q].x + y0[q].y) + (y0[q].z + y0[q].w) + (y1[q].x + y1[q].y) + (y1[q].z + y1[q].w);
;                 sq[q] = (y0[q].x * y0[q].x + y0[q].y * y0[q].y) + (y0[q].z * y0[q].z + y0[q].w * y0[q].w) + (y1[q].x * y1[q].x + y1[q].y * y1[q].y) + (y1[q].z * y1[q].z + y1[q].w * y1[q].w); }
; #pragma unroll
;             for (int o = 1; o < 64; o <<= 1) { const float a0 = __shfl_xor(sm[0], o), a1 = __shfl_xor(sq[0], o), a2 = __shfl_xor(sm[1], o), a3 = __shfl_xor(sq[1], o); sm[0] += a0; sq[0] += a1; sm[1] += a2; sq[1] += a3; }
;             const f32x4 g0 = *(const f32x4*)(lng + lane * 8), g1 = *(const f32x4*)(lng + lane * 8 + 4), b0 = *(const f32x4*)(lnb + lane * 8), b1 = *(const f32x4*)(lnb + lane * 8 + 4);
; #pragma unroll
;             for (int q = 0; q < 2; ++q) { const float mu = sm[q] * (1.f / CONVC); const float var = fmaxf(sq[q] * (1.f / CONVC) - mu * mu, 0.f);
;                 const float rs = 1.0f / sqrtf(var + 1e-5f);
;                 const f32x4 z0 = (y0[q] - mu) * rs * g0 + b0, z1 = (y1[q] - mu) * rs * g1 + b1;
;                 u32x4 w; w.x = cvt_pk_bf16(fast_silu(z0.x), fast_silu(z0.y)); w.y = cvt_pk_bf16(fast_silu(z0.z), fast_silu(z0.w)); w.z = cvt_pk_bf16(fast_silu(z1.x), fast_silu(z1.y)); w.w = cvt_pk_bf16(fast_silu(z1.z), fast_silu(z1.w));
	v_pk_fma_f32 v[146:147], v[8:9], v[146:147], v[12:13]
	v_pk_fma_f32 v[148:149], v[10:11], v[148:149], v[14:15]
	v_mul_f32_e32 v145, 0xbfb8aa3b, v146
	v_exp_f32_e32 v145, v145
	v_mul_f32_e32 v155, 0xbfb8aa3b, v147
	v_exp_f32_e32 v155, v155
	v_mul_f32_e32 v157, 0xbfb8aa3b, v149
	v_add_f32_e32 v145, 1.0, v145
	v_rcp_f32_e32 v145, v145
	v_exp_f32_e32 v157, v157
	v_pk_mul_f32 v[150:151], v[150:151], v[170:171] op_sel_hi:[1,0]
	v_pk_mul_f32 v[152:153], v[152:153], v[170:171] op_sel_hi:[1,0]
	v_mul_f32_e32 v145, v146, v145
	v_add_f32_e32 v146, 1.0, v155
	v_mul_f32_e32 v155, 0xbfb8aa3b, v148
	v_rcp_f32_e32 v146, v146
	v_exp_f32_e32 v155, v155
	v_mov_b32_e32 v159, v20
	v_mov_b32_e32 v161, v21
	v_mul_f32_e32 v170, v147, v146
	v_add_f32_e32 v146, 1.0, v155
	v_rcp_f32_e32 v171, v146
	v_add_f32_e32 v146, 1.0, v157
	v_mov_b32_e32 v155, v22
	v_mov_b32_e32 v163, v23
	v_rcp_f32_e32 v172, v146
	v_pk_add_f32 v[146:147], v[158:159], v[160:161]
	v_pk_add_f32 v[154:155], v[154:155], v[162:163]
	v_mov_b32_e32 v157, v16
	v_mov_b32_e32 v165, v17
	v_pk_add_f32 v[146:147], v[146:147], v[154:155]
	v_pk_add_f32 v[154:155], v[156:157], v[164:165]
	s_waitcnt vmcnt(0)
	v_pk_fma_f32 v[150:151], v[0:1], v[150:151], v[4:5]
	v_pk_add_f32 v[146:147], v[146:147], v[154:155]
	v_pk_add_f32 v[154:155], v[166:167], v[168:169]
	v_pk_fma_f32 v[152:153], v[2:3], v[152:153], v[6:7]
	v_pk_add_f32 v[154:155], v[154:155], v[146:147]
	ds_bpermute_b32 v157, v25, v155
	ds_bpermute_b32 v156, v25, v154
	v_cvt_pk_bf16_f32 v146, v145, v170
	v_mul_f32_e32 v145, v148, v171
	v_mul_f32_e32 v147, v149, v172
	v_cvt_pk_bf16_f32 v147, v145, v147
	s_waitcnt lgkmcnt(0)
	v_pk_add_f32 v[148:149], v[154:155], v[156:157]
	ds_bpermute_b32 v155, v99, v149
	ds_bpermute_b32 v154, v99, v148
	v_mul_f32_e32 v145, 0xbfb8aa3b, v150
	v_exp_f32_e32 v145, v145
	v_mul_f32_e32 v156, 0xbfb8aa3b, v151
	v_exp_f32_e32 v156, v156
	s_waitcnt lgkmcnt(0)
	v_pk_add_f32 v[148:149], v[148:149], v[154:155]
	ds_bpermute_b32 v155, v100, v149
	ds_bpermute_b32 v154, v100, v148
	v_add_f32_e32 v145, 1.0, v145
	v_rcp_f32_e32 v145, v145
	v_add_f32_e32 v156, 1.0, v156
	v_rcp_f32_e32 v156, v156
	s_waitcnt lgkmcnt(0)
	v_pk_add_f32 v[148:149], v[148:149], v[154:155]
	ds_bpermute_b32 v155, v101, v149
	ds_bpermute_b32 v154, v101, v148
	v_mul_f32_e32 v145, v150, v145
	v_mul_f32_e32 v150, 0xbfb8aa3b, v152
	v_mul_f32_e32 v156, v151, v156
	v_exp_f32_e32 v157, v150
	s_waitcnt lgkmcnt(0)
	v_pk_add_f32 v[148:149], v[148:149], v[154:155]
	ds_bpermute_b32 v151, v102, v149
	ds_bpermute_b32 v150, v102, v148
	v_add_f32_e32 v154, 1.0, v157
	v_rcp_f32_e32 v157, v154
	v_mul_f32_e32 v154, 0xbfb8aa3b, v153
	v_exp_f32_e32 v158, v154
	s_waitcnt lgkmcnt(0)
	v_pk_add_f32 v[150:151], v[148:149], v[150:151]
	ds_bpermute_b32 v155, v103, v151
	ds_bpermute_b32 v154, v103, v150
	v_cvt_pk_bf16_f32 v148, v145, v156
	v_mul_f32_e32 v145, v152, v157
	v_add_f32_e32 v149, 1.0, v158
	v_rcp_f32_e32 v149, v149
	s_waitcnt lgkmcnt(0)
; __device__ __forceinline__ unsigned cvt_pk_bf16(float lo, float hi) { unsigned r; asm volatile("v_cvt_pk_bf16_f32 %0, %1, %2" : "=v"(r) : "v"(lo), "v"(hi)); return r; }
; __device__ __forceinline__ float fast_silu(float x) { return x * fast_sigmoid(x); }
; #define CONV_LOAD(dst, it_) do { const int t0_ = (it_) * 16 + th * 8, tb_ = t0_ & (SEQ - 1); \
;         _Pragma("unroll") for (int r = 0; r < 38; ++r) { const int pos = tb_ - 30 + r; dst[r] = *(const unsigned*)(VC + (size_t)(t0_ - tb_ + (pos < 0 ? 0 : pos)) * CONVC + 2 * cp); } } while (0)
; __device__ __forceinline__ void conv_phase(LAS unsigned char* lds, const bf16_t* VC, const float* cw, const float* cb, const float* lng, const float* lnb, bf16_t* CAT, int tid, int lane, int wave) {
;     ...
;         unsigned vv[38];
; #pragma unroll
;         for (int r = 0; r < 38; ++r) vv[r] = vn[r];
;         if (it + (int)gridDim.x < T / 16) CONV_LOAD(vn, it + (int)gridDim.x);
;     ...
;             for (int q = 0; q < 2; ++q) { const float mu = sm[q] * (1.f / CONVC); const float var = fmaxf(sq[q] * (1.f / CONVC) - mu * mu, 0.f);
;                 const float rs = 1.0f / sqrtf(var + 1e-5f);
;                 const f32x4 z0 = (y0[q] - mu) * rs * g0 + b0, z1 = (y1[q] - mu) * rs * g1 + b1;
;                 u32x4 w; w.x = cvt_pk_bf16(fast_silu(z0.x), fast_silu(z0.y)); w.y = cvt_pk_bf16(fast_silu(z0.z), fast_silu(z0.w)); w.z = cvt_pk_bf16(fast_silu(z1.x), fast_silu(z1.y)); w.w = cvt_pk_bf16(fast_silu(z1.z), fast_silu(z1.w));
;                 *(u32x4*)(CAT + (size_t)(it * 16 + wave * 2 + q) * D + lane * 8) = w; } }
;         __syncthreads();
	v_pk_add_f32 v[150:151], v[150:151], v[154:155]
	v_mov_b32_e32 v159, v107
	v_pk_mul_f32 v[150:151], v[150:151], s[4:5] op_sel_hi:[1,0]
	v_mul_f32_e32 v149, v153, v149
	v_fma_f32 v150, -v151, v151, v150
	v_max_f32_e32 v150, 0, v150
	v_add_f32_e32 v150, 0x3727c5ac, v150
	v_mul_f32_e32 v152, 0x4f800000, v150
	v_cmp_gt_f32_e32 vcc, s16, v150
	v_cvt_pk_bf16_f32 v149, v145, v149
	v_sub_f32_e32 v21, v21, v151
	v_sub_f32_e32 v20, v20, v151
	v_cndmask_b32_e32 v150, v150, v152, vcc
	v_sqrt_f32_e32 v152, v150
	v_sub_f32_e32 v23, v23, v151
	v_sub_f32_e32 v22, v22, v151
	v_mov_b32_e32 v158, v108
	v_add_u32_e32 v145, -1, v152
	v_fma_f32 v153, -v145, v152, v150
	v_cmp_ge_f32_e64 s[0:1], 0, v153
	v_add_u32_e32 v153, 1, v152
	v_mov_b32_e32 v156, v109
	v_cndmask_b32_e64 v145, v152, v145, s[0:1]
	v_fma_f32 v152, -v153, v152, v150
	v_cmp_lt_f32_e64 s[0:1], 0, v152
	v_mov_b32_e32 v155, v110
	v_mov_b32_e32 v160, v115
	v_cndmask_b32_e64 v145, v145, v153, s[0:1]
	v_mul_f32_e32 v152, 0x37800000, v145
	v_cndmask_b32_e32 v145, v145, v152, vcc
	v_cmp_class_f32_e32 vcc, v150, v106
	v_mov_b32_e32 v157, v116
	s_nop 0
	v_cndmask_b32_e32 v145, v145, v150, vcc
	v_div_scale_f32 v150, s[0:1], v145, v145, 1.0
	v_rcp_f32_e32 v154, v150
	s_lshl_b64 s[0:1], s[12:13], 11
	v_lshl_add_u64 v[152:153], v[96:97], 0, s[0:1]
	global_store_dwordx4 v[152:153], v[146:149], off sc1
	s_add_i32 s0, s12, 1
	s_ashr_i32 s1, s0, 31
	v_fma_f32 v146, -v150, v154, 1.0
	v_fmac_f32_e32 v154, v146, v154
	v_div_scale_f32 v146, vcc, 1.0, v145, 1.0
	v_mul_f32_e32 v147, v146, v154
	v_fma_f32 v148, -v150, v147, v146
	v_fmac_f32_e32 v147, v148, v154
	v_fma_f32 v146, -v150, v147, v146
	v_div_fmas_f32 v146, v146, v154, v147
	v_div_fixup_f32 v146, v146, v145, 1.0
	v_pk_mul_f32 v[20:21], v[20:21], v[146:147] op_sel_hi:[1,0]
	v_pk_mul_f32 v[22:23], v[22:23], v[146:147] op_sel_hi:[1,0]
	v_pk_fma_f32 v[8:9], v[8:9], v[20:21], v[12:13]
	v_sub_f32_e32 v13, v19, v151
	v_sub_f32_e32 v12, v18, v151
	v_pk_mul_f32 v[12:13], v[12:13], v[146:147] op_sel_hi:[1,0]
	v_pk_fma_f32 v[10:11], v[10:11], v[22:23], v[14:15]
	v_pk_fma_f32 v[6:7], v[2:3], v[12:13], v[6:7]
	v_mul_f32_e32 v2, 0xbfb8aa3b, v8
	v_exp_f32_e32 v12, v2
	v_mul_f32_e32 v2, 0xbfb8aa3b, v9
	v_exp_f32_e32 v13, v2
	v_sub_f32_e32 v15, v17, v151
	v_sub_f32_e32 v14, v16, v151
	v_pk_mul_f32 v[14:15], v[14:15], v[146:147] op_sel_hi:[1,0]
	s_lshl_b64 s[0:1], s[0:1], 11
	v_pk_fma_f32 v[2:3], v[0:1], v[14:15], v[4:5]
	v_add_f32_e32 v0, 1.0, v12
	v_add_f32_e32 v1, 1.0, v13
	v_rcp_f32_e32 v0, v0
	v_rcp_f32_e32 v1, v1
	v_mul_f32_e32 v4, 0xbfb8aa3b, v10
	v_exp_f32_e32 v4, v4
	v_mul_f32_e32 v0, v8, v0
	v_mul_f32_e32 v1, v9, v1
	v_cvt_pk_bf16_f32 v0, v0, v1
	v_add_f32_e32 v1, 1.0, v4
	v_mul_f32_e32 v4, 0xbfb8aa3b, v11
	v_exp_f32_e32 v4, v4
	v_mul_f32_e32 v5, 0xbfb8aa3b, v2
	v_exp_f32_e32 v5, v5
	v_rcp_f32_e32 v1, v1
	v_add_f32_e32 v4, 1.0, v4
	v_rcp_f32_e32 v4, v4
	v_add_f32_e32 v5, 1.0, v5
	v_mul_f32_e32 v8, 0xbfb8aa3b, v3
	v_rcp_f32_e32 v5, v5
	v_exp_f32_e32 v8, v8
	v_mul_f32_e32 v1, v10, v1
	v_mul_f32_e32 v4, v11, v4
	v_cvt_pk_bf16_f32 v1, v1, v4
	v_mul_f32_e32 v2, v2, v5
	v_add_f32_e32 v4, 1.0, v8
	v_mul_f32_e32 v5, 0xbfb8aa3b, v6
	v_mul_f32_e32 v8, 0xbfb8aa3b, v7
	v_exp_f32_e32 v5, v5
	v_exp_f32_e32 v8, v8
	v_rcp_f32_e32 v4, v4
	s_andn2_b64 vcc, exec, s[10:11]
	v_add_f32_e32 v5, 1.0, v5
	v_add_f32_e32 v8, 1.0, v8
	v_rcp_f32_e32 v5, v5
	v_rcp_f32_e32 v8, v8
	v_mul_f32_e32 v3, v3, v4
	v_cvt_pk_bf16_f32 v2, v2, v3
	v_mul_f32_e32 v3, v6, v5
	v_mul_f32_e32 v4, v7, v8
	v_cvt_pk_bf16_f32 v3, v3, v4
	v_lshl_add_u64 v[4:5], v[96:97], 0, s[0:1]
	global_store_dwordx4 v[4:5], v[0:3], off sc1
	v_mov_b32_e32 v152, v111
	v_mov_b32_e32 v149, v112
	v_mov_b32_e32 v147, v113
	v_mov_b32_e32 v23, v114
	v_mov_b32_e32 v154, v117
	v_mov_b32_e32 v151, v118
	v_mov_b32_e32 v148, v119
	v_mov_b32_e32 v22, v120
	v_mov_b32_e32 v19, v121
	v_mov_b32_e32 v15, v122
	v_mov_b32_e32 v153, v123
	v_mov_b32_e32 v150, v124
	v_mov_b32_e32 v146, v125
	v_mov_b32_e32 v21, v126
	v_mov_b32_e32 v17, v127
	v_mov_b32_e32 v14, v128
	v_mov_b32_e32 v10, v129
	v_mov_b32_e32 v7, v130
	v_mov_b32_e32 v145, v131
	v_mov_b32_e32 v20, v132
	v_mov_b32_e32 v18, v133
	v_mov_b32_e32 v16, v134
	v_mov_b32_e32 v12, v135
	v_mov_b32_e32 v8, v136
	v_mov_b32_e32 v3, v137
	v_mov_b32_e32 v2, v138
	v_mov_b32_e32 v13, v139
	v_mov_b32_e32 v11, v140
	v_mov_b32_e32 v9, v141
	v_mov_b32_e32 v6, v142
	v_mov_b32_e32 v5, v143
	v_mov_b32_e32 v4, v144
	s_barrier
	s_cbranch_vccz .LBB0_485

; __device__ __forceinline__ unsigned cvt_pk_bf16(float lo, float hi) { unsigned r; asm volatile("v_cvt_pk_bf16_f32 %0, %1, %2" : "=v"(r) : "v"(lo), "v"(hi)); return r; }
; __device__ __forceinline__ float fast_sigmoid(float x) { return __builtin_amdgcn_rcpf(1.f + __builtin_amdgcn_exp2f(-x * LOG2E)); }
;     __device__ __forceinline__ void operator()(const f32x4 (&acc)[2][2][4][2], const pg8::Unit& u, int wr, int wc, int fr, int fq) const {
;         const int row0 = u.pm * 256 + wr * 64 + fr, col0 = u.pn * 256 + wc * 32 + 8 * fq;
; #pragma unroll
;         for (int bj = 0; bj < 2; ++bj) { const int c = col0 + bj * 128; const f32x4 b0 = *(const f32x4*)(bias + c), b1 = *(const f32x4*)(bias + c + 4);
; #pragma unroll
;             for (int ai = 0; ai < 2; ++ai)
; #pragma unroll
;                 for (int m = 0; m < 4; ++m) { const size_t r = (size_t)(row0 + ai * 128 + m * 16);
;                     const u32x4 y = *(const u32x4*)(YB + r * SSMW + c); const f32x4 v0 = acc[ai][bj][m][0] + b0, v1 = acc[ai][bj][m][1] + b1;
;                     u32x4 w; w.x = cvt_pk_bf16(bf_lo(y.x) * fast_sigmoid(v0[0]), bf_hi(y.x) * fast_sigmoid(v0[1])); w.y = cvt_pk_bf16(bf_lo(y.y) * fast_sigmoid(v0[2]), bf_hi(y.y) * fast_sigmoid(v0[3]));
;                     w.z = cvt_pk_bf16(bf_lo(y.z) * fast_sigmoid(v1[0]), bf_hi(y.z) * fast_sigmoid(v1[1])); w.w = cvt_pk_bf16(bf_lo(y.w) * fast_sigmoid(v1[2]), bf_hi(y.w) * fast_sigmoid(v1[3]));
;                     *(u32x4*)(CAT + r * D + 512 + c) = w; } }
.LBB0_627:
	v_lshl_or_b32 v152, s62, 8, v166
	v_ashrrev_i32_e32 v153, 31, v152
	v_lshl_add_u64 v[156:157], v[152:153], 2, s[44:45]
	global_load_dwordx4 v[116:119], v[156:157], off
	global_load_dwordx4 v[112:115], v[156:157], off offset:16
	v_lshl_add_u32 v162, s34, 8, v164
	v_ashrrev_i32_e32 v163, 31, v162
	v_lshlrev_b64 v[154:155], 10, v[162:163]
	v_lshlrev_b64 v[158:159], 1, v[152:153]
	v_lshl_add_u64 v[152:153], s[0:1], 0, v[154:155]
	v_lshl_add_u64 v[160:161], v[152:153], 0, v[158:159]
	global_load_dwordx4 v[170:173], v[160:161], off
	v_or_b32_e32 v174, 16, v162
	v_lshlrev_b64 v[152:153], 11, v[162:163]
	v_ashrrev_i32_e32 v175, 31, v174
	v_lshl_add_u64 v[152:153], s[42:43], 0, v[152:153]
	v_lshlrev_b64 v[154:155], 10, v[174:175]
	v_lshl_add_u64 v[152:153], v[152:153], 0, v[158:159]
	v_lshl_add_u64 v[154:155], s[0:1], 0, v[154:155]
	v_lshl_add_u64 v[154:155], v[154:155], 0, v[158:159]
	s_andn2_b64 vcc, exec, s[4:5]
	s_mov_b64 s[4:5], -1
	s_waitcnt vmcnt(0)
	v_pk_add_f32 v[134:135], v[134:135], v[118:119]
	v_pk_add_f32 v[130:131], v[130:131], v[114:115]
	v_pk_add_f32 v[132:133], v[132:133], v[116:117]
	v_pk_add_f32 v[128:129], v[128:129], v[112:113]
	v_mul_f32_e32 v131, 0xbfb8aa3b, v131
	v_mul_f32_e32 v132, 0xbfb8aa3b, v132
	v_mul_f32_e32 v133, 0xbfb8aa3b, v133
	v_mul_f32_e32 v134, 0xbfb8aa3b, v134
	v_mul_f32_e32 v135, 0xbfb8aa3b, v135
	v_mul_f32_e32 v128, 0xbfb8aa3b, v128
	v_mul_f32_e32 v129, 0xbfb8aa3b, v129
	v_mul_f32_e32 v130, 0xbfb8aa3b, v130
	v_exp_f32_e32 v131, v131
	v_exp_f32_e32 v132, v132
	v_exp_f32_e32 v133, v133
	v_exp_f32_e32 v134, v134
	v_exp_f32_e32 v135, v135
	v_exp_f32_e32 v128, v128
	v_exp_f32_e32 v129, v129
	v_exp_f32_e32 v130, v130
	v_add_f32_e32 v131, 1.0, v131
	v_add_f32_e32 v132, 1.0, v132
	v_add_f32_e32 v133, 1.0, v133
	v_add_f32_e32 v134, 1.0, v134
	v_add_f32_e32 v135, 1.0, v135
	v_add_f32_e32 v128, 1.0, v128
	v_add_f32_e32 v129, 1.0, v129
	v_add_f32_e32 v130, 1.0, v130
	v_rcp_f32_e32 v131, v131
	v_rcp_f32_e32 v132, v132
	v_rcp_f32_e32 v133, v133
	v_rcp_f32_e32 v134, v134
	v_rcp_f32_e32 v135, v135
	v_rcp_f32_e32 v128, v128
	v_rcp_f32_e32 v129, v129
	v_rcp_f32_e32 v130, v130
	v_lshlrev_b32_e32 v178, 16, v173
	v_and_b32_e32 v173, 0xffff0000, v173
	v_lshlrev_b32_e32 v163, 16, v170
	v_and_b32_e32 v170, 0xffff0000, v170
	v_lshlrev_b32_e32 v176, 16, v171
	v_and_b32_e32 v171, 0xffff0000, v171
	v_lshlrev_b32_e32 v177, 16, v172
	v_and_b32_e32 v172, 0xffff0000, v172
	v_mul_f32_e32 v131, v131, v173
	v_mul_f32_e32 v132, v132, v163
	v_mul_f32_e32 v133, v133, v170
	v_mul_f32_e32 v134, v134, v176
	v_mul_f32_e32 v135, v135, v171
	v_mul_f32_e32 v163, v128, v177
	v_mul_f32_e32 v170, v129, v172
	v_mul_f32_e32 v171, v130, v178
	v_cvt_pk_bf16_f32 v128, v132, v133
	v_cvt_pk_bf16_f32 v129, v134, v135
	v_cvt_pk_bf16_f32 v130, v163, v170
	v_cvt_pk_bf16_f32 v131, v171, v131
	global_store_dwordx4 v[152:153], v[128:131], off offset:1024 sc1
	global_load_dwordx4 v[132:135], v[154:155], off
	v_pk_add_f32 v[122:123], v[122:123], v[114:115]
	v_pk_add_f32 v[126:127], v[126:127], v[118:119]
	v_pk_add_f32 v[124:125], v[124:125], v[116:117]
	v_pk_add_f32 v[120:121], v[120:121], v[112:113]
	v_mul_f32_e32 v123, 0xbfb8aa3b, v123
	v_mul_f32_e32 v124, 0xbfb8aa3b, v124
	v_mul_f32_e32 v125, 0xbfb8aa3b, v125
	v_mul_f32_e32 v126, 0xbfb8aa3b, v126
	v_mul_f32_e32 v127, 0xbfb8aa3b, v127
	v_mul_f32_e32 v120, 0xbfb8aa3b, v120
	v_mul_f32_e32 v121, 0xbfb8aa3b, v121
	v_mul_f32_e32 v122, 0xbfb8aa3b, v122
	v_exp_f32_e32 v123, v123
	v_exp_f32_e32 v124, v124
	v_exp_f32_e32 v125, v125
	v_exp_f32_e32 v126, v126
	v_exp_f32_e32 v127, v127
	v_exp_f32_e32 v120, v120
	v_exp_f32_e32 v121, v121
	v_exp_f32_e32 v122, v122
	v_add_f32_e32 v123, 1.0, v123
	v_add_f32_e32 v124, 1.0, v124
	v_add_f32_e32 v125, 1.0, v125
	v_add_f32_e32 v126, 1.0, v126
	v_add_f32_e32 v127, 1.0, v127
	v_add_f32_e32 v120, 1.0, v120
	v_add_f32_e32 v121, 1.0, v121
	v_add_f32_e32 v122, 1.0, v122
	v_rcp_f32_e32 v123, v123
	v_or_b32_e32 v170, 32, v162
	v_rcp_f32_e32 v124, v124
	v_rcp_f32_e32 v125, v125
	v_rcp_f32_e32 v126, v126
	v_rcp_f32_e32 v127, v127
	v_rcp_f32_e32 v120, v120
	v_rcp_f32_e32 v121, v121
	v_rcp_f32_e32 v122, v122
	v_ashrrev_i32_e32 v171, 31, v170
	v_lshlrev_b64 v[128:129], 11, v[174:175]
	v_lshlrev_b64 v[130:131], 10, v[170:171]
	v_lshl_add_u64 v[128:129], s[42:43], 0, v[128:129]
	v_lshl_add_u64 v[130:131], s[0:1], 0, v[130:131]
	v_lshl_add_u64 v[128:129], v[128:129], 0, v[158:159]
	v_lshl_add_u64 v[130:131], v[130:131], 0, v[158:159]
	v_pk_add_f32 v[106:107], v[106:107], v[114:115]
	v_pk_add_f32 v[110:111], v[110:111], v[118:119]
	v_pk_add_f32 v[108:109], v[108:109], v[116:117]
	v_pk_add_f32 v[104:105], v[104:105], v[112:113]
	v_mul_f32_e32 v107, 0xbfb8aa3b, v107
	v_mul_f32_e32 v108, 0xbfb8aa3b, v108
	v_mul_f32_e32 v109, 0xbfb8aa3b, v109
	v_mul_f32_e32 v110, 0xbfb8aa3b, v110
	v_mul_f32_e32 v111, 0xbfb8aa3b, v111
	v_mul_f32_e32 v104, 0xbfb8aa3b, v104
	v_mul_f32_e32 v105, 0xbfb8aa3b, v105
	v_mul_f32_e32 v106, 0xbfb8aa3b, v106
	v_exp_f32_e32 v107, v107
	v_exp_f32_e32 v108, v108
	v_exp_f32_e32 v109, v109
	v_exp_f32_e32 v110, v110
	v_exp_f32_e32 v111, v111
	v_exp_f32_e32 v104, v104
	v_exp_f32_e32 v105, v105
	v_exp_f32_e32 v106, v106
	v_add_f32_e32 v107, 1.0, v107
	v_add_f32_e32 v108, 1.0, v108
	v_add_f32_e32 v109, 1.0, v109
	v_add_f32_e32 v110, 1.0, v110
	v_add_f32_e32 v111, 1.0, v111
	v_add_f32_e32 v104, 1.0, v104
	v_add_f32_e32 v105, 1.0, v105
	v_add_f32_e32 v106, 1.0, v106
	v_rcp_f32_e32 v107, v107
	v_rcp_f32_e32 v108, v108
	v_rcp_f32_e32 v109, v109
	v_rcp_f32_e32 v110, v110
	v_rcp_f32_e32 v111, v111
	v_rcp_f32_e32 v104, v104
	v_rcp_f32_e32 v105, v105
	s_waitcnt vmcnt(0)
; __device__ __forceinline__ unsigned cvt_pk_bf16(float lo, float hi) { unsigned r; asm volatile("v_cvt_pk_bf16_f32 %0, %1, %2" : "=v"(r) : "v"(lo), "v"(hi)); return r; }
; __device__ __forceinline__ float fast_sigmoid(float x) { return __builtin_amdgcn_rcpf(1.f + __builtin_amdgcn_exp2f(-x * LOG2E)); }
;     __device__ __forceinline__ void operator()(const f32x4 (&acc)[2][2][4][2], const pg8::Unit& u, int wr, int wc, int fr, int fq) const {
;     ...
;             for (int ai = 0; ai < 2; ++ai)
; #pragma unroll
;                 for (int m = 0; m < 4; ++m) { const size_t r = (size_t)(row0 + ai * 128 + m * 16);
;                     const u32x4 y = *(const u32x4*)(YB + r * SSMW + c); const f32x4 v0 = acc[ai][bj][m][0] + b0, v1 = acc[ai][bj][m][1] + b1;
;                     u32x4 w; w.x = cvt_pk_bf16(bf_lo(y.x) * fast_sigmoid(v0[0]), bf_hi(y.x) * fast_sigmoid(v0[1])); w.y = cvt_pk_bf16(bf_lo(y.y) * fast_sigmoid(v0[2]), bf_hi(y.y) * fast_sigmoid(v0[3]));
;                     w.z = cvt_pk_bf16(bf_lo(y.z) * fast_sigmoid(v1[0]), bf_hi(y.z) * fast_sigmoid(v1[1])); w.w = cvt_pk_bf16(bf_lo(y.w) * fast_sigmoid(v1[2]), bf_hi(y.w) * fast_sigmoid(v1[3]));
;                     *(u32x4*)(CAT + r * D + 512 + c) = w; } }
	v_lshlrev_b32_e32 v174, 16, v135
	v_and_b32_e32 v135, 0xffff0000, v135
	v_lshlrev_b32_e32 v163, 16, v132
	v_and_b32_e32 v132, 0xffff0000, v132
	v_lshlrev_b32_e32 v172, 16, v133
	v_and_b32_e32 v133, 0xffff0000, v133
	v_lshlrev_b32_e32 v173, 16, v134
	v_and_b32_e32 v134, 0xffff0000, v134
	v_mul_f32_e32 v123, v123, v135
	v_mul_f32_e32 v124, v124, v163
	v_mul_f32_e32 v125, v125, v132
	v_mul_f32_e32 v126, v126, v172
	v_mul_f32_e32 v127, v127, v133
	v_mul_f32_e32 v132, v120, v173
	v_mul_f32_e32 v133, v121, v134
	v_mul_f32_e32 v134, v122, v174
	v_cvt_pk_bf16_f32 v120, v124, v125
	v_cvt_pk_bf16_f32 v121, v126, v127
	v_cvt_pk_bf16_f32 v122, v132, v133
	v_cvt_pk_bf16_f32 v123, v134, v123
	global_store_dwordx4 v[128:129], v[120:123], off offset:1024 sc1
	global_load_dwordx4 v[124:127], v[130:131], off
	v_or_b32_e32 v132, 48, v162
	v_rcp_f32_e32 v106, v106
	v_ashrrev_i32_e32 v133, 31, v132
	v_lshlrev_b64 v[120:121], 11, v[170:171]
	v_lshlrev_b64 v[122:123], 10, v[132:133]
	v_lshl_add_u64 v[120:121], s[42:43], 0, v[120:121]
	v_lshl_add_u64 v[122:123], s[0:1], 0, v[122:123]
	v_lshl_add_u64 v[120:121], v[120:121], 0, v[158:159]
	v_lshl_add_u64 v[122:123], v[122:123], 0, v[158:159]
	v_pk_add_f32 v[98:99], v[98:99], v[114:115]
	v_pk_add_f32 v[102:103], v[102:103], v[118:119]
	v_pk_add_f32 v[100:101], v[100:101], v[116:117]
	v_pk_add_f32 v[96:97], v[96:97], v[112:113]
	v_mul_f32_e32 v99, 0xbfb8aa3b, v99
	v_mul_f32_e32 v100, 0xbfb8aa3b, v100
	v_mul_f32_e32 v101, 0xbfb8aa3b, v101
	v_mul_f32_e32 v102, 0xbfb8aa3b, v102
	v_mul_f32_e32 v103, 0xbfb8aa3b, v103
	v_mul_f32_e32 v96, 0xbfb8aa3b, v96
	v_mul_f32_e32 v97, 0xbfb8aa3b, v97
	v_mul_f32_e32 v98, 0xbfb8aa3b, v98
	v_exp_f32_e32 v99, v99
	v_exp_f32_e32 v100, v100
	v_exp_f32_e32 v101, v101
	v_exp_f32_e32 v102, v102
	v_exp_f32_e32 v103, v103
	v_exp_f32_e32 v96, v96
	v_exp_f32_e32 v97, v97
	v_exp_f32_e32 v98, v98
	v_add_f32_e32 v99, 1.0, v99
	v_add_f32_e32 v100, 1.0, v100
	v_add_f32_e32 v101, 1.0, v101
	v_add_f32_e32 v102, 1.0, v102
	v_add_f32_e32 v103, 1.0, v103
	v_add_f32_e32 v96, 1.0, v96
	v_add_f32_e32 v97, 1.0, v97
	v_add_f32_e32 v98, 1.0, v98
	v_rcp_f32_e32 v99, v99
	v_rcp_f32_e32 v100, v100
	v_rcp_f32_e32 v101, v101
	v_rcp_f32_e32 v102, v102
	v_rcp_f32_e32 v103, v103
	v_rcp_f32_e32 v96, v96
	v_rcp_f32_e32 v97, v97
	v_rcp_f32_e32 v98, v98
	v_pk_add_f32 v[90:91], v[90:91], v[114:115]
	v_pk_add_f32 v[94:95], v[94:95], v[118:119]
	v_pk_add_f32 v[92:93], v[92:93], v[116:117]
	v_pk_add_f32 v[88:89], v[88:89], v[112:113]
	v_mul_f32_e32 v91, 0xbfb8aa3b, v91
	v_mul_f32_e32 v92, 0xbfb8aa3b, v92
	v_mul_f32_e32 v93, 0xbfb8aa3b, v93
	v_mul_f32_e32 v94, 0xbfb8aa3b, v94
	v_mul_f32_e32 v95, 0xbfb8aa3b, v95
	v_mul_f32_e32 v88, 0xbfb8aa3b, v88
	v_mul_f32_e32 v89, 0xbfb8aa3b, v89
	v_mul_f32_e32 v90, 0xbfb8aa3b, v90
	v_exp_f32_e32 v91, v91
	v_exp_f32_e32 v92, v92
	v_exp_f32_e32 v93, v93
	v_exp_f32_e32 v94, v94
	v_exp_f32_e32 v95, v95
	v_exp_f32_e32 v88, v88
	v_exp_f32_e32 v89, v89
	v_exp_f32_e32 v90, v90
	v_add_f32_e32 v91, 1.0, v91
	v_add_f32_e32 v92, 1.0, v92
	v_add_f32_e32 v93, 1.0, v93
	v_add_f32_e32 v94, 1.0, v94
	v_add_f32_e32 v95, 1.0, v95
	v_add_f32_e32 v88, 1.0, v88
	v_add_f32_e32 v89, 1.0, v89
	v_add_f32_e32 v90, 1.0, v90
	v_rcp_f32_e32 v91, v91
	v_rcp_f32_e32 v92, v92
	v_rcp_f32_e32 v93, v93
	v_rcp_f32_e32 v94, v94
	v_rcp_f32_e32 v95, v95
	v_rcp_f32_e32 v88, v88
	s_waitcnt vmcnt(0)
	v_lshlrev_b32_e32 v170, 16, v127
	v_and_b32_e32 v127, 0xffff0000, v127
	v_lshlrev_b32_e32 v134, 16, v124
	v_and_b32_e32 v124, 0xffff0000, v124
	v_lshlrev_b32_e32 v135, 16, v125
	v_and_b32_e32 v125, 0xffff0000, v125
	v_lshlrev_b32_e32 v163, 16, v126
	v_and_b32_e32 v126, 0xffff0000, v126
	v_mul_f32_e32 v107, v107, v127
	v_mul_f32_e32 v108, v108, v134
	v_mul_f32_e32 v109, v109, v124
	v_mul_f32_e32 v110, v110, v135
	v_mul_f32_e32 v111, v111, v125
	v_mul_f32_e32 v124, v104, v163
	v_mul_f32_e32 v125, v105, v126
	v_mul_f32_e32 v126, v106, v170
	v_cvt_pk_bf16_f32 v104, v108, v109
	v_cvt_pk_bf16_f32 v105, v110, v111
	v_cvt_pk_bf16_f32 v106, v124, v125
	v_cvt_pk_bf16_f32 v107, v126, v107
	global_store_dwordx4 v[120:121], v[104:107], off offset:1024 sc1
	global_load_dwordx4 v[108:111], v[122:123], off
	v_add_u32_e32 v124, 0x80, v162
	v_ashrrev_i32_e32 v125, 31, v124
	v_lshlrev_b64 v[104:105], 11, v[132:133]
	v_lshlrev_b64 v[106:107], 10, v[124:125]
	v_lshl_add_u64 v[104:105], s[42:43], 0, v[104:105]
	v_lshl_add_u64 v[106:107], s[0:1], 0, v[106:107]
	v_lshl_add_u64 v[104:105], v[104:105], 0, v[158:159]
	v_lshl_add_u64 v[106:107], v[106:107], 0, v[158:159]
	v_rcp_f32_e32 v89, v89
	v_rcp_f32_e32 v90, v90
	v_pk_add_f32 v[82:83], v[82:83], v[114:115]
	v_pk_add_f32 v[86:87], v[86:87], v[118:119]
	v_pk_add_f32 v[84:85], v[84:85], v[116:117]
	v_pk_add_f32 v[80:81], v[80:81], v[112:113]
	v_mul_f32_e32 v83, 0xbfb8aa3b, v83
	v_mul_f32_e32 v84, 0xbfb8aa3b, v84
	v_mul_f32_e32 v85, 0xbfb8aa3b, v85
	v_mul_f32_e32 v86, 0xbfb8aa3b, v86
	v_mul_f32_e32 v87, 0xbfb8aa3b, v87
	v_mul_f32_e32 v80, 0xbfb8aa3b, v80
	v_mul_f32_e32 v81, 0xbfb8aa3b, v81
	v_mul_f32_e32 v82, 0xbfb8aa3b, v82
	v_exp_f32_e32 v83, v83
	v_exp_f32_e32 v84, v84
	v_exp_f32_e32 v85, v85
	v_exp_f32_e32 v86, v86
	v_exp_f32_e32 v87, v87
	v_exp_f32_e32 v80, v80
	v_exp_f32_e32 v81, v81
	v_exp_f32_e32 v82, v82
	v_add_f32_e32 v83, 1.0, v83
	v_add_f32_e32 v84, 1.0, v84
	v_add_f32_e32 v85, 1.0, v85
	v_add_f32_e32 v86, 1.0, v86
	v_add_f32_e32 v87, 1.0, v87
	v_add_f32_e32 v80, 1.0, v80
	v_add_f32_e32 v81, 1.0, v81
	v_add_f32_e32 v82, 1.0, v82
	v_rcp_f32_e32 v83, v83
	v_rcp_f32_e32 v84, v84
	v_rcp_f32_e32 v85, v85
	v_rcp_f32_e32 v86, v86
	v_rcp_f32_e32 v87, v87
	v_rcp_f32_e32 v80, v80
	v_rcp_f32_e32 v81, v81
	v_rcp_f32_e32 v82, v82
	v_pk_add_f32 v[74:75], v[74:75], v[114:115]
	v_pk_add_f32 v[78:79], v[78:79], v[118:119]
	v_pk_add_f32 v[76:77], v[76:77], v[116:117]
	v_pk_add_f32 v[72:73], v[72:73], v[112:113]
	v_mul_f32_e32 v75, 0xbfb8aa3b, v75
	v_mul_f32_e32 v76, 0xbfb8aa3b, v76
	v_mul_f32_e32 v77, 0xbfb8aa3b, v77
	v_mul_f32_e32 v78, 0xbfb8aa3b, v78
	v_mul_f32_e32 v79, 0xbfb8aa3b, v79
	v_mul_f32_e32 v72, 0xbfb8aa3b, v72
	v_mul_f32_e32 v73, 0xbfb8aa3b, v73
	v_mul_f32_e32 v74, 0xbfb8aa3b, v74
	v_exp_f32_e32 v75, v75
	v_exp_f32_e32 v76, v76
	v_exp_f32_e32 v77, v77
	v_exp_f32_e32 v78, v78
	v_exp_f32_e32 v79, v79
	v_exp_f32_e32 v72, v72
	v_exp_f32_e32 v73, v73
	v_exp_f32_e32 v74, v74
	v_add_f32_e32 v75, 1.0, v75
	v_add_f32_e32 v76, 1.0, v76
	v_add_f32_e32 v77, 1.0, v77
	v_add_f32_e32 v78, 1.0, v78
	v_add_f32_e32 v79, 1.0, v79
	v_add_f32_e32 v72, 1.0, v72
	v_add_f32_e32 v73, 1.0, v73
	v_add_f32_e32 v74, 1.0, v74
	v_rcp_f32_e32 v75, v75
	v_rcp_f32_e32 v76, v76
	v_rcp_f32_e32 v77, v77
	v_rcp_f32_e32 v78, v78
	v_rcp_f32_e32 v79, v79
	s_waitcnt vmcnt(0)
; __device__ __forceinline__ unsigned cvt_pk_bf16(float lo, float hi) { unsigned r; asm volatile("v_cvt_pk_bf16_f32 %0, %1, %2" : "=v"(r) : "v"(lo), "v"(hi)); return r; }
; __device__ __forceinline__ float fast_sigmoid(float x) { return __builtin_amdgcn_rcpf(1.f + __builtin_amdgcn_exp2f(-x * LOG2E)); }
;     __device__ __forceinline__ void operator()(const f32x4 (&acc)[2][2][4][2], const pg8::Unit& u, int wr, int wc, int fr, int fq) const {
;     ...
;             for (int ai = 0; ai < 2; ++ai)
; #pragma unroll
;                 for (int m = 0; m < 4; ++m) { const size_t r = (size_t)(row0 + ai * 128 + m * 16);
;                     const u32x4 y = *(const u32x4*)(YB + r * SSMW + c); const f32x4 v0 = acc[ai][bj][m][0] + b0, v1 = acc[ai][bj][m][1] + b1;
;                     u32x4 w; w.x = cvt_pk_bf16(bf_lo(y.x) * fast_sigmoid(v0[0]), bf_hi(y.x) * fast_sigmoid(v0[1])); w.y = cvt_pk_bf16(bf_lo(y.y) * fast_sigmoid(v0[2]), bf_hi(y.y) * fast_sigmoid(v0[3]));
;                     w.z = cvt_pk_bf16(bf_lo(y.z) * fast_sigmoid(v1[0]), bf_hi(y.z) * fast_sigmoid(v1[1])); w.w = cvt_pk_bf16(bf_lo(y.w) * fast_sigmoid(v1[2]), bf_hi(y.w) * fast_sigmoid(v1[3]));
;                     *(u32x4*)(CAT + r * D + 512 + c) = w; } }
	v_lshlrev_b32_e32 v133, 16, v111
	v_and_b32_e32 v111, 0xffff0000, v111
	v_lshlrev_b32_e32 v126, 16, v108
	v_and_b32_e32 v108, 0xffff0000, v108
	v_lshlrev_b32_e32 v127, 16, v109
	v_and_b32_e32 v109, 0xffff0000, v109
	v_lshlrev_b32_e32 v132, 16, v110
	v_and_b32_e32 v110, 0xffff0000, v110
	v_mul_f32_e32 v99, v99, v111
	v_mul_f32_e32 v100, v100, v126
	v_mul_f32_e32 v101, v101, v108
	v_mul_f32_e32 v102, v102, v127
	v_mul_f32_e32 v103, v103, v109
	v_mul_f32_e32 v108, v96, v132
	v_mul_f32_e32 v109, v97, v110
	v_mul_f32_e32 v110, v98, v133
	v_cvt_pk_bf16_f32 v96, v100, v101
	v_cvt_pk_bf16_f32 v97, v102, v103
	v_cvt_pk_bf16_f32 v98, v108, v109
	v_cvt_pk_bf16_f32 v99, v110, v99
	global_store_dwordx4 v[104:105], v[96:99], off offset:1024 sc1
	global_load_dwordx4 v[100:103], v[106:107], off
	v_add_u32_e32 v108, 0x90, v162
	v_ashrrev_i32_e32 v109, 31, v108
	v_lshlrev_b64 v[96:97], 11, v[124:125]
	v_lshlrev_b64 v[98:99], 10, v[108:109]
	v_lshl_add_u64 v[96:97], s[42:43], 0, v[96:97]
	v_lshl_add_u64 v[98:99], s[0:1], 0, v[98:99]
	v_lshl_add_u64 v[96:97], v[96:97], 0, v[158:159]
	v_lshl_add_u64 v[98:99], v[98:99], 0, v[158:159]
	v_rcp_f32_e32 v72, v72
	v_rcp_f32_e32 v73, v73
	v_rcp_f32_e32 v74, v74
	v_pk_add_f32 v[68:69], v[68:69], v[116:117]
	v_pk_add_f32 v[64:65], v[64:65], v[112:113]
	v_mul_f32_e32 v68, 0xbfb8aa3b, v68
	v_mul_f32_e32 v69, 0xbfb8aa3b, v69
	v_pk_add_f32 v[70:71], v[70:71], v[118:119]
	v_mul_f32_e32 v64, 0xbfb8aa3b, v64
	v_exp_f32_e32 v68, v68
	v_exp_f32_e32 v69, v69
	v_pk_add_f32 v[66:67], v[66:67], v[114:115]
	v_mul_f32_e32 v71, 0xbfb8aa3b, v71
	v_mul_f32_e32 v65, 0xbfb8aa3b, v65
	v_exp_f32_e32 v64, v64
	v_mul_f32_e32 v70, 0xbfb8aa3b, v70
	v_mul_f32_e32 v66, 0xbfb8aa3b, v66
	v_mul_f32_e32 v67, 0xbfb8aa3b, v67
	v_exp_f32_e32 v71, v71
	v_exp_f32_e32 v65, v65
	v_exp_f32_e32 v70, v70
	v_exp_f32_e32 v66, v66
	v_exp_f32_e32 v67, v67
	v_add_f32_e32 v68, 1.0, v68
	v_add_f32_e32 v69, 1.0, v69
	v_add_f32_e32 v64, 1.0, v64
	v_rcp_f32_e32 v68, v68
	v_rcp_f32_e32 v69, v69
	v_add_f32_e32 v71, 1.0, v71
	v_add_f32_e32 v65, 1.0, v65
	v_rcp_f32_e32 v64, v64
	v_add_f32_e32 v70, 1.0, v70
	v_add_f32_e32 v66, 1.0, v66
	v_add_f32_e32 v67, 1.0, v67
	v_rcp_f32_e32 v71, v71
	v_rcp_f32_e32 v65, v65
	v_rcp_f32_e32 v70, v70
	v_rcp_f32_e32 v66, v66
	v_rcp_f32_e32 v67, v67
	s_waitcnt vmcnt(0)
	v_lshlrev_b32_e32 v125, 16, v103
	v_and_b32_e32 v103, 0xffff0000, v103
	v_lshlrev_b32_e32 v110, 16, v100
	v_and_b32_e32 v100, 0xffff0000, v100
	v_lshlrev_b32_e32 v111, 16, v101
	v_and_b32_e32 v101, 0xffff0000, v101
	v_lshlrev_b32_e32 v124, 16, v102
	v_and_b32_e32 v102, 0xffff0000, v102
	v_mul_f32_e32 v91, v91, v103
	v_mul_f32_e32 v92, v92, v110
	v_mul_f32_e32 v93, v93, v100
	v_mul_f32_e32 v94, v94, v111
	v_mul_f32_e32 v95, v95, v101
	v_mul_f32_e32 v100, v88, v124
	v_mul_f32_e32 v101, v89, v102
	v_mul_f32_e32 v102, v90, v125
	v_cvt_pk_bf16_f32 v88, v92, v93
	v_cvt_pk_bf16_f32 v89, v94, v95
	v_cvt_pk_bf16_f32 v90, v100, v101
	v_cvt_pk_bf16_f32 v91, v102, v91
	global_store_dwordx4 v[96:97], v[88:91], off offset:1024 sc1
	global_load_dwordx4 v[92:95], v[98:99], off
	v_add_u32_e32 v100, 0xa0, v162
	v_ashrrev_i32_e32 v101, 31, v100
	v_lshlrev_b64 v[88:89], 11, v[108:109]
	v_lshlrev_b64 v[90:91], 10, v[100:101]
	v_lshl_add_u64 v[88:89], s[42:43], 0, v[88:89]
	v_lshl_add_u64 v[90:91], s[0:1], 0, v[90:91]
	v_lshl_add_u64 v[88:89], v[88:89], 0, v[158:159]
	v_lshl_add_u64 v[90:91], v[90:91], 0, v[158:159]
	s_waitcnt vmcnt(0)
	v_lshlrev_b32_e32 v109, 16, v95
	v_and_b32_e32 v95, 0xffff0000, v95
	v_lshlrev_b32_e32 v102, 16, v92
	v_and_b32_e32 v92, 0xffff0000, v92
	v_lshlrev_b32_e32 v103, 16, v93
	v_and_b32_e32 v93, 0xffff0000, v93
	v_lshlrev_b32_e32 v108, 16, v94
	v_and_b32_e32 v94, 0xffff0000, v94
	v_mul_f32_e32 v83, v83, v95
	v_mul_f32_e32 v84, v84, v102
	v_mul_f32_e32 v85, v85, v92
	v_mul_f32_e32 v86, v86, v103
	v_mul_f32_e32 v87, v87, v93
	v_mul_f32_e32 v92, v80, v108
	v_mul_f32_e32 v93, v81, v94
	v_mul_f32_e32 v94, v82, v109
	v_cvt_pk_bf16_f32 v80, v84, v85
	v_cvt_pk_bf16_f32 v81, v86, v87
	v_cvt_pk_bf16_f32 v82, v92, v93
	v_cvt_pk_bf16_f32 v83, v94, v83
	global_store_dwordx4 v[88:89], v[80:83], off offset:1024 sc1
	global_load_dwordx4 v[84:87], v[90:91], off
	v_add_u32_e32 v92, 0xb0, v162
	v_ashrrev_i32_e32 v93, 31, v92
	v_lshlrev_b64 v[80:81], 11, v[100:101]
	v_lshlrev_b64 v[82:83], 10, v[92:93]
	v_lshl_add_u64 v[80:81], s[42:43], 0, v[80:81]
	v_lshl_add_u64 v[82:83], s[0:1], 0, v[82:83]
	v_lshl_add_u64 v[80:81], v[80:81], 0, v[158:159]
	v_lshl_add_u64 v[82:83], v[82:83], 0, v[158:159]
	s_waitcnt vmcnt(0)
	v_lshlrev_b32_e32 v101, 16, v87
	v_and_b32_e32 v87, 0xffff0000, v87
	v_lshlrev_b32_e32 v94, 16, v84
	v_and_b32_e32 v84, 0xffff0000, v84
	v_lshlrev_b32_e32 v95, 16, v85
	v_and_b32_e32 v85, 0xffff0000, v85
	v_lshlrev_b32_e32 v100, 16, v86
	v_and_b32_e32 v86, 0xffff0000, v86
	v_mul_f32_e32 v75, v75, v87
	v_mul_f32_e32 v76, v76, v94
	v_mul_f32_e32 v77, v77, v84
	v_mul_f32_e32 v78, v78, v95
	v_mul_f32_e32 v79, v79, v85
	v_mul_f32_e32 v84, v72, v100
	v_mul_f32_e32 v85, v73, v86
	v_mul_f32_e32 v86, v74, v101
	v_cvt_pk_bf16_f32 v72, v76, v77
	v_cvt_pk_bf16_f32 v73, v78, v79
	v_cvt_pk_bf16_f32 v74, v84, v85
	v_cvt_pk_bf16_f32 v75, v86, v75
	global_store_dwordx4 v[80:81], v[72:75], off offset:1024 sc1
	global_load_dwordx4 v[72:75], v[82:83], off
	s_waitcnt vmcnt(0)
; __device__ __forceinline__ unsigned cvt_pk_bf16(float lo, float hi) { unsigned r; asm volatile("v_cvt_pk_bf16_f32 %0, %1, %2" : "=v"(r) : "v"(lo), "v"(hi)); return r; }
; __device__ __forceinline__ float fast_sigmoid(float x) { return __builtin_amdgcn_rcpf(1.f + __builtin_amdgcn_exp2f(-x * LOG2E)); }
;     __device__ __forceinline__ void operator()(const f32x4 (&acc)[2][2][4][2], const pg8::Unit& u, int wr, int wc, int fr, int fq) const {
;     ...
;         for (int bj = 0; bj < 2; ++bj) { const int c = col0 + bj * 128; const f32x4 b0 = *(const f32x4*)(bias + c), b1 = *(const f32x4*)(bias + c + 4);
; #pragma unroll
;             for (int ai = 0; ai < 2; ++ai)
; #pragma unroll
;                 for (int m = 0; m < 4; ++m) { const size_t r = (size_t)(row0 + ai * 128 + m * 16);
;                     const u32x4 y = *(const u32x4*)(YB + r * SSMW + c); const f32x4 v0 = acc[ai][bj][m][0] + b0, v1 = acc[ai][bj][m][1] + b1;
;                     u32x4 w; w.x = cvt_pk_bf16(bf_lo(y.x) * fast_sigmoid(v0[0]), bf_hi(y.x) * fast_sigmoid(v0[1])); w.y = cvt_pk_bf16(bf_lo(y.y) * fast_sigmoid(v0[2]), bf_hi(y.y) * fast_sigmoid(v0[3]));
;                     w.z = cvt_pk_bf16(bf_lo(y.z) * fast_sigmoid(v1[0]), bf_hi(y.z) * fast_sigmoid(v1[1])); w.w = cvt_pk_bf16(bf_lo(y.w) * fast_sigmoid(v1[2]), bf_hi(y.w) * fast_sigmoid(v1[3]));
;                     *(u32x4*)(CAT + r * D + 512 + c) = w; } }
	v_lshlrev_b32_e32 v76, 16, v72
	v_and_b32_e32 v72, 0xffff0000, v72
	v_lshlrev_b32_e32 v78, 16, v74
	v_mul_f32_e32 v68, v68, v76
	v_mul_f32_e32 v69, v69, v72
	v_lshlrev_b32_e32 v77, 16, v73
	v_and_b32_e32 v73, 0xffff0000, v73
	v_and_b32_e32 v74, 0xffff0000, v74
	v_mul_f32_e32 v72, v64, v78
	v_cvt_pk_bf16_f32 v64, v68, v69
	v_lshlrev_b64 v[68:69], 11, v[92:93]
	v_lshlrev_b32_e32 v79, 16, v75
	v_and_b32_e32 v75, 0xffff0000, v75
	v_mul_f32_e32 v71, v71, v73
	v_mul_f32_e32 v73, v65, v74
	v_lshl_add_u64 v[68:69], s[42:43], 0, v[68:69]
	v_mul_f32_e32 v70, v70, v77
	v_mul_f32_e32 v74, v66, v79
	v_mul_f32_e32 v67, v67, v75
	v_cvt_pk_bf16_f32 v65, v70, v71
	v_cvt_pk_bf16_f32 v66, v72, v73
	v_lshl_add_u64 v[72:73], v[68:69], 0, v[158:159]
	v_cvt_pk_bf16_f32 v67, v74, v67
	global_store_dwordx4 v[72:73], v[64:67], off offset:1024 sc1
	global_load_dwordx4 v[74:77], v[160:161], off offset:256
	global_load_dwordx4 v[68:71], v[156:157], off offset:512
	s_nop 0
	global_load_dwordx4 v[64:67], v[156:157], off offset:528
	s_waitcnt vmcnt(1)
	v_pk_add_f32 v[62:63], v[62:63], v[70:71]
	s_waitcnt vmcnt(0)
	v_pk_add_f32 v[58:59], v[58:59], v[66:67]
	v_pk_add_f32 v[60:61], v[60:61], v[68:69]
	v_pk_add_f32 v[56:57], v[56:57], v[64:65]
	v_mul_f32_e32 v59, 0xbfb8aa3b, v59
	v_mul_f32_e32 v60, 0xbfb8aa3b, v60
	v_mul_f32_e32 v61, 0xbfb8aa3b, v61
	v_mul_f32_e32 v62, 0xbfb8aa3b, v62
	v_mul_f32_e32 v63, 0xbfb8aa3b, v63
	v_mul_f32_e32 v56, 0xbfb8aa3b, v56
	v_mul_f32_e32 v57, 0xbfb8aa3b, v57
	v_mul_f32_e32 v58, 0xbfb8aa3b, v58
	v_exp_f32_e32 v59, v59
	v_exp_f32_e32 v60, v60
	v_exp_f32_e32 v61, v61
	v_exp_f32_e32 v62, v62
	v_exp_f32_e32 v63, v63
	v_exp_f32_e32 v56, v56
	v_exp_f32_e32 v57, v57
	v_exp_f32_e32 v58, v58
	v_add_f32_e32 v59, 1.0, v59
	v_add_f32_e32 v60, 1.0, v60
	v_add_f32_e32 v61, 1.0, v61
	v_add_f32_e32 v62, 1.0, v62
	v_add_f32_e32 v63, 1.0, v63
	v_add_f32_e32 v56, 1.0, v56
	v_add_f32_e32 v57, 1.0, v57
	v_add_f32_e32 v58, 1.0, v58
	v_rcp_f32_e32 v59, v59
	v_rcp_f32_e32 v60, v60
	v_rcp_f32_e32 v61, v61
	v_rcp_f32_e32 v62, v62
	v_rcp_f32_e32 v63, v63
	v_rcp_f32_e32 v56, v56
	v_rcp_f32_e32 v57, v57
	v_rcp_f32_e32 v58, v58
	v_lshlrev_b32_e32 v85, 16, v77
	v_and_b32_e32 v77, 0xffff0000, v77
	v_lshlrev_b32_e32 v78, 16, v74
	v_and_b32_e32 v74, 0xffff0000, v74
	v_lshlrev_b32_e32 v79, 16, v75
	v_and_b32_e32 v75, 0xffff0000, v75
	v_lshlrev_b32_e32 v84, 16, v76
	v_and_b32_e32 v76, 0xffff0000, v76
	v_mul_f32_e32 v59, v59, v77
	v_mul_f32_e32 v60, v60, v78
	v_mul_f32_e32 v61, v61, v74
	v_mul_f32_e32 v62, v62, v79
	v_mul_f32_e32 v63, v63, v75
	v_mul_f32_e32 v74, v56, v84
	v_mul_f32_e32 v75, v57, v76
	v_mul_f32_e32 v76, v58, v85
	v_cvt_pk_bf16_f32 v56, v60, v61
	v_cvt_pk_bf16_f32 v57, v62, v63
	v_cvt_pk_bf16_f32 v58, v74, v75
	v_cvt_pk_bf16_f32 v59, v76, v59
	global_store_dwordx4 v[152:153], v[56:59], off offset:1280 sc1
	global_load_dwordx4 v[56:59], v[154:155], off offset:256
	v_pk_add_f32 v[50:51], v[50:51], v[66:67]
	v_pk_add_f32 v[54:55], v[54:55], v[70:71]
	v_pk_add_f32 v[52:53], v[52:53], v[68:69]
	v_pk_add_f32 v[48:49], v[48:49], v[64:65]
	v_mul_f32_e32 v51, 0xbfb8aa3b, v51
	v_mul_f32_e32 v52, 0xbfb8aa3b, v52
	v_mul_f32_e32 v53, 0xbfb8aa3b, v53
	v_mul_f32_e32 v54, 0xbfb8aa3b, v54
	v_mul_f32_e32 v55, 0xbfb8aa3b, v55
	v_mul_f32_e32 v48, 0xbfb8aa3b, v48
	v_mul_f32_e32 v49, 0xbfb8aa3b, v49
	v_mul_f32_e32 v50, 0xbfb8aa3b, v50
	v_exp_f32_e32 v51, v51
	v_exp_f32_e32 v52, v52
	v_exp_f32_e32 v53, v53
	v_exp_f32_e32 v54, v54
	v_exp_f32_e32 v55, v55
	v_exp_f32_e32 v48, v48
	v_exp_f32_e32 v49, v49
	v_exp_f32_e32 v50, v50
	v_add_f32_e32 v51, 1.0, v51
	v_add_f32_e32 v52, 1.0, v52
	v_add_f32_e32 v53, 1.0, v53
	v_add_f32_e32 v54, 1.0, v54
	v_add_f32_e32 v55, 1.0, v55
	v_add_f32_e32 v48, 1.0, v48
	v_add_f32_e32 v49, 1.0, v49
	v_add_f32_e32 v50, 1.0, v50
	v_rcp_f32_e32 v51, v51
	v_rcp_f32_e32 v52, v52
	v_rcp_f32_e32 v53, v53
	v_rcp_f32_e32 v54, v54
	v_rcp_f32_e32 v55, v55
	v_rcp_f32_e32 v48, v48
	v_rcp_f32_e32 v49, v49
	v_rcp_f32_e32 v50, v50
	v_pk_add_f32 v[42:43], v[42:43], v[66:67]
	v_pk_add_f32 v[46:47], v[46:47], v[70:71]
	v_pk_add_f32 v[44:45], v[44:45], v[68:69]
	v_pk_add_f32 v[40:41], v[40:41], v[64:65]
	v_mul_f32_e32 v43, 0xbfb8aa3b, v43
	v_mul_f32_e32 v44, 0xbfb8aa3b, v44
	v_mul_f32_e32 v45, 0xbfb8aa3b, v45
	v_mul_f32_e32 v46, 0xbfb8aa3b, v46
	v_mul_f32_e32 v47, 0xbfb8aa3b, v47
	v_mul_f32_e32 v40, 0xbfb8aa3b, v40
	v_mul_f32_e32 v41, 0xbfb8aa3b, v41
	v_mul_f32_e32 v42, 0xbfb8aa3b, v42
	v_exp_f32_e32 v43, v43
	v_exp_f32_e32 v44, v44
	v_exp_f32_e32 v45, v45
	v_exp_f32_e32 v46, v46
	v_exp_f32_e32 v47, v47
	v_exp_f32_e32 v40, v40
	v_exp_f32_e32 v41, v41
	v_exp_f32_e32 v42, v42
	v_add_f32_e32 v43, 1.0, v43
	v_add_f32_e32 v44, 1.0, v44
	v_add_f32_e32 v45, 1.0, v45
	v_add_f32_e32 v46, 1.0, v46
	v_add_f32_e32 v47, 1.0, v47
	v_add_f32_e32 v40, 1.0, v40
	v_add_f32_e32 v41, 1.0, v41
	v_add_f32_e32 v42, 1.0, v42
	v_rcp_f32_e32 v43, v43
	v_rcp_f32_e32 v44, v44
	v_rcp_f32_e32 v45, v45
	v_rcp_f32_e32 v46, v46
	v_rcp_f32_e32 v47, v47
	v_rcp_f32_e32 v40, v40
	v_rcp_f32_e32 v41, v41
	v_rcp_f32_e32 v42, v42
	v_pk_add_f32 v[34:35], v[34:35], v[66:67]
	v_pk_add_f32 v[38:39], v[38:39], v[70:71]
	v_pk_add_f32 v[36:37], v[36:37], v[68:69]
	v_pk_add_f32 v[32:33], v[32:33], v[64:65]
	v_mul_f32_e32 v35, 0xbfb8aa3b, v35
	v_mul_f32_e32 v36, 0xbfb8aa3b, v36
	v_mul_f32_e32 v37, 0xbfb8aa3b, v37
	s_waitcnt vmcnt(0)
; __device__ __forceinline__ unsigned cvt_pk_bf16(float lo, float hi) { unsigned r; asm volatile("v_cvt_pk_bf16_f32 %0, %1, %2" : "=v"(r) : "v"(lo), "v"(hi)); return r; }
; __device__ __forceinline__ float fast_sigmoid(float x) { return __builtin_amdgcn_rcpf(1.f + __builtin_amdgcn_exp2f(-x * LOG2E)); }
;     __device__ __forceinline__ void operator()(const f32x4 (&acc)[2][2][4][2], const pg8::Unit& u, int wr, int wc, int fr, int fq) const {
;     ...
;             for (int ai = 0; ai < 2; ++ai)
; #pragma unroll
;                 for (int m = 0; m < 4; ++m) { const size_t r = (size_t)(row0 + ai * 128 + m * 16);
;                     const u32x4 y = *(const u32x4*)(YB + r * SSMW + c); const f32x4 v0 = acc[ai][bj][m][0] + b0, v1 = acc[ai][bj][m][1] + b1;
;                     u32x4 w; w.x = cvt_pk_bf16(bf_lo(y.x) * fast_sigmoid(v0[0]), bf_hi(y.x) * fast_sigmoid(v0[1])); w.y = cvt_pk_bf16(bf_lo(y.y) * fast_sigmoid(v0[2]), bf_hi(y.y) * fast_sigmoid(v0[3]));
;                     w.z = cvt_pk_bf16(bf_lo(y.z) * fast_sigmoid(v1[0]), bf_hi(y.z) * fast_sigmoid(v1[1])); w.w = cvt_pk_bf16(bf_lo(y.w) * fast_sigmoid(v1[2]), bf_hi(y.w) * fast_sigmoid(v1[3]));
;                     *(u32x4*)(CAT + r * D + 512 + c) = w; } }
	v_lshlrev_b32_e32 v63, 16, v59
	v_and_b32_e32 v59, 0xffff0000, v59
	v_lshlrev_b32_e32 v60, 16, v56
	v_and_b32_e32 v56, 0xffff0000, v56
	v_lshlrev_b32_e32 v61, 16, v57
	v_and_b32_e32 v57, 0xffff0000, v57
	v_lshlrev_b32_e32 v62, 16, v58
	v_and_b32_e32 v58, 0xffff0000, v58
	v_mul_f32_e32 v51, v51, v59
	v_mul_f32_e32 v52, v52, v60
	v_mul_f32_e32 v53, v53, v56
	v_mul_f32_e32 v54, v54, v61
	v_mul_f32_e32 v55, v55, v57
	v_mul_f32_e32 v56, v48, v62
	v_mul_f32_e32 v57, v49, v58
	v_mul_f32_e32 v58, v50, v63
	v_cvt_pk_bf16_f32 v48, v52, v53
	v_cvt_pk_bf16_f32 v49, v54, v55
	v_cvt_pk_bf16_f32 v50, v56, v57
	v_cvt_pk_bf16_f32 v51, v58, v51
	global_store_dwordx4 v[128:129], v[48:51], off offset:1280 sc1
	global_load_dwordx4 v[48:51], v[130:131], off offset:256
	v_mul_f32_e32 v38, 0xbfb8aa3b, v38
	v_mul_f32_e32 v39, 0xbfb8aa3b, v39
	v_mul_f32_e32 v32, 0xbfb8aa3b, v32
	v_mul_f32_e32 v33, 0xbfb8aa3b, v33
	v_mul_f32_e32 v34, 0xbfb8aa3b, v34
	v_exp_f32_e32 v35, v35
	v_exp_f32_e32 v36, v36
	v_exp_f32_e32 v37, v37
	v_exp_f32_e32 v38, v38
	v_exp_f32_e32 v39, v39
	v_exp_f32_e32 v32, v32
	v_exp_f32_e32 v33, v33
	v_exp_f32_e32 v34, v34
	v_add_f32_e32 v35, 1.0, v35
	v_add_f32_e32 v36, 1.0, v36
	v_add_f32_e32 v37, 1.0, v37
	v_add_f32_e32 v38, 1.0, v38
	v_add_f32_e32 v39, 1.0, v39
	v_add_f32_e32 v32, 1.0, v32
	v_add_f32_e32 v33, 1.0, v33
	v_add_f32_e32 v34, 1.0, v34
	v_rcp_f32_e32 v35, v35
	v_rcp_f32_e32 v36, v36
	v_rcp_f32_e32 v37, v37
	v_rcp_f32_e32 v38, v38
	v_rcp_f32_e32 v39, v39
	v_rcp_f32_e32 v32, v32
	v_rcp_f32_e32 v33, v33
	v_rcp_f32_e32 v34, v34
	v_pk_add_f32 v[26:27], v[26:27], v[66:67]
	v_pk_add_f32 v[30:31], v[30:31], v[70:71]
	v_pk_add_f32 v[28:29], v[28:29], v[68:69]
	v_pk_add_f32 v[24:25], v[24:25], v[64:65]
	v_mul_f32_e32 v27, 0xbfb8aa3b, v27
	v_mul_f32_e32 v28, 0xbfb8aa3b, v28
	v_mul_f32_e32 v29, 0xbfb8aa3b, v29
	v_mul_f32_e32 v30, 0xbfb8aa3b, v30
	v_mul_f32_e32 v31, 0xbfb8aa3b, v31
	v_mul_f32_e32 v24, 0xbfb8aa3b, v24
	v_mul_f32_e32 v25, 0xbfb8aa3b, v25
	v_mul_f32_e32 v26, 0xbfb8aa3b, v26
	v_exp_f32_e32 v27, v27
	v_exp_f32_e32 v28, v28
	v_exp_f32_e32 v29, v29
	v_exp_f32_e32 v30, v30
	v_exp_f32_e32 v31, v31
	v_exp_f32_e32 v24, v24
	v_exp_f32_e32 v25, v25
	v_exp_f32_e32 v26, v26
	v_add_f32_e32 v27, 1.0, v27
	v_add_f32_e32 v28, 1.0, v28
	v_add_f32_e32 v29, 1.0, v29
	v_add_f32_e32 v30, 1.0, v30
	v_add_f32_e32 v31, 1.0, v31
	v_add_f32_e32 v24, 1.0, v24
	v_add_f32_e32 v25, 1.0, v25
	v_add_f32_e32 v26, 1.0, v26
	v_rcp_f32_e32 v27, v27
	v_rcp_f32_e32 v28, v28
	v_rcp_f32_e32 v29, v29
	v_rcp_f32_e32 v30, v30
	v_rcp_f32_e32 v31, v31
	v_rcp_f32_e32 v24, v24
	v_rcp_f32_e32 v25, v25
	v_rcp_f32_e32 v26, v26
	v_pk_add_f32 v[18:19], v[18:19], v[66:67]
	v_pk_add_f32 v[22:23], v[22:23], v[70:71]
	v_pk_add_f32 v[20:21], v[20:21], v[68:69]
	v_pk_add_f32 v[16:17], v[16:17], v[64:65]
	v_mul_f32_e32 v19, 0xbfb8aa3b, v19
	v_mul_f32_e32 v20, 0xbfb8aa3b, v20
	v_mul_f32_e32 v21, 0xbfb8aa3b, v21
	v_mul_f32_e32 v22, 0xbfb8aa3b, v22
	v_mul_f32_e32 v23, 0xbfb8aa3b, v23
	v_mul_f32_e32 v16, 0xbfb8aa3b, v16
	v_mul_f32_e32 v17, 0xbfb8aa3b, v17
	v_mul_f32_e32 v18, 0xbfb8aa3b, v18
	v_exp_f32_e32 v19, v19
	v_exp_f32_e32 v20, v20
	s_waitcnt vmcnt(0)
	v_lshlrev_b32_e32 v55, 16, v51
	v_and_b32_e32 v51, 0xffff0000, v51
	v_lshlrev_b32_e32 v52, 16, v48
	v_and_b32_e32 v48, 0xffff0000, v48
	v_lshlrev_b32_e32 v53, 16, v49
	v_and_b32_e32 v49, 0xffff0000, v49
	v_lshlrev_b32_e32 v54, 16, v50
	v_and_b32_e32 v50, 0xffff0000, v50
	v_mul_f32_e32 v43, v43, v51
	v_mul_f32_e32 v44, v44, v52
	v_mul_f32_e32 v45, v45, v48
	v_mul_f32_e32 v46, v46, v53
	v_mul_f32_e32 v47, v47, v49
	v_mul_f32_e32 v48, v40, v54
	v_mul_f32_e32 v49, v41, v50
	v_mul_f32_e32 v50, v42, v55
	v_cvt_pk_bf16_f32 v40, v44, v45
	v_cvt_pk_bf16_f32 v41, v46, v47
	v_cvt_pk_bf16_f32 v42, v48, v49
	v_cvt_pk_bf16_f32 v43, v50, v43
	global_store_dwordx4 v[120:121], v[40:43], off offset:1280 sc1
	global_load_dwordx4 v[40:43], v[122:123], off offset:256
	v_exp_f32_e32 v21, v21
	v_exp_f32_e32 v22, v22
	v_exp_f32_e32 v23, v23
	v_exp_f32_e32 v16, v16
	v_exp_f32_e32 v17, v17
	v_exp_f32_e32 v18, v18
	v_add_f32_e32 v19, 1.0, v19
	v_add_f32_e32 v20, 1.0, v20
	v_add_f32_e32 v21, 1.0, v21
	v_add_f32_e32 v22, 1.0, v22
	v_add_f32_e32 v23, 1.0, v23
	v_add_f32_e32 v16, 1.0, v16
	v_add_f32_e32 v17, 1.0, v17
	v_add_f32_e32 v18, 1.0, v18
	v_rcp_f32_e32 v19, v19
	v_rcp_f32_e32 v20, v20
	v_rcp_f32_e32 v21, v21
	v_rcp_f32_e32 v22, v22
	v_rcp_f32_e32 v23, v23
	v_rcp_f32_e32 v16, v16
	v_rcp_f32_e32 v17, v17
	v_rcp_f32_e32 v18, v18
	v_pk_add_f32 v[10:11], v[10:11], v[66:67]
	v_pk_add_f32 v[14:15], v[14:15], v[70:71]
	v_pk_add_f32 v[12:13], v[12:13], v[68:69]
	v_pk_add_f32 v[8:9], v[8:9], v[64:65]
	v_mul_f32_e32 v11, 0xbfb8aa3b, v11
	v_mul_f32_e32 v12, 0xbfb8aa3b, v12
	v_mul_f32_e32 v13, 0xbfb8aa3b, v13
	v_mul_f32_e32 v14, 0xbfb8aa3b, v14
	v_mul_f32_e32 v15, 0xbfb8aa3b, v15
	v_mul_f32_e32 v8, 0xbfb8aa3b, v8
	v_mul_f32_e32 v9, 0xbfb8aa3b, v9
	v_mul_f32_e32 v10, 0xbfb8aa3b, v10
	v_exp_f32_e32 v11, v11
	v_exp_f32_e32 v12, v12
	v_exp_f32_e32 v13, v13
	v_exp_f32_e32 v14, v14
	v_exp_f32_e32 v15, v15
	v_exp_f32_e32 v8, v8
	v_exp_f32_e32 v9, v9
	v_exp_f32_e32 v10, v10
	v_add_f32_e32 v11, 1.0, v11
	v_add_f32_e32 v12, 1.0, v12
	v_add_f32_e32 v13, 1.0, v13
	v_add_f32_e32 v14, 1.0, v14
	v_add_f32_e32 v15, 1.0, v15
	v_add_f32_e32 v8, 1.0, v8
	v_add_f32_e32 v9, 1.0, v9
	v_add_f32_e32 v10, 1.0, v10
	v_rcp_f32_e32 v11, v11
	v_rcp_f32_e32 v12, v12
	v_rcp_f32_e32 v13, v13
	v_rcp_f32_e32 v14, v14
	v_rcp_f32_e32 v15, v15
	v_rcp_f32_e32 v8, v8
	v_rcp_f32_e32 v9, v9
	v_rcp_f32_e32 v10, v10
	v_pk_add_f32 v[2:3], v[2:3], v[66:67]
	v_pk_add_f32 v[6:7], v[6:7], v[70:71]
	v_pk_add_f32 v[4:5], v[4:5], v[68:69]
	v_pk_add_f32 v[0:1], v[0:1], v[64:65]
	v_mul_f32_e32 v3, 0xbfb8aa3b, v3
	v_mul_f32_e32 v4, 0xbfb8aa3b, v4
	v_mul_f32_e32 v5, 0xbfb8aa3b, v5
	v_mul_f32_e32 v6, 0xbfb8aa3b, v6
	v_mul_f32_e32 v7, 0xbfb8aa3b, v7
	v_mul_f32_e32 v0, 0xbfb8aa3b, v0
	v_mul_f32_e32 v1, 0xbfb8aa3b, v1
	v_mul_f32_e32 v2, 0xbfb8aa3b, v2
	v_exp_f32_e32 v3, v3
	v_exp_f32_e32 v4, v4
	v_exp_f32_e32 v5, v5
	v_exp_f32_e32 v6, v6
	v_exp_f32_e32 v7, v7
	v_exp_f32_e32 v0, v0
	v_exp_f32_e32 v1, v1
	v_exp_f32_e32 v2, v2
	v_add_f32_e32 v3, 1.0, v3
	s_waitcnt vmcnt(0)
; __device__ __forceinline__ unsigned cvt_pk_bf16(float lo, float hi) { unsigned r; asm volatile("v_cvt_pk_bf16_f32 %0, %1, %2" : "=v"(r) : "v"(lo), "v"(hi)); return r; }
; __device__ __forceinline__ float fast_sigmoid(float x) { return __builtin_amdgcn_rcpf(1.f + __builtin_amdgcn_exp2f(-x * LOG2E)); }
;     __device__ __forceinline__ void operator()(const f32x4 (&acc)[2][2][4][2], const pg8::Unit& u, int wr, int wc, int fr, int fq) const {
;     ...
;             for (int ai = 0; ai < 2; ++ai)
; #pragma unroll
;                 for (int m = 0; m < 4; ++m) { const size_t r = (size_t)(row0 + ai * 128 + m * 16);
;                     const u32x4 y = *(const u32x4*)(YB + r * SSMW + c); const f32x4 v0 = acc[ai][bj][m][0] + b0, v1 = acc[ai][bj][m][1] + b1;
;                     u32x4 w; w.x = cvt_pk_bf16(bf_lo(y.x) * fast_sigmoid(v0[0]), bf_hi(y.x) * fast_sigmoid(v0[1])); w.y = cvt_pk_bf16(bf_lo(y.y) * fast_sigmoid(v0[2]), bf_hi(y.y) * fast_sigmoid(v0[3]));
;                     w.z = cvt_pk_bf16(bf_lo(y.z) * fast_sigmoid(v1[0]), bf_hi(y.z) * fast_sigmoid(v1[1])); w.w = cvt_pk_bf16(bf_lo(y.w) * fast_sigmoid(v1[2]), bf_hi(y.w) * fast_sigmoid(v1[3]));
;                     *(u32x4*)(CAT + r * D + 512 + c) = w; } }
	v_lshlrev_b32_e32 v47, 16, v43
	v_and_b32_e32 v43, 0xffff0000, v43
	v_lshlrev_b32_e32 v44, 16, v40
	v_and_b32_e32 v40, 0xffff0000, v40
	v_lshlrev_b32_e32 v45, 16, v41
	v_and_b32_e32 v41, 0xffff0000, v41
	v_lshlrev_b32_e32 v46, 16, v42
	v_and_b32_e32 v42, 0xffff0000, v42
	v_mul_f32_e32 v35, v35, v43
	v_mul_f32_e32 v36, v36, v44
	v_mul_f32_e32 v37, v37, v40
	v_mul_f32_e32 v38, v38, v45
	v_mul_f32_e32 v39, v39, v41
	v_mul_f32_e32 v40, v32, v46
	v_mul_f32_e32 v41, v33, v42
	v_mul_f32_e32 v42, v34, v47
	v_cvt_pk_bf16_f32 v32, v36, v37
	v_cvt_pk_bf16_f32 v33, v38, v39
	v_cvt_pk_bf16_f32 v34, v40, v41
	v_cvt_pk_bf16_f32 v35, v42, v35
	global_store_dwordx4 v[104:105], v[32:35], off offset:1280 sc1
	global_load_dwordx4 v[32:35], v[106:107], off offset:256
	v_add_f32_e32 v4, 1.0, v4
	v_add_f32_e32 v5, 1.0, v5
	v_add_f32_e32 v6, 1.0, v6
	v_add_f32_e32 v7, 1.0, v7
	v_add_f32_e32 v0, 1.0, v0
	v_add_f32_e32 v1, 1.0, v1
	v_add_f32_e32 v2, 1.0, v2
	v_rcp_f32_e32 v3, v3
	v_rcp_f32_e32 v4, v4
	v_rcp_f32_e32 v5, v5
	v_rcp_f32_e32 v6, v6
	v_rcp_f32_e32 v7, v7
	v_rcp_f32_e32 v0, v0
	v_rcp_f32_e32 v1, v1
	v_rcp_f32_e32 v2, v2
	s_waitcnt vmcnt(0)
	v_lshlrev_b32_e32 v39, 16, v35
	v_and_b32_e32 v35, 0xffff0000, v35
	v_lshlrev_b32_e32 v36, 16, v32
	v_and_b32_e32 v32, 0xffff0000, v32
	v_lshlrev_b32_e32 v37, 16, v33
	v_and_b32_e32 v33, 0xffff0000, v33
	v_lshlrev_b32_e32 v38, 16, v34
	v_and_b32_e32 v34, 0xffff0000, v34
	v_mul_f32_e32 v27, v27, v35
	v_mul_f32_e32 v28, v28, v36
	v_mul_f32_e32 v29, v29, v32
	v_mul_f32_e32 v30, v30, v37
	v_mul_f32_e32 v31, v31, v33
	v_mul_f32_e32 v32, v24, v38
	v_mul_f32_e32 v33, v25, v34
	v_mul_f32_e32 v34, v26, v39
	v_cvt_pk_bf16_f32 v24, v28, v29
	v_cvt_pk_bf16_f32 v25, v30, v31
	v_cvt_pk_bf16_f32 v26, v32, v33
	v_cvt_pk_bf16_f32 v27, v34, v27
	global_store_dwordx4 v[96:97], v[24:27], off offset:1280 sc1
	global_load_dwordx4 v[24:27], v[98:99], off offset:256
	s_waitcnt vmcnt(0)
	v_lshlrev_b32_e32 v31, 16, v27
	v_and_b32_e32 v27, 0xffff0000, v27
	v_lshlrev_b32_e32 v28, 16, v24
	v_and_b32_e32 v24, 0xffff0000, v24
	v_lshlrev_b32_e32 v29, 16, v25
	v_and_b32_e32 v25, 0xffff0000, v25
	v_lshlrev_b32_e32 v30, 16, v26
	v_and_b32_e32 v26, 0xffff0000, v26
	v_mul_f32_e32 v19, v19, v27
	v_mul_f32_e32 v20, v20, v28
	v_mul_f32_e32 v21, v21, v24
	v_mul_f32_e32 v22, v22, v29
	v_mul_f32_e32 v23, v23, v25
	v_mul_f32_e32 v24, v16, v30
	v_mul_f32_e32 v25, v17, v26
	v_mul_f32_e32 v26, v18, v31
	v_cvt_pk_bf16_f32 v16, v20, v21
	v_cvt_pk_bf16_f32 v17, v22, v23
	v_cvt_pk_bf16_f32 v18, v24, v25
	v_cvt_pk_bf16_f32 v19, v26, v19
	global_store_dwordx4 v[88:89], v[16:19], off offset:1280 sc1
	global_load_dwordx4 v[16:19], v[90:91], off offset:256
	s_waitcnt vmcnt(0)
	v_lshlrev_b32_e32 v23, 16, v19
	v_and_b32_e32 v19, 0xffff0000, v19
	v_lshlrev_b32_e32 v20, 16, v16
	v_and_b32_e32 v16, 0xffff0000, v16
	v_lshlrev_b32_e32 v21, 16, v17
	v_and_b32_e32 v17, 0xffff0000, v17
	v_lshlrev_b32_e32 v22, 16, v18
	v_and_b32_e32 v18, 0xffff0000, v18
	v_mul_f32_e32 v11, v11, v19
	v_mul_f32_e32 v12, v12, v20
	v_mul_f32_e32 v13, v13, v16
	v_mul_f32_e32 v14, v14, v21
	v_mul_f32_e32 v15, v15, v17
	v_mul_f32_e32 v16, v8, v22
	v_mul_f32_e32 v17, v9, v18
	v_mul_f32_e32 v18, v10, v23
	v_cvt_pk_bf16_f32 v8, v12, v13
	v_cvt_pk_bf16_f32 v9, v14, v15
	v_cvt_pk_bf16_f32 v10, v16, v17
	v_cvt_pk_bf16_f32 v11, v18, v11
	global_store_dwordx4 v[80:81], v[8:11], off offset:1280 sc1
	global_load_dwordx4 v[8:11], v[82:83], off offset:256
	s_waitcnt vmcnt(0)
	v_lshlrev_b32_e32 v15, 16, v11
	v_and_b32_e32 v11, 0xffff0000, v11
	v_lshlrev_b32_e32 v12, 16, v8
	v_and_b32_e32 v8, 0xffff0000, v8
	v_lshlrev_b32_e32 v13, 16, v9
	v_and_b32_e32 v9, 0xffff0000, v9
	v_lshlrev_b32_e32 v14, 16, v10
	v_and_b32_e32 v10, 0xffff0000, v10
	v_mul_f32_e32 v3, v3, v11
	v_mul_f32_e32 v4, v4, v12
	v_mul_f32_e32 v5, v5, v8
	v_mul_f32_e32 v6, v6, v13
	v_mul_f32_e32 v7, v7, v9
	v_mul_f32_e32 v8, v0, v14
	v_mul_f32_e32 v9, v1, v10
	v_mul_f32_e32 v10, v2, v15
	v_cvt_pk_bf16_f32 v0, v4, v5
	v_cvt_pk_bf16_f32 v1, v6, v7
	v_cvt_pk_bf16_f32 v2, v8, v9
	v_cvt_pk_bf16_f32 v3, v10, v3
	global_store_dwordx4 v[72:73], v[0:3], off offset:1280 sc1
	s_cbranch_vccnz .LBB0_616
	s_andn2_b64 vcc, exec, s[8:9]
	s_cbranch_vccnz .LBB0_615
	s_barrier
	s_branch .LBB0_615

; __device__ __forceinline__ unsigned cvt_pk_bf16(float lo, float hi) { unsigned r; asm volatile("v_cvt_pk_bf16_f32 %0, %1, %2" : "=v"(r) : "v"(lo), "v"(hi)); return r; }
;     __device__ __forceinline__ void operator()(const f32x4 (&acc)[2][2][4][2], const pg8::Unit& u, int wr, int wc, int fr, int fq) const {
;         const int row0 = u.pm * 256 + wr * 64 + fr, col0 = u.pn * 256 + wc * 32 + 8 * fq;
;         u32x4 xin[2][4][2];
; #pragma unroll
;         for (int ai = 0; ai < 2; ++ai)
; #pragma unroll
;             for (int m = 0; m < 4; ++m)
; #pragma unroll
;                 for (int bj = 0; bj < 2; ++bj) xin[ai][m][bj] = *(const u32x4*)(XB + (size_t)(row0 + ai * 128 + m * 16) * D + col0 + bj * 128);
; #pragma unroll
;         for (int ai = 0; ai < 2; ++ai)
; #pragma unroll
;             for (int m = 0; m < 4; ++m) { const size_t ro = (size_t)(row0 + ai * 128 + m * 16) * D + col0; float sq = 0.f;
; #pragma unroll
;                 for (int bj = 0; bj < 2; ++bj) { const u32x4 xb = xin[ai][m][bj];
;                     const f32x4 x0 = (f32x4){bf_lo(xb.x), bf_hi(xb.x), bf_lo(xb.y), bf_hi(xb.y)} + acc[ai][bj][m][0] * s, x1 = (f32x4){bf_lo(xb.z), bf_hi(xb.z), bf_lo(xb.w), bf_hi(xb.w)} + acc[ai][bj][m][1] * s;
;                     sq += (x0[0] * x0[0] + x0[1] * x0[1]) + (x0[2] * x0[2] + x0[3] * x0[3]) + (x1[0] * x1[0] + x1[1] * x1[1]) + (x1[2] * x1[2] + x1[3] * x1[3]);
;                     u32x4 w; w.x = cvt_pk_bf16(x0[0], x0[1]); w.y = cvt_pk_bf16(x0[2], x0[3]); w.z = cvt_pk_bf16(x1[0], x1[1]); w.w = cvt_pk_bf16(x1[2], x1[3]);
;                     *(u32x4*)(XB + ro + bj * 128) = w; }
;                 sq += __shfl_xor(sq, 16); sq += __shfl_xor(sq, 32);
;                 if (fq == 0) SSo[(size_t)(u.pn * 4 + wc) * T + row0 + ai * 128 + m * 16] = sq; }
.LBB0_708:
	v_lshl_or_b32 v204, s34, 8, v222
	v_lshl_add_u32 v202, s52, 8, v220
	v_ashrrev_i32_e32 v205, 31, v204
	v_lshlrev_b64 v[236:237], 1, v[204:205]
	v_ashrrev_i32_e32 v203, 31, v202
	v_lshl_add_u64 v[96:97], s[36:37], 0, v[236:237]
	v_lshlrev_b64 v[238:239], 11, v[202:203]
	v_lshl_add_u64 v[98:99], v[96:97], 0, v[238:239]
	global_load_dwordx4 v[228:231], v[98:99], off
	global_load_dwordx4 v[232:235], v[98:99], off offset:256
	v_or_b32_e32 v98, 16, v202
	v_or_b32_e32 v108, 32, v202
	v_or_b32_e32 v110, 48, v202
	v_ashrrev_i32_e32 v99, 31, v98
	v_ashrrev_i32_e32 v109, 31, v108
	v_ashrrev_i32_e32 v111, 31, v110
	v_lshlrev_b64 v[218:219], 11, v[98:99]
	v_lshlrev_b64 v[216:217], 11, v[108:109]
	v_lshlrev_b64 v[214:215], 11, v[110:111]
	v_lshl_add_u64 v[212:213], v[238:239], 0, s[8:9]
	v_lshl_add_u64 v[210:211], v[238:239], 0, s[16:17]
	v_lshl_add_u64 v[208:209], v[238:239], 0, s[18:19]
	v_lshl_add_u64 v[206:207], v[238:239], 0, s[38:39]
	v_lshl_add_u64 v[98:99], v[96:97], 0, v[218:219]
	v_lshl_add_u64 v[108:109], v[96:97], 0, v[216:217]
	v_lshl_add_u64 v[110:111], v[96:97], 0, v[214:215]
	v_lshl_add_u64 v[120:121], v[96:97], 0, v[212:213]
	v_lshl_add_u64 v[122:123], v[96:97], 0, v[210:211]
	v_lshl_add_u64 v[240:241], v[96:97], 0, v[208:209]
	v_lshl_add_u64 v[96:97], v[96:97], 0, v[206:207]
	global_load_dwordx4 v[180:183], v[98:99], off
	global_load_dwordx4 v[176:179], v[98:99], off offset:256
	global_load_dwordx4 v[172:175], v[108:109], off
	global_load_dwordx4 v[168:171], v[108:109], off offset:256
	global_load_dwordx4 v[164:167], v[110:111], off
	global_load_dwordx4 v[160:163], v[110:111], off offset:256
	global_load_dwordx4 v[156:159], v[120:121], off
	global_load_dwordx4 v[152:155], v[120:121], off offset:256
	global_load_dwordx4 v[148:151], v[122:123], off
	global_load_dwordx4 v[144:147], v[122:123], off offset:256
	global_load_dwordx4 v[128:131], v[240:241], off
	s_nop 0
	global_load_dwordx4 v[120:123], v[240:241], off offset:256
	global_load_dwordx4 v[108:111], v[96:97], off
	s_nop 0
	global_load_dwordx4 v[96:99], v[96:97], off offset:256
	s_lshl_b32 s20, s34, 2
	s_or_b32 s20, s20, s65
	s_ashr_i32 s21, s20, 31
	s_lshl_b64 s[20:21], s[20:21], 17
	s_waitcnt vmcnt(0)
	v_lshlrev_b32_e32 v240, 16, v228
	v_and_b32_e32 v241, 0xffff0000, v228
	v_lshlrev_b32_e32 v228, 16, v229
	v_and_b32_e32 v229, 0xffff0000, v229
	v_lshlrev_b32_e32 v242, 16, v230
	v_and_b32_e32 v243, 0xffff0000, v230
	v_lshlrev_b32_e32 v244, 16, v232
	v_and_b32_e32 v245, 0xffff0000, v232
	v_lshlrev_b32_e32 v232, 16, v233
	v_and_b32_e32 v233, 0xffff0000, v233
	v_lshlrev_b32_e32 v246, 16, v234
	v_and_b32_e32 v247, 0xffff0000, v234
	v_lshlrev_b32_e32 v234, 16, v235
	v_and_b32_e32 v235, 0xffff0000, v235
	v_pk_add_f32 v[142:143], v[142:143], v[228:229]
	v_pk_add_f32 v[140:141], v[140:141], v[240:241]
	v_lshlrev_b32_e32 v230, 16, v231
	v_and_b32_e32 v231, 0xffff0000, v231
	v_pk_add_f32 v[136:137], v[136:137], v[242:243]
	v_pk_add_f32 v[228:229], v[134:135], v[232:233]
	v_pk_add_f32 v[232:233], v[126:127], v[234:235]
	v_pk_add_f32 v[234:235], v[124:125], v[246:247]
	v_mul_f32_e32 v124, v141, v141
	v_mul_f32_e32 v125, v143, v143
	v_pk_add_f32 v[138:139], v[138:139], v[230:231]
	v_pk_add_f32 v[230:231], v[132:133], v[244:245]
	v_mul_f32_e32 v126, v137, v137
	v_fmac_f32_e32 v124, v140, v140
	v_fmac_f32_e32 v125, v142, v142
	v_mul_f32_e32 v127, v139, v139
	v_cvt_pk_bf16_f32 v132, v140, v141
	v_cvt_pk_bf16_f32 v133, v142, v143
	v_cvt_pk_bf16_f32 v134, v136, v137
	v_cvt_pk_bf16_f32 v135, v138, v139
	v_mul_f32_e32 v137, v231, v231
	v_mul_f32_e32 v139, v229, v229
	v_fmac_f32_e32 v126, v136, v136
	v_add_f32_e32 v124, v124, v125
	v_fmac_f32_e32 v137, v230, v230
	v_fmac_f32_e32 v139, v228, v228
	v_add_f32_e32 v124, v126, v124
	v_mul_f32_e32 v126, v235, v235
	v_add_f32_e32 v125, v137, v139
	v_fmac_f32_e32 v126, v234, v234
	v_add_f32_e32 v125, v126, v125
	v_mul_f32_e32 v126, v233, v233
	v_fmac_f32_e32 v127, v138, v138
	v_fmac_f32_e32 v126, v232, v232
	v_add_f32_e32 v124, v127, v124
	v_add_f32_e32 v125, v126, v125
	v_and_b32_e32 v126, 64, v226
	v_add_f32_e32 v125, v124, v125
	v_add_u32_e32 v138, 64, v126
	v_lshl_add_u64 v[126:127], s[36:37], 0, v[238:239]
	v_lshl_add_u64 v[136:137], v[126:127], 0, v[236:237]
	v_mov_b32_e32 v139, v125
	s_nop 1
	v_permlane16_swap_b32_e32 v139, v125
	global_store_dwordx4 v[136:137], v[132:135], off sc1
	s_waitcnt lgkmcnt(0)
	v_add_f32_e32 v126, v125, v139
	v_cvt_pk_bf16_f32 v132, v230, v231
	v_cvt_pk_bf16_f32 v133, v228, v229
	v_cvt_pk_bf16_f32 v134, v234, v235
	v_cvt_pk_bf16_f32 v135, v232, v233
	global_store_dwordx4 v[136:137], v[132:135], off offset:256 sc1
	s_nop 0
	v_mov_b32_e32 v127, v126
	s_nop 1
	v_permlane32_swap_b32_e32 v127, v126
	s_and_saveexec_b64 s[34:35], s[4:5]
	s_cbranch_execz .LBB0_710
	s_add_u32 s54, s63, s20
	s_addc_u32 s55, s64, s21
	v_lshl_add_u64 v[132:133], v[202:203], 2, s[54:55]
	s_waitcnt lgkmcnt(0)
	v_add_f32_e32 v126, v126, v127
	global_store_dword v[132:133], v126, off
; __device__ __forceinline__ unsigned cvt_pk_bf16(float lo, float hi) { unsigned r; asm volatile("v_cvt_pk_bf16_f32 %0, %1, %2" : "=v"(r) : "v"(lo), "v"(hi)); return r; }
;     __device__ __forceinline__ void operator()(const f32x4 (&acc)[2][2][4][2], const pg8::Unit& u, int wr, int wc, int fr, int fq) const {
;     ...
;             for (int m = 0; m < 4; ++m) { const size_t ro = (size_t)(row0 + ai * 128 + m * 16) * D + col0; float sq = 0.f;
; #pragma unroll
;                 for (int bj = 0; bj < 2; ++bj) { const u32x4 xb = xin[ai][m][bj];
;                     const f32x4 x0 = (f32x4){bf_lo(xb.x), bf_hi(xb.x), bf_lo(xb.y), bf_hi(xb.y)} + acc[ai][bj][m][0] * s, x1 = (f32x4){bf_lo(xb.z), bf_hi(xb.z), bf_lo(xb.w), bf_hi(xb.w)} + acc[ai][bj][m][1] * s;
;                     sq += (x0[0] * x0[0] + x0[1] * x0[1]) + (x0[2] * x0[2] + x0[3] * x0[3]) + (x1[0] * x1[0] + x1[1] * x1[1]) + (x1[2] * x1[2] + x1[3] * x1[3]);
;                     u32x4 w; w.x = cvt_pk_bf16(x0[0], x0[1]); w.y = cvt_pk_bf16(x0[2], x0[3]); w.z = cvt_pk_bf16(x1[0], x1[1]); w.w = cvt_pk_bf16(x1[2], x1[3]);
;                     *(u32x4*)(XB + ro + bj * 128) = w; }
;                 sq += __shfl_xor(sq, 16); sq += __shfl_xor(sq, 32);
;                 if (fq == 0) SSo[(size_t)(u.pn * 4 + wc) * T + row0 + ai * 128 + m * 16] = sq; }
.LBB0_710:
	s_or_b64 exec, exec, s[34:35]
	v_lshlrev_b32_e32 v126, 16, v180
	s_waitcnt lgkmcnt(0)
	v_and_b32_e32 v127, 0xffff0000, v180
	v_lshlrev_b32_e32 v132, 16, v181
	v_and_b32_e32 v133, 0xffff0000, v181
	v_pk_add_f32 v[118:119], v[118:119], v[132:133]
	v_pk_add_f32 v[116:117], v[116:117], v[126:127]
	v_lshlrev_b32_e32 v126, 16, v182
	v_and_b32_e32 v127, 0xffff0000, v182
	v_lshlrev_b32_e32 v132, 16, v183
	v_and_b32_e32 v133, 0xffff0000, v183
	v_pk_add_f32 v[132:133], v[114:115], v[132:133]
	v_pk_add_f32 v[114:115], v[112:113], v[126:127]
	v_mul_f32_e32 v112, v117, v117
	v_mul_f32_e32 v113, v119, v119
	v_fmac_f32_e32 v112, v116, v116
	v_fmac_f32_e32 v113, v118, v118
	v_add_f32_e32 v112, v112, v113
	v_mul_f32_e32 v113, v115, v115
	v_fmac_f32_e32 v113, v114, v114
	v_add_f32_e32 v112, v113, v112
	v_mul_f32_e32 v113, v133, v133
	v_fmac_f32_e32 v113, v132, v132
	v_add_f32_e32 v126, v113, v112
	v_cvt_pk_bf16_f32 v112, v116, v117
	v_cvt_pk_bf16_f32 v113, v118, v119
	v_lshlrev_b32_e32 v116, 16, v176
	v_and_b32_e32 v117, 0xffff0000, v176
	v_lshlrev_b32_e32 v118, 16, v177
	v_and_b32_e32 v119, 0xffff0000, v177
	v_pk_add_f32 v[106:107], v[106:107], v[118:119]
	v_pk_add_f32 v[104:105], v[104:105], v[116:117]
	v_lshlrev_b32_e32 v116, 16, v178
	v_and_b32_e32 v117, 0xffff0000, v178
	v_pk_add_f32 v[116:117], v[100:101], v[116:117]
	v_mul_f32_e32 v100, v105, v105
	v_mul_f32_e32 v101, v107, v107
	v_fmac_f32_e32 v100, v104, v104
	v_fmac_f32_e32 v101, v106, v106
	v_lshlrev_b32_e32 v118, 16, v179
	v_and_b32_e32 v119, 0xffff0000, v179
	v_add_f32_e32 v100, v100, v101
	v_mul_f32_e32 v101, v117, v117
	v_pk_add_f32 v[118:119], v[102:103], v[118:119]
	v_fmac_f32_e32 v101, v116, v116
	v_add_f32_e32 v100, v101, v100
	v_mul_f32_e32 v101, v119, v119
	v_fmac_f32_e32 v101, v118, v118
	v_add_f32_e32 v100, v101, v100
	v_add_f32_e32 v103, v126, v100
	v_cvt_pk_bf16_f32 v114, v114, v115
	v_cvt_pk_bf16_f32 v115, v132, v133
	v_mov_b32_e32 v132, v103
	s_nop 1
	v_permlane16_swap_b32_e32 v132, v103
	v_lshl_add_u64 v[100:101], s[36:37], 0, v[218:219]
	v_lshl_add_u64 v[126:127], v[204:205], 1, v[100:101]
	global_store_dwordx4 v[126:127], v[112:115], off sc1
	v_cvt_pk_bf16_f32 v102, v104, v105
	s_waitcnt lgkmcnt(0)
	v_add_f32_e32 v100, v103, v132
	v_mov_b32_e32 v101, v100
	s_nop 1
	v_permlane32_swap_b32_e32 v101, v100
	v_cvt_pk_bf16_f32 v103, v106, v107
	v_cvt_pk_bf16_f32 v104, v116, v117
	v_cvt_pk_bf16_f32 v105, v118, v119
	global_store_dwordx4 v[126:127], v[102:105], off offset:256 sc1
	s_and_saveexec_b64 s[34:35], s[4:5]
	s_cbranch_execz .LBB0_712
	s_add_u32 s54, s63, s20
	s_addc_u32 s55, s64, s21
	v_lshl_add_u64 v[102:103], v[202:203], 2, s[54:55]
	s_waitcnt lgkmcnt(0)
	v_add_f32_e32 v100, v100, v101
	global_store_dword v[102:103], v100, off offset:64
.LBB0_712:
	s_or_b64 exec, exec, s[34:35]
	v_lshlrev_b32_e32 v100, 16, v172
	s_waitcnt lgkmcnt(0)
	v_and_b32_e32 v101, 0xffff0000, v172
	v_lshlrev_b32_e32 v102, 16, v173
	v_and_b32_e32 v103, 0xffff0000, v173
	v_pk_add_f32 v[94:95], v[94:95], v[102:103]
	v_pk_add_f32 v[92:93], v[92:93], v[100:101]
	v_lshlrev_b32_e32 v100, 16, v174
	v_and_b32_e32 v101, 0xffff0000, v174
	v_lshlrev_b32_e32 v102, 16, v175
	v_and_b32_e32 v103, 0xffff0000, v175
	v_pk_add_f32 v[102:103], v[90:91], v[102:103]
	v_pk_add_f32 v[90:91], v[88:89], v[100:101]
	v_mul_f32_e32 v88, v93, v93
	v_mul_f32_e32 v89, v95, v95
	v_fmac_f32_e32 v88, v92, v92
	v_fmac_f32_e32 v89, v94, v94
	v_add_f32_e32 v88, v88, v89
	v_mul_f32_e32 v89, v91, v91
	v_fmac_f32_e32 v89, v90, v90
	v_add_f32_e32 v88, v89, v88
	v_mul_f32_e32 v89, v103, v103
	v_fmac_f32_e32 v89, v102, v102
	v_add_f32_e32 v100, v89, v88
	v_cvt_pk_bf16_f32 v88, v92, v93
	v_cvt_pk_bf16_f32 v89, v94, v95
	v_lshlrev_b32_e32 v92, 16, v168
	v_and_b32_e32 v93, 0xffff0000, v168
	v_lshlrev_b32_e32 v94, 16, v169
	v_and_b32_e32 v95, 0xffff0000, v169
	v_pk_add_f32 v[86:87], v[86:87], v[94:95]
	v_pk_add_f32 v[84:85], v[84:85], v[92:93]
	v_lshlrev_b32_e32 v92, 16, v170
	v_and_b32_e32 v93, 0xffff0000, v170
	v_pk_add_f32 v[92:93], v[80:81], v[92:93]
	v_mul_f32_e32 v80, v85, v85
	v_mul_f32_e32 v81, v87, v87
	v_fmac_f32_e32 v80, v84, v84
	v_fmac_f32_e32 v81, v86, v86
	v_lshlrev_b32_e32 v94, 16, v171
	v_and_b32_e32 v95, 0xffff0000, v171
	v_add_f32_e32 v80, v80, v81
	v_mul_f32_e32 v81, v93, v93
	v_pk_add_f32 v[94:95], v[82:83], v[94:95]
	v_fmac_f32_e32 v81, v92, v92
	v_add_f32_e32 v80, v81, v80
	v_mul_f32_e32 v81, v95, v95
	v_fmac_f32_e32 v81, v94, v94
	v_add_f32_e32 v80, v81, v80
	v_add_f32_e32 v83, v100, v80
	v_cvt_pk_bf16_f32 v90, v90, v91
	v_cvt_pk_bf16_f32 v91, v102, v103
	v_mov_b32_e32 v102, v83
	s_nop 1
	v_permlane16_swap_b32_e32 v102, v83
	v_lshl_add_u64 v[80:81], s[36:37], 0, v[216:217]
	v_lshl_add_u64 v[100:101], v[204:205], 1, v[80:81]
	global_store_dwordx4 v[100:101], v[88:91], off sc1
	v_cvt_pk_bf16_f32 v82, v84, v85
	s_waitcnt lgkmcnt(0)
	v_add_f32_e32 v80, v83, v102
	v_mov_b32_e32 v81, v80
	s_nop 1
	v_permlane32_swap_b32_e32 v81, v80
	v_cvt_pk_bf16_f32 v83, v86, v87
	v_cvt_pk_bf16_f32 v84, v92, v93
	v_cvt_pk_bf16_f32 v85, v94, v95
	global_store_dwordx4 v[100:101], v[82:85], off offset:256 sc1
	s_and_saveexec_b64 s[34:35], s[4:5]
	s_cbranch_execz .LBB0_714
	s_add_u32 s54, s63, s20
	s_addc_u32 s55, s64, s21
	v_lshl_add_u64 v[82:83], v[202:203], 2, s[54:55]
	s_waitcnt lgkmcnt(0)
	v_add_f32_e32 v80, v80, v81
	global_store_dword v[82:83], v80, off offset:128
; __device__ __forceinline__ unsigned cvt_pk_bf16(float lo, float hi) { unsigned r; asm volatile("v_cvt_pk_bf16_f32 %0, %1, %2" : "=v"(r) : "v"(lo), "v"(hi)); return r; }
;     __device__ __forceinline__ void operator()(const f32x4 (&acc)[2][2][4][2], const pg8::Unit& u, int wr, int wc, int fr, int fq) const {
;     ...
;             for (int m = 0; m < 4; ++m) { const size_t ro = (size_t)(row0 + ai * 128 + m * 16) * D + col0; float sq = 0.f;
; #pragma unroll
;                 for (int bj = 0; bj < 2; ++bj) { const u32x4 xb = xin[ai][m][bj];
;                     const f32x4 x0 = (f32x4){bf_lo(xb.x), bf_hi(xb.x), bf_lo(xb.y), bf_hi(xb.y)} + acc[ai][bj][m][0] * s, x1 = (f32x4){bf_lo(xb.z), bf_hi(xb.z), bf_lo(xb.w), bf_hi(xb.w)} + acc[ai][bj][m][1] * s;
;                     sq += (x0[0] * x0[0] + x0[1] * x0[1]) + (x0[2] * x0[2] + x0[3] * x0[3]) + (x1[0] * x1[0] + x1[1] * x1[1]) + (x1[2] * x1[2] + x1[3] * x1[3]);
;                     u32x4 w; w.x = cvt_pk_bf16(x0[0], x0[1]); w.y = cvt_pk_bf16(x0[2], x0[3]); w.z = cvt_pk_bf16(x1[0], x1[1]); w.w = cvt_pk_bf16(x1[2], x1[3]);
;                     *(u32x4*)(XB + ro + bj * 128) = w; }
;                 sq += __shfl_xor(sq, 16); sq += __shfl_xor(sq, 32);
;                 if (fq == 0) SSo[(size_t)(u.pn * 4 + wc) * T + row0 + ai * 128 + m * 16] = sq; }
.LBB0_714:
	s_or_b64 exec, exec, s[34:35]
	v_lshlrev_b32_e32 v80, 16, v164
	s_waitcnt lgkmcnt(0)
	v_and_b32_e32 v81, 0xffff0000, v164
	v_lshlrev_b32_e32 v82, 16, v165
	v_and_b32_e32 v83, 0xffff0000, v165
	v_pk_add_f32 v[78:79], v[78:79], v[82:83]
	v_pk_add_f32 v[76:77], v[76:77], v[80:81]
	v_lshlrev_b32_e32 v80, 16, v166
	v_and_b32_e32 v81, 0xffff0000, v166
	v_lshlrev_b32_e32 v82, 16, v167
	v_and_b32_e32 v83, 0xffff0000, v167
	v_pk_add_f32 v[82:83], v[74:75], v[82:83]
	v_pk_add_f32 v[74:75], v[72:73], v[80:81]
	v_mul_f32_e32 v72, v77, v77
	v_mul_f32_e32 v73, v79, v79
	v_fmac_f32_e32 v72, v76, v76
	v_fmac_f32_e32 v73, v78, v78
	v_add_f32_e32 v72, v72, v73
	v_mul_f32_e32 v73, v75, v75
	v_fmac_f32_e32 v73, v74, v74
	v_add_f32_e32 v72, v73, v72
	v_mul_f32_e32 v73, v83, v83
	v_fmac_f32_e32 v73, v82, v82
	v_add_f32_e32 v80, v73, v72
	v_cvt_pk_bf16_f32 v72, v76, v77
	v_cvt_pk_bf16_f32 v73, v78, v79
	v_lshlrev_b32_e32 v76, 16, v160
	v_and_b32_e32 v77, 0xffff0000, v160
	v_lshlrev_b32_e32 v78, 16, v161
	v_and_b32_e32 v79, 0xffff0000, v161
	v_pk_add_f32 v[70:71], v[70:71], v[78:79]
	v_pk_add_f32 v[68:69], v[68:69], v[76:77]
	v_lshlrev_b32_e32 v76, 16, v162
	v_and_b32_e32 v77, 0xffff0000, v162
	v_pk_add_f32 v[76:77], v[64:65], v[76:77]
	v_mul_f32_e32 v64, v69, v69
	v_mul_f32_e32 v65, v71, v71
	v_fmac_f32_e32 v64, v68, v68
	v_fmac_f32_e32 v65, v70, v70
	v_lshlrev_b32_e32 v78, 16, v163
	v_and_b32_e32 v79, 0xffff0000, v163
	v_add_f32_e32 v64, v64, v65
	v_mul_f32_e32 v65, v77, v77
	v_pk_add_f32 v[78:79], v[66:67], v[78:79]
	v_fmac_f32_e32 v65, v76, v76
	v_add_f32_e32 v64, v65, v64
	v_mul_f32_e32 v65, v79, v79
	v_fmac_f32_e32 v65, v78, v78
	v_add_f32_e32 v64, v65, v64
	v_add_f32_e32 v67, v80, v64
	v_cvt_pk_bf16_f32 v74, v74, v75
	v_cvt_pk_bf16_f32 v75, v82, v83
	v_mov_b32_e32 v82, v67
	s_nop 1
	v_permlane16_swap_b32_e32 v82, v67
	v_lshl_add_u64 v[64:65], s[36:37], 0, v[214:215]
	v_lshl_add_u64 v[80:81], v[204:205], 1, v[64:65]
	global_store_dwordx4 v[80:81], v[72:75], off sc1
	v_cvt_pk_bf16_f32 v66, v68, v69
	s_waitcnt lgkmcnt(0)
	v_add_f32_e32 v64, v67, v82
	v_mov_b32_e32 v65, v64
	s_nop 1
	v_permlane32_swap_b32_e32 v65, v64
	v_cvt_pk_bf16_f32 v67, v70, v71
	v_cvt_pk_bf16_f32 v68, v76, v77
	v_cvt_pk_bf16_f32 v69, v78, v79
	global_store_dwordx4 v[80:81], v[66:69], off offset:256 sc1
	s_and_saveexec_b64 s[34:35], s[4:5]
	s_cbranch_execz .LBB0_716
	s_add_u32 s54, s63, s20
	s_addc_u32 s55, s64, s21
	v_lshl_add_u64 v[66:67], v[202:203], 2, s[54:55]
	s_waitcnt lgkmcnt(0)
	v_add_f32_e32 v64, v64, v65
	global_store_dword v[66:67], v64, off offset:192
.LBB0_716:
	s_or_b64 exec, exec, s[34:35]
	v_lshlrev_b32_e32 v64, 16, v156
	s_waitcnt lgkmcnt(0)
	v_and_b32_e32 v65, 0xffff0000, v156
	v_lshlrev_b32_e32 v66, 16, v157
	v_and_b32_e32 v67, 0xffff0000, v157
	v_pk_add_f32 v[62:63], v[62:63], v[66:67]
	v_pk_add_f32 v[60:61], v[60:61], v[64:65]
	v_lshlrev_b32_e32 v64, 16, v158
	v_and_b32_e32 v65, 0xffff0000, v158
	v_lshlrev_b32_e32 v66, 16, v159
	v_and_b32_e32 v67, 0xffff0000, v159
	v_pk_add_f32 v[66:67], v[58:59], v[66:67]
	v_pk_add_f32 v[58:59], v[56:57], v[64:65]
	v_mul_f32_e32 v56, v61, v61
	v_mul_f32_e32 v57, v63, v63
	v_fmac_f32_e32 v56, v60, v60
	v_fmac_f32_e32 v57, v62, v62
	v_add_f32_e32 v56, v56, v57
	v_mul_f32_e32 v57, v59, v59
	v_fmac_f32_e32 v57, v58, v58
	v_add_f32_e32 v56, v57, v56
	v_mul_f32_e32 v57, v67, v67
	v_fmac_f32_e32 v57, v66, v66
	v_add_f32_e32 v64, v57, v56
	v_cvt_pk_bf16_f32 v56, v60, v61
	v_cvt_pk_bf16_f32 v57, v62, v63
	v_lshlrev_b32_e32 v60, 16, v152
	v_and_b32_e32 v61, 0xffff0000, v152
	v_lshlrev_b32_e32 v62, 16, v153
	v_and_b32_e32 v63, 0xffff0000, v153
	v_pk_add_f32 v[54:55], v[54:55], v[62:63]
	v_pk_add_f32 v[52:53], v[52:53], v[60:61]
	v_lshlrev_b32_e32 v60, 16, v154
	v_and_b32_e32 v61, 0xffff0000, v154
	v_pk_add_f32 v[60:61], v[48:49], v[60:61]
	v_mul_f32_e32 v48, v53, v53
	v_mul_f32_e32 v49, v55, v55
	v_fmac_f32_e32 v48, v52, v52
	v_fmac_f32_e32 v49, v54, v54
	v_lshlrev_b32_e32 v62, 16, v155
	v_and_b32_e32 v63, 0xffff0000, v155
	v_add_f32_e32 v48, v48, v49
	v_mul_f32_e32 v49, v61, v61
	v_pk_add_f32 v[62:63], v[50:51], v[62:63]
	v_fmac_f32_e32 v49, v60, v60
	v_add_f32_e32 v48, v49, v48
	v_mul_f32_e32 v49, v63, v63
	v_fmac_f32_e32 v49, v62, v62
	v_add_f32_e32 v48, v49, v48
	v_add_f32_e32 v51, v64, v48
	v_cvt_pk_bf16_f32 v58, v58, v59
	v_cvt_pk_bf16_f32 v59, v66, v67
	v_mov_b32_e32 v66, v51
	s_nop 1
	v_permlane16_swap_b32_e32 v66, v51
	v_lshl_add_u64 v[48:49], s[36:37], 0, v[212:213]
	v_lshl_add_u64 v[64:65], v[204:205], 1, v[48:49]
	global_store_dwordx4 v[64:65], v[56:59], off sc1
	v_cvt_pk_bf16_f32 v50, v52, v53
	s_waitcnt lgkmcnt(0)
	v_add_f32_e32 v48, v51, v66
	v_mov_b32_e32 v49, v48
	s_nop 1
	v_permlane32_swap_b32_e32 v49, v48
	v_cvt_pk_bf16_f32 v51, v54, v55
	v_cvt_pk_bf16_f32 v52, v60, v61
	v_cvt_pk_bf16_f32 v53, v62, v63
	global_store_dwordx4 v[64:65], v[50:53], off offset:256 sc1
	s_and_saveexec_b64 s[34:35], s[4:5]
	s_cbranch_execz .LBB0_718
	s_add_u32 s54, s63, s20
	s_addc_u32 s55, s64, s21
	v_lshl_add_u64 v[50:51], v[202:203], 2, s[54:55]
	s_waitcnt lgkmcnt(0)
	v_add_f32_e32 v48, v48, v49
	global_store_dword v[50:51], v48, off offset:512
; __device__ __forceinline__ unsigned cvt_pk_bf16(float lo, float hi) { unsigned r; asm volatile("v_cvt_pk_bf16_f32 %0, %1, %2" : "=v"(r) : "v"(lo), "v"(hi)); return r; }
;     __device__ __forceinline__ void operator()(const f32x4 (&acc)[2][2][4][2], const pg8::Unit& u, int wr, int wc, int fr, int fq) const {
;     ...
;             for (int m = 0; m < 4; ++m) { const size_t ro = (size_t)(row0 + ai * 128 + m * 16) * D + col0; float sq = 0.f;
; #pragma unroll
;                 for (int bj = 0; bj < 2; ++bj) { const u32x4 xb = xin[ai][m][bj];
;                     const f32x4 x0 = (f32x4){bf_lo(xb.x), bf_hi(xb.x), bf_lo(xb.y), bf_hi(xb.y)} + acc[ai][bj][m][0] * s, x1 = (f32x4){bf_lo(xb.z), bf_hi(xb.z), bf_lo(xb.w), bf_hi(xb.w)} + acc[ai][bj][m][1] * s;
;                     sq += (x0[0] * x0[0] + x0[1] * x0[1]) + (x0[2] * x0[2] + x0[3] * x0[3]) + (x1[0] * x1[0] + x1[1] * x1[1]) + (x1[2] * x1[2] + x1[3] * x1[3]);
;                     u32x4 w; w.x = cvt_pk_bf16(x0[0], x0[1]); w.y = cvt_pk_bf16(x0[2], x0[3]); w.z = cvt_pk_bf16(x1[0], x1[1]); w.w = cvt_pk_bf16(x1[2], x1[3]);
;                     *(u32x4*)(XB + ro + bj * 128) = w; }
;                 sq += __shfl_xor(sq, 16); sq += __shfl_xor(sq, 32);
;                 if (fq == 0) SSo[(size_t)(u.pn * 4 + wc) * T + row0 + ai * 128 + m * 16] = sq; }
.LBB0_718:
	s_or_b64 exec, exec, s[34:35]
	v_lshlrev_b32_e32 v48, 16, v148
	s_waitcnt lgkmcnt(0)
	v_and_b32_e32 v49, 0xffff0000, v148
	v_lshlrev_b32_e32 v50, 16, v149
	v_and_b32_e32 v51, 0xffff0000, v149
	v_pk_add_f32 v[46:47], v[46:47], v[50:51]
	v_pk_add_f32 v[44:45], v[44:45], v[48:49]
	v_lshlrev_b32_e32 v48, 16, v150
	v_and_b32_e32 v49, 0xffff0000, v150
	v_lshlrev_b32_e32 v50, 16, v151
	v_and_b32_e32 v51, 0xffff0000, v151
	v_pk_add_f32 v[50:51], v[42:43], v[50:51]
	v_pk_add_f32 v[42:43], v[40:41], v[48:49]
	v_mul_f32_e32 v40, v45, v45
	v_mul_f32_e32 v41, v47, v47
	v_fmac_f32_e32 v40, v44, v44
	v_fmac_f32_e32 v41, v46, v46
	v_add_f32_e32 v40, v40, v41
	v_mul_f32_e32 v41, v43, v43
	v_fmac_f32_e32 v41, v42, v42
	v_add_f32_e32 v40, v41, v40
	v_mul_f32_e32 v41, v51, v51
	v_fmac_f32_e32 v41, v50, v50
	v_add_f32_e32 v48, v41, v40
	v_cvt_pk_bf16_f32 v40, v44, v45
	v_cvt_pk_bf16_f32 v41, v46, v47
	v_lshlrev_b32_e32 v44, 16, v144
	v_and_b32_e32 v45, 0xffff0000, v144
	v_lshlrev_b32_e32 v46, 16, v145
	v_and_b32_e32 v47, 0xffff0000, v145
	v_pk_add_f32 v[38:39], v[38:39], v[46:47]
	v_pk_add_f32 v[36:37], v[36:37], v[44:45]
	v_lshlrev_b32_e32 v44, 16, v146
	v_and_b32_e32 v45, 0xffff0000, v146
	v_pk_add_f32 v[44:45], v[32:33], v[44:45]
	v_mul_f32_e32 v32, v37, v37
	v_mul_f32_e32 v33, v39, v39
	v_fmac_f32_e32 v32, v36, v36
	v_fmac_f32_e32 v33, v38, v38
	v_lshlrev_b32_e32 v46, 16, v147
	v_and_b32_e32 v47, 0xffff0000, v147
	v_add_f32_e32 v32, v32, v33
	v_mul_f32_e32 v33, v45, v45
	v_pk_add_f32 v[46:47], v[34:35], v[46:47]
	v_fmac_f32_e32 v33, v44, v44
	v_add_f32_e32 v32, v33, v32
	v_mul_f32_e32 v33, v47, v47
	v_fmac_f32_e32 v33, v46, v46
	v_add_f32_e32 v32, v33, v32
	v_add_f32_e32 v35, v48, v32
	v_cvt_pk_bf16_f32 v42, v42, v43
	v_cvt_pk_bf16_f32 v43, v50, v51
	v_mov_b32_e32 v50, v35
	s_nop 1
	v_permlane16_swap_b32_e32 v50, v35
	v_lshl_add_u64 v[32:33], s[36:37], 0, v[210:211]
	v_lshl_add_u64 v[48:49], v[204:205], 1, v[32:33]
	global_store_dwordx4 v[48:49], v[40:43], off sc1
	v_cvt_pk_bf16_f32 v34, v36, v37
	s_waitcnt lgkmcnt(0)
	v_add_f32_e32 v32, v35, v50
	v_mov_b32_e32 v33, v32
	s_nop 1
	v_permlane32_swap_b32_e32 v33, v32
	v_cvt_pk_bf16_f32 v35, v38, v39
	v_cvt_pk_bf16_f32 v36, v44, v45
	v_cvt_pk_bf16_f32 v37, v46, v47
	global_store_dwordx4 v[48:49], v[34:37], off offset:256 sc1
	s_and_saveexec_b64 s[34:35], s[4:5]
	s_cbranch_execz .LBB0_720
	s_add_u32 s54, s63, s20
	s_addc_u32 s55, s64, s21
	v_lshl_add_u64 v[34:35], v[202:203], 2, s[54:55]
	s_waitcnt lgkmcnt(0)
	v_add_f32_e32 v32, v32, v33
	global_store_dword v[34:35], v32, off offset:576
; __device__ __forceinline__ unsigned cvt_pk_bf16(float lo, float hi) { unsigned r; asm volatile("v_cvt_pk_bf16_f32 %0, %1, %2" : "=v"(r) : "v"(lo), "v"(hi)); return r; }
;     __device__ __forceinline__ void operator()(const f32x4 (&acc)[2][2][4][2], const pg8::Unit& u, int wr, int wc, int fr, int fq) const {
;     ...
;             for (int m = 0; m < 4; ++m) { const size_t ro = (size_t)(row0 + ai * 128 + m * 16) * D + col0; float sq = 0.f;
; #pragma unroll
;                 for (int bj = 0; bj < 2; ++bj) { const u32x4 xb = xin[ai][m][bj];
;                     const f32x4 x0 = (f32x4){bf_lo(xb.x), bf_hi(xb.x), bf_lo(xb.y), bf_hi(xb.y)} + acc[ai][bj][m][0] * s, x1 = (f32x4){bf_lo(xb.z), bf_hi(xb.z), bf_lo(xb.w), bf_hi(xb.w)} + acc[ai][bj][m][1] * s;
;                     sq += (x0[0] * x0[0] + x0[1] * x0[1]) + (x0[2] * x0[2] + x0[3] * x0[3]) + (x1[0] * x1[0] + x1[1] * x1[1]) + (x1[2] * x1[2] + x1[3] * x1[3]);
;                     u32x4 w; w.x = cvt_pk_bf16(x0[0], x0[1]); w.y = cvt_pk_bf16(x0[2], x0[3]); w.z = cvt_pk_bf16(x1[0], x1[1]); w.w = cvt_pk_bf16(x1[2], x1[3]);
;                     *(u32x4*)(XB + ro + bj * 128) = w; }
;                 sq += __shfl_xor(sq, 16); sq += __shfl_xor(sq, 32);
;                 if (fq == 0) SSo[(size_t)(u.pn * 4 + wc) * T + row0 + ai * 128 + m * 16] = sq; }
.LBB0_720:
	s_or_b64 exec, exec, s[34:35]
	v_lshlrev_b32_e32 v32, 16, v128
	s_waitcnt lgkmcnt(0)
	v_and_b32_e32 v33, 0xffff0000, v128
	v_lshlrev_b32_e32 v34, 16, v129
	v_and_b32_e32 v35, 0xffff0000, v129
	v_pk_add_f32 v[30:31], v[30:31], v[34:35]
	v_pk_add_f32 v[28:29], v[28:29], v[32:33]
	v_lshlrev_b32_e32 v32, 16, v130
	v_and_b32_e32 v33, 0xffff0000, v130
	v_lshlrev_b32_e32 v34, 16, v131
	v_and_b32_e32 v35, 0xffff0000, v131
	v_pk_add_f32 v[34:35], v[26:27], v[34:35]
	v_pk_add_f32 v[26:27], v[24:25], v[32:33]
	v_mul_f32_e32 v24, v29, v29
	v_mul_f32_e32 v25, v31, v31
	v_fmac_f32_e32 v24, v28, v28
	v_fmac_f32_e32 v25, v30, v30
	v_add_f32_e32 v24, v24, v25
	v_mul_f32_e32 v25, v27, v27
	v_fmac_f32_e32 v25, v26, v26
	v_add_f32_e32 v24, v25, v24
	v_mul_f32_e32 v25, v35, v35
	v_fmac_f32_e32 v25, v34, v34
	v_add_f32_e32 v32, v25, v24
	v_cvt_pk_bf16_f32 v24, v28, v29
	v_cvt_pk_bf16_f32 v25, v30, v31
	v_lshlrev_b32_e32 v28, 16, v120
	v_and_b32_e32 v29, 0xffff0000, v120
	v_lshlrev_b32_e32 v30, 16, v121
	v_and_b32_e32 v31, 0xffff0000, v121
	v_pk_add_f32 v[22:23], v[22:23], v[30:31]
	v_pk_add_f32 v[20:21], v[20:21], v[28:29]
	v_lshlrev_b32_e32 v28, 16, v122
	v_and_b32_e32 v29, 0xffff0000, v122
	v_pk_add_f32 v[28:29], v[16:17], v[28:29]
	v_mul_f32_e32 v16, v21, v21
	v_mul_f32_e32 v17, v23, v23
	v_fmac_f32_e32 v16, v20, v20
	v_fmac_f32_e32 v17, v22, v22
	v_lshlrev_b32_e32 v30, 16, v123
	v_and_b32_e32 v31, 0xffff0000, v123
	v_add_f32_e32 v16, v16, v17
	v_mul_f32_e32 v17, v29, v29
	v_pk_add_f32 v[30:31], v[18:19], v[30:31]
	v_fmac_f32_e32 v17, v28, v28
	v_add_f32_e32 v16, v17, v16
	v_mul_f32_e32 v17, v31, v31
	v_fmac_f32_e32 v17, v30, v30
	v_add_f32_e32 v16, v17, v16
	v_add_f32_e32 v19, v32, v16
	v_cvt_pk_bf16_f32 v26, v26, v27
	v_cvt_pk_bf16_f32 v27, v34, v35
	v_mov_b32_e32 v34, v19
	s_nop 1
	v_permlane16_swap_b32_e32 v34, v19
	v_lshl_add_u64 v[16:17], s[36:37], 0, v[208:209]
	v_lshl_add_u64 v[32:33], v[204:205], 1, v[16:17]
	global_store_dwordx4 v[32:33], v[24:27], off sc1
	v_cvt_pk_bf16_f32 v18, v20, v21
	s_waitcnt lgkmcnt(0)
	v_add_f32_e32 v16, v19, v34
	v_mov_b32_e32 v17, v16
	s_nop 1
	v_permlane32_swap_b32_e32 v17, v16
	v_cvt_pk_bf16_f32 v19, v22, v23
	v_cvt_pk_bf16_f32 v20, v28, v29
	v_cvt_pk_bf16_f32 v21, v30, v31
	global_store_dwordx4 v[32:33], v[18:21], off offset:256 sc1
	s_and_saveexec_b64 s[34:35], s[4:5]
	s_cbranch_execz .LBB0_722
	s_add_u32 s54, s63, s20
	s_addc_u32 s55, s64, s21
	v_lshl_add_u64 v[18:19], v[202:203], 2, s[54:55]
	s_waitcnt lgkmcnt(0)
	v_add_f32_e32 v16, v16, v17
	global_store_dword v[18:19], v16, off offset:640
.LBB0_722:
	s_or_b64 exec, exec, s[34:35]
	v_lshlrev_b32_e32 v16, 16, v108
	s_waitcnt lgkmcnt(0)
	v_and_b32_e32 v17, 0xffff0000, v108
	v_lshlrev_b32_e32 v18, 16, v109
	v_and_b32_e32 v19, 0xffff0000, v109
	v_pk_add_f32 v[14:15], v[14:15], v[18:19]
	v_pk_add_f32 v[12:13], v[12:13], v[16:17]
	v_lshlrev_b32_e32 v16, 16, v110
	v_and_b32_e32 v17, 0xffff0000, v110
	v_lshlrev_b32_e32 v18, 16, v111
	v_and_b32_e32 v19, 0xffff0000, v111
	v_pk_add_f32 v[18:19], v[10:11], v[18:19]
	v_pk_add_f32 v[10:11], v[8:9], v[16:17]
	v_mul_f32_e32 v8, v13, v13
	v_mul_f32_e32 v9, v15, v15
	v_fmac_f32_e32 v8, v12, v12
	v_fmac_f32_e32 v9, v14, v14
	v_add_f32_e32 v8, v8, v9
	v_mul_f32_e32 v9, v11, v11
	v_fmac_f32_e32 v9, v10, v10
	v_add_f32_e32 v8, v9, v8
	v_mul_f32_e32 v9, v19, v19
	v_fmac_f32_e32 v9, v18, v18
	v_add_f32_e32 v16, v9, v8
	v_cvt_pk_bf16_f32 v8, v12, v13
	v_cvt_pk_bf16_f32 v9, v14, v15
	v_lshlrev_b32_e32 v12, 16, v96
	v_and_b32_e32 v13, 0xffff0000, v96
	v_lshlrev_b32_e32 v14, 16, v97
	v_and_b32_e32 v15, 0xffff0000, v97
	v_pk_add_f32 v[6:7], v[6:7], v[14:15]
	v_pk_add_f32 v[4:5], v[4:5], v[12:13]
	v_lshlrev_b32_e32 v12, 16, v98
	v_and_b32_e32 v13, 0xffff0000, v98
	v_pk_add_f32 v[12:13], v[0:1], v[12:13]
	v_mul_f32_e32 v0, v5, v5
	v_mul_f32_e32 v1, v7, v7
	v_fmac_f32_e32 v0, v4, v4
	v_fmac_f32_e32 v1, v6, v6
	v_lshlrev_b32_e32 v14, 16, v99
	v_and_b32_e32 v15, 0xffff0000, v99
	v_add_f32_e32 v0, v0, v1
	v_mul_f32_e32 v1, v13, v13
	v_pk_add_f32 v[14:15], v[2:3], v[14:15]
	v_fmac_f32_e32 v1, v12, v12
	v_add_f32_e32 v0, v1, v0
	v_mul_f32_e32 v1, v15, v15
	v_fmac_f32_e32 v1, v14, v14
	v_add_f32_e32 v0, v1, v0
	v_add_f32_e32 v3, v16, v0
	v_cvt_pk_bf16_f32 v10, v10, v11
	v_cvt_pk_bf16_f32 v11, v18, v19
	v_mov_b32_e32 v18, v3
	s_nop 1
	v_permlane16_swap_b32_e32 v18, v3
	v_lshl_add_u64 v[0:1], s[36:37], 0, v[206:207]
	v_lshl_add_u64 v[16:17], v[204:205], 1, v[0:1]
	global_store_dwordx4 v[16:17], v[8:11], off sc1
	v_cvt_pk_bf16_f32 v2, v4, v5
	s_waitcnt lgkmcnt(0)
	v_add_f32_e32 v0, v3, v18
	v_mov_b32_e32 v1, v0
	s_nop 1
	v_permlane32_swap_b32_e32 v1, v0
	v_cvt_pk_bf16_f32 v3, v6, v7
	v_cvt_pk_bf16_f32 v4, v12, v13
	v_cvt_pk_bf16_f32 v5, v14, v15
	global_store_dwordx4 v[16:17], v[2:5], off offset:256 sc1
	s_and_saveexec_b64 s[34:35], s[4:5]
	s_cbranch_execz .LBB0_724
	s_add_u32 s20, s63, s20
	s_addc_u32 s21, s64, s21
	v_lshl_add_u64 v[2:3], v[202:203], 2, s[20:21]
	s_waitcnt lgkmcnt(0)
	v_add_f32_e32 v0, v0, v1
	global_store_dword v[2:3], v0, off offset:704

; #define LAS __attribute__((address_space(3)))
; __device__ __forceinline__ unsigned cvt_pk2(float lo, float hi) { f32x2c v = {lo, hi}; bf16x2c q = __builtin_convertvector(v, bf16x2c); return __builtin_bit_cast(unsigned, q); }
;     __device__ __forceinline__ void operator()(const f32x4 (&acc)[2][2][4][2], const pg8::Unit& u, int wr, int wc, int fr, int fq) const {
;         const int row0 = u.pm * 256 + wr * 64 + fr, col0 = u.pn * 128 + wc * 32 + 8 * fq;
;         const LAS float* rt = rt_.of(u.pm) + wr * 64 + fr;
; #pragma unroll
;         for (int ai = 0; ai < 2; ++ai)
; #pragma unroll
;             for (int m = 0; m < 4; ++m) { bf16_t* rowp = O + (size_t)(row0 + ai * 128 + m * 16) * FF + col0; const float r = rt[ai * 128 + m * 16];
;                 const float rl = -r * LOG2E, r2 = r * r; unsigned w[4];
; #pragma unroll
;                 for (int n = 0; n < 2; ++n)
; #pragma unroll
;                     for (int h = 0; h < 2; ++h) { const f32x2v g = {acc[ai][0][m][n][2 * h], acc[ai][0][m][n][2 * h + 1]}, uu = {acc[ai][1][m][n][2 * h], acc[ai][1][m][n][2 * h + 1]};
;                         const f32x2v t = g * rl; f32x2v d = {__builtin_amdgcn_exp2f(t.x), __builtin_amdgcn_exp2f(t.y)}; d = d + 1.0f;
;                         const f32x2v q = {__builtin_amdgcn_rcpf(d.x), __builtin_amdgcn_rcpf(d.y)}; const f32x2v o = ((g * uu) * r2) * q;
;                         w[2 * n + h] = cvt_pk2(o.x, o.y); }
;                 u32x4 wv; wv.x = w[0]; wv.y = w[1]; wv.z = w[2]; wv.w = w[3];
;                 *(u32x4*)rowp = wv; }
.LBB0_813:
	s_cmp_eq_u32 s34, s48
	s_cselect_b32 s13, s62, 0x300
	s_cmp_lg_u32 s34, s49
	s_cselect_b32 s13, s13, 0x100
	s_cmp_lg_u32 s34, s47
	s_cselect_b32 s13, s13, 0
	v_lshl_add_u32 v154, s13, 2, v148
	ds_read2_b32 v[200:201], v154 offset1:16
	ds_read2_b32 v[202:203], v154 offset0:32 offset1:48
	ds_read2_b32 v[204:205], v154 offset0:128 offset1:144
	ds_read2_b32 v[206:207], v154 offset0:160 offset1:176
	v_lshl_add_u32 v153, s34, 8, v146
	v_lshl_or_b32 v158, s64, 7, v149
	v_mov_b64_e32 v[178:179], s[40:41]
	s_mov_b32 s98, 0x1600
	v_lshlrev_b32_e32 v158, 1, v158
	v_mov_b32_e32 v159, 0
	v_mad_i64_i32 v[178:179], s[20:21], v153, s98, v[178:179]
	s_mov_b32 s98, 0x16000
	s_mov_b32 s99, 0
	s_mov_b32 s100, 0x6e000
	s_mov_b32 s101, 0
	v_lshl_add_u64 v[178:179], v[178:179], 0, v[158:159]
	s_waitcnt lgkmcnt(0)
	v_mul_f32_e32 v208, 0xbfb8aa3b, v200
	v_mul_f32_e32 v228, v200, v200
	v_mul_f32_e32 v210, 0xbfb8aa3b, v201
	v_mul_f32_e32 v230, v201, v201
	v_mul_f32_e32 v212, 0xbfb8aa3b, v202
	v_mul_f32_e32 v232, v202, v202
	v_mul_f32_e32 v214, 0xbfb8aa3b, v203
	v_mul_f32_e32 v234, v203, v203
	v_mul_f32_e32 v216, 0xbfb8aa3b, v204
	v_mul_f32_e32 v236, v204, v204
	v_mul_f32_e32 v218, 0xbfb8aa3b, v205
	v_mul_f32_e32 v238, v205, v205
	v_mul_f32_e32 v220, 0xbfb8aa3b, v206
	v_mul_f32_e32 v240, v206, v206
	v_mul_f32_e32 v222, 0xbfb8aa3b, v207
	v_mul_f32_e32 v242, v207, v207
	v_rcp_f32_e32 v228, v228
	v_rcp_f32_e32 v230, v230
	v_rcp_f32_e32 v232, v232
	v_rcp_f32_e32 v234, v234
	v_rcp_f32_e32 v236, v236
	v_rcp_f32_e32 v238, v238
	v_rcp_f32_e32 v240, v240
	v_rcp_f32_e32 v242, v242
	v_pk_mul_f32 v[154:155], v[124:125], v[208:209] op_sel_hi:[1,0]
	v_pk_mul_f32 v[156:157], v[126:127], v[208:209] op_sel_hi:[1,0]
	v_pk_mul_f32 v[158:159], v[116:117], v[208:209] op_sel_hi:[1,0]
	v_pk_mul_f32 v[160:161], v[118:119], v[208:209] op_sel_hi:[1,0]
	v_exp_f32_e32 v154, v154
	v_exp_f32_e32 v155, v155
	v_exp_f32_e32 v156, v156
	v_exp_f32_e32 v157, v157
	v_exp_f32_e32 v158, v158
	v_exp_f32_e32 v159, v159
	v_exp_f32_e32 v160, v160
	v_exp_f32_e32 v161, v161
	v_pk_mul_f32 v[162:163], v[108:109], v[210:211] op_sel_hi:[1,0]
	v_pk_mul_f32 v[164:165], v[110:111], v[210:211] op_sel_hi:[1,0]
	v_pk_mul_f32 v[166:167], v[100:101], v[210:211] op_sel_hi:[1,0]
	v_pk_mul_f32 v[168:169], v[102:103], v[210:211] op_sel_hi:[1,0]
	v_exp_f32_e32 v162, v162
	v_exp_f32_e32 v163, v163
	v_exp_f32_e32 v164, v164
	v_exp_f32_e32 v165, v165
	v_exp_f32_e32 v166, v166
	v_exp_f32_e32 v167, v167
	v_exp_f32_e32 v168, v168
	v_exp_f32_e32 v169, v169
	v_pk_mul_f32 v[120:121], v[124:125], v[120:121]
	v_pk_mul_f32 v[122:123], v[126:127], v[122:123]
	v_pk_mul_f32 v[112:113], v[116:117], v[112:113]
	v_pk_mul_f32 v[114:115], v[118:119], v[114:115]
	v_pk_fma_f32 v[154:155], v[154:155], v[228:229], v[228:229] op_sel_hi:[1,0,0]
	v_pk_fma_f32 v[156:157], v[156:157], v[228:229], v[228:229] op_sel_hi:[1,0,0]
	v_pk_fma_f32 v[158:159], v[158:159], v[228:229], v[228:229] op_sel_hi:[1,0,0]
	v_pk_fma_f32 v[160:161], v[160:161], v[228:229], v[228:229] op_sel_hi:[1,0,0]
	v_rcp_f32_e32 v154, v154
	v_rcp_f32_e32 v155, v155
	v_rcp_f32_e32 v156, v156
	v_rcp_f32_e32 v157, v157
	v_rcp_f32_e32 v158, v158
	v_rcp_f32_e32 v159, v159
	v_rcp_f32_e32 v160, v160
	v_rcp_f32_e32 v161, v161
	v_pk_mul_f32 v[170:171], v[92:93], v[212:213] op_sel_hi:[1,0]
	v_pk_mul_f32 v[172:173], v[94:95], v[212:213] op_sel_hi:[1,0]
	v_pk_mul_f32 v[174:175], v[84:85], v[212:213] op_sel_hi:[1,0]
	v_pk_mul_f32 v[176:177], v[86:87], v[212:213] op_sel_hi:[1,0]
	v_exp_f32_e32 v170, v170
	v_exp_f32_e32 v171, v171
	v_exp_f32_e32 v172, v172
	v_exp_f32_e32 v173, v173
	v_exp_f32_e32 v174, v174
	v_exp_f32_e32 v175, v175
	v_exp_f32_e32 v176, v176
	v_exp_f32_e32 v177, v177
	v_pk_mul_f32 v[104:105], v[108:109], v[104:105]
	v_pk_mul_f32 v[106:107], v[110:111], v[106:107]
	v_pk_mul_f32 v[96:97], v[100:101], v[96:97]
	v_pk_mul_f32 v[98:99], v[102:103], v[98:99]
	v_pk_fma_f32 v[162:163], v[162:163], v[230:231], v[230:231] op_sel_hi:[1,0,0]
	v_pk_fma_f32 v[164:165], v[164:165], v[230:231], v[230:231] op_sel_hi:[1,0,0]
	v_pk_fma_f32 v[166:167], v[166:167], v[230:231], v[230:231] op_sel_hi:[1,0,0]
	v_pk_fma_f32 v[168:169], v[168:169], v[230:231], v[230:231] op_sel_hi:[1,0,0]
	v_rcp_f32_e32 v162, v162
	v_rcp_f32_e32 v163, v163
	v_rcp_f32_e32 v164, v164
	v_rcp_f32_e32 v165, v165
	v_rcp_f32_e32 v166, v166
	v_rcp_f32_e32 v167, v167
	v_rcp_f32_e32 v168, v168
	v_rcp_f32_e32 v169, v169
	v_pk_mul_f32 v[120:121], v[120:121], v[154:155]
	v_pk_mul_f32 v[122:123], v[122:123], v[156:157]
	v_pk_mul_f32 v[112:113], v[112:113], v[158:159]
	v_pk_mul_f32 v[114:115], v[114:115], v[160:161]
	v_cvt_pk_bf16_f32 v154, v120, v121
	v_cvt_pk_bf16_f32 v155, v122, v123
	v_cvt_pk_bf16_f32 v156, v112, v113
	v_cvt_pk_bf16_f32 v157, v114, v115
	global_store_dwordx4 v[178:179], v[154:157], off sc1
	v_lshl_add_u64 v[178:179], v[178:179], 0, s[98:99]
	s_nop 1
	v_pk_mul_f32 v[154:155], v[76:77], v[214:215] op_sel_hi:[1,0]
	v_pk_mul_f32 v[156:157], v[78:79], v[214:215] op_sel_hi:[1,0]
	v_pk_mul_f32 v[158:159], v[68:69], v[214:215] op_sel_hi:[1,0]
	v_pk_mul_f32 v[160:161], v[70:71], v[214:215] op_sel_hi:[1,0]
	v_exp_f32_e32 v154, v154
	v_exp_f32_e32 v155, v155
	v_exp_f32_e32 v156, v156
	v_exp_f32_e32 v157, v157
	v_exp_f32_e32 v158, v158
	v_exp_f32_e32 v159, v159
	v_exp_f32_e32 v160, v160
	v_exp_f32_e32 v161, v161
	v_pk_mul_f32 v[88:89], v[92:93], v[88:89]
	v_pk_mul_f32 v[90:91], v[94:95], v[90:91]
	v_pk_mul_f32 v[80:81], v[84:85], v[80:81]
	v_pk_mul_f32 v[82:83], v[86:87], v[82:83]
	v_pk_fma_f32 v[170:171], v[170:171], v[232:233], v[232:233] op_sel_hi:[1,0,0]
	v_pk_fma_f32 v[172:173], v[172:173], v[232:233], v[232:233] op_sel_hi:[1,0,0]
; __device__ __forceinline__ unsigned cvt_pk2(float lo, float hi) { f32x2c v = {lo, hi}; bf16x2c q = __builtin_convertvector(v, bf16x2c); return __builtin_bit_cast(unsigned, q); }
;     __device__ __forceinline__ void operator()(const f32x4 (&acc)[2][2][4][2], const pg8::Unit& u, int wr, int wc, int fr, int fq) const {
;     ...
;             for (int m = 0; m < 4; ++m) { bf16_t* rowp = O + (size_t)(row0 + ai * 128 + m * 16) * FF + col0; const float r = rt[ai * 128 + m * 16];
;                 const float rl = -r * LOG2E, r2 = r * r; unsigned w[4];
; #pragma unroll
;                 for (int n = 0; n < 2; ++n)
; #pragma unroll
;                     for (int h = 0; h < 2; ++h) { const f32x2v g = {acc[ai][0][m][n][2 * h], acc[ai][0][m][n][2 * h + 1]}, uu = {acc[ai][1][m][n][2 * h], acc[ai][1][m][n][2 * h + 1]};
;                         const f32x2v t = g * rl; f32x2v d = {__builtin_amdgcn_exp2f(t.x), __builtin_amdgcn_exp2f(t.y)}; d = d + 1.0f;
;                         const f32x2v q = {__builtin_amdgcn_rcpf(d.x), __builtin_amdgcn_rcpf(d.y)}; const f32x2v o = ((g * uu) * r2) * q;
;                         w[2 * n + h] = cvt_pk2(o.x, o.y); }
;                 u32x4 wv; wv.x = w[0]; wv.y = w[1]; wv.z = w[2]; wv.w = w[3];
;                 *(u32x4*)rowp = wv; }
	v_pk_fma_f32 v[174:175], v[174:175], v[232:233], v[232:233] op_sel_hi:[1,0,0]
	v_pk_fma_f32 v[176:177], v[176:177], v[232:233], v[232:233] op_sel_hi:[1,0,0]
	v_rcp_f32_e32 v170, v170
	v_rcp_f32_e32 v171, v171
	v_rcp_f32_e32 v172, v172
	v_rcp_f32_e32 v173, v173
	v_rcp_f32_e32 v174, v174
	v_rcp_f32_e32 v175, v175
	v_rcp_f32_e32 v176, v176
	v_rcp_f32_e32 v177, v177
	v_pk_mul_f32 v[104:105], v[104:105], v[162:163]
	v_pk_mul_f32 v[106:107], v[106:107], v[164:165]
	v_pk_mul_f32 v[96:97], v[96:97], v[166:167]
	v_pk_mul_f32 v[98:99], v[98:99], v[168:169]
	v_cvt_pk_bf16_f32 v162, v104, v105
	v_cvt_pk_bf16_f32 v163, v106, v107
	v_cvt_pk_bf16_f32 v164, v96, v97
	v_cvt_pk_bf16_f32 v165, v98, v99
	global_store_dwordx4 v[178:179], v[162:165], off sc1
	v_lshl_add_u64 v[178:179], v[178:179], 0, s[98:99]
	s_nop 1
	v_pk_mul_f32 v[162:163], v[60:61], v[216:217] op_sel_hi:[1,0]
	v_pk_mul_f32 v[164:165], v[62:63], v[216:217] op_sel_hi:[1,0]
	v_pk_mul_f32 v[166:167], v[52:53], v[216:217] op_sel_hi:[1,0]
	v_pk_mul_f32 v[168:169], v[54:55], v[216:217] op_sel_hi:[1,0]
	v_exp_f32_e32 v162, v162
	v_exp_f32_e32 v163, v163
	v_exp_f32_e32 v164, v164
	v_exp_f32_e32 v165, v165
	v_exp_f32_e32 v166, v166
	v_exp_f32_e32 v167, v167
	v_exp_f32_e32 v168, v168
	v_exp_f32_e32 v169, v169
	v_pk_mul_f32 v[72:73], v[76:77], v[72:73]
	v_pk_mul_f32 v[74:75], v[78:79], v[74:75]
	v_pk_mul_f32 v[64:65], v[68:69], v[64:65]
	v_pk_mul_f32 v[66:67], v[70:71], v[66:67]
	v_pk_fma_f32 v[154:155], v[154:155], v[234:235], v[234:235] op_sel_hi:[1,0,0]
	v_pk_fma_f32 v[156:157], v[156:157], v[234:235], v[234:235] op_sel_hi:[1,0,0]
	v_pk_fma_f32 v[158:159], v[158:159], v[234:235], v[234:235] op_sel_hi:[1,0,0]
	v_pk_fma_f32 v[160:161], v[160:161], v[234:235], v[234:235] op_sel_hi:[1,0,0]
	v_rcp_f32_e32 v154, v154
	v_rcp_f32_e32 v155, v155
	v_rcp_f32_e32 v156, v156
	v_rcp_f32_e32 v157, v157
	v_rcp_f32_e32 v158, v158
	v_rcp_f32_e32 v159, v159
	v_rcp_f32_e32 v160, v160
	v_rcp_f32_e32 v161, v161
	v_pk_mul_f32 v[88:89], v[88:89], v[170:171]
	v_pk_mul_f32 v[90:91], v[90:91], v[172:173]
	v_pk_mul_f32 v[80:81], v[80:81], v[174:175]
	v_pk_mul_f32 v[82:83], v[82:83], v[176:177]
	v_cvt_pk_bf16_f32 v170, v88, v89
	v_cvt_pk_bf16_f32 v171, v90, v91
	v_cvt_pk_bf16_f32 v172, v80, v81
	v_cvt_pk_bf16_f32 v173, v82, v83
	global_store_dwordx4 v[178:179], v[170:173], off sc1
	v_lshl_add_u64 v[178:179], v[178:179], 0, s[98:99]
	s_nop 1
	v_pk_mul_f32 v[170:171], v[44:45], v[218:219] op_sel_hi:[1,0]
	v_pk_mul_f32 v[172:173], v[46:47], v[218:219] op_sel_hi:[1,0]
	v_pk_mul_f32 v[174:175], v[36:37], v[218:219] op_sel_hi:[1,0]
	v_pk_mul_f32 v[176:177], v[38:39], v[218:219] op_sel_hi:[1,0]
	v_exp_f32_e32 v170, v170
	v_exp_f32_e32 v171, v171
	v_exp_f32_e32 v172, v172
	v_exp_f32_e32 v173, v173
	v_exp_f32_e32 v174, v174
	v_exp_f32_e32 v175, v175
	v_exp_f32_e32 v176, v176
	v_exp_f32_e32 v177, v177
	v_pk_mul_f32 v[56:57], v[60:61], v[56:57]
	v_pk_mul_f32 v[58:59], v[62:63], v[58:59]
	v_pk_mul_f32 v[48:49], v[52:53], v[48:49]
	v_pk_mul_f32 v[50:51], v[54:55], v[50:51]
	v_pk_fma_f32 v[162:163], v[162:163], v[236:237], v[236:237] op_sel_hi:[1,0,0]
	v_pk_fma_f32 v[164:165], v[164:165], v[236:237], v[236:237] op_sel_hi:[1,0,0]
	v_pk_fma_f32 v[166:167], v[166:167], v[236:237], v[236:237] op_sel_hi:[1,0,0]
	v_pk_fma_f32 v[168:169], v[168:169], v[236:237], v[236:237] op_sel_hi:[1,0,0]
	v_rcp_f32_e32 v162, v162
	v_rcp_f32_e32 v163, v163
	v_rcp_f32_e32 v164, v164
	v_rcp_f32_e32 v165, v165
	v_rcp_f32_e32 v166, v166
	v_rcp_f32_e32 v167, v167
	v_rcp_f32_e32 v168, v168
	v_rcp_f32_e32 v169, v169
	v_pk_mul_f32 v[72:73], v[72:73], v[154:155]
	v_pk_mul_f32 v[74:75], v[74:75], v[156:157]
	v_pk_mul_f32 v[64:65], v[64:65], v[158:159]
	v_pk_mul_f32 v[66:67], v[66:67], v[160:161]
	v_cvt_pk_bf16_f32 v154, v72, v73
	v_cvt_pk_bf16_f32 v155, v74, v75
	v_cvt_pk_bf16_f32 v156, v64, v65
	v_cvt_pk_bf16_f32 v157, v66, v67
	global_store_dwordx4 v[178:179], v[154:157], off sc1
	v_lshl_add_u64 v[178:179], v[178:179], 0, s[100:101]
	s_nop 1
	v_pk_mul_f32 v[154:155], v[28:29], v[220:221] op_sel_hi:[1,0]
	v_pk_mul_f32 v[156:157], v[30:31], v[220:221] op_sel_hi:[1,0]
	v_pk_mul_f32 v[158:159], v[20:21], v[220:221] op_sel_hi:[1,0]
	v_pk_mul_f32 v[160:161], v[22:23], v[220:221] op_sel_hi:[1,0]
	v_exp_f32_e32 v154, v154
	v_exp_f32_e32 v155, v155
	v_exp_f32_e32 v156, v156
	v_exp_f32_e32 v157, v157
	v_exp_f32_e32 v158, v158
	v_exp_f32_e32 v159, v159
; #define PG8_BAR __builtin_amdgcn_s_barrier()
; __device__ __forceinline__ unsigned cvt_pk2(float lo, float hi) { f32x2c v = {lo, hi}; bf16x2c q = __builtin_convertvector(v, bf16x2c); return __builtin_bit_cast(unsigned, q); }
; template <class Epi, class Sched, bool ALIGN_EPI = false, bool SP2 = false>
; __device__ __forceinline__ void gemm_phase(PG8_LAS unsigned char* lds, const Gemm g, const Sched& S, const Epi& E) {
;     ...
;         if constexpr (ALIGN_EPI) { if (wr == 0) PG8_BAR; }
;         if constexpr (!Epi::AFTER_DRAIN) { E(acc, cur, wr, wc, fr, fq); S.done(cur); }
;         if (!has_next) break;
; #pragma unroll
;         for (int a = 0; a < 2; ++a)
; #pragma unroll
;             for (int b = 0; b < 2; ++b)
; #pragma unroll
;                 for (int m = 0; m < 4; ++m)
; #pragma unroll
;                     for (int n = 0; n < 2; ++n) acc[a][b][m][n] = (f32x4){0.f, 0.f, 0.f, 0.f};
;         cur = nxt; cA = nA; cB = nB; ++ui;
;         if constexpr (ALIGN_EPI) { if (wr == 1) PG8_BAR; }
;     __device__ __forceinline__ void operator()(const f32x4 (&acc)[2][2][4][2], const pg8::Unit& u, int wr, int wc, int fr, int fq) const {
;     ...
;             for (int m = 0; m < 4; ++m) { bf16_t* rowp = O + (size_t)(row0 + ai * 128 + m * 16) * FF + col0; const float r = rt[ai * 128 + m * 16];
;                 const float rl = -r * LOG2E, r2 = r * r; unsigned w[4];
; #pragma unroll
;                 for (int n = 0; n < 2; ++n)
; #pragma unroll
;                     for (int h = 0; h < 2; ++h) { const f32x2v g = {acc[ai][0][m][n][2 * h], acc[ai][0][m][n][2 * h + 1]}, uu = {acc[ai][1][m][n][2 * h], acc[ai][1][m][n][2 * h + 1]};
;                         const f32x2v t = g * rl; f32x2v d = {__builtin_amdgcn_exp2f(t.x), __builtin_amdgcn_exp2f(t.y)}; d = d + 1.0f;
;                         const f32x2v q = {__builtin_amdgcn_rcpf(d.x), __builtin_amdgcn_rcpf(d.y)}; const f32x2v o = ((g * uu) * r2) * q;
;                         w[2 * n + h] = cvt_pk2(o.x, o.y); }
;                 u32x4 wv; wv.x = w[0]; wv.y = w[1]; wv.z = w[2]; wv.w = w[3];
;                 *(u32x4*)rowp = wv; }
	v_exp_f32_e32 v160, v160
	v_exp_f32_e32 v161, v161
	v_pk_mul_f32 v[40:41], v[44:45], v[40:41]
	v_pk_mul_f32 v[42:43], v[46:47], v[42:43]
	v_pk_mul_f32 v[32:33], v[36:37], v[32:33]
	v_pk_mul_f32 v[34:35], v[38:39], v[34:35]
	v_pk_fma_f32 v[170:171], v[170:171], v[238:239], v[238:239] op_sel_hi:[1,0,0]
	v_pk_fma_f32 v[172:173], v[172:173], v[238:239], v[238:239] op_sel_hi:[1,0,0]
	v_pk_fma_f32 v[174:175], v[174:175], v[238:239], v[238:239] op_sel_hi:[1,0,0]
	v_pk_fma_f32 v[176:177], v[176:177], v[238:239], v[238:239] op_sel_hi:[1,0,0]
	v_rcp_f32_e32 v170, v170
	v_rcp_f32_e32 v171, v171
	v_rcp_f32_e32 v172, v172
	v_rcp_f32_e32 v173, v173
	v_rcp_f32_e32 v174, v174
	v_rcp_f32_e32 v175, v175
	v_rcp_f32_e32 v176, v176
	v_rcp_f32_e32 v177, v177
	v_pk_mul_f32 v[56:57], v[56:57], v[162:163]
	v_pk_mul_f32 v[58:59], v[58:59], v[164:165]
	v_pk_mul_f32 v[48:49], v[48:49], v[166:167]
	v_pk_mul_f32 v[50:51], v[50:51], v[168:169]
	v_cvt_pk_bf16_f32 v162, v56, v57
	v_cvt_pk_bf16_f32 v163, v58, v59
	v_cvt_pk_bf16_f32 v164, v48, v49
	v_cvt_pk_bf16_f32 v165, v50, v51
	global_store_dwordx4 v[178:179], v[162:165], off sc1
	v_lshl_add_u64 v[178:179], v[178:179], 0, s[98:99]
	s_nop 1
	v_pk_mul_f32 v[162:163], v[12:13], v[222:223] op_sel_hi:[1,0]
	v_pk_mul_f32 v[164:165], v[14:15], v[222:223] op_sel_hi:[1,0]
	v_pk_mul_f32 v[166:167], v[4:5], v[222:223] op_sel_hi:[1,0]
	v_pk_mul_f32 v[168:169], v[6:7], v[222:223] op_sel_hi:[1,0]
	v_exp_f32_e32 v162, v162
	v_exp_f32_e32 v163, v163
	v_exp_f32_e32 v164, v164
	v_exp_f32_e32 v165, v165
	v_exp_f32_e32 v166, v166
	v_exp_f32_e32 v167, v167
	v_exp_f32_e32 v168, v168
	v_exp_f32_e32 v169, v169
	v_pk_mul_f32 v[24:25], v[28:29], v[24:25]
	v_pk_mul_f32 v[26:27], v[30:31], v[26:27]
	v_pk_mul_f32 v[16:17], v[20:21], v[16:17]
	v_pk_mul_f32 v[18:19], v[22:23], v[18:19]
	v_pk_fma_f32 v[154:155], v[154:155], v[240:241], v[240:241] op_sel_hi:[1,0,0]
	v_pk_fma_f32 v[156:157], v[156:157], v[240:241], v[240:241] op_sel_hi:[1,0,0]
	v_pk_fma_f32 v[158:159], v[158:159], v[240:241], v[240:241] op_sel_hi:[1,0,0]
	v_pk_fma_f32 v[160:161], v[160:161], v[240:241], v[240:241] op_sel_hi:[1,0,0]
	v_rcp_f32_e32 v154, v154
	v_rcp_f32_e32 v155, v155
	v_rcp_f32_e32 v156, v156
	v_rcp_f32_e32 v157, v157
	v_rcp_f32_e32 v158, v158
	v_rcp_f32_e32 v159, v159
	v_rcp_f32_e32 v160, v160
	v_rcp_f32_e32 v161, v161
	v_pk_mul_f32 v[40:41], v[40:41], v[170:171]
	v_pk_mul_f32 v[42:43], v[42:43], v[172:173]
	v_pk_mul_f32 v[32:33], v[32:33], v[174:175]
	v_pk_mul_f32 v[34:35], v[34:35], v[176:177]
	v_cvt_pk_bf16_f32 v170, v40, v41
	v_cvt_pk_bf16_f32 v171, v42, v43
	v_cvt_pk_bf16_f32 v172, v32, v33
	v_cvt_pk_bf16_f32 v173, v34, v35
	global_store_dwordx4 v[178:179], v[170:173], off sc1
	v_lshl_add_u64 v[178:179], v[178:179], 0, s[98:99]
	s_nop 1
	v_pk_mul_f32 v[8:9], v[12:13], v[8:9]
	v_pk_mul_f32 v[10:11], v[14:15], v[10:11]
	v_pk_mul_f32 v[0:1], v[4:5], v[0:1]
	v_pk_mul_f32 v[2:3], v[6:7], v[2:3]
	v_pk_fma_f32 v[162:163], v[162:163], v[242:243], v[242:243] op_sel_hi:[1,0,0]
	v_pk_fma_f32 v[164:165], v[164:165], v[242:243], v[242:243] op_sel_hi:[1,0,0]
	v_pk_fma_f32 v[166:167], v[166:167], v[242:243], v[242:243] op_sel_hi:[1,0,0]
	v_pk_fma_f32 v[168:169], v[168:169], v[242:243], v[242:243] op_sel_hi:[1,0,0]
	v_rcp_f32_e32 v162, v162
	v_rcp_f32_e32 v163, v163
	v_rcp_f32_e32 v164, v164
	v_rcp_f32_e32 v165, v165
	v_rcp_f32_e32 v166, v166
	v_rcp_f32_e32 v167, v167
	v_rcp_f32_e32 v168, v168
	v_rcp_f32_e32 v169, v169
	v_pk_mul_f32 v[24:25], v[24:25], v[154:155]
	v_pk_mul_f32 v[26:27], v[26:27], v[156:157]
	v_pk_mul_f32 v[16:17], v[16:17], v[158:159]
	v_pk_mul_f32 v[18:19], v[18:19], v[160:161]
	v_cvt_pk_bf16_f32 v154, v24, v25
	v_cvt_pk_bf16_f32 v155, v26, v27
	v_cvt_pk_bf16_f32 v156, v16, v17
	v_cvt_pk_bf16_f32 v157, v18, v19
	global_store_dwordx4 v[178:179], v[154:157], off sc1
	v_lshl_add_u64 v[178:179], v[178:179], 0, s[98:99]
	s_nop 1
	v_pk_mul_f32 v[8:9], v[8:9], v[162:163]
	v_pk_mul_f32 v[10:11], v[10:11], v[164:165]
	v_pk_mul_f32 v[0:1], v[0:1], v[166:167]
	v_pk_mul_f32 v[2:3], v[2:3], v[168:169]
	v_cvt_pk_bf16_f32 v162, v8, v9
	v_cvt_pk_bf16_f32 v163, v10, v11
	v_cvt_pk_bf16_f32 v164, v0, v1
	v_cvt_pk_bf16_f32 v165, v2, v3
	global_store_dwordx4 v[178:179], v[162:165], off sc1
	s_andn2_b64 vcc, exec, s[4:5]
	s_mov_b64 s[4:5], -1
	s_cbranch_vccnz .LBB0_806
	s_andn2_b64 vcc, exec, s[0:1]
	s_cbranch_vccnz .LBB0_805
	s_barrier
	s_branch .LBB0_805

; __device__ __forceinline__ unsigned cvt_pk_bf16(float lo, float hi) { unsigned r; asm volatile("v_cvt_pk_bf16_f32 %0, %1, %2" : "=v"(r) : "v"(lo), "v"(hi)); return r; }
;     __device__ __forceinline__ void operator()(const f32x4 (&acc)[2][2][4][2], const pg8::Unit& u, int wr, int wc, int fr, int fq) const {
;     ...
;                 for (int bj = 0; bj < 2; ++bj) xin[ai][m][bj] = *(const u32x4*)(XB + (size_t)(row0 + ai * 128 + m * 16) * D + col0 + bj * 128);
; #pragma unroll
;         for (int ai = 0; ai < 2; ++ai)
; #pragma unroll
;             for (int m = 0; m < 4; ++m) { const size_t ro = (size_t)(row0 + ai * 128 + m * 16) * D + col0; float sq = 0.f;
; #pragma unroll
;                 for (int bj = 0; bj < 2; ++bj) { const u32x4 xb = xin[ai][m][bj];
;                     const f32x4 x0 = (f32x4){bf_lo(xb.x), bf_hi(xb.x), bf_lo(xb.y), bf_hi(xb.y)} + acc[ai][bj][m][0] * s, x1 = (f32x4){bf_lo(xb.z), bf_hi(xb.z), bf_lo(xb.w), bf_hi(xb.w)} + acc[ai][bj][m][1] * s;
;                     sq += (x0[0] * x0[0] + x0[1] * x0[1]) + (x0[2] * x0[2] + x0[3] * x0[3]) + (x1[0] * x1[0] + x1[1] * x1[1]) + (x1[2] * x1[2] + x1[3] * x1[3]);
;                     u32x4 w; w.x = cvt_pk_bf16(x0[0], x0[1]); w.y = cvt_pk_bf16(x0[2], x0[3]); w.z = cvt_pk_bf16(x1[0], x1[1]); w.w = cvt_pk_bf16(x1[2], x1[3]);
;                     *(u32x4*)(XB + ro + bj * 128) = w; }
;                 sq += __shfl_xor(sq, 16); sq += __shfl_xor(sq, 32);
;                 if (fq == 0) SSo[(size_t)(u.pn * 4 + wc) * T + row0 + ai * 128 + m * 16] = sq; }
.LBB0_898:
	v_lshl_or_b32 v204, s68, 8, v222
	v_lshl_add_u32 v202, s69, 8, v220
	v_ashrrev_i32_e32 v205, 31, v204
	v_lshlrev_b64 v[236:237], 1, v[204:205]
	v_ashrrev_i32_e32 v203, 31, v202
	v_lshl_add_u64 v[96:97], s[36:37], 0, v[236:237]
	v_lshlrev_b64 v[238:239], 11, v[202:203]
	v_lshl_add_u64 v[98:99], v[96:97], 0, v[238:239]
	global_load_dwordx4 v[228:231], v[98:99], off
	global_load_dwordx4 v[232:235], v[98:99], off offset:256
	v_or_b32_e32 v98, 16, v202
	v_or_b32_e32 v108, 32, v202
	v_or_b32_e32 v110, 48, v202
	v_ashrrev_i32_e32 v99, 31, v98
	v_ashrrev_i32_e32 v109, 31, v108
	v_ashrrev_i32_e32 v111, 31, v110
	v_lshlrev_b64 v[218:219], 11, v[98:99]
	v_lshlrev_b64 v[216:217], 11, v[108:109]
	v_lshlrev_b64 v[214:215], 11, v[110:111]
	v_lshl_add_u64 v[212:213], v[238:239], 0, s[16:17]
	v_lshl_add_u64 v[210:211], v[238:239], 0, s[18:19]
	v_lshl_add_u64 v[208:209], v[238:239], 0, s[38:39]
	v_lshl_add_u64 v[206:207], v[238:239], 0, s[44:45]
	v_lshl_add_u64 v[98:99], v[96:97], 0, v[218:219]
	v_lshl_add_u64 v[108:109], v[96:97], 0, v[216:217]
	v_lshl_add_u64 v[110:111], v[96:97], 0, v[214:215]
	v_lshl_add_u64 v[120:121], v[96:97], 0, v[212:213]
	v_lshl_add_u64 v[122:123], v[96:97], 0, v[210:211]
	v_lshl_add_u64 v[240:241], v[96:97], 0, v[208:209]
	v_lshl_add_u64 v[96:97], v[96:97], 0, v[206:207]
	global_load_dwordx4 v[180:183], v[98:99], off
	global_load_dwordx4 v[176:179], v[98:99], off offset:256
	global_load_dwordx4 v[172:175], v[108:109], off
	global_load_dwordx4 v[168:171], v[108:109], off offset:256
	global_load_dwordx4 v[164:167], v[110:111], off
	global_load_dwordx4 v[160:163], v[110:111], off offset:256
	global_load_dwordx4 v[156:159], v[120:121], off
	global_load_dwordx4 v[152:155], v[120:121], off offset:256
	global_load_dwordx4 v[148:151], v[122:123], off
	global_load_dwordx4 v[144:147], v[122:123], off offset:256
	global_load_dwordx4 v[128:131], v[240:241], off
	s_nop 0
	global_load_dwordx4 v[120:123], v[240:241], off offset:256
	global_load_dwordx4 v[108:111], v[96:97], off
	s_nop 0
	global_load_dwordx4 v[96:99], v[96:97], off offset:256
	s_lshl_b32 s20, s68, 2
	s_or_b32 s20, s20, s58
	s_ashr_i32 s21, s20, 31
	s_lshl_b64 s[20:21], s[20:21], 17
	s_waitcnt vmcnt(0)
	v_lshlrev_b32_e32 v240, 16, v228
	v_and_b32_e32 v241, 0xffff0000, v228
	v_lshlrev_b32_e32 v228, 16, v229
	v_and_b32_e32 v229, 0xffff0000, v229
	v_lshlrev_b32_e32 v242, 16, v230
	v_and_b32_e32 v243, 0xffff0000, v230
	v_lshlrev_b32_e32 v244, 16, v232
	v_and_b32_e32 v245, 0xffff0000, v232
	v_lshlrev_b32_e32 v232, 16, v233
	v_and_b32_e32 v233, 0xffff0000, v233
	v_lshlrev_b32_e32 v246, 16, v234
	v_and_b32_e32 v247, 0xffff0000, v234
	v_lshlrev_b32_e32 v234, 16, v235
	v_and_b32_e32 v235, 0xffff0000, v235
	v_pk_fma_f32 v[142:143], v[142:143], 0.5, v[228:229] op_sel_hi:[1,0,1]
	v_pk_fma_f32 v[140:141], v[140:141], 0.5, v[240:241] op_sel_hi:[1,0,1]
	v_lshlrev_b32_e32 v230, 16, v231
	v_and_b32_e32 v231, 0xffff0000, v231
	v_pk_fma_f32 v[136:137], v[136:137], 0.5, v[242:243] op_sel_hi:[1,0,1]
	v_pk_fma_f32 v[228:229], v[134:135], 0.5, v[232:233] op_sel_hi:[1,0,1]
	v_pk_fma_f32 v[232:233], v[126:127], 0.5, v[234:235] op_sel_hi:[1,0,1]
	v_pk_fma_f32 v[234:235], v[124:125], 0.5, v[246:247] op_sel_hi:[1,0,1]
	v_mul_f32_e32 v124, v141, v141
	v_mul_f32_e32 v125, v143, v143
	v_pk_fma_f32 v[138:139], v[138:139], 0.5, v[230:231] op_sel_hi:[1,0,1]
	v_pk_fma_f32 v[230:231], v[132:133], 0.5, v[244:245] op_sel_hi:[1,0,1]
	v_mul_f32_e32 v126, v137, v137
	v_fmac_f32_e32 v124, v140, v140
	v_fmac_f32_e32 v125, v142, v142
	v_mul_f32_e32 v127, v139, v139
	v_cvt_pk_bf16_f32 v132, v140, v141
	v_cvt_pk_bf16_f32 v133, v142, v143
	v_cvt_pk_bf16_f32 v134, v136, v137
	v_cvt_pk_bf16_f32 v135, v138, v139
	v_mul_f32_e32 v137, v231, v231
	v_mul_f32_e32 v139, v229, v229
	v_fmac_f32_e32 v126, v136, v136
	v_add_f32_e32 v124, v124, v125
	v_fmac_f32_e32 v137, v230, v230
	v_fmac_f32_e32 v139, v228, v228
	v_add_f32_e32 v124, v126, v124
	v_mul_f32_e32 v126, v235, v235
	v_add_f32_e32 v125, v137, v139
	v_fmac_f32_e32 v126, v234, v234
	v_add_f32_e32 v125, v126, v125
	v_mul_f32_e32 v126, v233, v233
	v_fmac_f32_e32 v127, v138, v138
	v_fmac_f32_e32 v126, v232, v232
	v_add_f32_e32 v124, v127, v124
	v_add_f32_e32 v125, v126, v125
	v_and_b32_e32 v126, 64, v226
	v_add_f32_e32 v125, v124, v125
	v_add_u32_e32 v138, 64, v126
	v_lshl_add_u64 v[126:127], s[36:37], 0, v[238:239]
	v_lshl_add_u64 v[136:137], v[126:127], 0, v[236:237]
	v_mov_b32_e32 v139, v125
	s_nop 1
	v_permlane16_swap_b32_e32 v139, v125
	global_store_dwordx4 v[136:137], v[132:135], off sc1
	s_waitcnt lgkmcnt(0)
	v_add_f32_e32 v126, v125, v139
	v_cvt_pk_bf16_f32 v132, v230, v231
	v_cvt_pk_bf16_f32 v133, v228, v229
	v_cvt_pk_bf16_f32 v134, v234, v235
	v_cvt_pk_bf16_f32 v135, v232, v233
	global_store_dwordx4 v[136:137], v[132:135], off offset:256 sc1
	s_nop 0
	v_mov_b32_e32 v127, v126
	s_nop 1
	v_permlane32_swap_b32_e32 v127, v126
	s_and_saveexec_b64 s[34:35], s[4:5]
	s_cbranch_execz .LBB0_900
	s_add_u32 s48, s56, s20
	s_addc_u32 s49, s57, s21
	v_lshl_add_u64 v[132:133], v[202:203], 2, s[48:49]
	s_waitcnt lgkmcnt(0)
	v_add_f32_e32 v126, v126, v127
	global_store_dword v[132:133], v126, off
; __device__ __forceinline__ unsigned cvt_pk_bf16(float lo, float hi) { unsigned r; asm volatile("v_cvt_pk_bf16_f32 %0, %1, %2" : "=v"(r) : "v"(lo), "v"(hi)); return r; }
;     __device__ __forceinline__ void operator()(const f32x4 (&acc)[2][2][4][2], const pg8::Unit& u, int wr, int wc, int fr, int fq) const {
;     ...
;             for (int m = 0; m < 4; ++m) { const size_t ro = (size_t)(row0 + ai * 128 + m * 16) * D + col0; float sq = 0.f;
; #pragma unroll
;                 for (int bj = 0; bj < 2; ++bj) { const u32x4 xb = xin[ai][m][bj];
;                     const f32x4 x0 = (f32x4){bf_lo(xb.x), bf_hi(xb.x), bf_lo(xb.y), bf_hi(xb.y)} + acc[ai][bj][m][0] * s, x1 = (f32x4){bf_lo(xb.z), bf_hi(xb.z), bf_lo(xb.w), bf_hi(xb.w)} + acc[ai][bj][m][1] * s;
;                     sq += (x0[0] * x0[0] + x0[1] * x0[1]) + (x0[2] * x0[2] + x0[3] * x0[3]) + (x1[0] * x1[0] + x1[1] * x1[1]) + (x1[2] * x1[2] + x1[3] * x1[3]);
;                     u32x4 w; w.x = cvt_pk_bf16(x0[0], x0[1]); w.y = cvt_pk_bf16(x0[2], x0[3]); w.z = cvt_pk_bf16(x1[0], x1[1]); w.w = cvt_pk_bf16(x1[2], x1[3]);
;                     *(u32x4*)(XB + ro + bj * 128) = w; }
;                 sq += __shfl_xor(sq, 16); sq += __shfl_xor(sq, 32);
;                 if (fq == 0) SSo[(size_t)(u.pn * 4 + wc) * T + row0 + ai * 128 + m * 16] = sq; }
.LBB0_900:
	s_or_b64 exec, exec, s[34:35]
	v_lshlrev_b32_e32 v126, 16, v180
	s_waitcnt lgkmcnt(0)
	v_and_b32_e32 v127, 0xffff0000, v180
	v_lshlrev_b32_e32 v132, 16, v181
	v_and_b32_e32 v133, 0xffff0000, v181
	v_pk_fma_f32 v[118:119], v[118:119], 0.5, v[132:133] op_sel_hi:[1,0,1]
	v_pk_fma_f32 v[116:117], v[116:117], 0.5, v[126:127] op_sel_hi:[1,0,1]
	v_lshlrev_b32_e32 v126, 16, v182
	v_and_b32_e32 v127, 0xffff0000, v182
	v_lshlrev_b32_e32 v132, 16, v183
	v_and_b32_e32 v133, 0xffff0000, v183
	v_pk_fma_f32 v[132:133], v[114:115], 0.5, v[132:133] op_sel_hi:[1,0,1]
	v_pk_fma_f32 v[114:115], v[112:113], 0.5, v[126:127] op_sel_hi:[1,0,1]
	v_mul_f32_e32 v112, v117, v117
	v_mul_f32_e32 v113, v119, v119
	v_fmac_f32_e32 v112, v116, v116
	v_fmac_f32_e32 v113, v118, v118
	v_add_f32_e32 v112, v112, v113
	v_mul_f32_e32 v113, v115, v115
	v_fmac_f32_e32 v113, v114, v114
	v_add_f32_e32 v112, v113, v112
	v_mul_f32_e32 v113, v133, v133
	v_fmac_f32_e32 v113, v132, v132
	v_add_f32_e32 v126, v113, v112
	v_cvt_pk_bf16_f32 v112, v116, v117
	v_cvt_pk_bf16_f32 v113, v118, v119
	v_lshlrev_b32_e32 v116, 16, v176
	v_and_b32_e32 v117, 0xffff0000, v176
	v_lshlrev_b32_e32 v118, 16, v177
	v_and_b32_e32 v119, 0xffff0000, v177
	v_pk_fma_f32 v[106:107], v[106:107], 0.5, v[118:119] op_sel_hi:[1,0,1]
	v_pk_fma_f32 v[104:105], v[104:105], 0.5, v[116:117] op_sel_hi:[1,0,1]
	v_lshlrev_b32_e32 v116, 16, v178
	v_and_b32_e32 v117, 0xffff0000, v178
	v_pk_fma_f32 v[116:117], v[100:101], 0.5, v[116:117] op_sel_hi:[1,0,1]
	v_mul_f32_e32 v100, v105, v105
	v_mul_f32_e32 v101, v107, v107
	v_fmac_f32_e32 v100, v104, v104
	v_fmac_f32_e32 v101, v106, v106
	v_lshlrev_b32_e32 v118, 16, v179
	v_and_b32_e32 v119, 0xffff0000, v179
	v_add_f32_e32 v100, v100, v101
	v_mul_f32_e32 v101, v117, v117
	v_pk_fma_f32 v[118:119], v[102:103], 0.5, v[118:119] op_sel_hi:[1,0,1]
	v_fmac_f32_e32 v101, v116, v116
	v_add_f32_e32 v100, v101, v100
	v_mul_f32_e32 v101, v119, v119
	v_fmac_f32_e32 v101, v118, v118
	v_add_f32_e32 v100, v101, v100
	v_add_f32_e32 v103, v126, v100
	v_cvt_pk_bf16_f32 v114, v114, v115
	v_cvt_pk_bf16_f32 v115, v132, v133
	v_mov_b32_e32 v132, v103
	s_nop 1
	v_permlane16_swap_b32_e32 v132, v103
	v_lshl_add_u64 v[100:101], s[36:37], 0, v[218:219]
	v_lshl_add_u64 v[126:127], v[204:205], 1, v[100:101]
	global_store_dwordx4 v[126:127], v[112:115], off sc1
	v_cvt_pk_bf16_f32 v102, v104, v105
	s_waitcnt lgkmcnt(0)
	v_add_f32_e32 v100, v103, v132
	v_mov_b32_e32 v101, v100
	s_nop 1
	v_permlane32_swap_b32_e32 v101, v100
	v_cvt_pk_bf16_f32 v103, v106, v107
	v_cvt_pk_bf16_f32 v104, v116, v117
	v_cvt_pk_bf16_f32 v105, v118, v119
	global_store_dwordx4 v[126:127], v[102:105], off offset:256 sc1
	s_and_saveexec_b64 s[34:35], s[4:5]
	s_cbranch_execz .LBB0_902
	s_add_u32 s48, s56, s20
	s_addc_u32 s49, s57, s21
	v_lshl_add_u64 v[102:103], v[202:203], 2, s[48:49]
	s_waitcnt lgkmcnt(0)
	v_add_f32_e32 v100, v100, v101
	global_store_dword v[102:103], v100, off offset:64
.LBB0_902:
	s_or_b64 exec, exec, s[34:35]
	v_lshlrev_b32_e32 v100, 16, v172
	s_waitcnt lgkmcnt(0)
	v_and_b32_e32 v101, 0xffff0000, v172
	v_lshlrev_b32_e32 v102, 16, v173
	v_and_b32_e32 v103, 0xffff0000, v173
	v_pk_fma_f32 v[94:95], v[94:95], 0.5, v[102:103] op_sel_hi:[1,0,1]
	v_pk_fma_f32 v[92:93], v[92:93], 0.5, v[100:101] op_sel_hi:[1,0,1]
	v_lshlrev_b32_e32 v100, 16, v174
	v_and_b32_e32 v101, 0xffff0000, v174
	v_lshlrev_b32_e32 v102, 16, v175
	v_and_b32_e32 v103, 0xffff0000, v175
	v_pk_fma_f32 v[102:103], v[90:91], 0.5, v[102:103] op_sel_hi:[1,0,1]
	v_pk_fma_f32 v[90:91], v[88:89], 0.5, v[100:101] op_sel_hi:[1,0,1]
	v_mul_f32_e32 v88, v93, v93
	v_mul_f32_e32 v89, v95, v95
	v_fmac_f32_e32 v88, v92, v92
	v_fmac_f32_e32 v89, v94, v94
	v_add_f32_e32 v88, v88, v89
	v_mul_f32_e32 v89, v91, v91
	v_fmac_f32_e32 v89, v90, v90
	v_add_f32_e32 v88, v89, v88
	v_mul_f32_e32 v89, v103, v103
	v_fmac_f32_e32 v89, v102, v102
	v_add_f32_e32 v100, v89, v88
	v_cvt_pk_bf16_f32 v88, v92, v93
	v_cvt_pk_bf16_f32 v89, v94, v95
	v_lshlrev_b32_e32 v92, 16, v168
	v_and_b32_e32 v93, 0xffff0000, v168
	v_lshlrev_b32_e32 v94, 16, v169
	v_and_b32_e32 v95, 0xffff0000, v169
	v_pk_fma_f32 v[86:87], v[86:87], 0.5, v[94:95] op_sel_hi:[1,0,1]
	v_pk_fma_f32 v[84:85], v[84:85], 0.5, v[92:93] op_sel_hi:[1,0,1]
	v_lshlrev_b32_e32 v92, 16, v170
	v_and_b32_e32 v93, 0xffff0000, v170
	v_pk_fma_f32 v[92:93], v[80:81], 0.5, v[92:93] op_sel_hi:[1,0,1]
	v_mul_f32_e32 v80, v85, v85
	v_mul_f32_e32 v81, v87, v87
	v_fmac_f32_e32 v80, v84, v84
	v_fmac_f32_e32 v81, v86, v86
	v_lshlrev_b32_e32 v94, 16, v171
	v_and_b32_e32 v95, 0xffff0000, v171
	v_add_f32_e32 v80, v80, v81
	v_mul_f32_e32 v81, v93, v93
	v_pk_fma_f32 v[94:95], v[82:83], 0.5, v[94:95] op_sel_hi:[1,0,1]
	v_fmac_f32_e32 v81, v92, v92
	v_add_f32_e32 v80, v81, v80
	v_mul_f32_e32 v81, v95, v95
	v_fmac_f32_e32 v81, v94, v94
	v_add_f32_e32 v80, v81, v80
	v_add_f32_e32 v83, v100, v80
	v_cvt_pk_bf16_f32 v90, v90, v91
	v_cvt_pk_bf16_f32 v91, v102, v103
	v_mov_b32_e32 v102, v83
	s_nop 1
	v_permlane16_swap_b32_e32 v102, v83
	v_lshl_add_u64 v[80:81], s[36:37], 0, v[216:217]
	v_lshl_add_u64 v[100:101], v[204:205], 1, v[80:81]
	global_store_dwordx4 v[100:101], v[88:91], off sc1
	v_cvt_pk_bf16_f32 v82, v84, v85
	s_waitcnt lgkmcnt(0)
	v_add_f32_e32 v80, v83, v102
	v_mov_b32_e32 v81, v80
	s_nop 1
	v_permlane32_swap_b32_e32 v81, v80
	v_cvt_pk_bf16_f32 v83, v86, v87
	v_cvt_pk_bf16_f32 v84, v92, v93
	v_cvt_pk_bf16_f32 v85, v94, v95
	global_store_dwordx4 v[100:101], v[82:85], off offset:256 sc1
	s_and_saveexec_b64 s[34:35], s[4:5]
	s_cbranch_execz .LBB0_904
	s_add_u32 s48, s56, s20
	s_addc_u32 s49, s57, s21
	v_lshl_add_u64 v[82:83], v[202:203], 2, s[48:49]
	s_waitcnt lgkmcnt(0)
	v_add_f32_e32 v80, v80, v81
	global_store_dword v[82:83], v80, off offset:128
; __device__ __forceinline__ unsigned cvt_pk_bf16(float lo, float hi) { unsigned r; asm volatile("v_cvt_pk_bf16_f32 %0, %1, %2" : "=v"(r) : "v"(lo), "v"(hi)); return r; }
;     __device__ __forceinline__ void operator()(const f32x4 (&acc)[2][2][4][2], const pg8::Unit& u, int wr, int wc, int fr, int fq) const {
;     ...
;             for (int m = 0; m < 4; ++m) { const size_t ro = (size_t)(row0 + ai * 128 + m * 16) * D + col0; float sq = 0.f;
; #pragma unroll
;                 for (int bj = 0; bj < 2; ++bj) { const u32x4 xb = xin[ai][m][bj];
;                     const f32x4 x0 = (f32x4){bf_lo(xb.x), bf_hi(xb.x), bf_lo(xb.y), bf_hi(xb.y)} + acc[ai][bj][m][0] * s, x1 = (f32x4){bf_lo(xb.z), bf_hi(xb.z), bf_lo(xb.w), bf_hi(xb.w)} + acc[ai][bj][m][1] * s;
;                     sq += (x0[0] * x0[0] + x0[1] * x0[1]) + (x0[2] * x0[2] + x0[3] * x0[3]) + (x1[0] * x1[0] + x1[1] * x1[1]) + (x1[2] * x1[2] + x1[3] * x1[3]);
;                     u32x4 w; w.x = cvt_pk_bf16(x0[0], x0[1]); w.y = cvt_pk_bf16(x0[2], x0[3]); w.z = cvt_pk_bf16(x1[0], x1[1]); w.w = cvt_pk_bf16(x1[2], x1[3]);
;                     *(u32x4*)(XB + ro + bj * 128) = w; }
;                 sq += __shfl_xor(sq, 16); sq += __shfl_xor(sq, 32);
;                 if (fq == 0) SSo[(size_t)(u.pn * 4 + wc) * T + row0 + ai * 128 + m * 16] = sq; }
.LBB0_904:
	s_or_b64 exec, exec, s[34:35]
	v_lshlrev_b32_e32 v80, 16, v164
	s_waitcnt lgkmcnt(0)
	v_and_b32_e32 v81, 0xffff0000, v164
	v_lshlrev_b32_e32 v82, 16, v165
	v_and_b32_e32 v83, 0xffff0000, v165
	v_pk_fma_f32 v[78:79], v[78:79], 0.5, v[82:83] op_sel_hi:[1,0,1]
	v_pk_fma_f32 v[76:77], v[76:77], 0.5, v[80:81] op_sel_hi:[1,0,1]
	v_lshlrev_b32_e32 v80, 16, v166
	v_and_b32_e32 v81, 0xffff0000, v166
	v_lshlrev_b32_e32 v82, 16, v167
	v_and_b32_e32 v83, 0xffff0000, v167
	v_pk_fma_f32 v[82:83], v[74:75], 0.5, v[82:83] op_sel_hi:[1,0,1]
	v_pk_fma_f32 v[74:75], v[72:73], 0.5, v[80:81] op_sel_hi:[1,0,1]
	v_mul_f32_e32 v72, v77, v77
	v_mul_f32_e32 v73, v79, v79
	v_fmac_f32_e32 v72, v76, v76
	v_fmac_f32_e32 v73, v78, v78
	v_add_f32_e32 v72, v72, v73
	v_mul_f32_e32 v73, v75, v75
	v_fmac_f32_e32 v73, v74, v74
	v_add_f32_e32 v72, v73, v72
	v_mul_f32_e32 v73, v83, v83
	v_fmac_f32_e32 v73, v82, v82
	v_add_f32_e32 v80, v73, v72
	v_cvt_pk_bf16_f32 v72, v76, v77
	v_cvt_pk_bf16_f32 v73, v78, v79
	v_lshlrev_b32_e32 v76, 16, v160
	v_and_b32_e32 v77, 0xffff0000, v160
	v_lshlrev_b32_e32 v78, 16, v161
	v_and_b32_e32 v79, 0xffff0000, v161
	v_pk_fma_f32 v[70:71], v[70:71], 0.5, v[78:79] op_sel_hi:[1,0,1]
	v_pk_fma_f32 v[68:69], v[68:69], 0.5, v[76:77] op_sel_hi:[1,0,1]
	v_lshlrev_b32_e32 v76, 16, v162
	v_and_b32_e32 v77, 0xffff0000, v162
	v_pk_fma_f32 v[76:77], v[64:65], 0.5, v[76:77] op_sel_hi:[1,0,1]
	v_mul_f32_e32 v64, v69, v69
	v_mul_f32_e32 v65, v71, v71
	v_fmac_f32_e32 v64, v68, v68
	v_fmac_f32_e32 v65, v70, v70
	v_lshlrev_b32_e32 v78, 16, v163
	v_and_b32_e32 v79, 0xffff0000, v163
	v_add_f32_e32 v64, v64, v65
	v_mul_f32_e32 v65, v77, v77
	v_pk_fma_f32 v[78:79], v[66:67], 0.5, v[78:79] op_sel_hi:[1,0,1]
	v_fmac_f32_e32 v65, v76, v76
	v_add_f32_e32 v64, v65, v64
	v_mul_f32_e32 v65, v79, v79
	v_fmac_f32_e32 v65, v78, v78
	v_add_f32_e32 v64, v65, v64
	v_add_f32_e32 v67, v80, v64
	v_cvt_pk_bf16_f32 v74, v74, v75
	v_cvt_pk_bf16_f32 v75, v82, v83
	v_mov_b32_e32 v82, v67
	s_nop 1
	v_permlane16_swap_b32_e32 v82, v67
	v_lshl_add_u64 v[64:65], s[36:37], 0, v[214:215]
	v_lshl_add_u64 v[80:81], v[204:205], 1, v[64:65]
	global_store_dwordx4 v[80:81], v[72:75], off sc1
	v_cvt_pk_bf16_f32 v66, v68, v69
	s_waitcnt lgkmcnt(0)
	v_add_f32_e32 v64, v67, v82
	v_mov_b32_e32 v65, v64
	s_nop 1
	v_permlane32_swap_b32_e32 v65, v64
	v_cvt_pk_bf16_f32 v67, v70, v71
	v_cvt_pk_bf16_f32 v68, v76, v77
	v_cvt_pk_bf16_f32 v69, v78, v79
	global_store_dwordx4 v[80:81], v[66:69], off offset:256 sc1
	s_and_saveexec_b64 s[34:35], s[4:5]
	s_cbranch_execz .LBB0_906
	s_add_u32 s48, s56, s20
	s_addc_u32 s49, s57, s21
	v_lshl_add_u64 v[66:67], v[202:203], 2, s[48:49]
	s_waitcnt lgkmcnt(0)
	v_add_f32_e32 v64, v64, v65
	global_store_dword v[66:67], v64, off offset:192
.LBB0_906:
	s_or_b64 exec, exec, s[34:35]
	v_lshlrev_b32_e32 v64, 16, v156
	s_waitcnt lgkmcnt(0)
	v_and_b32_e32 v65, 0xffff0000, v156
	v_lshlrev_b32_e32 v66, 16, v157
	v_and_b32_e32 v67, 0xffff0000, v157
	v_pk_fma_f32 v[62:63], v[62:63], 0.5, v[66:67] op_sel_hi:[1,0,1]
	v_pk_fma_f32 v[60:61], v[60:61], 0.5, v[64:65] op_sel_hi:[1,0,1]
	v_lshlrev_b32_e32 v64, 16, v158
	v_and_b32_e32 v65, 0xffff0000, v158
	v_lshlrev_b32_e32 v66, 16, v159
	v_and_b32_e32 v67, 0xffff0000, v159
	v_pk_fma_f32 v[66:67], v[58:59], 0.5, v[66:67] op_sel_hi:[1,0,1]
	v_pk_fma_f32 v[58:59], v[56:57], 0.5, v[64:65] op_sel_hi:[1,0,1]
	v_mul_f32_e32 v56, v61, v61
	v_mul_f32_e32 v57, v63, v63
	v_fmac_f32_e32 v56, v60, v60
	v_fmac_f32_e32 v57, v62, v62
	v_add_f32_e32 v56, v56, v57
	v_mul_f32_e32 v57, v59, v59
	v_fmac_f32_e32 v57, v58, v58
	v_add_f32_e32 v56, v57, v56
	v_mul_f32_e32 v57, v67, v67
	v_fmac_f32_e32 v57, v66, v66
	v_add_f32_e32 v64, v57, v56
	v_cvt_pk_bf16_f32 v56, v60, v61
	v_cvt_pk_bf16_f32 v57, v62, v63
	v_lshlrev_b32_e32 v60, 16, v152
	v_and_b32_e32 v61, 0xffff0000, v152
	v_lshlrev_b32_e32 v62, 16, v153
	v_and_b32_e32 v63, 0xffff0000, v153
	v_pk_fma_f32 v[54:55], v[54:55], 0.5, v[62:63] op_sel_hi:[1,0,1]
	v_pk_fma_f32 v[52:53], v[52:53], 0.5, v[60:61] op_sel_hi:[1,0,1]
	v_lshlrev_b32_e32 v60, 16, v154
	v_and_b32_e32 v61, 0xffff0000, v154
	v_pk_fma_f32 v[60:61], v[48:49], 0.5, v[60:61] op_sel_hi:[1,0,1]
	v_mul_f32_e32 v48, v53, v53
	v_mul_f32_e32 v49, v55, v55
	v_fmac_f32_e32 v48, v52, v52
	v_fmac_f32_e32 v49, v54, v54
	v_lshlrev_b32_e32 v62, 16, v155
	v_and_b32_e32 v63, 0xffff0000, v155
	v_add_f32_e32 v48, v48, v49
	v_mul_f32_e32 v49, v61, v61
	v_pk_fma_f32 v[62:63], v[50:51], 0.5, v[62:63] op_sel_hi:[1,0,1]
	v_fmac_f32_e32 v49, v60, v60
	v_add_f32_e32 v48, v49, v48
	v_mul_f32_e32 v49, v63, v63
	v_fmac_f32_e32 v49, v62, v62
	v_add_f32_e32 v48, v49, v48
	v_add_f32_e32 v51, v64, v48
	v_cvt_pk_bf16_f32 v58, v58, v59
	v_cvt_pk_bf16_f32 v59, v66, v67
	v_mov_b32_e32 v66, v51
	s_nop 1
	v_permlane16_swap_b32_e32 v66, v51
	v_lshl_add_u64 v[48:49], s[36:37], 0, v[212:213]
	v_lshl_add_u64 v[64:65], v[204:205], 1, v[48:49]
	global_store_dwordx4 v[64:65], v[56:59], off sc1
	v_cvt_pk_bf16_f32 v50, v52, v53
	s_waitcnt lgkmcnt(0)
	v_add_f32_e32 v48, v51, v66
	v_mov_b32_e32 v49, v48
	s_nop 1
	v_permlane32_swap_b32_e32 v49, v48
	v_cvt_pk_bf16_f32 v51, v54, v55
	v_cvt_pk_bf16_f32 v52, v60, v61
	v_cvt_pk_bf16_f32 v53, v62, v63
	global_store_dwordx4 v[64:65], v[50:53], off offset:256 sc1
	s_and_saveexec_b64 s[34:35], s[4:5]
	s_cbranch_execz .LBB0_908
	s_add_u32 s48, s56, s20
	s_addc_u32 s49, s57, s21
	v_lshl_add_u64 v[50:51], v[202:203], 2, s[48:49]
	s_waitcnt lgkmcnt(0)
	v_add_f32_e32 v48, v48, v49
	global_store_dword v[50:51], v48, off offset:512
; __device__ __forceinline__ unsigned cvt_pk_bf16(float lo, float hi) { unsigned r; asm volatile("v_cvt_pk_bf16_f32 %0, %1, %2" : "=v"(r) : "v"(lo), "v"(hi)); return r; }
;     __device__ __forceinline__ void operator()(const f32x4 (&acc)[2][2][4][2], const pg8::Unit& u, int wr, int wc, int fr, int fq) const {
;     ...
;             for (int m = 0; m < 4; ++m) { const size_t ro = (size_t)(row0 + ai * 128 + m * 16) * D + col0; float sq = 0.f;
; #pragma unroll
;                 for (int bj = 0; bj < 2; ++bj) { const u32x4 xb = xin[ai][m][bj];
;                     const f32x4 x0 = (f32x4){bf_lo(xb.x), bf_hi(xb.x), bf_lo(xb.y), bf_hi(xb.y)} + acc[ai][bj][m][0] * s, x1 = (f32x4){bf_lo(xb.z), bf_hi(xb.z), bf_lo(xb.w), bf_hi(xb.w)} + acc[ai][bj][m][1] * s;
;                     sq += (x0[0] * x0[0] + x0[1] * x0[1]) + (x0[2] * x0[2] + x0[3] * x0[3]) + (x1[0] * x1[0] + x1[1] * x1[1]) + (x1[2] * x1[2] + x1[3] * x1[3]);
;                     u32x4 w; w.x = cvt_pk_bf16(x0[0], x0[1]); w.y = cvt_pk_bf16(x0[2], x0[3]); w.z = cvt_pk_bf16(x1[0], x1[1]); w.w = cvt_pk_bf16(x1[2], x1[3]);
;                     *(u32x4*)(XB + ro + bj * 128) = w; }
;                 sq += __shfl_xor(sq, 16); sq += __shfl_xor(sq, 32);
;                 if (fq == 0) SSo[(size_t)(u.pn * 4 + wc) * T + row0 + ai * 128 + m * 16] = sq; }
.LBB0_908:
	s_or_b64 exec, exec, s[34:35]
	v_lshlrev_b32_e32 v48, 16, v148
	s_waitcnt lgkmcnt(0)
	v_and_b32_e32 v49, 0xffff0000, v148
	v_lshlrev_b32_e32 v50, 16, v149
	v_and_b32_e32 v51, 0xffff0000, v149
	v_pk_fma_f32 v[46:47], v[46:47], 0.5, v[50:51] op_sel_hi:[1,0,1]
	v_pk_fma_f32 v[44:45], v[44:45], 0.5, v[48:49] op_sel_hi:[1,0,1]
	v_lshlrev_b32_e32 v48, 16, v150
	v_and_b32_e32 v49, 0xffff0000, v150
	v_lshlrev_b32_e32 v50, 16, v151
	v_and_b32_e32 v51, 0xffff0000, v151
	v_pk_fma_f32 v[50:51], v[42:43], 0.5, v[50:51] op_sel_hi:[1,0,1]
	v_pk_fma_f32 v[42:43], v[40:41], 0.5, v[48:49] op_sel_hi:[1,0,1]
	v_mul_f32_e32 v40, v45, v45
	v_mul_f32_e32 v41, v47, v47
	v_fmac_f32_e32 v40, v44, v44
	v_fmac_f32_e32 v41, v46, v46
	v_add_f32_e32 v40, v40, v41
	v_mul_f32_e32 v41, v43, v43
	v_fmac_f32_e32 v41, v42, v42
	v_add_f32_e32 v40, v41, v40
	v_mul_f32_e32 v41, v51, v51
	v_fmac_f32_e32 v41, v50, v50
	v_add_f32_e32 v48, v41, v40
	v_cvt_pk_bf16_f32 v40, v44, v45
	v_cvt_pk_bf16_f32 v41, v46, v47
	v_lshlrev_b32_e32 v44, 16, v144
	v_and_b32_e32 v45, 0xffff0000, v144
	v_lshlrev_b32_e32 v46, 16, v145
	v_and_b32_e32 v47, 0xffff0000, v145
	v_pk_fma_f32 v[38:39], v[38:39], 0.5, v[46:47] op_sel_hi:[1,0,1]
	v_pk_fma_f32 v[36:37], v[36:37], 0.5, v[44:45] op_sel_hi:[1,0,1]
	v_lshlrev_b32_e32 v44, 16, v146
	v_and_b32_e32 v45, 0xffff0000, v146
	v_pk_fma_f32 v[44:45], v[32:33], 0.5, v[44:45] op_sel_hi:[1,0,1]
	v_mul_f32_e32 v32, v37, v37
	v_mul_f32_e32 v33, v39, v39
	v_fmac_f32_e32 v32, v36, v36
	v_fmac_f32_e32 v33, v38, v38
	v_lshlrev_b32_e32 v46, 16, v147
	v_and_b32_e32 v47, 0xffff0000, v147
	v_add_f32_e32 v32, v32, v33
	v_mul_f32_e32 v33, v45, v45
	v_pk_fma_f32 v[46:47], v[34:35], 0.5, v[46:47] op_sel_hi:[1,0,1]
	v_fmac_f32_e32 v33, v44, v44
	v_add_f32_e32 v32, v33, v32
	v_mul_f32_e32 v33, v47, v47
	v_fmac_f32_e32 v33, v46, v46
	v_add_f32_e32 v32, v33, v32
	v_add_f32_e32 v35, v48, v32
	v_cvt_pk_bf16_f32 v42, v42, v43
	v_cvt_pk_bf16_f32 v43, v50, v51
	v_mov_b32_e32 v50, v35
	s_nop 1
	v_permlane16_swap_b32_e32 v50, v35
	v_lshl_add_u64 v[32:33], s[36:37], 0, v[210:211]
	v_lshl_add_u64 v[48:49], v[204:205], 1, v[32:33]
	global_store_dwordx4 v[48:49], v[40:43], off sc1
	v_cvt_pk_bf16_f32 v34, v36, v37
	s_waitcnt lgkmcnt(0)
	v_add_f32_e32 v32, v35, v50
	v_mov_b32_e32 v33, v32
	s_nop 1
	v_permlane32_swap_b32_e32 v33, v32
	v_cvt_pk_bf16_f32 v35, v38, v39
	v_cvt_pk_bf16_f32 v36, v44, v45
	v_cvt_pk_bf16_f32 v37, v46, v47
	global_store_dwordx4 v[48:49], v[34:37], off offset:256 sc1
	s_and_saveexec_b64 s[34:35], s[4:5]
	s_cbranch_execz .LBB0_910
	s_add_u32 s48, s56, s20
	s_addc_u32 s49, s57, s21
	v_lshl_add_u64 v[34:35], v[202:203], 2, s[48:49]
	s_waitcnt lgkmcnt(0)
	v_add_f32_e32 v32, v32, v33
	global_store_dword v[34:35], v32, off offset:576
; __device__ __forceinline__ unsigned cvt_pk_bf16(float lo, float hi) { unsigned r; asm volatile("v_cvt_pk_bf16_f32 %0, %1, %2" : "=v"(r) : "v"(lo), "v"(hi)); return r; }
;     __device__ __forceinline__ void operator()(const f32x4 (&acc)[2][2][4][2], const pg8::Unit& u, int wr, int wc, int fr, int fq) const {
;     ...
;             for (int m = 0; m < 4; ++m) { const size_t ro = (size_t)(row0 + ai * 128 + m * 16) * D + col0; float sq = 0.f;
; #pragma unroll
;                 for (int bj = 0; bj < 2; ++bj) { const u32x4 xb = xin[ai][m][bj];
;                     const f32x4 x0 = (f32x4){bf_lo(xb.x), bf_hi(xb.x), bf_lo(xb.y), bf_hi(xb.y)} + acc[ai][bj][m][0] * s, x1 = (f32x4){bf_lo(xb.z), bf_hi(xb.z), bf_lo(xb.w), bf_hi(xb.w)} + acc[ai][bj][m][1] * s;
;                     sq += (x0[0] * x0[0] + x0[1] * x0[1]) + (x0[2] * x0[2] + x0[3] * x0[3]) + (x1[0] * x1[0] + x1[1] * x1[1]) + (x1[2] * x1[2] + x1[3] * x1[3]);
;                     u32x4 w; w.x = cvt_pk_bf16(x0[0], x0[1]); w.y = cvt_pk_bf16(x0[2], x0[3]); w.z = cvt_pk_bf16(x1[0], x1[1]); w.w = cvt_pk_bf16(x1[2], x1[3]);
;                     *(u32x4*)(XB + ro + bj * 128) = w; }
;                 sq += __shfl_xor(sq, 16); sq += __shfl_xor(sq, 32);
;                 if (fq == 0) SSo[(size_t)(u.pn * 4 + wc) * T + row0 + ai * 128 + m * 16] = sq; }
.LBB0_910:
	s_or_b64 exec, exec, s[34:35]
	v_lshlrev_b32_e32 v32, 16, v128
	s_waitcnt lgkmcnt(0)
	v_and_b32_e32 v33, 0xffff0000, v128
	v_lshlrev_b32_e32 v34, 16, v129
	v_and_b32_e32 v35, 0xffff0000, v129
	v_pk_fma_f32 v[30:31], v[30:31], 0.5, v[34:35] op_sel_hi:[1,0,1]
	v_pk_fma_f32 v[28:29], v[28:29], 0.5, v[32:33] op_sel_hi:[1,0,1]
	v_lshlrev_b32_e32 v32, 16, v130
	v_and_b32_e32 v33, 0xffff0000, v130
	v_lshlrev_b32_e32 v34, 16, v131
	v_and_b32_e32 v35, 0xffff0000, v131
	v_pk_fma_f32 v[34:35], v[26:27], 0.5, v[34:35] op_sel_hi:[1,0,1]
	v_pk_fma_f32 v[26:27], v[24:25], 0.5, v[32:33] op_sel_hi:[1,0,1]
	v_mul_f32_e32 v24, v29, v29
	v_mul_f32_e32 v25, v31, v31
	v_fmac_f32_e32 v24, v28, v28
	v_fmac_f32_e32 v25, v30, v30
	v_add_f32_e32 v24, v24, v25
	v_mul_f32_e32 v25, v27, v27
	v_fmac_f32_e32 v25, v26, v26
	v_add_f32_e32 v24, v25, v24
	v_mul_f32_e32 v25, v35, v35
	v_fmac_f32_e32 v25, v34, v34
	v_add_f32_e32 v32, v25, v24
	v_cvt_pk_bf16_f32 v24, v28, v29
	v_cvt_pk_bf16_f32 v25, v30, v31
	v_lshlrev_b32_e32 v28, 16, v120
	v_and_b32_e32 v29, 0xffff0000, v120
	v_lshlrev_b32_e32 v30, 16, v121
	v_and_b32_e32 v31, 0xffff0000, v121
	v_pk_fma_f32 v[22:23], v[22:23], 0.5, v[30:31] op_sel_hi:[1,0,1]
	v_pk_fma_f32 v[20:21], v[20:21], 0.5, v[28:29] op_sel_hi:[1,0,1]
	v_lshlrev_b32_e32 v28, 16, v122
	v_and_b32_e32 v29, 0xffff0000, v122
	v_pk_fma_f32 v[28:29], v[16:17], 0.5, v[28:29] op_sel_hi:[1,0,1]
	v_mul_f32_e32 v16, v21, v21
	v_mul_f32_e32 v17, v23, v23
	v_fmac_f32_e32 v16, v20, v20
	v_fmac_f32_e32 v17, v22, v22
	v_lshlrev_b32_e32 v30, 16, v123
	v_and_b32_e32 v31, 0xffff0000, v123
	v_add_f32_e32 v16, v16, v17
	v_mul_f32_e32 v17, v29, v29
	v_pk_fma_f32 v[30:31], v[18:19], 0.5, v[30:31] op_sel_hi:[1,0,1]
	v_fmac_f32_e32 v17, v28, v28
	v_add_f32_e32 v16, v17, v16
	v_mul_f32_e32 v17, v31, v31
	v_fmac_f32_e32 v17, v30, v30
	v_add_f32_e32 v16, v17, v16
	v_add_f32_e32 v19, v32, v16
	v_cvt_pk_bf16_f32 v26, v26, v27
	v_cvt_pk_bf16_f32 v27, v34, v35
	v_mov_b32_e32 v34, v19
	s_nop 1
	v_permlane16_swap_b32_e32 v34, v19
	v_lshl_add_u64 v[16:17], s[36:37], 0, v[208:209]
	v_lshl_add_u64 v[32:33], v[204:205], 1, v[16:17]
	global_store_dwordx4 v[32:33], v[24:27], off sc1
	v_cvt_pk_bf16_f32 v18, v20, v21
	s_waitcnt lgkmcnt(0)
	v_add_f32_e32 v16, v19, v34
	v_mov_b32_e32 v17, v16
	s_nop 1
	v_permlane32_swap_b32_e32 v17, v16
	v_cvt_pk_bf16_f32 v19, v22, v23
	v_cvt_pk_bf16_f32 v20, v28, v29
	v_cvt_pk_bf16_f32 v21, v30, v31
	global_store_dwordx4 v[32:33], v[18:21], off offset:256 sc1
	s_and_saveexec_b64 s[34:35], s[4:5]
	s_cbranch_execz .LBB0_912
	s_add_u32 s48, s56, s20
	s_addc_u32 s49, s57, s21
	v_lshl_add_u64 v[18:19], v[202:203], 2, s[48:49]
	s_waitcnt lgkmcnt(0)
	v_add_f32_e32 v16, v16, v17
	global_store_dword v[18:19], v16, off offset:640
.LBB0_912:
	s_or_b64 exec, exec, s[34:35]
	v_lshlrev_b32_e32 v16, 16, v108
	s_waitcnt lgkmcnt(0)
	v_and_b32_e32 v17, 0xffff0000, v108
	v_lshlrev_b32_e32 v18, 16, v109
	v_and_b32_e32 v19, 0xffff0000, v109
	v_pk_fma_f32 v[14:15], v[14:15], 0.5, v[18:19] op_sel_hi:[1,0,1]
	v_pk_fma_f32 v[12:13], v[12:13], 0.5, v[16:17] op_sel_hi:[1,0,1]
	v_lshlrev_b32_e32 v16, 16, v110
	v_and_b32_e32 v17, 0xffff0000, v110
	v_lshlrev_b32_e32 v18, 16, v111
	v_and_b32_e32 v19, 0xffff0000, v111
	v_pk_fma_f32 v[18:19], v[10:11], 0.5, v[18:19] op_sel_hi:[1,0,1]
	v_pk_fma_f32 v[10:11], v[8:9], 0.5, v[16:17] op_sel_hi:[1,0,1]
	v_mul_f32_e32 v8, v13, v13
	v_mul_f32_e32 v9, v15, v15
	v_fmac_f32_e32 v8, v12, v12
	v_fmac_f32_e32 v9, v14, v14
	v_add_f32_e32 v8, v8, v9
	v_mul_f32_e32 v9, v11, v11
	v_fmac_f32_e32 v9, v10, v10
	v_add_f32_e32 v8, v9, v8
	v_mul_f32_e32 v9, v19, v19
	v_fmac_f32_e32 v9, v18, v18
	v_add_f32_e32 v16, v9, v8
	v_cvt_pk_bf16_f32 v8, v12, v13
	v_cvt_pk_bf16_f32 v9, v14, v15
	v_lshlrev_b32_e32 v12, 16, v96
	v_and_b32_e32 v13, 0xffff0000, v96
	v_lshlrev_b32_e32 v14, 16, v97
	v_and_b32_e32 v15, 0xffff0000, v97
	v_pk_fma_f32 v[6:7], v[6:7], 0.5, v[14:15] op_sel_hi:[1,0,1]
	v_pk_fma_f32 v[4:5], v[4:5], 0.5, v[12:13] op_sel_hi:[1,0,1]
	v_lshlrev_b32_e32 v12, 16, v98
	v_and_b32_e32 v13, 0xffff0000, v98
	v_pk_fma_f32 v[12:13], v[0:1], 0.5, v[12:13] op_sel_hi:[1,0,1]
	v_mul_f32_e32 v0, v5, v5
	v_mul_f32_e32 v1, v7, v7
	v_fmac_f32_e32 v0, v4, v4
	v_fmac_f32_e32 v1, v6, v6
	v_lshlrev_b32_e32 v14, 16, v99
	v_and_b32_e32 v15, 0xffff0000, v99
	v_add_f32_e32 v0, v0, v1
	v_mul_f32_e32 v1, v13, v13
	v_pk_fma_f32 v[14:15], v[2:3], 0.5, v[14:15] op_sel_hi:[1,0,1]
	v_fmac_f32_e32 v1, v12, v12
	v_add_f32_e32 v0, v1, v0
	v_mul_f32_e32 v1, v15, v15
	v_fmac_f32_e32 v1, v14, v14
	v_add_f32_e32 v0, v1, v0
	v_add_f32_e32 v3, v16, v0
	v_cvt_pk_bf16_f32 v10, v10, v11
	v_cvt_pk_bf16_f32 v11, v18, v19
	v_mov_b32_e32 v18, v3
	s_nop 1
	v_permlane16_swap_b32_e32 v18, v3
	v_lshl_add_u64 v[0:1], s[36:37], 0, v[206:207]
	v_lshl_add_u64 v[16:17], v[204:205], 1, v[0:1]
	global_store_dwordx4 v[16:17], v[8:11], off sc1
	v_cvt_pk_bf16_f32 v2, v4, v5
	s_waitcnt lgkmcnt(0)
	v_add_f32_e32 v0, v3, v18
	v_mov_b32_e32 v1, v0
	s_nop 1
	v_permlane32_swap_b32_e32 v1, v0
	v_cvt_pk_bf16_f32 v3, v6, v7
	v_cvt_pk_bf16_f32 v4, v12, v13
	v_cvt_pk_bf16_f32 v5, v14, v15
	global_store_dwordx4 v[16:17], v[2:5], off offset:256 sc1
	s_and_saveexec_b64 s[34:35], s[4:5]
	s_cbranch_execz .LBB0_914
	s_add_u32 s20, s56, s20
	s_addc_u32 s21, s57, s21
	v_lshl_add_u64 v[2:3], v[202:203], 2, s[20:21]
	s_waitcnt lgkmcnt(0)
	v_add_f32_e32 v0, v0, v1
	global_store_dword v[2:3], v0, off offset:704

; __device__ __forceinline__ unsigned cvt_pk_bf16(float lo, float hi) { unsigned r; asm volatile("v_cvt_pk_bf16_f32 %0, %1, %2" : "=v"(r) : "v"(lo), "v"(hi)); return r; }
;     __device__ __forceinline__ void operator()(const f32x4 (&acc)[2][2][4][2], const pg8::Unit& u, int wr, int wc, int fr, int fq) const {
;     ...
;             for (int m = 0; m < 4; ++m) { bf16_t* rowp = O + (size_t)(row0 + ai * 128 + m * 16) * ldc + col0; const float r = s * rt[ai * 128 + m * 16];
; #pragma unroll
;                 for (int bj = 0; bj < 2; ++bj) { const f32x4 v0 = acc[ai][bj][m][0] * r, v1 = acc[ai][bj][m][1] * r; cs[bj][0] += v0; cs[bj][1] += v1;
;                     u32x4 w; w.x = cvt_pk_bf16(v0[0], v0[1]); w.y = cvt_pk_bf16(v0[2], v0[3]); w.z = cvt_pk_bf16(v1[0], v1[1]); w.w = cvt_pk_bf16(v1[2], v1[3]);
;                     *(u32x4*)(rowp + bj * 128) = w; } }
.LBB0_1203:
	s_lshl_b32 s34, s0, 8
	s_cmp_lt_i32 s0, 4
	s_cselect_b64 vcc, -1, 0
	s_cmp_eq_u32 s14, s66
	s_cselect_b32 s0, s79, 0x300
	s_cmp_lg_u32 s14, s67
	s_cselect_b32 s0, s0, 0x100
	s_cmp_lg_u32 s14, s65
	s_cselect_b32 s0, s0, 0
	v_lshl_add_u32 v179, s0, 2, v162
	ds_read_b32 v128, v179
	v_lshl_add_u32 v172, s14, 8, v158
	v_or_b32_e32 v140, s34, v130
	v_ashrrev_i32_e32 v173, 31, v172
	v_cndmask_b32_e32 v178, 1.0, v166, vcc
	v_ashrrev_i32_e32 v141, 31, v140
	v_lshlrev_b64 v[142:143], 12, v[172:173]
	v_lshl_add_u64 v[142:143], s[40:41], 0, v[142:143]
	v_lshlrev_b64 v[174:175], 1, v[140:141]
	s_waitcnt lgkmcnt(0)
	v_mul_f32_e32 v128, v178, v128
	v_lshl_add_u64 v[142:143], v[142:143], 0, v[174:175]
	v_pk_mul_f32 v[126:127], v[126:127], v[128:129] op_sel_hi:[1,0]
	v_pk_mul_f32 v[124:125], v[124:125], v[128:129] op_sel_hi:[1,0]
	v_pk_mul_f32 v[122:123], v[122:123], v[128:129] op_sel_hi:[1,0]
	v_pk_mul_f32 v[120:121], v[120:121], v[128:129] op_sel_hi:[1,0]
	v_cvt_pk_bf16_f32 v168, v124, v125
	v_cvt_pk_bf16_f32 v169, v126, v127
	v_pk_mul_f32 v[118:119], v[118:119], v[128:129] op_sel_hi:[1,0]
	v_cvt_pk_bf16_f32 v170, v120, v121
	v_cvt_pk_bf16_f32 v171, v122, v123
	global_store_dwordx4 v[142:143], v[168:171], off sc1
	v_pk_mul_f32 v[116:117], v[116:117], v[128:129] op_sel_hi:[1,0]
	v_pk_mul_f32 v[114:115], v[114:115], v[128:129] op_sel_hi:[1,0]
	v_pk_mul_f32 v[112:113], v[112:113], v[128:129] op_sel_hi:[1,0]
	v_cvt_pk_bf16_f32 v168, v116, v117
	v_cvt_pk_bf16_f32 v169, v118, v119
	s_nop 0
	v_cvt_pk_bf16_f32 v170, v112, v113
	v_cvt_pk_bf16_f32 v171, v114, v115
	ds_read_b32 v128, v179 offset:64
	global_store_dwordx4 v[142:143], v[168:171], off offset:256 sc1
	s_waitcnt lgkmcnt(0)
	v_mul_f32_e32 v128, v178, v128
	v_or_b32_e32 v168, 16, v172
	v_ashrrev_i32_e32 v169, 31, v168
	v_lshlrev_b64 v[168:169], 12, v[168:169]
	v_lshl_add_u64 v[168:169], s[40:41], 0, v[168:169]
	v_lshl_add_u64 v[176:177], v[168:169], 0, v[174:175]
	v_pk_mul_f32 v[110:111], v[110:111], v[128:129] op_sel_hi:[1,0]
	v_pk_mul_f32 v[108:109], v[108:109], v[128:129] op_sel_hi:[1,0]
	v_pk_mul_f32 v[106:107], v[106:107], v[128:129] op_sel_hi:[1,0]
	v_pk_mul_f32 v[104:105], v[104:105], v[128:129] op_sel_hi:[1,0]
	v_cvt_pk_bf16_f32 v168, v108, v109
	v_cvt_pk_bf16_f32 v169, v110, v111
	v_pk_mul_f32 v[102:103], v[102:103], v[128:129] op_sel_hi:[1,0]
	v_cvt_pk_bf16_f32 v170, v104, v105
	v_cvt_pk_bf16_f32 v171, v106, v107
	global_store_dwordx4 v[176:177], v[168:171], off sc1
	v_pk_mul_f32 v[100:101], v[100:101], v[128:129] op_sel_hi:[1,0]
	v_pk_mul_f32 v[98:99], v[98:99], v[128:129] op_sel_hi:[1,0]
	v_pk_mul_f32 v[96:97], v[96:97], v[128:129] op_sel_hi:[1,0]
	v_cvt_pk_bf16_f32 v168, v100, v101
	v_cvt_pk_bf16_f32 v169, v102, v103
	s_nop 0
	v_cvt_pk_bf16_f32 v170, v96, v97
	v_cvt_pk_bf16_f32 v171, v98, v99
	ds_read_b32 v128, v179 offset:128
	global_store_dwordx4 v[176:177], v[168:171], off offset:256 sc1
	s_waitcnt lgkmcnt(0)
	v_mul_f32_e32 v128, v178, v128
	v_or_b32_e32 v168, 32, v172
	v_ashrrev_i32_e32 v169, 31, v168
	v_lshlrev_b64 v[168:169], 12, v[168:169]
	v_lshl_add_u64 v[168:169], s[40:41], 0, v[168:169]
	v_lshl_add_u64 v[176:177], v[168:169], 0, v[174:175]
	v_pk_mul_f32 v[94:95], v[94:95], v[128:129] op_sel_hi:[1,0]
	v_pk_mul_f32 v[92:93], v[92:93], v[128:129] op_sel_hi:[1,0]
	v_pk_mul_f32 v[90:91], v[90:91], v[128:129] op_sel_hi:[1,0]
	v_pk_mul_f32 v[88:89], v[88:89], v[128:129] op_sel_hi:[1,0]
	v_cvt_pk_bf16_f32 v168, v92, v93
	v_cvt_pk_bf16_f32 v169, v94, v95
	v_pk_mul_f32 v[86:87], v[86:87], v[128:129] op_sel_hi:[1,0]
	v_cvt_pk_bf16_f32 v170, v88, v89
	v_cvt_pk_bf16_f32 v171, v90, v91
	global_store_dwordx4 v[176:177], v[168:171], off sc1
	v_pk_mul_f32 v[84:85], v[84:85], v[128:129] op_sel_hi:[1,0]
	v_pk_mul_f32 v[82:83], v[82:83], v[128:129] op_sel_hi:[1,0]
	v_pk_mul_f32 v[80:81], v[80:81], v[128:129] op_sel_hi:[1,0]
	v_cvt_pk_bf16_f32 v168, v84, v85
	v_cvt_pk_bf16_f32 v169, v86, v87
	s_nop 0
	v_cvt_pk_bf16_f32 v170, v80, v81
	v_cvt_pk_bf16_f32 v171, v82, v83
	ds_read_b32 v128, v179 offset:192
	global_store_dwordx4 v[176:177], v[168:171], off offset:256 sc1
	s_waitcnt lgkmcnt(0)
	v_mul_f32_e32 v128, v178, v128
	v_or_b32_e32 v168, 48, v172
	v_ashrrev_i32_e32 v169, 31, v168
	v_lshlrev_b64 v[168:169], 12, v[168:169]
	v_lshl_add_u64 v[168:169], s[40:41], 0, v[168:169]
	v_lshl_add_u64 v[172:173], v[168:169], 0, v[174:175]
	v_pk_mul_f32 v[78:79], v[78:79], v[128:129] op_sel_hi:[1,0]
	v_pk_mul_f32 v[76:77], v[76:77], v[128:129] op_sel_hi:[1,0]
	v_pk_mul_f32 v[74:75], v[74:75], v[128:129] op_sel_hi:[1,0]
	v_pk_mul_f32 v[72:73], v[72:73], v[128:129] op_sel_hi:[1,0]
	v_cvt_pk_bf16_f32 v168, v76, v77
	v_cvt_pk_bf16_f32 v169, v78, v79
	v_pk_mul_f32 v[70:71], v[70:71], v[128:129] op_sel_hi:[1,0]
	v_cvt_pk_bf16_f32 v170, v72, v73
	v_cvt_pk_bf16_f32 v171, v74, v75
	global_store_dwordx4 v[172:173], v[168:171], off sc1
	v_pk_mul_f32 v[68:69], v[68:69], v[128:129] op_sel_hi:[1,0]
	v_pk_mul_f32 v[66:67], v[66:67], v[128:129] op_sel_hi:[1,0]
	v_pk_mul_f32 v[64:65], v[64:65], v[128:129] op_sel_hi:[1,0]
	v_cvt_pk_bf16_f32 v168, v68, v69
	v_cvt_pk_bf16_f32 v169, v70, v71
	s_nop 0
	v_cvt_pk_bf16_f32 v170, v64, v65
	v_cvt_pk_bf16_f32 v171, v66, v67
	ds_read_b32 v128, v179 offset:512
	global_store_dwordx4 v[172:173], v[168:171], off offset:256 sc1
	v_add_co_u32_e64 v172, s[0:1], s80, v142
	s_waitcnt lgkmcnt(0)
; __device__ __forceinline__ unsigned cvt_pk_bf16(float lo, float hi) { unsigned r; asm volatile("v_cvt_pk_bf16_f32 %0, %1, %2" : "=v"(r) : "v"(lo), "v"(hi)); return r; }
;     __device__ __forceinline__ void operator()(const f32x4 (&acc)[2][2][4][2], const pg8::Unit& u, int wr, int wc, int fr, int fq) const {
;     ...
;             for (int m = 0; m < 4; ++m) { bf16_t* rowp = O + (size_t)(row0 + ai * 128 + m * 16) * ldc + col0; const float r = s * rt[ai * 128 + m * 16];
; #pragma unroll
;                 for (int bj = 0; bj < 2; ++bj) { const f32x4 v0 = acc[ai][bj][m][0] * r, v1 = acc[ai][bj][m][1] * r; cs[bj][0] += v0; cs[bj][1] += v1;
;                     u32x4 w; w.x = cvt_pk_bf16(v0[0], v0[1]); w.y = cvt_pk_bf16(v0[2], v0[3]); w.z = cvt_pk_bf16(v1[0], v1[1]); w.w = cvt_pk_bf16(v1[2], v1[3]);
;                     *(u32x4*)(rowp + bj * 128) = w; } }
;         if (KMs && u.pn >= 4) {
; #pragma unroll
;             for (int bj = 0; bj < 2; ++bj)
; #pragma unroll
;                 for (int n = 0; n < 2; ++n)
; #pragma unroll
;                     for (int e = 0; e < 4; ++e) { float t = cs[bj][n][e]; t += __shfl_xor(t, 1); t += __shfl_xor(t, 2); t += __shfl_xor(t, 4); t += __shfl_xor(t, 8);
;                         if (fr == 0) { const int c = col0 + bj * 128 + 4 * n + e - 1024; unsafeAtomicAdd(KMs + ((size_t)((u.pm >> 3) * NH + (c >> 7)) * 8 + (u.pm & 7)) * HD + (c & 127), t); } }
	v_mul_f32_e32 v128, v178, v128
	v_pk_mul_f32 v[62:63], v[62:63], v[128:129] op_sel_hi:[1,0]
	v_pk_mul_f32 v[60:61], v[60:61], v[128:129] op_sel_hi:[1,0]
	v_pk_mul_f32 v[58:59], v[58:59], v[128:129] op_sel_hi:[1,0]
	v_pk_mul_f32 v[56:57], v[56:57], v[128:129] op_sel_hi:[1,0]
	v_cvt_pk_bf16_f32 v168, v60, v61
	v_cvt_pk_bf16_f32 v169, v62, v63
	v_addc_co_u32_e64 v173, s[0:1], 0, v143, s[0:1]
	v_cvt_pk_bf16_f32 v170, v56, v57
	v_cvt_pk_bf16_f32 v171, v58, v59
	global_store_dwordx4 v[172:173], v[168:171], off sc1
	v_pk_mul_f32 v[54:55], v[54:55], v[128:129] op_sel_hi:[1,0]
	v_pk_mul_f32 v[52:53], v[52:53], v[128:129] op_sel_hi:[1,0]
	v_pk_mul_f32 v[46:47], v[46:47], v[128:129] op_sel_hi:[1,0]
	v_pk_mul_f32 v[44:45], v[44:45], v[128:129] op_sel_hi:[1,0]
	v_cvt_pk_bf16_f32 v168, v52, v53
	v_cvt_pk_bf16_f32 v169, v54, v55
	v_lshl_add_u64 v[172:173], v[142:143], 0, s[44:45]
	v_cvt_pk_bf16_f32 v170, v44, v45
	v_cvt_pk_bf16_f32 v171, v46, v47
	ds_read_b32 v128, v179 offset:576
	global_store_dwordx4 v[172:173], v[168:171], off offset:256 sc1
	v_add_co_u32_e64 v172, s[0:1], s81, v142
	s_waitcnt lgkmcnt(0)
	v_mul_f32_e32 v128, v178, v128
	v_pk_mul_f32 v[50:51], v[50:51], v[128:129] op_sel_hi:[1,0]
	v_pk_mul_f32 v[48:49], v[48:49], v[128:129] op_sel_hi:[1,0]
	v_pk_mul_f32 v[42:43], v[42:43], v[128:129] op_sel_hi:[1,0]
	v_pk_mul_f32 v[40:41], v[40:41], v[128:129] op_sel_hi:[1,0]
	v_cvt_pk_bf16_f32 v168, v48, v49
	v_cvt_pk_bf16_f32 v169, v50, v51
	v_addc_co_u32_e64 v173, s[0:1], 0, v143, s[0:1]
	v_cvt_pk_bf16_f32 v170, v40, v41
	v_cvt_pk_bf16_f32 v171, v42, v43
	global_store_dwordx4 v[172:173], v[168:171], off sc1
	v_pk_mul_f32 v[38:39], v[38:39], v[128:129] op_sel_hi:[1,0]
	v_pk_mul_f32 v[36:37], v[36:37], v[128:129] op_sel_hi:[1,0]
	v_pk_mul_f32 v[30:31], v[30:31], v[128:129] op_sel_hi:[1,0]
	v_pk_mul_f32 v[28:29], v[28:29], v[128:129] op_sel_hi:[1,0]
	v_cvt_pk_bf16_f32 v168, v36, v37
	v_cvt_pk_bf16_f32 v169, v38, v39
	v_lshl_add_u64 v[172:173], v[142:143], 0, s[46:47]
	v_cvt_pk_bf16_f32 v170, v28, v29
	v_cvt_pk_bf16_f32 v171, v30, v31
	ds_read_b32 v128, v179 offset:640
	global_store_dwordx4 v[172:173], v[168:171], off offset:256 sc1
	v_add_co_u32_e64 v172, s[0:1], s82, v142
	s_waitcnt lgkmcnt(0)
	v_mul_f32_e32 v128, v178, v128
	v_pk_mul_f32 v[34:35], v[34:35], v[128:129] op_sel_hi:[1,0]
	v_pk_mul_f32 v[32:33], v[32:33], v[128:129] op_sel_hi:[1,0]
	v_pk_mul_f32 v[26:27], v[26:27], v[128:129] op_sel_hi:[1,0]
	v_pk_mul_f32 v[24:25], v[24:25], v[128:129] op_sel_hi:[1,0]
	v_cvt_pk_bf16_f32 v168, v32, v33
	v_cvt_pk_bf16_f32 v169, v34, v35
	v_addc_co_u32_e64 v173, s[0:1], 0, v143, s[0:1]
	v_cvt_pk_bf16_f32 v170, v24, v25
	v_cvt_pk_bf16_f32 v171, v26, v27
	global_store_dwordx4 v[172:173], v[168:171], off sc1
	v_pk_mul_f32 v[22:23], v[22:23], v[128:129] op_sel_hi:[1,0]
	v_pk_mul_f32 v[20:21], v[20:21], v[128:129] op_sel_hi:[1,0]
	v_pk_mul_f32 v[14:15], v[14:15], v[128:129] op_sel_hi:[1,0]
	v_pk_mul_f32 v[12:13], v[12:13], v[128:129] op_sel_hi:[1,0]
	v_cvt_pk_bf16_f32 v168, v20, v21
	v_cvt_pk_bf16_f32 v169, v22, v23
	v_lshl_add_u64 v[172:173], v[142:143], 0, s[48:49]
	v_cvt_pk_bf16_f32 v170, v12, v13
	v_cvt_pk_bf16_f32 v171, v14, v15
	ds_read_b32 v128, v179 offset:704
	global_store_dwordx4 v[172:173], v[168:171], off offset:256 sc1
	v_lshl_add_u64 v[172:173], v[142:143], 0, s[50:51]
	v_add_co_u32_e64 v142, s[0:1], s83, v142
	s_waitcnt lgkmcnt(0)
	v_mul_f32_e32 v128, v178, v128
	v_addc_co_u32_e64 v143, s[0:1], 0, v143, s[0:1]
	s_or_b64 s[0:1], s[52:53], vcc
	v_pk_mul_f32 v[18:19], v[18:19], v[128:129] op_sel_hi:[1,0]
	v_pk_mul_f32 v[16:17], v[16:17], v[128:129] op_sel_hi:[1,0]
	v_pk_mul_f32 v[10:11], v[10:11], v[128:129] op_sel_hi:[1,0]
	v_pk_mul_f32 v[8:9], v[8:9], v[128:129] op_sel_hi:[1,0]
	v_cvt_pk_bf16_f32 v168, v16, v17
	v_cvt_pk_bf16_f32 v169, v18, v19
	v_pk_mul_f32 v[6:7], v[6:7], v[128:129] op_sel_hi:[1,0]
	v_cvt_pk_bf16_f32 v170, v8, v9
	v_cvt_pk_bf16_f32 v171, v10, v11
	v_pk_mul_f32 v[4:5], v[4:5], v[128:129] op_sel_hi:[1,0]
	v_pk_mul_f32 v[2:3], v[2:3], v[128:129] op_sel_hi:[1,0]
	v_pk_mul_f32 v[0:1], v[0:1], v[128:129] op_sel_hi:[1,0]
	s_and_b64 vcc, exec, s[0:1]
	global_store_dwordx4 v[142:143], v[168:171], off sc1
	s_nop 1
	v_cvt_pk_bf16_f32 v168, v4, v5
	v_cvt_pk_bf16_f32 v169, v6, v7
	v_cvt_pk_bf16_f32 v170, v0, v1
	v_cvt_pk_bf16_f32 v171, v2, v3
	global_store_dwordx4 v[172:173], v[168:171], off offset:256 sc1
	s_cbranch_vccnz .LBB0_1237
	v_pk_add_f32 v[124:125], v[124:125], 0 op_sel_hi:[1,0]
	s_lshl_b32 s0, s14, 7
	v_pk_add_f32 v[108:109], v[124:125], v[108:109]
	s_and_b32 s35, s0, 0x380
	v_pk_add_f32 v[92:93], v[108:109], v[92:93]
	s_add_i32 s0, s34, 0xfffffc00
	v_pk_add_f32 v[76:77], v[92:93], v[76:77]
	s_and_b32 s55, s14, -8
	v_pk_add_f32 v[60:61], v[76:77], v[60:61]
	s_ashr_i32 s0, s0, 7
	v_pk_add_f32 v[48:49], v[60:61], v[48:49]
	v_xor_b32_e32 v61, 8, v167
	v_pk_add_f32 v[32:33], v[48:49], v[32:33]
	v_xor_b32_e32 v48, 4, v167
	v_pk_add_f32 v[16:17], v[32:33], v[16:17]
	v_and_b32_e32 v33, 64, v167
	v_xor_b32_e32 v32, 1, v167
	v_add_u32_e32 v49, 64, v33
	v_cmp_lt_i32_e32 vcc, v32, v49
	v_xor_b32_e32 v33, 2, v167
	s_add_i32 s0, s0, s55
	v_cndmask_b32_e32 v32, v167, v32, vcc
	v_lshlrev_b32_e32 v32, 2, v32
	ds_bpermute_b32 v60, v32, v16
	v_cmp_lt_i32_e32 vcc, v33, v49
	s_ashr_i32 s1, s0, 31
	s_lshl_b64 s[0:1], s[0:1], 12
	v_cndmask_b32_e32 v33, v167, v33, vcc
	v_lshlrev_b32_e32 v33, 2, v33
	s_waitcnt lgkmcnt(0)
	v_add_f32_e32 v16, v16, v60
	ds_bpermute_b32 v60, v33, v16
	v_cmp_lt_i32_e32 vcc, v48, v49
	v_lshlrev_b32_e32 v128, 2, v130
	s_waitcnt lgkmcnt(0)
	v_add_f32_e32 v16, v16, v60
	v_cndmask_b32_e32 v48, v167, v48, vcc
	v_lshlrev_b32_e32 v48, 2, v48
	ds_bpermute_b32 v60, v48, v16
	v_cmp_lt_i32_e32 vcc, v61, v49
	s_waitcnt lgkmcnt(0)
	v_add_f32_e32 v16, v16, v60
	v_cndmask_b32_e32 v49, v167, v61, vcc
	v_lshlrev_b32_e32 v49, 2, v49
	ds_bpermute_b32 v60, v49, v16
	s_and_saveexec_b64 s[20:21], s[6:7]
	s_cbranch_execz .LBB0_1206
	s_add_u32 s14, s28, s0
	s_addc_u32 s57, s29, s1
	s_lshl_b32 s62, s35, 2
	s_add_u32 s62, s14, s62
	s_addc_u32 s63, s57, 0
	s_waitcnt lgkmcnt(0)
	v_add_f32_e32 v16, v16, v60
	global_atomic_add_f32 v128, v16, s[62:63]

; __device__ __forceinline__ unsigned cvt_pk_bf16(float lo, float hi) { unsigned r; asm volatile("v_cvt_pk_bf16_f32 %0, %1, %2" : "=v"(r) : "v"(lo), "v"(hi)); return r; }
; #define LAS __attribute__((address_space(3)))
;     __device__ __forceinline__ void operator()(const f32x4 (&acc)[2][2][4][2], const pg8::Unit& u, int wr, int wc, int fr, int fq) const {
;     ...
;         f32x4 rv[2][2]; const LAS float* rt = rt_.of(u.pn) + wc * 32 + 8 * fq;
; #pragma unroll
;         for (int bj = 0; bj < 2; ++bj)
; #pragma unroll
;             for (int n = 0; n < 2; ++n) rv[bj][n] = *(const LAS f32x4*)(rt + bj * 128 + 4 * n);
; #pragma unroll
;         for (int ai = 0; ai < 2; ++ai)
; #pragma unroll
;             for (int m = 0; m < 4; ++m) { const int dg = row0 + ai * 128 + m * 16, hh = dg >> 7, d = dg & 127;
; #pragma unroll
;                 for (int bj = 0; bj < 2; ++bj) { const int tok = col0 + bj * 128, bb = tok >> 11, tl = tok & 2047;
;                     const f32x4 v0 = acc[ai][bj][m][0] * rv[bj][0], v1 = acc[ai][bj][m][1] * rv[bj][1];
;                     u32x4 w; w.x = cvt_pk_bf16(v0[0], v0[1]); w.y = cvt_pk_bf16(v0[2], v0[3]); w.z = cvt_pk_bf16(v1[0], v1[1]); w.w = cvt_pk_bf16(v1[2], v1[3]);
;                     *(u32x4*)(O + ((((size_t)(bb * 8 + hh) * 32 + (tl >> 6)) * 128 + d) * 64 + (tl & 63))) = w; } }
.LBB0_1449:
	s_cmp_eq_u32 s63, s46
	s_cselect_b32 s13, s62, 0x300
	s_cmp_lg_u32 s63, s47
	s_cselect_b32 s13, s13, 0x100
	s_cmp_lg_u32 s63, s48
	s_cselect_b32 s13, s13, 0
	s_lshl_b32 s34, s34, 8
	s_add_i32 s34, s34, s56
	v_lshl_add_u32 v128, s13, 2, v171
	s_and_b32 s38, s63, -8
	s_ashr_i32 s13, s34, 7
	s_add_i32 s20, s13, s38
	s_ashr_i32 s21, s20, 31
	s_lshl_b32 s13, s57, 1
	s_lshl_b32 s15, s63, 9
	ds_read_b128 v[140:143], v128
	ds_read_b128 v[136:139], v128 offset:16
	ds_read_b128 v[132:135], v128 offset:512
	ds_read_b128 v[128:131], v128 offset:528
	s_lshl_b64 s[20:21], s[20:21], 12
	s_or_b32 s13, s15, s13
	v_or_b32_e32 v159, s20, v152
	s_and_b32 s13, s13, 0xe80
	v_mov_b32_e32 v173, s21
	s_waitcnt lgkmcnt(0)
	v_pk_mul_f32 v[124:125], v[124:125], v[140:141]
	v_or_b32_e32 v172, s13, v159
	v_pk_mul_f32 v[174:175], v[122:123], v[138:139]
	v_pk_mul_f32 v[122:123], v[120:121], v[136:137]
	v_cvt_pk_bf16_f32 v120, v124, v125
	v_lshlrev_b64 v[124:125], 7, v[172:173]
	s_or_b32 s15, s13, 0x100
	v_pk_mul_f32 v[126:127], v[126:127], v[142:143]
	v_lshl_add_u64 v[124:125], v[160:161], 0, v[124:125]
	v_cvt_pk_bf16_f32 v121, v126, v127
	v_pk_mul_f32 v[116:117], v[116:117], v[132:133]
	v_or_b32_e32 v172, s15, v159
	v_cvt_pk_bf16_f32 v122, v122, v123
	v_cvt_pk_bf16_f32 v123, v174, v175
	global_store_dwordx4 v[124:125], v[120:123], off sc1
	v_pk_mul_f32 v[118:119], v[118:119], v[134:135]
	v_pk_mul_f32 v[108:109], v[108:109], v[140:141]
	v_pk_mul_f32 v[120:121], v[114:115], v[130:131]
	v_pk_mul_f32 v[114:115], v[112:113], v[128:129]
	v_cvt_pk_bf16_f32 v112, v116, v117
	v_lshlrev_b64 v[116:117], 7, v[172:173]
	v_lshl_add_u64 v[116:117], v[160:161], 0, v[116:117]
	v_cvt_pk_bf16_f32 v113, v118, v119
	v_cvt_pk_bf16_f32 v114, v114, v115
	v_cvt_pk_bf16_f32 v115, v120, v121
	global_store_dwordx4 v[116:117], v[112:115], off sc1
	v_or_b32_e32 v116, s20, v154
	v_pk_mul_f32 v[110:111], v[110:111], v[142:143]
	v_mov_b32_e32 v113, s21
	v_or_b32_e32 v112, s13, v116
	v_pk_mul_f32 v[114:115], v[106:107], v[138:139]
	v_pk_mul_f32 v[106:107], v[104:105], v[136:137]
	v_cvt_pk_bf16_f32 v104, v108, v109
	v_lshlrev_b64 v[108:109], 7, v[112:113]
	v_cvt_pk_bf16_f32 v105, v110, v111
	v_lshl_add_u64 v[108:109], v[160:161], 0, v[108:109]
	v_pk_mul_f32 v[100:101], v[100:101], v[132:133]
	v_or_b32_e32 v112, s15, v116
	v_cvt_pk_bf16_f32 v106, v106, v107
	v_cvt_pk_bf16_f32 v107, v114, v115
	global_store_dwordx4 v[108:109], v[104:107], off sc1
	v_pk_mul_f32 v[102:103], v[102:103], v[134:135]
	v_pk_mul_f32 v[96:97], v[96:97], v[140:141]
	v_pk_mul_f32 v[104:105], v[94:95], v[130:131]
	v_pk_mul_f32 v[94:95], v[92:93], v[128:129]
	v_cvt_pk_bf16_f32 v92, v100, v101
	v_lshlrev_b64 v[100:101], 7, v[112:113]
	v_lshl_add_u64 v[100:101], v[160:161], 0, v[100:101]
	v_cvt_pk_bf16_f32 v93, v102, v103
	v_cvt_pk_bf16_f32 v94, v94, v95
	v_cvt_pk_bf16_f32 v95, v104, v105
	global_store_dwordx4 v[100:101], v[92:95], off sc1
	v_or_b32_e32 v100, s20, v156
	v_pk_mul_f32 v[84:85], v[84:85], v[132:133]
	v_mov_b32_e32 v93, s21
	v_pk_mul_f32 v[94:95], v[98:99], v[142:143]
	v_or_b32_e32 v92, s13, v100
	v_pk_mul_f32 v[98:99], v[90:91], v[138:139]
	v_pk_mul_f32 v[90:91], v[88:89], v[136:137]
	v_cvt_pk_bf16_f32 v88, v96, v97
	v_cvt_pk_bf16_f32 v89, v94, v95
	v_lshlrev_b64 v[94:95], 7, v[92:93]
	v_lshl_add_u64 v[94:95], v[160:161], 0, v[94:95]
	v_or_b32_e32 v92, s15, v100
	v_cvt_pk_bf16_f32 v90, v90, v91
	v_cvt_pk_bf16_f32 v91, v98, v99
	global_store_dwordx4 v[94:95], v[88:91], off sc1
	v_pk_mul_f32 v[86:87], v[86:87], v[134:135]
	s_addk_i32 s34, 0x80
	v_pk_mul_f32 v[88:89], v[78:79], v[130:131]
	v_pk_mul_f32 v[78:79], v[76:77], v[128:129]
	v_cvt_pk_bf16_f32 v76, v84, v85
	v_lshlrev_b64 v[84:85], 7, v[92:93]
	v_lshl_add_u64 v[84:85], v[160:161], 0, v[84:85]
	v_cvt_pk_bf16_f32 v77, v86, v87
	v_cvt_pk_bf16_f32 v78, v78, v79
	v_cvt_pk_bf16_f32 v79, v88, v89
	global_store_dwordx4 v[84:85], v[76:79], off sc1
	v_or_b32_e32 v84, s20, v158
	v_pk_mul_f32 v[80:81], v[80:81], v[140:141]
	v_mov_b32_e32 v77, s21
	v_pk_mul_f32 v[78:79], v[82:83], v[142:143]
	v_or_b32_e32 v76, s13, v84
	v_pk_mul_f32 v[82:83], v[74:75], v[138:139]
	v_pk_mul_f32 v[74:75], v[72:73], v[136:137]
	v_cvt_pk_bf16_f32 v72, v80, v81
	v_cvt_pk_bf16_f32 v73, v78, v79
	v_lshlrev_b64 v[78:79], 7, v[76:77]
	s_ashr_i32 s20, s34, 7
	v_lshl_add_u64 v[78:79], v[160:161], 0, v[78:79]
	v_pk_mul_f32 v[68:69], v[68:69], v[132:133]
	v_or_b32_e32 v76, s15, v84
	s_add_i32 s20, s20, s38
	v_cvt_pk_bf16_f32 v74, v74, v75
	v_cvt_pk_bf16_f32 v75, v82, v83
	global_store_dwordx4 v[78:79], v[72:75], off sc1
	s_ashr_i32 s21, s20, 31
; __device__ __forceinline__ unsigned cvt_pk_bf16(float lo, float hi) { unsigned r; asm volatile("v_cvt_pk_bf16_f32 %0, %1, %2" : "=v"(r) : "v"(lo), "v"(hi)); return r; }
; #define PG8_BAR __builtin_amdgcn_s_barrier()
; template <class Epi, class Sched, bool ALIGN_EPI = false, bool SP2 = false>
; __device__ __forceinline__ void gemm_phase(PG8_LAS unsigned char* lds, const Gemm g, const Sched& S, const Epi& E) {
;     ...
;         if constexpr (ALIGN_EPI) { if (wr == 0) PG8_BAR; }
;         if constexpr (!Epi::AFTER_DRAIN) { E(acc, cur, wr, wc, fr, fq); S.done(cur); }
;         if (!has_next) break;
; #pragma unroll
;         for (int a = 0; a < 2; ++a)
; #pragma unroll
;             for (int b = 0; b < 2; ++b)
; #pragma unroll
;                 for (int m = 0; m < 4; ++m)
; #pragma unroll
;                     for (int n = 0; n < 2; ++n) acc[a][b][m][n] = (f32x4){0.f, 0.f, 0.f, 0.f};
;         cur = nxt; cA = nA; cB = nB; ++ui;
;         if constexpr (ALIGN_EPI) { if (wr == 1) PG8_BAR; }
;     __device__ __forceinline__ void operator()(const f32x4 (&acc)[2][2][4][2], const pg8::Unit& u, int wr, int wc, int fr, int fq) const {
;     ...
; #pragma unroll
;         for (int ai = 0; ai < 2; ++ai)
; #pragma unroll
;             for (int m = 0; m < 4; ++m) { const int dg = row0 + ai * 128 + m * 16, hh = dg >> 7, d = dg & 127;
; #pragma unroll
;                 for (int bj = 0; bj < 2; ++bj) { const int tok = col0 + bj * 128, bb = tok >> 11, tl = tok & 2047;
;                     const f32x4 v0 = acc[ai][bj][m][0] * rv[bj][0], v1 = acc[ai][bj][m][1] * rv[bj][1];
;                     u32x4 w; w.x = cvt_pk_bf16(v0[0], v0[1]); w.y = cvt_pk_bf16(v0[2], v0[3]); w.z = cvt_pk_bf16(v1[0], v1[1]); w.w = cvt_pk_bf16(v1[2], v1[3]);
;                     *(u32x4*)(O + ((((size_t)(bb * 8 + hh) * 32 + (tl >> 6)) * 128 + d) * 64 + (tl & 63))) = w; } }
	s_lshl_b64 s[20:21], s[20:21], 12
	v_pk_mul_f32 v[72:73], v[66:67], v[130:131]
	v_pk_mul_f32 v[66:67], v[64:65], v[128:129]
	v_cvt_pk_bf16_f32 v64, v68, v69
	v_lshlrev_b64 v[68:69], 7, v[76:77]
	v_lshl_add_u64 v[68:69], v[160:161], 0, v[68:69]
	v_pk_mul_f32 v[70:71], v[70:71], v[134:135]
	v_pk_mul_f32 v[60:61], v[60:61], v[140:141]
	v_cvt_pk_bf16_f32 v65, v70, v71
	v_cvt_pk_bf16_f32 v66, v66, v67
	v_cvt_pk_bf16_f32 v67, v72, v73
	global_store_dwordx4 v[68:69], v[64:67], off sc1
	v_or_b32_e32 v68, s20, v152
	v_pk_mul_f32 v[62:63], v[62:63], v[142:143]
	v_mov_b32_e32 v65, s21
	v_or_b32_e32 v64, s13, v68
	v_pk_mul_f32 v[66:67], v[58:59], v[138:139]
	v_pk_mul_f32 v[58:59], v[56:57], v[136:137]
	v_cvt_pk_bf16_f32 v56, v60, v61
	v_lshlrev_b64 v[60:61], 7, v[64:65]
	v_cvt_pk_bf16_f32 v57, v62, v63
	v_lshl_add_u64 v[60:61], v[160:161], 0, v[60:61]
	v_pk_mul_f32 v[52:53], v[52:53], v[132:133]
	v_or_b32_e32 v64, s15, v68
	v_cvt_pk_bf16_f32 v58, v58, v59
	v_cvt_pk_bf16_f32 v59, v66, v67
	global_store_dwordx4 v[60:61], v[56:59], off sc1
	v_pk_mul_f32 v[54:55], v[54:55], v[134:135]
	v_pk_mul_f32 v[48:49], v[48:49], v[140:141]
	v_pk_mul_f32 v[56:57], v[46:47], v[130:131]
	v_pk_mul_f32 v[46:47], v[44:45], v[128:129]
	v_cvt_pk_bf16_f32 v44, v52, v53
	v_lshlrev_b64 v[52:53], 7, v[64:65]
	v_lshl_add_u64 v[52:53], v[160:161], 0, v[52:53]
	v_cvt_pk_bf16_f32 v45, v54, v55
	v_cvt_pk_bf16_f32 v46, v46, v47
	v_cvt_pk_bf16_f32 v47, v56, v57
	global_store_dwordx4 v[52:53], v[44:47], off sc1
	v_or_b32_e32 v52, s20, v154
	v_pk_mul_f32 v[36:37], v[36:37], v[132:133]
	v_mov_b32_e32 v45, s21
	v_pk_mul_f32 v[46:47], v[50:51], v[142:143]
	v_or_b32_e32 v44, s13, v52
	v_pk_mul_f32 v[50:51], v[42:43], v[138:139]
	v_pk_mul_f32 v[42:43], v[40:41], v[136:137]
	v_cvt_pk_bf16_f32 v40, v48, v49
	v_cvt_pk_bf16_f32 v41, v46, v47
	v_lshlrev_b64 v[46:47], 7, v[44:45]
	v_lshl_add_u64 v[46:47], v[160:161], 0, v[46:47]
	v_or_b32_e32 v44, s15, v52
	v_cvt_pk_bf16_f32 v42, v42, v43
	v_cvt_pk_bf16_f32 v43, v50, v51
	global_store_dwordx4 v[46:47], v[40:43], off sc1
	v_pk_mul_f32 v[38:39], v[38:39], v[134:135]
	v_pk_mul_f32 v[32:33], v[32:33], v[140:141]
	v_pk_mul_f32 v[40:41], v[30:31], v[130:131]
	v_pk_mul_f32 v[30:31], v[28:29], v[128:129]
	v_cvt_pk_bf16_f32 v28, v36, v37
	v_lshlrev_b64 v[36:37], 7, v[44:45]
	v_lshl_add_u64 v[36:37], v[160:161], 0, v[36:37]
	v_cvt_pk_bf16_f32 v29, v38, v39
	v_cvt_pk_bf16_f32 v30, v30, v31
	v_cvt_pk_bf16_f32 v31, v40, v41
	global_store_dwordx4 v[36:37], v[28:31], off sc1
	v_or_b32_e32 v36, s20, v156
	v_pk_mul_f32 v[20:21], v[20:21], v[132:133]
	v_mov_b32_e32 v29, s21
	v_pk_mul_f32 v[30:31], v[34:35], v[142:143]
	v_or_b32_e32 v28, s13, v36
	v_pk_mul_f32 v[34:35], v[26:27], v[138:139]
	v_pk_mul_f32 v[26:27], v[24:25], v[136:137]
	v_cvt_pk_bf16_f32 v24, v32, v33
	v_cvt_pk_bf16_f32 v25, v30, v31
	v_lshlrev_b64 v[30:31], 7, v[28:29]
	v_lshl_add_u64 v[30:31], v[160:161], 0, v[30:31]
	v_or_b32_e32 v28, s15, v36
	v_cvt_pk_bf16_f32 v26, v26, v27
	v_cvt_pk_bf16_f32 v27, v34, v35
	global_store_dwordx4 v[30:31], v[24:27], off sc1
	v_pk_mul_f32 v[22:23], v[22:23], v[134:135]
	v_pk_mul_f32 v[16:17], v[16:17], v[140:141]
	v_pk_mul_f32 v[24:25], v[14:15], v[130:131]
	v_pk_mul_f32 v[14:15], v[12:13], v[128:129]
	v_cvt_pk_bf16_f32 v12, v20, v21
	v_lshlrev_b64 v[20:21], 7, v[28:29]
	v_lshl_add_u64 v[20:21], v[160:161], 0, v[20:21]
	v_cvt_pk_bf16_f32 v13, v22, v23
	v_cvt_pk_bf16_f32 v14, v14, v15
	v_cvt_pk_bf16_f32 v15, v24, v25
	global_store_dwordx4 v[20:21], v[12:15], off sc1
	v_or_b32_e32 v20, s20, v158
	v_pk_mul_f32 v[4:5], v[4:5], v[132:133]
	v_mov_b32_e32 v13, s21
	v_pk_mul_f32 v[14:15], v[18:19], v[142:143]
	v_or_b32_e32 v12, s13, v20
	v_pk_mul_f32 v[18:19], v[10:11], v[138:139]
	v_pk_mul_f32 v[10:11], v[8:9], v[136:137]
	v_cvt_pk_bf16_f32 v8, v16, v17
	v_cvt_pk_bf16_f32 v9, v14, v15
	v_lshlrev_b64 v[14:15], 7, v[12:13]
	v_lshl_add_u64 v[14:15], v[160:161], 0, v[14:15]
	v_or_b32_e32 v12, s15, v20
	v_cvt_pk_bf16_f32 v10, v10, v11
	v_cvt_pk_bf16_f32 v11, v18, v19
	global_store_dwordx4 v[14:15], v[8:11], off sc1
	s_andn2_b64 vcc, exec, s[4:5]
	s_mov_b64 s[4:5], -1
	v_pk_mul_f32 v[8:9], v[2:3], v[130:131]
	v_pk_mul_f32 v[2:3], v[0:1], v[128:129]
	v_cvt_pk_bf16_f32 v0, v4, v5
	v_lshlrev_b64 v[4:5], 7, v[12:13]
	v_lshl_add_u64 v[4:5], v[160:161], 0, v[4:5]
	v_pk_mul_f32 v[6:7], v[6:7], v[134:135]
	s_nop 0
	v_cvt_pk_bf16_f32 v1, v6, v7
	v_cvt_pk_bf16_f32 v2, v2, v3
	v_cvt_pk_bf16_f32 v3, v8, v9
	global_store_dwordx4 v[4:5], v[0:3], off sc1
	s_cbranch_vccnz .LBB0_1438
	s_andn2_b64 vcc, exec, s[0:1]
	s_cbranch_vccnz .LBB0_1437
	s_barrier
	s_branch .LBB0_1437

; __device__ __forceinline__ unsigned cvt_pk_bf16(float lo, float hi) { unsigned r; asm volatile("v_cvt_pk_bf16_f32 %0, %1, %2" : "=v"(r) : "v"(lo), "v"(hi)); return r; }
; __device__ __forceinline__ void attn_unit(LAS unsigned char* lds, const bf16_t* QK, const bf16_t* VTt, const float* KM, bf16_t* OA, int b, int h, int qb, int tid, int lane, int wave) {
;     ...
;     const float inv = 1.f / (lrun + __shfl_xor(lrun, 32));
;     bf16_t* op = OA + (size_t)(row0 + r32) * D + h * HD + hf * 4;
; #pragma unroll
;     for (int db = 0; db < 4; ++db)
; #pragma unroll
;         for (int rg = 0; rg < 4; ++rg) { u32x2 w; w.x = cvt_pk_bf16(o[db][4 * rg] * inv, o[db][4 * rg + 1] * inv); w.y = cvt_pk_bf16(o[db][4 * rg + 2] * inv, o[db][4 * rg + 3] * inv);
;             *(u32x2*)(op + db * 32 + rg * 8) = w; }
.LBB0_1512:
	ds_bpermute_b32 v1, v219, v211
	v_lshlrev_b64 v[2:3], 11, v[216:217]
	v_lshl_add_u64 v[2:3], s[18:19], 0, v[2:3]
	v_lshl_add_u64 v[2:3], v[2:3], 0, s[44:45]
	s_add_i32 s3, s3, s22
	s_waitcnt lgkmcnt(0)
	v_add_f32_e32 v1, v211, v1
	v_div_scale_f32 v4, s[0:1], v1, v1, 1.0
	v_rcp_f32_e32 v5, v4
	v_div_scale_f32 v6, vcc, 1.0, v1, 1.0
	v_mov_b32_e32 v211, v0
	v_fma_f32 v7, -v4, v5, 1.0
	v_fmac_f32_e32 v5, v7, v5
	v_mul_f32_e32 v7, v6, v5
	v_fma_f32 v8, -v4, v7, v6
	v_fmac_f32_e32 v7, v8, v5
	v_fma_f32 v4, -v4, v7, v6
	v_div_fmas_f32 v4, v4, v5, v7
	v_div_fixup_f32 v1, v4, v1, 1.0
	v_lshl_add_u64 v[2:3], v[2:3], 0, v[210:211]
	v_and_b32_e32 v88, 32, v196
	v_lshrrev_b32_e32 v88, 2, v88
	v_mov_b32_e32 v89, 0
	v_lshl_add_u64 v[2:3], v[2:3], 0, v[88:89]
	v_mul_f32_e32 v80, v64, v1
	v_mul_f32_e32 v81, v65, v1
	v_cvt_pk_bf16_f32 v84, v80, v81
	v_mul_f32_e32 v82, v66, v1
	v_mul_f32_e32 v83, v67, v1
	v_cvt_pk_bf16_f32 v85, v82, v83
	v_mul_f32_e32 v80, v68, v1
	v_mul_f32_e32 v81, v69, v1
	v_cvt_pk_bf16_f32 v86, v80, v81
	v_mul_f32_e32 v82, v70, v1
	v_mul_f32_e32 v83, v71, v1
	v_cvt_pk_bf16_f32 v87, v82, v83
	s_nop 1
	v_permlane32_swap_b32_e32 v84, v86
	v_permlane32_swap_b32_e32 v85, v87
	global_store_dwordx4 v[2:3], v[84:87], off sc1
	s_add_i32 s65, s65, s22
	s_cmpk_lt_i32 s3, 0x200
	v_mul_f32_e32 v80, v72, v1
	v_mul_f32_e32 v81, v73, v1
	v_cvt_pk_bf16_f32 v84, v80, v81
	v_mul_f32_e32 v82, v74, v1
	v_mul_f32_e32 v83, v75, v1
	v_cvt_pk_bf16_f32 v85, v82, v83
	v_mul_f32_e32 v80, v76, v1
	v_mul_f32_e32 v81, v77, v1
	v_cvt_pk_bf16_f32 v86, v80, v81
	v_mul_f32_e32 v82, v78, v1
	v_mul_f32_e32 v83, v79, v1
	v_cvt_pk_bf16_f32 v87, v82, v83
	s_nop 1
	v_permlane32_swap_b32_e32 v84, v86
	v_permlane32_swap_b32_e32 v85, v87
	global_store_dwordx4 v[2:3], v[84:87], off offset:32 sc1
	v_mul_f32_e32 v80, v48, v1
	v_mul_f32_e32 v81, v49, v1
	v_cvt_pk_bf16_f32 v84, v80, v81
	v_mul_f32_e32 v82, v50, v1
	v_mul_f32_e32 v83, v51, v1
	v_cvt_pk_bf16_f32 v85, v82, v83
	v_mul_f32_e32 v80, v52, v1
	v_mul_f32_e32 v81, v53, v1
	v_cvt_pk_bf16_f32 v86, v80, v81
	v_mul_f32_e32 v82, v54, v1
	v_mul_f32_e32 v83, v55, v1
	v_cvt_pk_bf16_f32 v87, v82, v83
	s_nop 1
	v_permlane32_swap_b32_e32 v84, v86
	v_permlane32_swap_b32_e32 v85, v87
	global_store_dwordx4 v[2:3], v[84:87], off offset:64 sc1
	v_mul_f32_e32 v80, v56, v1
	v_mul_f32_e32 v81, v57, v1
	v_cvt_pk_bf16_f32 v84, v80, v81
	v_mul_f32_e32 v82, v58, v1
	v_mul_f32_e32 v83, v59, v1
	v_cvt_pk_bf16_f32 v85, v82, v83
	v_mul_f32_e32 v80, v60, v1
	v_mul_f32_e32 v81, v61, v1
	v_cvt_pk_bf16_f32 v86, v80, v81
	v_mul_f32_e32 v82, v62, v1
	v_mul_f32_e32 v83, v63, v1
	v_cvt_pk_bf16_f32 v87, v82, v83
	s_nop 1
	v_permlane32_swap_b32_e32 v84, v86
	v_permlane32_swap_b32_e32 v85, v87
	global_store_dwordx4 v[2:3], v[84:87], off offset:96 sc1
	v_mul_f32_e32 v80, v32, v1
	v_mul_f32_e32 v81, v33, v1
	v_cvt_pk_bf16_f32 v84, v80, v81
	v_mul_f32_e32 v82, v34, v1
	v_mul_f32_e32 v83, v35, v1
	v_cvt_pk_bf16_f32 v85, v82, v83
	v_mul_f32_e32 v80, v36, v1
	v_mul_f32_e32 v81, v37, v1
	v_cvt_pk_bf16_f32 v86, v80, v81
	v_mul_f32_e32 v82, v38, v1
	v_mul_f32_e32 v83, v39, v1
	v_cvt_pk_bf16_f32 v87, v82, v83
	s_nop 1
	v_permlane32_swap_b32_e32 v84, v86
	v_permlane32_swap_b32_e32 v85, v87
	global_store_dwordx4 v[2:3], v[84:87], off offset:128 sc1
	v_mul_f32_e32 v80, v40, v1
	v_mul_f32_e32 v81, v41, v1
	v_cvt_pk_bf16_f32 v84, v80, v81
	v_mul_f32_e32 v82, v42, v1
	v_mul_f32_e32 v83, v43, v1
	v_cvt_pk_bf16_f32 v85, v82, v83
	v_mul_f32_e32 v80, v44, v1
	v_mul_f32_e32 v81, v45, v1
	v_cvt_pk_bf16_f32 v86, v80, v81
	v_mul_f32_e32 v82, v46, v1
	v_mul_f32_e32 v83, v47, v1
	v_cvt_pk_bf16_f32 v87, v82, v83
	s_nop 1
	v_permlane32_swap_b32_e32 v84, v86
	v_permlane32_swap_b32_e32 v85, v87
	global_store_dwordx4 v[2:3], v[84:87], off offset:160 sc1
	v_mul_f32_e32 v80, v16, v1
	v_mul_f32_e32 v81, v17, v1
	v_cvt_pk_bf16_f32 v84, v80, v81
	v_mul_f32_e32 v82, v18, v1
	v_mul_f32_e32 v83, v19, v1
	v_cvt_pk_bf16_f32 v85, v82, v83
	v_mul_f32_e32 v80, v20, v1
	v_mul_f32_e32 v81, v21, v1
	v_cvt_pk_bf16_f32 v86, v80, v81
	v_mul_f32_e32 v82, v22, v1
	v_mul_f32_e32 v83, v23, v1
	v_cvt_pk_bf16_f32 v87, v82, v83
	s_nop 1
	v_permlane32_swap_b32_e32 v84, v86
	v_permlane32_swap_b32_e32 v85, v87
	global_store_dwordx4 v[2:3], v[84:87], off offset:192 sc1
	v_mul_f32_e32 v80, v24, v1
	v_mul_f32_e32 v81, v25, v1
	v_cvt_pk_bf16_f32 v84, v80, v81
	v_mul_f32_e32 v82, v26, v1
	v_mul_f32_e32 v83, v27, v1
	v_cvt_pk_bf16_f32 v85, v82, v83
	v_mul_f32_e32 v80, v28, v1
	v_mul_f32_e32 v81, v29, v1
	v_cvt_pk_bf16_f32 v86, v80, v81
	v_mul_f32_e32 v82, v30, v1
	v_mul_f32_e32 v83, v31, v1
	v_cvt_pk_bf16_f32 v87, v82, v83
	s_nop 1
	v_permlane32_swap_b32_e32 v84, v86
	v_permlane32_swap_b32_e32 v85, v87
	global_store_dwordx4 v[2:3], v[84:87], off offset:224 sc1
	s_cbranch_scc0 .LBB0_1561

; __device__ __forceinline__ unsigned cvt_pk_bf16(float lo, float hi) { unsigned r; asm volatile("v_cvt_pk_bf16_f32 %0, %1, %2" : "=v"(r) : "v"(lo), "v"(hi)); return r; }
; __device__ __forceinline__ void attn_unit(LAS unsigned char* lds, const bf16_t* QK, const bf16_t* VTt, const float* KM, bf16_t* OA, int b, int h, int qb, int tid, int lane, int wave) {
;     ...
;     const float inv = 1.f / (lrun + __shfl_xor(lrun, 32));
;     bf16_t* op = OA + (size_t)(row0 + r32) * D + h * HD + hf * 4;
; #pragma unroll
;     for (int db = 0; db < 4; ++db)
; #pragma unroll
;         for (int rg = 0; rg < 4; ++rg) { u32x2 w; w.x = cvt_pk_bf16(o[db][4 * rg] * inv, o[db][4 * rg + 1] * inv); w.y = cvt_pk_bf16(o[db][4 * rg + 2] * inv, o[db][4 * rg + 3] * inv);
;             *(u32x2*)(op + db * 32 + rg * 8) = w; }
.LBB0_1540:
	ds_bpermute_b32 v1, v219, v226
	s_and_b32 s0, s65, 3
	s_lshl_b32 s20, s0, 8
	s_lshl_b32 s44, s44, 1
	v_mov_b32_e32 v211, v0
	s_waitcnt lgkmcnt(0)
	v_add_f32_e32 v1, v226, v1
	v_div_scale_f32 v2, s[0:1], v1, v1, 1.0
	v_rcp_f32_e32 v3, v2
	v_div_scale_f32 v4, vcc, 1.0, v1, 1.0
	s_addk_i32 s20, 0x100
	v_fma_f32 v5, -v2, v3, 1.0
	v_fmac_f32_e32 v3, v5, v3
	v_mul_f32_e32 v5, v4, v3
	v_fma_f32 v6, -v2, v5, v4
	v_fmac_f32_e32 v5, v6, v3
	v_fma_f32 v2, -v2, v5, v4
	v_div_fmas_f32 v2, v2, v3, v5
	v_div_fixup_f32 v1, v2, v1, 1.0
	v_lshlrev_b64 v[2:3], 11, v[216:217]
	v_lshl_add_u64 v[2:3], s[18:19], 0, v[2:3]
	v_lshl_add_u64 v[2:3], v[2:3], 0, s[44:45]
	v_lshl_add_u64 v[2:3], v[2:3], 0, v[210:211]
	v_and_b32_e32 v88, 32, v196
	v_lshrrev_b32_e32 v88, 2, v88
	v_mov_b32_e32 v89, 0
	v_lshl_add_u64 v[2:3], v[2:3], 0, v[88:89]
	v_mul_f32_e32 v80, v64, v1
	v_mul_f32_e32 v81, v65, v1
	v_cvt_pk_bf16_f32 v84, v80, v81
	v_mul_f32_e32 v82, v66, v1
	v_mul_f32_e32 v83, v67, v1
	v_cvt_pk_bf16_f32 v85, v82, v83
	v_mul_f32_e32 v80, v68, v1
	v_mul_f32_e32 v81, v69, v1
	v_cvt_pk_bf16_f32 v86, v80, v81
	v_mul_f32_e32 v82, v70, v1
	v_mul_f32_e32 v83, v71, v1
	v_cvt_pk_bf16_f32 v87, v82, v83
	s_nop 1
	v_permlane32_swap_b32_e32 v84, v86
	v_permlane32_swap_b32_e32 v85, v87
	global_store_dwordx4 v[2:3], v[84:87], off sc1
	s_lshl_b32 s12, s66, 8
	s_lshl_b32 s34, s66, 2
	s_lshl_b32 s0, s66, 20
	s_add_u32 s0, s67, s0
	s_addc_u32 s1, s68, 0
	s_add_u32 s13, s0, 0x800
	s_addc_u32 s14, s1, 0
	s_lshl_b32 s0, s66, 16
	s_add_u32 s0, s69, s0
	s_addc_u32 s1, s70, 0
	s_and_b64 s[10:11], s[4:5], exec
	s_cselect_b32 s11, s14, s1
	s_cselect_b32 s10, s13, s0
	v_mul_f32_e32 v80, v72, v1
	v_mul_f32_e32 v81, v73, v1
	v_cvt_pk_bf16_f32 v84, v80, v81
	v_mul_f32_e32 v82, v74, v1
	v_mul_f32_e32 v83, v75, v1
	v_cvt_pk_bf16_f32 v85, v82, v83
	v_mul_f32_e32 v80, v76, v1
	v_mul_f32_e32 v81, v77, v1
	v_cvt_pk_bf16_f32 v86, v80, v81
	v_mul_f32_e32 v82, v78, v1
	v_mul_f32_e32 v83, v79, v1
	v_cvt_pk_bf16_f32 v87, v82, v83
	s_nop 1
	v_permlane32_swap_b32_e32 v84, v86
	v_permlane32_swap_b32_e32 v85, v87
	global_store_dwordx4 v[2:3], v[84:87], off offset:32 sc1
	v_mul_f32_e32 v80, v48, v1
	v_mul_f32_e32 v81, v49, v1
	v_cvt_pk_bf16_f32 v84, v80, v81
	v_mul_f32_e32 v82, v50, v1
	v_mul_f32_e32 v83, v51, v1
	v_cvt_pk_bf16_f32 v85, v82, v83
	v_mul_f32_e32 v80, v52, v1
	v_mul_f32_e32 v81, v53, v1
	v_cvt_pk_bf16_f32 v86, v80, v81
	v_mul_f32_e32 v82, v54, v1
	v_mul_f32_e32 v83, v55, v1
	v_cvt_pk_bf16_f32 v87, v82, v83
	s_nop 1
	v_permlane32_swap_b32_e32 v84, v86
	v_permlane32_swap_b32_e32 v85, v87
	global_store_dwordx4 v[2:3], v[84:87], off offset:64 sc1
	v_mul_f32_e32 v80, v56, v1
	v_mul_f32_e32 v81, v57, v1
	v_cvt_pk_bf16_f32 v84, v80, v81
	v_mul_f32_e32 v82, v58, v1
	v_mul_f32_e32 v83, v59, v1
	v_cvt_pk_bf16_f32 v85, v82, v83
	v_mul_f32_e32 v80, v60, v1
	v_mul_f32_e32 v81, v61, v1
	v_cvt_pk_bf16_f32 v86, v80, v81
	v_mul_f32_e32 v82, v62, v1
	v_mul_f32_e32 v83, v63, v1
	v_cvt_pk_bf16_f32 v87, v82, v83
	s_nop 1
	v_permlane32_swap_b32_e32 v84, v86
	v_permlane32_swap_b32_e32 v85, v87
	global_store_dwordx4 v[2:3], v[84:87], off offset:96 sc1
	v_mul_f32_e32 v80, v32, v1
	v_mul_f32_e32 v81, v33, v1
	v_cvt_pk_bf16_f32 v84, v80, v81
	v_mul_f32_e32 v82, v34, v1
	v_mul_f32_e32 v83, v35, v1
	v_cvt_pk_bf16_f32 v85, v82, v83
	v_mul_f32_e32 v80, v36, v1
	v_mul_f32_e32 v81, v37, v1
	v_cvt_pk_bf16_f32 v86, v80, v81
	v_mul_f32_e32 v82, v38, v1
	v_mul_f32_e32 v83, v39, v1
	v_cvt_pk_bf16_f32 v87, v82, v83
	s_nop 1
	v_permlane32_swap_b32_e32 v84, v86
	v_permlane32_swap_b32_e32 v85, v87
	global_store_dwordx4 v[2:3], v[84:87], off offset:128 sc1
	v_mul_f32_e32 v80, v40, v1
	v_mul_f32_e32 v81, v41, v1
	v_cvt_pk_bf16_f32 v84, v80, v81
	v_mul_f32_e32 v82, v42, v1
	v_mul_f32_e32 v83, v43, v1
	v_cvt_pk_bf16_f32 v85, v82, v83
	v_mul_f32_e32 v80, v44, v1
	v_mul_f32_e32 v81, v45, v1
	v_cvt_pk_bf16_f32 v86, v80, v81
	v_mul_f32_e32 v82, v46, v1
	v_mul_f32_e32 v83, v47, v1
	v_cvt_pk_bf16_f32 v87, v82, v83
	s_nop 1
	v_permlane32_swap_b32_e32 v84, v86
	v_permlane32_swap_b32_e32 v85, v87
	global_store_dwordx4 v[2:3], v[84:87], off offset:160 sc1
	v_mul_f32_e32 v80, v16, v1
	v_mul_f32_e32 v81, v17, v1
	v_cvt_pk_bf16_f32 v84, v80, v81
	v_mul_f32_e32 v82, v18, v1
	v_mul_f32_e32 v83, v19, v1
	v_cvt_pk_bf16_f32 v85, v82, v83
	v_mul_f32_e32 v80, v20, v1
	v_mul_f32_e32 v81, v21, v1
	v_cvt_pk_bf16_f32 v86, v80, v81
	v_mul_f32_e32 v82, v22, v1
	v_mul_f32_e32 v83, v23, v1
	v_cvt_pk_bf16_f32 v87, v82, v83
	s_nop 1
	v_permlane32_swap_b32_e32 v84, v86
	v_permlane32_swap_b32_e32 v85, v87
; __device__ __forceinline__ void attn_unit(LAS unsigned char* lds, const bf16_t* QK, const bf16_t* VTt, const float* KM, bf16_t* OA, int b, int h, int qb, int tid, int lane, int wave) {
;     ...
;     ATT_DMA(0, 0); ATT_DMA(1, 1);
;     bf16x8 qf[8];
;     { const bf16_t* qp = QK + (size_t)(row0 + r32) * 2048 + h * HD + hf * 8;
; #pragma unroll
;       for (int ks = 0; ks < 8; ++ks) qf[ks] = *(const bf16x8*)(qp + ks * 16); }
;     unsigned sel = (1u << qb) - 1u;
;     if (qb > 3) {
;         float gate[7];
; #pragma unroll
;         for (int n = 0; n < 7; ++n) { gate[n] = -INFINITY;
;             if (n < qb) { const float* kp = KM + ((size_t)(b * NH + h) * 8 + n) * HD + hf * 8; float s = 0.f;
; #pragma unroll
;                 for (int ks = 0; ks < 8; ++ks) { const f32x4 k0 = *(const f32x4*)(kp + ks * 16), k1 = *(const f32x4*)(kp + ks * 16 + 4); const u32x4 q = __builtin_bit_cast(u32x4, qf[ks]);
;                     s += bf_lo(q.x) * k0.x + bf_hi(q.x) * k0.y + bf_lo(q.y) * k0.z + bf_hi(q.y) * k0.w + bf_lo(q.z) * k1.x + bf_hi(q.z) * k1.y + bf_lo(q.w) * k1.z + bf_hi(q.w) * k1.w; }
;                 gate[n] = s + __shfl_xor(s, 32); } }
;         sel = 0u;
; #pragma unroll
;         for (int rnd = 0; rnd < 3; ++rnd) { float best = -INFINITY; int bi = 0;
; #pragma unroll
;             for (int n = 0; n < 7; ++n) { const bool ok = (n < qb) && !((sel >> n) & 1u) && (gate[n] > best); best = ok ? gate[n] : best; bi = ok ? n : bi; }
;             sel |= 1u << bi; }
;     }
;     f32x16 o[4];
; #pragma unroll
;     for (int db = 0; db < 4; ++db)
; #pragma unroll
;         for (int i = 0; i < 16; ++i) o[db][i] = 0.f;
;     float mrun = -1e30f, lrun = 0.f;
;     const int pi_r = ((r32 >> 2) & 1) * 16 + (r32 >> 3) * 4 + (r32 & 3);
;     const int qq = wave * 32 + r32;
;     const unsigned kread = pi_r * ATT_KROW + hf * 16, vread = ATT_KB + r32 * ATT_VROW + hf * 32;
;     ...
;     const float inv = 1.f / (lrun + __shfl_xor(lrun, 32));
;     bf16_t* op = OA + (size_t)(row0 + r32) * D + h * HD + hf * 4;
; #pragma unroll
;     for (int db = 0; db < 4; ++db)
; #pragma unroll
;         for (int rg = 0; rg < 4; ++rg) { u32x2 w; w.x = cvt_pk_bf16(o[db][4 * rg] * inv, o[db][4 * rg + 1] * inv); w.y = cvt_pk_bf16(o[db][4 * rg + 2] * inv, o[db][4 * rg + 3] * inv);
;             *(u32x2*)(op + db * 32 + rg * 8) = w; }
	global_store_dwordx4 v[2:3], v[84:87], off offset:192 sc1
	v_mul_f32_e32 v80, v24, v1
	v_mul_f32_e32 v81, v25, v1
	v_cvt_pk_bf16_f32 v84, v80, v81
	v_mul_f32_e32 v82, v26, v1
	v_mul_f32_e32 v83, v27, v1
	v_cvt_pk_bf16_f32 v85, v82, v83
	v_mul_f32_e32 v80, v28, v1
	v_mul_f32_e32 v81, v29, v1
	v_cvt_pk_bf16_f32 v86, v80, v81
	v_mul_f32_e32 v82, v30, v1
	v_mul_f32_e32 v83, v31, v1
	v_cvt_pk_bf16_f32 v87, v82, v83
	s_nop 1
	v_permlane32_swap_b32_e32 v84, v86
	v_permlane32_swap_b32_e32 v85, v87
	global_store_dwordx4 v[2:3], v[84:87], off offset:224 sc1
	v_lshl_add_u64 v[2:3], s[10:11], 0, v[204:205]
	s_and_b64 s[10:11], s[6:7], exec
	s_mov_b32 m0, s54
	s_cselect_b32 s11, s14, s1
	s_cselect_b32 s10, s13, s0
	global_load_lds_dwordx4 v[2:3], off
	v_lshl_add_u64 v[2:3], s[10:11], 0, v[206:207]
	s_and_b64 s[10:11], s[8:9], exec
	s_mov_b32 m0, s55
	s_cselect_b32 s11, s14, s1
	s_cselect_b32 s10, s13, s0
	global_load_lds_dwordx4 v[2:3], off
	v_lshl_add_u64 v[2:3], s[10:11], 0, v[208:209]
	s_mov_b32 m0, s56
	v_add_u32_e32 v216, s12, v213
	global_load_lds_dwordx4 v[2:3], off
	v_lshl_add_u64 v[2:3], s[0:1], 0, v[198:199]
	s_mov_b32 m0, s57
	v_ashrrev_i32_e32 v217, 31, v216
	global_load_lds_dwordx4 v[2:3], off
	v_lshl_add_u64 v[2:3], s[0:1], 0, v[200:201]
	s_or_b32 s0, s12, 64
	s_lshl_b32 s1, s0, 12
	s_add_u32 s1, s67, s1
	s_addc_u32 s10, s68, 0
	s_add_u32 s13, s1, 0x800
	s_addc_u32 s14, s10, 0
	s_lshl_b32 s0, s0, 8
	s_add_u32 s0, s69, s0
	s_addc_u32 s1, s70, 0
	s_and_b64 s[10:11], s[4:5], exec
	s_mov_b32 m0, s58
	s_cselect_b32 s11, s14, s1
	s_cselect_b32 s10, s13, s0
	global_load_lds_dwordx4 v[2:3], off
	v_lshl_add_u64 v[2:3], s[10:11], 0, v[204:205]
	s_and_b64 s[10:11], s[6:7], exec
	s_mov_b32 m0, s59
	s_cselect_b32 s11, s14, s1
	s_cselect_b32 s10, s13, s0
	global_load_lds_dwordx4 v[2:3], off
	v_lshl_add_u64 v[2:3], s[10:11], 0, v[206:207]
	s_and_b64 s[10:11], s[8:9], exec
	s_mov_b32 m0, s60
	s_cselect_b32 s11, s14, s1
	s_cselect_b32 s10, s13, s0
	global_load_lds_dwordx4 v[2:3], off
	v_lshl_add_u64 v[2:3], s[10:11], 0, v[208:209]
	s_mov_b32 m0, s61
	v_mov_b32_e32 v213, v0
	global_load_lds_dwordx4 v[2:3], off
	v_lshl_add_u64 v[2:3], s[0:1], 0, v[198:199]
	s_mov_b32 m0, s62
	v_mov_b32_e32 v14, v0
	global_load_lds_dwordx4 v[2:3], off
	v_lshl_add_u64 v[2:3], s[0:1], 0, v[200:201]
	s_mov_b32 m0, s63
	v_mov_b32_e32 v15, v0
	global_load_lds_dwordx4 v[2:3], off
	v_lshlrev_b64 v[2:3], 12, v[216:217]
	v_lshl_add_u64 v[2:3], s[40:41], 0, v[2:3]
	v_lshl_add_u64 v[2:3], v[2:3], 0, s[44:45]
	v_lshl_add_u64 v[2:3], v[2:3], 0, v[212:213]
	global_load_dwordx4 v[112:115], v[2:3], off
	global_load_dwordx4 v[116:119], v[2:3], off offset:32
	global_load_dwordx4 v[120:123], v[2:3], off offset:64
	global_load_dwordx4 v[124:127], v[2:3], off offset:96
	global_load_dwordx4 v[128:131], v[2:3], off offset:128
	global_load_dwordx4 v[132:135], v[2:3], off offset:160
	global_load_dwordx4 v[136:139], v[2:3], off offset:192
	global_load_dwordx4 v[140:143], v[2:3], off offset:224
	s_waitcnt vmcnt(0)
	s_barrier
	v_mov_b32_e32 v1, v0
	v_mov_b32_e32 v2, v0
	v_mov_b32_e32 v3, v0
	v_mov_b32_e32 v4, v0
	v_mov_b32_e32 v5, v0
	v_mov_b32_e32 v6, v0
	v_mov_b32_e32 v7, v0
	v_mov_b32_e32 v8, v0
	v_mov_b32_e32 v9, v0
	v_mov_b32_e32 v10, v0
	v_mov_b32_e32 v11, v0
	v_mov_b32_e32 v12, v0
	v_mov_b32_e32 v13, v0
	v_mov_b64_e32 v[30:31], v[14:15]
	v_mov_b64_e32 v[46:47], v[14:15]
	v_mov_b64_e32 v[62:63], v[14:15]
	v_mov_b64_e32 v[78:79], v[14:15]
	s_mov_b32 s21, 3
	s_add_i32 s34, s34, 4
	s_mov_b32 s35, 0
	v_mov_b32_e32 v213, 0xf149f2ca
	v_mov_b32_e32 v211, 0
	v_mov_b64_e32 v[28:29], v[12:13]
	v_mov_b64_e32 v[26:27], v[10:11]
	v_mov_b64_e32 v[24:25], v[8:9]
	v_mov_b64_e32 v[22:23], v[6:7]
	v_mov_b64_e32 v[20:21], v[4:5]
	v_mov_b64_e32 v[18:19], v[2:3]
	v_mov_b64_e32 v[16:17], v[0:1]
	v_mov_b64_e32 v[44:45], v[12:13]
	v_mov_b64_e32 v[42:43], v[10:11]
	v_mov_b64_e32 v[40:41], v[8:9]
	v_mov_b64_e32 v[38:39], v[6:7]
	v_mov_b64_e32 v[36:37], v[4:5]
	v_mov_b64_e32 v[34:35], v[2:3]
	v_mov_b64_e32 v[32:33], v[0:1]
	v_mov_b64_e32 v[60:61], v[12:13]
	v_mov_b64_e32 v[58:59], v[10:11]
	v_mov_b64_e32 v[56:57], v[8:9]
	v_mov_b64_e32 v[54:55], v[6:7]
	v_mov_b64_e32 v[52:53], v[4:5]
	v_mov_b64_e32 v[50:51], v[2:3]
	v_mov_b64_e32 v[48:49], v[0:1]
	v_mov_b64_e32 v[76:77], v[12:13]
	v_mov_b64_e32 v[74:75], v[10:11]
	v_mov_b64_e32 v[72:73], v[8:9]
	v_mov_b64_e32 v[70:71], v[6:7]
	v_mov_b64_e32 v[68:69], v[4:5]
	v_mov_b64_e32 v[66:67], v[2:3]
	v_mov_b64_e32 v[64:65], v[0:1]
	s_mov_b32 s46, 0
	s_waitcnt vmcnt(0)
	s_branch .LBB0_1542

; __device__ __forceinline__ unsigned cvt_pk_bf16(float lo, float hi) { unsigned r; asm volatile("v_cvt_pk_bf16_f32 %0, %1, %2" : "=v"(r) : "v"(lo), "v"(hi)); return r; }
;     __device__ __forceinline__ void operator()(const f32x4 (&acc)[2][2][4][2], const pg8::Unit& u, int wr, int wc, int fr, int fq) const {
;     ...
;                 for (int bj = 0; bj < 2; ++bj) xin[ai][m][bj] = *(const u32x4*)(XB + (size_t)(row0 + ai * 128 + m * 16) * D + col0 + bj * 128);
; #pragma unroll
;         for (int ai = 0; ai < 2; ++ai)
; #pragma unroll
;             for (int m = 0; m < 4; ++m) { const size_t ro = (size_t)(row0 + ai * 128 + m * 16) * D + col0; float sq = 0.f;
; #pragma unroll
;                 for (int bj = 0; bj < 2; ++bj) { const u32x4 xb = xin[ai][m][bj];
;                     const f32x4 x0 = (f32x4){bf_lo(xb.x), bf_hi(xb.x), bf_lo(xb.y), bf_hi(xb.y)} + acc[ai][bj][m][0] * s, x1 = (f32x4){bf_lo(xb.z), bf_hi(xb.z), bf_lo(xb.w), bf_hi(xb.w)} + acc[ai][bj][m][1] * s;
;                     sq += (x0[0] * x0[0] + x0[1] * x0[1]) + (x0[2] * x0[2] + x0[3] * x0[3]) + (x1[0] * x1[0] + x1[1] * x1[1]) + (x1[2] * x1[2] + x1[3] * x1[3]);
;                     u32x4 w; w.x = cvt_pk_bf16(x0[0], x0[1]); w.y = cvt_pk_bf16(x0[2], x0[3]); w.z = cvt_pk_bf16(x1[0], x1[1]); w.w = cvt_pk_bf16(x1[2], x1[3]);
;                     *(u32x4*)(XB + ro + bj * 128) = w; }
;                 sq += __shfl_xor(sq, 16); sq += __shfl_xor(sq, 32);
;                 if (fq == 0) SSo[(size_t)(u.pn * 4 + wc) * T + row0 + ai * 128 + m * 16] = sq; }
.LBB0_1638:
	v_lshl_or_b32 v204, s34, 8, v222
	v_lshl_add_u32 v202, s52, 8, v220
	v_ashrrev_i32_e32 v205, 31, v204
	v_lshlrev_b64 v[236:237], 1, v[204:205]
	v_ashrrev_i32_e32 v203, 31, v202
	v_lshl_add_u64 v[96:97], s[36:37], 0, v[236:237]
	v_lshlrev_b64 v[238:239], 11, v[202:203]
	v_lshl_add_u64 v[98:99], v[96:97], 0, v[238:239]
	global_load_dwordx4 v[228:231], v[98:99], off
	global_load_dwordx4 v[232:235], v[98:99], off offset:256
	v_or_b32_e32 v98, 16, v202
	v_or_b32_e32 v108, 32, v202
	v_or_b32_e32 v110, 48, v202
	v_ashrrev_i32_e32 v99, 31, v98
	v_ashrrev_i32_e32 v109, 31, v108
	v_ashrrev_i32_e32 v111, 31, v110
	v_lshlrev_b64 v[218:219], 11, v[98:99]
	v_lshlrev_b64 v[216:217], 11, v[108:109]
	v_lshlrev_b64 v[214:215], 11, v[110:111]
	v_lshl_add_u64 v[212:213], v[238:239], 0, s[8:9]
	v_lshl_add_u64 v[210:211], v[238:239], 0, s[16:17]
	v_lshl_add_u64 v[208:209], v[238:239], 0, s[38:39]
	v_lshl_add_u64 v[206:207], v[238:239], 0, s[42:43]
	v_lshl_add_u64 v[98:99], v[96:97], 0, v[218:219]
	v_lshl_add_u64 v[108:109], v[96:97], 0, v[216:217]
	v_lshl_add_u64 v[110:111], v[96:97], 0, v[214:215]
	v_lshl_add_u64 v[120:121], v[96:97], 0, v[212:213]
	v_lshl_add_u64 v[122:123], v[96:97], 0, v[210:211]
	v_lshl_add_u64 v[240:241], v[96:97], 0, v[208:209]
	v_lshl_add_u64 v[96:97], v[96:97], 0, v[206:207]
	global_load_dwordx4 v[180:183], v[98:99], off
	global_load_dwordx4 v[176:179], v[98:99], off offset:256
	global_load_dwordx4 v[172:175], v[108:109], off
	global_load_dwordx4 v[168:171], v[108:109], off offset:256
	global_load_dwordx4 v[164:167], v[110:111], off
	global_load_dwordx4 v[160:163], v[110:111], off offset:256
	global_load_dwordx4 v[156:159], v[120:121], off
	global_load_dwordx4 v[152:155], v[120:121], off offset:256
	global_load_dwordx4 v[148:151], v[122:123], off
	global_load_dwordx4 v[144:147], v[122:123], off offset:256
	global_load_dwordx4 v[128:131], v[240:241], off
	s_nop 0
	global_load_dwordx4 v[120:123], v[240:241], off offset:256
	global_load_dwordx4 v[108:111], v[96:97], off
	s_nop 0
	global_load_dwordx4 v[96:99], v[96:97], off offset:256
	s_lshl_b32 s20, s34, 2
	s_or_b32 s20, s20, s65
	s_ashr_i32 s21, s20, 31
	s_lshl_b64 s[20:21], s[20:21], 17
	s_waitcnt vmcnt(0)
	v_lshlrev_b32_e32 v240, 16, v228
	v_and_b32_e32 v241, 0xffff0000, v228
	v_lshlrev_b32_e32 v228, 16, v229
	v_and_b32_e32 v229, 0xffff0000, v229
	v_lshlrev_b32_e32 v242, 16, v230
	v_and_b32_e32 v243, 0xffff0000, v230
	v_lshlrev_b32_e32 v244, 16, v232
	v_and_b32_e32 v245, 0xffff0000, v232
	v_lshlrev_b32_e32 v232, 16, v233
	v_and_b32_e32 v233, 0xffff0000, v233
	v_lshlrev_b32_e32 v246, 16, v234
	v_and_b32_e32 v247, 0xffff0000, v234
	v_lshlrev_b32_e32 v234, 16, v235
	v_and_b32_e32 v235, 0xffff0000, v235
	v_pk_add_f32 v[142:143], v[142:143], v[228:229]
	v_pk_add_f32 v[140:141], v[140:141], v[240:241]
	v_lshlrev_b32_e32 v230, 16, v231
	v_and_b32_e32 v231, 0xffff0000, v231
	v_pk_add_f32 v[136:137], v[136:137], v[242:243]
	v_pk_add_f32 v[228:229], v[134:135], v[232:233]
	v_pk_add_f32 v[232:233], v[126:127], v[234:235]
	v_pk_add_f32 v[234:235], v[124:125], v[246:247]
	v_mul_f32_e32 v124, v141, v141
	v_mul_f32_e32 v125, v143, v143
	v_pk_add_f32 v[138:139], v[138:139], v[230:231]
	v_pk_add_f32 v[230:231], v[132:133], v[244:245]
	v_mul_f32_e32 v126, v137, v137
	v_fmac_f32_e32 v124, v140, v140
	v_fmac_f32_e32 v125, v142, v142
	v_mul_f32_e32 v127, v139, v139
	v_cvt_pk_bf16_f32 v132, v140, v141
	v_cvt_pk_bf16_f32 v133, v142, v143
	v_cvt_pk_bf16_f32 v134, v136, v137
	v_cvt_pk_bf16_f32 v135, v138, v139
	v_mul_f32_e32 v137, v231, v231
	v_mul_f32_e32 v139, v229, v229
	v_fmac_f32_e32 v126, v136, v136
	v_add_f32_e32 v124, v124, v125
	v_fmac_f32_e32 v137, v230, v230
	v_fmac_f32_e32 v139, v228, v228
	v_add_f32_e32 v124, v126, v124
	v_mul_f32_e32 v126, v235, v235
	v_add_f32_e32 v125, v137, v139
	v_fmac_f32_e32 v126, v234, v234
	v_add_f32_e32 v125, v126, v125
	v_mul_f32_e32 v126, v233, v233
	v_fmac_f32_e32 v127, v138, v138
	v_fmac_f32_e32 v126, v232, v232
	v_add_f32_e32 v124, v127, v124
	v_add_f32_e32 v125, v126, v125
	v_and_b32_e32 v126, 64, v226
	v_add_f32_e32 v125, v124, v125
	v_add_u32_e32 v138, 64, v126
	v_lshl_add_u64 v[126:127], s[36:37], 0, v[238:239]
	v_lshl_add_u64 v[136:137], v[126:127], 0, v[236:237]
	v_mov_b32_e32 v139, v125
	s_nop 1
	v_permlane16_swap_b32_e32 v139, v125
	global_store_dwordx4 v[136:137], v[132:135], off sc1
	s_waitcnt lgkmcnt(0)
	v_add_f32_e32 v126, v125, v139
	v_cvt_pk_bf16_f32 v132, v230, v231
	v_cvt_pk_bf16_f32 v133, v228, v229
	v_cvt_pk_bf16_f32 v134, v234, v235
	v_cvt_pk_bf16_f32 v135, v232, v233
	global_store_dwordx4 v[136:137], v[132:135], off offset:256 sc1
	s_nop 0
	v_mov_b32_e32 v127, v126
	s_nop 1
	v_permlane32_swap_b32_e32 v127, v126
	s_and_saveexec_b64 s[34:35], s[4:5]
	s_cbranch_execz .LBB0_1640
	s_add_u32 s54, s63, s20
	s_addc_u32 s55, s64, s21
	v_lshl_add_u64 v[132:133], v[202:203], 2, s[54:55]
	s_waitcnt lgkmcnt(0)
	v_add_f32_e32 v126, v126, v127
	global_store_dword v[132:133], v126, off

; __device__ __forceinline__ unsigned cvt_pk2(float lo, float hi) { f32x2c v = {lo, hi}; bf16x2c q = __builtin_convertvector(v, bf16x2c); return __builtin_bit_cast(unsigned, q); }
;     __device__ __forceinline__ void operator()(const f32x4 (&acc)[2][2][4][2], const pg8::Unit& u, int wr, int wc, int fr, int fq) const {
;     ...
;             for (int m = 0; m < 4; ++m) { bf16_t* rowp = O + (size_t)(row0 + ai * 128 + m * 16) * FF + col0; const float r = rt[ai * 128 + m * 16];
;                 const float rl = -r * LOG2E, r2 = r * r; unsigned w[4];
; #pragma unroll
;                 for (int n = 0; n < 2; ++n)
; #pragma unroll
;                     for (int h = 0; h < 2; ++h) { const f32x2v g = {acc[ai][0][m][n][2 * h], acc[ai][0][m][n][2 * h + 1]}, uu = {acc[ai][1][m][n][2 * h], acc[ai][1][m][n][2 * h + 1]};
;                         const f32x2v t = g * rl; f32x2v d = {__builtin_amdgcn_exp2f(t.x), __builtin_amdgcn_exp2f(t.y)}; d = d + 1.0f;
;                         const f32x2v q = {__builtin_amdgcn_rcpf(d.x), __builtin_amdgcn_rcpf(d.y)}; const f32x2v o = ((g * uu) * r2) * q;
;                         w[2 * n + h] = cvt_pk2(o.x, o.y); }
;                 u32x4 wv; wv.x = w[0]; wv.y = w[1]; wv.z = w[2]; wv.w = w[3];
;                 *(u32x4*)rowp = wv; }
.LBB0_1743:
	s_cmp_eq_u32 s34, s45
	s_cselect_b32 s13, s60, 0x300
	s_cmp_lg_u32 s34, s46
	s_cselect_b32 s13, s13, 0x100
	s_cmp_lg_u32 s34, s47
	s_cselect_b32 s13, s13, 0
	v_lshl_add_u32 v154, s13, 2, v148
	ds_read2_b32 v[200:201], v154 offset1:16
	ds_read2_b32 v[202:203], v154 offset0:32 offset1:48
	ds_read2_b32 v[204:205], v154 offset0:128 offset1:144
	ds_read2_b32 v[206:207], v154 offset0:160 offset1:176
	v_lshl_add_u32 v153, s34, 8, v146
	v_lshl_or_b32 v158, s62, 7, v149
	v_mov_b64_e32 v[178:179], s[40:41]
	s_mov_b32 s98, 0x1600
	v_lshlrev_b32_e32 v158, 1, v158
	v_mov_b32_e32 v159, 0
	v_mad_i64_i32 v[178:179], s[20:21], v153, s98, v[178:179]
	s_mov_b32 s98, 0x16000
	s_mov_b32 s99, 0
	s_mov_b32 s100, 0x6e000
	s_mov_b32 s101, 0
	v_lshl_add_u64 v[178:179], v[178:179], 0, v[158:159]
	s_waitcnt lgkmcnt(0)
	v_mul_f32_e32 v208, 0xbfb8aa3b, v200
	v_mul_f32_e32 v228, v200, v200
	v_mul_f32_e32 v210, 0xbfb8aa3b, v201
	v_mul_f32_e32 v230, v201, v201
	v_mul_f32_e32 v212, 0xbfb8aa3b, v202
	v_mul_f32_e32 v232, v202, v202
	v_mul_f32_e32 v214, 0xbfb8aa3b, v203
	v_mul_f32_e32 v234, v203, v203
	v_mul_f32_e32 v216, 0xbfb8aa3b, v204
	v_mul_f32_e32 v236, v204, v204
	v_mul_f32_e32 v218, 0xbfb8aa3b, v205
	v_mul_f32_e32 v238, v205, v205
	v_mul_f32_e32 v220, 0xbfb8aa3b, v206
	v_mul_f32_e32 v240, v206, v206
	v_mul_f32_e32 v222, 0xbfb8aa3b, v207
	v_mul_f32_e32 v242, v207, v207
	v_rcp_f32_e32 v228, v228
	v_rcp_f32_e32 v230, v230
	v_rcp_f32_e32 v232, v232
	v_rcp_f32_e32 v234, v234
	v_rcp_f32_e32 v236, v236
	v_rcp_f32_e32 v238, v238
	v_rcp_f32_e32 v240, v240
	v_rcp_f32_e32 v242, v242
	v_pk_mul_f32 v[154:155], v[124:125], v[208:209] op_sel_hi:[1,0]
	v_pk_mul_f32 v[156:157], v[126:127], v[208:209] op_sel_hi:[1,0]
	v_pk_mul_f32 v[158:159], v[116:117], v[208:209] op_sel_hi:[1,0]
	v_pk_mul_f32 v[160:161], v[118:119], v[208:209] op_sel_hi:[1,0]
	v_exp_f32_e32 v154, v154
	v_exp_f32_e32 v155, v155
	v_exp_f32_e32 v156, v156
	v_exp_f32_e32 v157, v157
	v_exp_f32_e32 v158, v158
	v_exp_f32_e32 v159, v159
	v_exp_f32_e32 v160, v160
	v_exp_f32_e32 v161, v161
	v_pk_mul_f32 v[162:163], v[108:109], v[210:211] op_sel_hi:[1,0]
	v_pk_mul_f32 v[164:165], v[110:111], v[210:211] op_sel_hi:[1,0]
	v_pk_mul_f32 v[166:167], v[100:101], v[210:211] op_sel_hi:[1,0]
	v_pk_mul_f32 v[168:169], v[102:103], v[210:211] op_sel_hi:[1,0]
	v_exp_f32_e32 v162, v162
	v_exp_f32_e32 v163, v163
	v_exp_f32_e32 v164, v164
	v_exp_f32_e32 v165, v165
	v_exp_f32_e32 v166, v166
	v_exp_f32_e32 v167, v167
	v_exp_f32_e32 v168, v168
	v_exp_f32_e32 v169, v169
	v_pk_mul_f32 v[120:121], v[124:125], v[120:121]
	v_pk_mul_f32 v[122:123], v[126:127], v[122:123]
	v_pk_mul_f32 v[112:113], v[116:117], v[112:113]
	v_pk_mul_f32 v[114:115], v[118:119], v[114:115]
	v_pk_fma_f32 v[154:155], v[154:155], v[228:229], v[228:229] op_sel_hi:[1,0,0]
	v_pk_fma_f32 v[156:157], v[156:157], v[228:229], v[228:229] op_sel_hi:[1,0,0]
	v_pk_fma_f32 v[158:159], v[158:159], v[228:229], v[228:229] op_sel_hi:[1,0,0]
	v_pk_fma_f32 v[160:161], v[160:161], v[228:229], v[228:229] op_sel_hi:[1,0,0]
	v_rcp_f32_e32 v154, v154
	v_rcp_f32_e32 v155, v155
	v_rcp_f32_e32 v156, v156
	v_rcp_f32_e32 v157, v157
	v_rcp_f32_e32 v158, v158
	v_rcp_f32_e32 v159, v159
	v_rcp_f32_e32 v160, v160
	v_rcp_f32_e32 v161, v161
	v_pk_mul_f32 v[170:171], v[92:93], v[212:213] op_sel_hi:[1,0]
	v_pk_mul_f32 v[172:173], v[94:95], v[212:213] op_sel_hi:[1,0]
	v_pk_mul_f32 v[174:175], v[84:85], v[212:213] op_sel_hi:[1,0]
	v_pk_mul_f32 v[176:177], v[86:87], v[212:213] op_sel_hi:[1,0]
	v_exp_f32_e32 v170, v170
	v_exp_f32_e32 v171, v171
	v_exp_f32_e32 v172, v172
	v_exp_f32_e32 v173, v173
	v_exp_f32_e32 v174, v174
	v_exp_f32_e32 v175, v175
	v_exp_f32_e32 v176, v176
	v_exp_f32_e32 v177, v177
	v_pk_mul_f32 v[104:105], v[108:109], v[104:105]
	v_pk_mul_f32 v[106:107], v[110:111], v[106:107]
	v_pk_mul_f32 v[96:97], v[100:101], v[96:97]
	v_pk_mul_f32 v[98:99], v[102:103], v[98:99]
	v_pk_fma_f32 v[162:163], v[162:163], v[230:231], v[230:231] op_sel_hi:[1,0,0]
	v_pk_fma_f32 v[164:165], v[164:165], v[230:231], v[230:231] op_sel_hi:[1,0,0]
	v_pk_fma_f32 v[166:167], v[166:167], v[230:231], v[230:231] op_sel_hi:[1,0,0]
	v_pk_fma_f32 v[168:169], v[168:169], v[230:231], v[230:231] op_sel_hi:[1,0,0]
	v_rcp_f32_e32 v162, v162
	v_rcp_f32_e32 v163, v163
	v_rcp_f32_e32 v164, v164
	v_rcp_f32_e32 v165, v165
	v_rcp_f32_e32 v166, v166
	v_rcp_f32_e32 v167, v167
	v_rcp_f32_e32 v168, v168
	v_rcp_f32_e32 v169, v169
	v_pk_mul_f32 v[120:121], v[120:121], v[154:155]
	v_pk_mul_f32 v[122:123], v[122:123], v[156:157]
	v_pk_mul_f32 v[112:113], v[112:113], v[158:159]
	v_pk_mul_f32 v[114:115], v[114:115], v[160:161]
	v_cvt_pk_bf16_f32 v154, v120, v121
	v_cvt_pk_bf16_f32 v155, v122, v123
	v_cvt_pk_bf16_f32 v156, v112, v113
	v_cvt_pk_bf16_f32 v157, v114, v115
	global_store_dwordx4 v[178:179], v[154:157], off sc1
	v_lshl_add_u64 v[178:179], v[178:179], 0, s[98:99]
	s_nop 1
	v_pk_mul_f32 v[154:155], v[76:77], v[214:215] op_sel_hi:[1,0]
	v_pk_mul_f32 v[156:157], v[78:79], v[214:215] op_sel_hi:[1,0]
	v_pk_mul_f32 v[158:159], v[68:69], v[214:215] op_sel_hi:[1,0]
	v_pk_mul_f32 v[160:161], v[70:71], v[214:215] op_sel_hi:[1,0]
	v_exp_f32_e32 v154, v154
	v_exp_f32_e32 v155, v155
	v_exp_f32_e32 v156, v156
	v_exp_f32_e32 v157, v157
	v_exp_f32_e32 v158, v158
	v_exp_f32_e32 v159, v159
	v_exp_f32_e32 v160, v160
	v_exp_f32_e32 v161, v161
	v_pk_mul_f32 v[88:89], v[92:93], v[88:89]
	v_pk_mul_f32 v[90:91], v[94:95], v[90:91]
	v_pk_mul_f32 v[80:81], v[84:85], v[80:81]
	v_pk_mul_f32 v[82:83], v[86:87], v[82:83]
	v_pk_fma_f32 v[170:171], v[170:171], v[232:233], v[232:233] op_sel_hi:[1,0,0]
	v_pk_fma_f32 v[172:173], v[172:173], v[232:233], v[232:233] op_sel_hi:[1,0,0]
; __device__ __forceinline__ unsigned cvt_pk2(float lo, float hi) { f32x2c v = {lo, hi}; bf16x2c q = __builtin_convertvector(v, bf16x2c); return __builtin_bit_cast(unsigned, q); }
;     __device__ __forceinline__ void operator()(const f32x4 (&acc)[2][2][4][2], const pg8::Unit& u, int wr, int wc, int fr, int fq) const {
;     ...
;             for (int m = 0; m < 4; ++m) { bf16_t* rowp = O + (size_t)(row0 + ai * 128 + m * 16) * FF + col0; const float r = rt[ai * 128 + m * 16];
;                 const float rl = -r * LOG2E, r2 = r * r; unsigned w[4];
; #pragma unroll
;                 for (int n = 0; n < 2; ++n)
; #pragma unroll
;                     for (int h = 0; h < 2; ++h) { const f32x2v g = {acc[ai][0][m][n][2 * h], acc[ai][0][m][n][2 * h + 1]}, uu = {acc[ai][1][m][n][2 * h], acc[ai][1][m][n][2 * h + 1]};
;                         const f32x2v t = g * rl; f32x2v d = {__builtin_amdgcn_exp2f(t.x), __builtin_amdgcn_exp2f(t.y)}; d = d + 1.0f;
;                         const f32x2v q = {__builtin_amdgcn_rcpf(d.x), __builtin_amdgcn_rcpf(d.y)}; const f32x2v o = ((g * uu) * r2) * q;
;                         w[2 * n + h] = cvt_pk2(o.x, o.y); }
;                 u32x4 wv; wv.x = w[0]; wv.y = w[1]; wv.z = w[2]; wv.w = w[3];
;                 *(u32x4*)rowp = wv; }
	v_pk_fma_f32 v[174:175], v[174:175], v[232:233], v[232:233] op_sel_hi:[1,0,0]
	v_pk_fma_f32 v[176:177], v[176:177], v[232:233], v[232:233] op_sel_hi:[1,0,0]
	v_rcp_f32_e32 v170, v170
	v_rcp_f32_e32 v171, v171
	v_rcp_f32_e32 v172, v172
	v_rcp_f32_e32 v173, v173
	v_rcp_f32_e32 v174, v174
	v_rcp_f32_e32 v175, v175
	v_rcp_f32_e32 v176, v176
	v_rcp_f32_e32 v177, v177
	v_pk_mul_f32 v[104:105], v[104:105], v[162:163]
	v_pk_mul_f32 v[106:107], v[106:107], v[164:165]
	v_pk_mul_f32 v[96:97], v[96:97], v[166:167]
	v_pk_mul_f32 v[98:99], v[98:99], v[168:169]
	v_cvt_pk_bf16_f32 v162, v104, v105
	v_cvt_pk_bf16_f32 v163, v106, v107
	v_cvt_pk_bf16_f32 v164, v96, v97
	v_cvt_pk_bf16_f32 v165, v98, v99
	global_store_dwordx4 v[178:179], v[162:165], off sc1
	v_lshl_add_u64 v[178:179], v[178:179], 0, s[98:99]
	s_nop 1
	v_pk_mul_f32 v[162:163], v[60:61], v[216:217] op_sel_hi:[1,0]
	v_pk_mul_f32 v[164:165], v[62:63], v[216:217] op_sel_hi:[1,0]
	v_pk_mul_f32 v[166:167], v[52:53], v[216:217] op_sel_hi:[1,0]
	v_pk_mul_f32 v[168:169], v[54:55], v[216:217] op_sel_hi:[1,0]
	v_exp_f32_e32 v162, v162
	v_exp_f32_e32 v163, v163
	v_exp_f32_e32 v164, v164
	v_exp_f32_e32 v165, v165
	v_exp_f32_e32 v166, v166
	v_exp_f32_e32 v167, v167
	v_exp_f32_e32 v168, v168
	v_exp_f32_e32 v169, v169
	v_pk_mul_f32 v[72:73], v[76:77], v[72:73]
	v_pk_mul_f32 v[74:75], v[78:79], v[74:75]
	v_pk_mul_f32 v[64:65], v[68:69], v[64:65]
	v_pk_mul_f32 v[66:67], v[70:71], v[66:67]
	v_pk_fma_f32 v[154:155], v[154:155], v[234:235], v[234:235] op_sel_hi:[1,0,0]
	v_pk_fma_f32 v[156:157], v[156:157], v[234:235], v[234:235] op_sel_hi:[1,0,0]
	v_pk_fma_f32 v[158:159], v[158:159], v[234:235], v[234:235] op_sel_hi:[1,0,0]
	v_pk_fma_f32 v[160:161], v[160:161], v[234:235], v[234:235] op_sel_hi:[1,0,0]
	v_rcp_f32_e32 v154, v154
	v_rcp_f32_e32 v155, v155
	v_rcp_f32_e32 v156, v156
	v_rcp_f32_e32 v157, v157
	v_rcp_f32_e32 v158, v158
	v_rcp_f32_e32 v159, v159
	v_rcp_f32_e32 v160, v160
	v_rcp_f32_e32 v161, v161
	v_pk_mul_f32 v[88:89], v[88:89], v[170:171]
	v_pk_mul_f32 v[90:91], v[90:91], v[172:173]
	v_pk_mul_f32 v[80:81], v[80:81], v[174:175]
	v_pk_mul_f32 v[82:83], v[82:83], v[176:177]
	v_cvt_pk_bf16_f32 v170, v88, v89
	v_cvt_pk_bf16_f32 v171, v90, v91
	v_cvt_pk_bf16_f32 v172, v80, v81
	v_cvt_pk_bf16_f32 v173, v82, v83
	global_store_dwordx4 v[178:179], v[170:173], off sc1
	v_lshl_add_u64 v[178:179], v[178:179], 0, s[98:99]
	s_nop 1
	v_pk_mul_f32 v[170:171], v[44:45], v[218:219] op_sel_hi:[1,0]
	v_pk_mul_f32 v[172:173], v[46:47], v[218:219] op_sel_hi:[1,0]
	v_pk_mul_f32 v[174:175], v[36:37], v[218:219] op_sel_hi:[1,0]
	v_pk_mul_f32 v[176:177], v[38:39], v[218:219] op_sel_hi:[1,0]
	v_exp_f32_e32 v170, v170
	v_exp_f32_e32 v171, v171
	v_exp_f32_e32 v172, v172
	v_exp_f32_e32 v173, v173
	v_exp_f32_e32 v174, v174
	v_exp_f32_e32 v175, v175
	v_exp_f32_e32 v176, v176
	v_exp_f32_e32 v177, v177
	v_pk_mul_f32 v[56:57], v[60:61], v[56:57]
	v_pk_mul_f32 v[58:59], v[62:63], v[58:59]
	v_pk_mul_f32 v[48:49], v[52:53], v[48:49]
	v_pk_mul_f32 v[50:51], v[54:55], v[50:51]
	v_pk_fma_f32 v[162:163], v[162:163], v[236:237], v[236:237] op_sel_hi:[1,0,0]
	v_pk_fma_f32 v[164:165], v[164:165], v[236:237], v[236:237] op_sel_hi:[1,0,0]
	v_pk_fma_f32 v[166:167], v[166:167], v[236:237], v[236:237] op_sel_hi:[1,0,0]
	v_pk_fma_f32 v[168:169], v[168:169], v[236:237], v[236:237] op_sel_hi:[1,0,0]
	v_rcp_f32_e32 v162, v162
	v_rcp_f32_e32 v163, v163
	v_rcp_f32_e32 v164, v164
	v_rcp_f32_e32 v165, v165
	v_rcp_f32_e32 v166, v166
	v_rcp_f32_e32 v167, v167
	v_rcp_f32_e32 v168, v168
	v_rcp_f32_e32 v169, v169
	v_pk_mul_f32 v[72:73], v[72:73], v[154:155]
	v_pk_mul_f32 v[74:75], v[74:75], v[156:157]
	v_pk_mul_f32 v[64:65], v[64:65], v[158:159]
	v_pk_mul_f32 v[66:67], v[66:67], v[160:161]
	v_cvt_pk_bf16_f32 v154, v72, v73
	v_cvt_pk_bf16_f32 v155, v74, v75
	v_cvt_pk_bf16_f32 v156, v64, v65
	v_cvt_pk_bf16_f32 v157, v66, v67
	global_store_dwordx4 v[178:179], v[154:157], off sc1
	v_lshl_add_u64 v[178:179], v[178:179], 0, s[100:101]
	s_nop 1
	v_pk_mul_f32 v[154:155], v[28:29], v[220:221] op_sel_hi:[1,0]
	v_pk_mul_f32 v[156:157], v[30:31], v[220:221] op_sel_hi:[1,0]
	v_pk_mul_f32 v[158:159], v[20:21], v[220:221] op_sel_hi:[1,0]
	v_pk_mul_f32 v[160:161], v[22:23], v[220:221] op_sel_hi:[1,0]
	v_exp_f32_e32 v154, v154
	v_exp_f32_e32 v155, v155
	v_exp_f32_e32 v156, v156
	v_exp_f32_e32 v157, v157
	v_exp_f32_e32 v158, v158
	v_exp_f32_e32 v159, v159
; #define PG8_BAR __builtin_amdgcn_s_barrier()
; __device__ __forceinline__ unsigned cvt_pk2(float lo, float hi) { f32x2c v = {lo, hi}; bf16x2c q = __builtin_convertvector(v, bf16x2c); return __builtin_bit_cast(unsigned, q); }
; template <class Epi, class Sched, bool ALIGN_EPI = false, bool SP2 = false>
; __device__ __forceinline__ void gemm_phase(PG8_LAS unsigned char* lds, const Gemm g, const Sched& S, const Epi& E) {
;     ...
;         if constexpr (ALIGN_EPI) { if (wr == 0) PG8_BAR; }
;         if constexpr (!Epi::AFTER_DRAIN) { E(acc, cur, wr, wc, fr, fq); S.done(cur); }
;         if (!has_next) break;
; #pragma unroll
;         for (int a = 0; a < 2; ++a)
; #pragma unroll
;             for (int b = 0; b < 2; ++b)
; #pragma unroll
;                 for (int m = 0; m < 4; ++m)
; #pragma unroll
;                     for (int n = 0; n < 2; ++n) acc[a][b][m][n] = (f32x4){0.f, 0.f, 0.f, 0.f};
;         cur = nxt; cA = nA; cB = nB; ++ui;
;         if constexpr (ALIGN_EPI) { if (wr == 1) PG8_BAR; }
;     __device__ __forceinline__ void operator()(const f32x4 (&acc)[2][2][4][2], const pg8::Unit& u, int wr, int wc, int fr, int fq) const {
;     ...
;             for (int m = 0; m < 4; ++m) { bf16_t* rowp = O + (size_t)(row0 + ai * 128 + m * 16) * FF + col0; const float r = rt[ai * 128 + m * 16];
;                 const float rl = -r * LOG2E, r2 = r * r; unsigned w[4];
; #pragma unroll
;                 for (int n = 0; n < 2; ++n)
; #pragma unroll
;                     for (int h = 0; h < 2; ++h) { const f32x2v g = {acc[ai][0][m][n][2 * h], acc[ai][0][m][n][2 * h + 1]}, uu = {acc[ai][1][m][n][2 * h], acc[ai][1][m][n][2 * h + 1]};
;                         const f32x2v t = g * rl; f32x2v d = {__builtin_amdgcn_exp2f(t.x), __builtin_amdgcn_exp2f(t.y)}; d = d + 1.0f;
;                         const f32x2v q = {__builtin_amdgcn_rcpf(d.x), __builtin_amdgcn_rcpf(d.y)}; const f32x2v o = ((g * uu) * r2) * q;
;                         w[2 * n + h] = cvt_pk2(o.x, o.y); }
;                 u32x4 wv; wv.x = w[0]; wv.y = w[1]; wv.z = w[2]; wv.w = w[3];
;                 *(u32x4*)rowp = wv; }
	v_exp_f32_e32 v160, v160
	v_exp_f32_e32 v161, v161
	v_pk_mul_f32 v[40:41], v[44:45], v[40:41]
	v_pk_mul_f32 v[42:43], v[46:47], v[42:43]
	v_pk_mul_f32 v[32:33], v[36:37], v[32:33]
	v_pk_mul_f32 v[34:35], v[38:39], v[34:35]
	v_pk_fma_f32 v[170:171], v[170:171], v[238:239], v[238:239] op_sel_hi:[1,0,0]
	v_pk_fma_f32 v[172:173], v[172:173], v[238:239], v[238:239] op_sel_hi:[1,0,0]
	v_pk_fma_f32 v[174:175], v[174:175], v[238:239], v[238:239] op_sel_hi:[1,0,0]
	v_pk_fma_f32 v[176:177], v[176:177], v[238:239], v[238:239] op_sel_hi:[1,0,0]
	v_rcp_f32_e32 v170, v170
	v_rcp_f32_e32 v171, v171
	v_rcp_f32_e32 v172, v172
	v_rcp_f32_e32 v173, v173
	v_rcp_f32_e32 v174, v174
	v_rcp_f32_e32 v175, v175
	v_rcp_f32_e32 v176, v176
	v_rcp_f32_e32 v177, v177
	v_pk_mul_f32 v[56:57], v[56:57], v[162:163]
	v_pk_mul_f32 v[58:59], v[58:59], v[164:165]
	v_pk_mul_f32 v[48:49], v[48:49], v[166:167]
	v_pk_mul_f32 v[50:51], v[50:51], v[168:169]
	v_cvt_pk_bf16_f32 v162, v56, v57
	v_cvt_pk_bf16_f32 v163, v58, v59
	v_cvt_pk_bf16_f32 v164, v48, v49
	v_cvt_pk_bf16_f32 v165, v50, v51
	global_store_dwordx4 v[178:179], v[162:165], off sc1
	v_lshl_add_u64 v[178:179], v[178:179], 0, s[98:99]
	s_nop 1
	v_pk_mul_f32 v[162:163], v[12:13], v[222:223] op_sel_hi:[1,0]
	v_pk_mul_f32 v[164:165], v[14:15], v[222:223] op_sel_hi:[1,0]
	v_pk_mul_f32 v[166:167], v[4:5], v[222:223] op_sel_hi:[1,0]
	v_pk_mul_f32 v[168:169], v[6:7], v[222:223] op_sel_hi:[1,0]
	v_exp_f32_e32 v162, v162
	v_exp_f32_e32 v163, v163
	v_exp_f32_e32 v164, v164
	v_exp_f32_e32 v165, v165
	v_exp_f32_e32 v166, v166
	v_exp_f32_e32 v167, v167
	v_exp_f32_e32 v168, v168
	v_exp_f32_e32 v169, v169
	v_pk_mul_f32 v[24:25], v[28:29], v[24:25]
	v_pk_mul_f32 v[26:27], v[30:31], v[26:27]
	v_pk_mul_f32 v[16:17], v[20:21], v[16:17]
	v_pk_mul_f32 v[18:19], v[22:23], v[18:19]
	v_pk_fma_f32 v[154:155], v[154:155], v[240:241], v[240:241] op_sel_hi:[1,0,0]
	v_pk_fma_f32 v[156:157], v[156:157], v[240:241], v[240:241] op_sel_hi:[1,0,0]
	v_pk_fma_f32 v[158:159], v[158:159], v[240:241], v[240:241] op_sel_hi:[1,0,0]
	v_pk_fma_f32 v[160:161], v[160:161], v[240:241], v[240:241] op_sel_hi:[1,0,0]
	v_rcp_f32_e32 v154, v154
	v_rcp_f32_e32 v155, v155
	v_rcp_f32_e32 v156, v156
	v_rcp_f32_e32 v157, v157
	v_rcp_f32_e32 v158, v158
	v_rcp_f32_e32 v159, v159
	v_rcp_f32_e32 v160, v160
	v_rcp_f32_e32 v161, v161
	v_pk_mul_f32 v[40:41], v[40:41], v[170:171]
	v_pk_mul_f32 v[42:43], v[42:43], v[172:173]
	v_pk_mul_f32 v[32:33], v[32:33], v[174:175]
	v_pk_mul_f32 v[34:35], v[34:35], v[176:177]
	v_cvt_pk_bf16_f32 v170, v40, v41
	v_cvt_pk_bf16_f32 v171, v42, v43
	v_cvt_pk_bf16_f32 v172, v32, v33
	v_cvt_pk_bf16_f32 v173, v34, v35
	global_store_dwordx4 v[178:179], v[170:173], off sc1
	v_lshl_add_u64 v[178:179], v[178:179], 0, s[98:99]
	s_nop 1
	v_pk_mul_f32 v[8:9], v[12:13], v[8:9]
	v_pk_mul_f32 v[10:11], v[14:15], v[10:11]
	v_pk_mul_f32 v[0:1], v[4:5], v[0:1]
	v_pk_mul_f32 v[2:3], v[6:7], v[2:3]
	v_pk_fma_f32 v[162:163], v[162:163], v[242:243], v[242:243] op_sel_hi:[1,0,0]
	v_pk_fma_f32 v[164:165], v[164:165], v[242:243], v[242:243] op_sel_hi:[1,0,0]
	v_pk_fma_f32 v[166:167], v[166:167], v[242:243], v[242:243] op_sel_hi:[1,0,0]
	v_pk_fma_f32 v[168:169], v[168:169], v[242:243], v[242:243] op_sel_hi:[1,0,0]
	v_rcp_f32_e32 v162, v162
	v_rcp_f32_e32 v163, v163
	v_rcp_f32_e32 v164, v164
	v_rcp_f32_e32 v165, v165
	v_rcp_f32_e32 v166, v166
	v_rcp_f32_e32 v167, v167
	v_rcp_f32_e32 v168, v168
	v_rcp_f32_e32 v169, v169
	v_pk_mul_f32 v[24:25], v[24:25], v[154:155]
	v_pk_mul_f32 v[26:27], v[26:27], v[156:157]
	v_pk_mul_f32 v[16:17], v[16:17], v[158:159]
	v_pk_mul_f32 v[18:19], v[18:19], v[160:161]
	v_cvt_pk_bf16_f32 v154, v24, v25
	v_cvt_pk_bf16_f32 v155, v26, v27
	v_cvt_pk_bf16_f32 v156, v16, v17
	v_cvt_pk_bf16_f32 v157, v18, v19
	global_store_dwordx4 v[178:179], v[154:157], off sc1
	v_lshl_add_u64 v[178:179], v[178:179], 0, s[98:99]
	s_nop 1
	v_pk_mul_f32 v[8:9], v[8:9], v[162:163]
	v_pk_mul_f32 v[10:11], v[10:11], v[164:165]
	v_pk_mul_f32 v[0:1], v[0:1], v[166:167]
	v_pk_mul_f32 v[2:3], v[2:3], v[168:169]
	v_cvt_pk_bf16_f32 v162, v8, v9
	v_cvt_pk_bf16_f32 v163, v10, v11
	v_cvt_pk_bf16_f32 v164, v0, v1
	v_cvt_pk_bf16_f32 v165, v2, v3
	global_store_dwordx4 v[178:179], v[162:165], off sc1
	s_andn2_b64 vcc, exec, s[4:5]
	s_mov_b64 s[4:5], -1
	s_cbranch_vccnz .LBB0_1736
	s_andn2_b64 vcc, exec, s[0:1]
	s_cbranch_vccnz .LBB0_1735
	s_barrier
	s_branch .LBB0_1735

; __device__ __forceinline__ unsigned cvt_pk_bf16(float lo, float hi) { unsigned r; asm volatile("v_cvt_pk_bf16_f32 %0, %1, %2" : "=v"(r) : "v"(lo), "v"(hi)); return r; }
;     __device__ __forceinline__ void operator()(const f32x4 (&acc)[2][2][4][2], const pg8::Unit& u, int wr, int wc, int fr, int fq) const {
;     ...
;                 for (int bj = 0; bj < 2; ++bj) xin[ai][m][bj] = *(const u32x4*)(XB + (size_t)(row0 + ai * 128 + m * 16) * D + col0 + bj * 128);
; #pragma unroll
;         for (int ai = 0; ai < 2; ++ai)
; #pragma unroll
;             for (int m = 0; m < 4; ++m) { const size_t ro = (size_t)(row0 + ai * 128 + m * 16) * D + col0; float sq = 0.f;
; #pragma unroll
;                 for (int bj = 0; bj < 2; ++bj) { const u32x4 xb = xin[ai][m][bj];
;                     const f32x4 x0 = (f32x4){bf_lo(xb.x), bf_hi(xb.x), bf_lo(xb.y), bf_hi(xb.y)} + acc[ai][bj][m][0] * s, x1 = (f32x4){bf_lo(xb.z), bf_hi(xb.z), bf_lo(xb.w), bf_hi(xb.w)} + acc[ai][bj][m][1] * s;
;                     sq += (x0[0] * x0[0] + x0[1] * x0[1]) + (x0[2] * x0[2] + x0[3] * x0[3]) + (x1[0] * x1[0] + x1[1] * x1[1]) + (x1[2] * x1[2] + x1[3] * x1[3]);
;                     u32x4 w; w.x = cvt_pk_bf16(x0[0], x0[1]); w.y = cvt_pk_bf16(x0[2], x0[3]); w.z = cvt_pk_bf16(x1[0], x1[1]); w.w = cvt_pk_bf16(x1[2], x1[3]);
;                     *(u32x4*)(XB + ro + bj * 128) = w; }
;                 sq += __shfl_xor(sq, 16); sq += __shfl_xor(sq, 32);
;                 if (fq == 0) SSo[(size_t)(u.pn * 4 + wc) * T + row0 + ai * 128 + m * 16] = sq; }
.LBB0_1828:
	v_lshl_or_b32 v204, s66, 8, v221
	v_lshl_add_u32 v202, s67, 8, v220
	v_ashrrev_i32_e32 v205, 31, v204
	v_lshlrev_b64 v[234:235], 1, v[204:205]
	v_ashrrev_i32_e32 v203, 31, v202
	v_lshl_add_u64 v[96:97], s[36:37], 0, v[234:235]
	v_lshlrev_b64 v[236:237], 11, v[202:203]
	v_lshl_add_u64 v[98:99], v[96:97], 0, v[236:237]
	global_load_dwordx4 v[226:229], v[98:99], off
	global_load_dwordx4 v[230:233], v[98:99], off offset:256
	v_or_b32_e32 v98, 16, v202
	v_or_b32_e32 v108, 32, v202
	v_or_b32_e32 v110, 48, v202
	v_ashrrev_i32_e32 v99, 31, v98
	v_ashrrev_i32_e32 v109, 31, v108
	v_ashrrev_i32_e32 v111, 31, v110
	v_lshlrev_b64 v[218:219], 11, v[98:99]
	v_lshlrev_b64 v[216:217], 11, v[108:109]
	v_lshlrev_b64 v[214:215], 11, v[110:111]
	v_lshl_add_u64 v[212:213], v[236:237], 0, s[16:17]
	v_lshl_add_u64 v[210:211], v[236:237], 0, s[18:19]
	v_lshl_add_u64 v[208:209], v[236:237], 0, s[38:39]
	v_lshl_add_u64 v[206:207], v[236:237], 0, s[42:43]
	v_lshl_add_u64 v[98:99], v[96:97], 0, v[218:219]
	v_lshl_add_u64 v[108:109], v[96:97], 0, v[216:217]
	v_lshl_add_u64 v[110:111], v[96:97], 0, v[214:215]
	v_lshl_add_u64 v[120:121], v[96:97], 0, v[212:213]
	v_lshl_add_u64 v[122:123], v[96:97], 0, v[210:211]
	v_lshl_add_u64 v[238:239], v[96:97], 0, v[208:209]
	v_lshl_add_u64 v[96:97], v[96:97], 0, v[206:207]
	global_load_dwordx4 v[180:183], v[98:99], off
	global_load_dwordx4 v[176:179], v[98:99], off offset:256
	global_load_dwordx4 v[172:175], v[108:109], off
	global_load_dwordx4 v[168:171], v[108:109], off offset:256
	global_load_dwordx4 v[164:167], v[110:111], off
	global_load_dwordx4 v[160:163], v[110:111], off offset:256
	global_load_dwordx4 v[156:159], v[120:121], off
	global_load_dwordx4 v[152:155], v[120:121], off offset:256
	global_load_dwordx4 v[148:151], v[122:123], off
	global_load_dwordx4 v[144:147], v[122:123], off offset:256
	global_load_dwordx4 v[128:131], v[238:239], off
	s_nop 0
	global_load_dwordx4 v[120:123], v[238:239], off offset:256
	global_load_dwordx4 v[108:111], v[96:97], off
	s_nop 0
	global_load_dwordx4 v[96:99], v[96:97], off offset:256
	s_lshl_b32 s20, s66, 2
	s_or_b32 s20, s20, s56
	s_ashr_i32 s21, s20, 31
	s_lshl_b64 s[20:21], s[20:21], 17
	s_waitcnt vmcnt(0)
	v_lshlrev_b32_e32 v238, 16, v226
	v_and_b32_e32 v239, 0xffff0000, v226
	v_lshlrev_b32_e32 v226, 16, v227
	v_and_b32_e32 v227, 0xffff0000, v227
	v_lshlrev_b32_e32 v240, 16, v228
	v_and_b32_e32 v241, 0xffff0000, v228
	v_lshlrev_b32_e32 v242, 16, v230
	v_and_b32_e32 v243, 0xffff0000, v230
	v_lshlrev_b32_e32 v230, 16, v231
	v_and_b32_e32 v231, 0xffff0000, v231
	v_lshlrev_b32_e32 v244, 16, v232
	v_and_b32_e32 v245, 0xffff0000, v232
	v_lshlrev_b32_e32 v232, 16, v233
	v_and_b32_e32 v233, 0xffff0000, v233
	v_pk_fma_f32 v[142:143], v[142:143], 0.5, v[226:227] op_sel_hi:[1,0,1]
	v_pk_fma_f32 v[140:141], v[140:141], 0.5, v[238:239] op_sel_hi:[1,0,1]
	v_lshlrev_b32_e32 v228, 16, v229
	v_and_b32_e32 v229, 0xffff0000, v229
	v_pk_fma_f32 v[136:137], v[136:137], 0.5, v[240:241] op_sel_hi:[1,0,1]
	v_pk_fma_f32 v[226:227], v[134:135], 0.5, v[230:231] op_sel_hi:[1,0,1]
	v_pk_fma_f32 v[230:231], v[126:127], 0.5, v[232:233] op_sel_hi:[1,0,1]
	v_pk_fma_f32 v[232:233], v[124:125], 0.5, v[244:245] op_sel_hi:[1,0,1]
	v_mul_f32_e32 v124, v141, v141
	v_mul_f32_e32 v125, v143, v143
	v_pk_fma_f32 v[138:139], v[138:139], 0.5, v[228:229] op_sel_hi:[1,0,1]
	v_pk_fma_f32 v[228:229], v[132:133], 0.5, v[242:243] op_sel_hi:[1,0,1]
	v_mul_f32_e32 v126, v137, v137
	v_fmac_f32_e32 v124, v140, v140
	v_fmac_f32_e32 v125, v142, v142
	v_mul_f32_e32 v127, v139, v139
	v_cvt_pk_bf16_f32 v132, v140, v141
	v_cvt_pk_bf16_f32 v133, v142, v143
	v_cvt_pk_bf16_f32 v134, v136, v137
	v_cvt_pk_bf16_f32 v135, v138, v139
	v_mul_f32_e32 v137, v229, v229
	v_mul_f32_e32 v139, v227, v227
	v_fmac_f32_e32 v126, v136, v136
	v_add_f32_e32 v124, v124, v125
	v_fmac_f32_e32 v137, v228, v228
	v_fmac_f32_e32 v139, v226, v226
	v_add_f32_e32 v124, v126, v124
	v_mul_f32_e32 v126, v233, v233
	v_add_f32_e32 v125, v137, v139
	v_fmac_f32_e32 v126, v232, v232
	v_add_f32_e32 v125, v126, v125
	v_mul_f32_e32 v126, v231, v231
	v_fmac_f32_e32 v127, v138, v138
	v_fmac_f32_e32 v126, v230, v230
	v_add_f32_e32 v124, v127, v124
	v_add_f32_e32 v125, v126, v125
	v_and_b32_e32 v126, 64, v225
	v_add_f32_e32 v125, v124, v125
	v_add_u32_e32 v138, 64, v126
	v_lshl_add_u64 v[126:127], s[36:37], 0, v[236:237]
	v_lshl_add_u64 v[136:137], v[126:127], 0, v[234:235]
	v_mov_b32_e32 v139, v125
	s_nop 1
	v_permlane16_swap_b32_e32 v139, v125
	global_store_dwordx4 v[136:137], v[132:135], off sc1
	s_waitcnt lgkmcnt(0)
	v_add_f32_e32 v126, v125, v139
	v_cvt_pk_bf16_f32 v132, v228, v229
	v_cvt_pk_bf16_f32 v133, v226, v227
	v_cvt_pk_bf16_f32 v134, v232, v233
	v_cvt_pk_bf16_f32 v135, v230, v231
	global_store_dwordx4 v[136:137], v[132:135], off offset:256 sc1
	s_nop 0
	v_mov_b32_e32 v127, v126
	s_nop 1
	v_permlane32_swap_b32_e32 v127, v126
	s_and_saveexec_b64 s[34:35], s[4:5]
	s_cbranch_execz .LBB0_1830
	s_add_u32 s46, s54, s20
	s_addc_u32 s47, s55, s21
	v_lshl_add_u64 v[132:133], v[202:203], 2, s[46:47]
	s_waitcnt lgkmcnt(0)
	v_add_f32_e32 v126, v126, v127
	global_store_dword v[132:133], v126, off
; __device__ __forceinline__ unsigned cvt_pk_bf16(float lo, float hi) { unsigned r; asm volatile("v_cvt_pk_bf16_f32 %0, %1, %2" : "=v"(r) : "v"(lo), "v"(hi)); return r; }
;     __device__ __forceinline__ void operator()(const f32x4 (&acc)[2][2][4][2], const pg8::Unit& u, int wr, int wc, int fr, int fq) const {
;     ...
;             for (int m = 0; m < 4; ++m) { const size_t ro = (size_t)(row0 + ai * 128 + m * 16) * D + col0; float sq = 0.f;
; #pragma unroll
;                 for (int bj = 0; bj < 2; ++bj) { const u32x4 xb = xin[ai][m][bj];
;                     const f32x4 x0 = (f32x4){bf_lo(xb.x), bf_hi(xb.x), bf_lo(xb.y), bf_hi(xb.y)} + acc[ai][bj][m][0] * s, x1 = (f32x4){bf_lo(xb.z), bf_hi(xb.z), bf_lo(xb.w), bf_hi(xb.w)} + acc[ai][bj][m][1] * s;
;                     sq += (x0[0] * x0[0] + x0[1] * x0[1]) + (x0[2] * x0[2] + x0[3] * x0[3]) + (x1[0] * x1[0] + x1[1] * x1[1]) + (x1[2] * x1[2] + x1[3] * x1[3]);
;                     u32x4 w; w.x = cvt_pk_bf16(x0[0], x0[1]); w.y = cvt_pk_bf16(x0[2], x0[3]); w.z = cvt_pk_bf16(x1[0], x1[1]); w.w = cvt_pk_bf16(x1[2], x1[3]);
;                     *(u32x4*)(XB + ro + bj * 128) = w; }
;                 sq += __shfl_xor(sq, 16); sq += __shfl_xor(sq, 32);
;                 if (fq == 0) SSo[(size_t)(u.pn * 4 + wc) * T + row0 + ai * 128 + m * 16] = sq; }
.LBB0_1830:
	s_or_b64 exec, exec, s[34:35]
	v_lshlrev_b32_e32 v126, 16, v180
	s_waitcnt lgkmcnt(0)
	v_and_b32_e32 v127, 0xffff0000, v180
	v_lshlrev_b32_e32 v132, 16, v181
	v_and_b32_e32 v133, 0xffff0000, v181
	v_pk_fma_f32 v[118:119], v[118:119], 0.5, v[132:133] op_sel_hi:[1,0,1]
	v_pk_fma_f32 v[116:117], v[116:117], 0.5, v[126:127] op_sel_hi:[1,0,1]
	v_lshlrev_b32_e32 v126, 16, v182
	v_and_b32_e32 v127, 0xffff0000, v182
	v_lshlrev_b32_e32 v132, 16, v183
	v_and_b32_e32 v133, 0xffff0000, v183
	v_pk_fma_f32 v[132:133], v[114:115], 0.5, v[132:133] op_sel_hi:[1,0,1]
	v_pk_fma_f32 v[114:115], v[112:113], 0.5, v[126:127] op_sel_hi:[1,0,1]
	v_mul_f32_e32 v112, v117, v117
	v_mul_f32_e32 v113, v119, v119
	v_fmac_f32_e32 v112, v116, v116
	v_fmac_f32_e32 v113, v118, v118
	v_add_f32_e32 v112, v112, v113
	v_mul_f32_e32 v113, v115, v115
	v_fmac_f32_e32 v113, v114, v114
	v_add_f32_e32 v112, v113, v112
	v_mul_f32_e32 v113, v133, v133
	v_fmac_f32_e32 v113, v132, v132
	v_add_f32_e32 v126, v113, v112
	v_cvt_pk_bf16_f32 v112, v116, v117
	v_cvt_pk_bf16_f32 v113, v118, v119
	v_lshlrev_b32_e32 v116, 16, v176
	v_and_b32_e32 v117, 0xffff0000, v176
	v_lshlrev_b32_e32 v118, 16, v177
	v_and_b32_e32 v119, 0xffff0000, v177
	v_pk_fma_f32 v[106:107], v[106:107], 0.5, v[118:119] op_sel_hi:[1,0,1]
	v_pk_fma_f32 v[104:105], v[104:105], 0.5, v[116:117] op_sel_hi:[1,0,1]
	v_lshlrev_b32_e32 v116, 16, v178
	v_and_b32_e32 v117, 0xffff0000, v178
	v_pk_fma_f32 v[116:117], v[100:101], 0.5, v[116:117] op_sel_hi:[1,0,1]
	v_mul_f32_e32 v100, v105, v105
	v_mul_f32_e32 v101, v107, v107
	v_fmac_f32_e32 v100, v104, v104
	v_fmac_f32_e32 v101, v106, v106
	v_lshlrev_b32_e32 v118, 16, v179
	v_and_b32_e32 v119, 0xffff0000, v179
	v_add_f32_e32 v100, v100, v101
	v_mul_f32_e32 v101, v117, v117
	v_pk_fma_f32 v[118:119], v[102:103], 0.5, v[118:119] op_sel_hi:[1,0,1]
	v_fmac_f32_e32 v101, v116, v116
	v_add_f32_e32 v100, v101, v100
	v_mul_f32_e32 v101, v119, v119
	v_fmac_f32_e32 v101, v118, v118
	v_add_f32_e32 v100, v101, v100
	v_add_f32_e32 v103, v126, v100
	v_cvt_pk_bf16_f32 v114, v114, v115
	v_cvt_pk_bf16_f32 v115, v132, v133
	v_mov_b32_e32 v132, v103
	s_nop 1
	v_permlane16_swap_b32_e32 v132, v103
	v_lshl_add_u64 v[100:101], s[36:37], 0, v[218:219]
	v_lshl_add_u64 v[126:127], v[204:205], 1, v[100:101]
	global_store_dwordx4 v[126:127], v[112:115], off sc1
	v_cvt_pk_bf16_f32 v102, v104, v105
	s_waitcnt lgkmcnt(0)
	v_add_f32_e32 v100, v103, v132
	v_mov_b32_e32 v101, v100
	s_nop 1
	v_permlane32_swap_b32_e32 v101, v100
	v_cvt_pk_bf16_f32 v103, v106, v107
	v_cvt_pk_bf16_f32 v104, v116, v117
	v_cvt_pk_bf16_f32 v105, v118, v119
	global_store_dwordx4 v[126:127], v[102:105], off offset:256 sc1
	s_and_saveexec_b64 s[34:35], s[4:5]
	s_cbranch_execz .LBB0_1832
	s_add_u32 s46, s54, s20
	s_addc_u32 s47, s55, s21
	v_lshl_add_u64 v[102:103], v[202:203], 2, s[46:47]
	s_waitcnt lgkmcnt(0)
	v_add_f32_e32 v100, v100, v101
	global_store_dword v[102:103], v100, off offset:64
.LBB0_1832:
	s_or_b64 exec, exec, s[34:35]
	v_lshlrev_b32_e32 v100, 16, v172
	s_waitcnt lgkmcnt(0)
	v_and_b32_e32 v101, 0xffff0000, v172
	v_lshlrev_b32_e32 v102, 16, v173
	v_and_b32_e32 v103, 0xffff0000, v173
	v_pk_fma_f32 v[94:95], v[94:95], 0.5, v[102:103] op_sel_hi:[1,0,1]
	v_pk_fma_f32 v[92:93], v[92:93], 0.5, v[100:101] op_sel_hi:[1,0,1]
	v_lshlrev_b32_e32 v100, 16, v174
	v_and_b32_e32 v101, 0xffff0000, v174
	v_lshlrev_b32_e32 v102, 16, v175
	v_and_b32_e32 v103, 0xffff0000, v175
	v_pk_fma_f32 v[102:103], v[90:91], 0.5, v[102:103] op_sel_hi:[1,0,1]
	v_pk_fma_f32 v[90:91], v[88:89], 0.5, v[100:101] op_sel_hi:[1,0,1]
	v_mul_f32_e32 v88, v93, v93
	v_mul_f32_e32 v89, v95, v95
	v_fmac_f32_e32 v88, v92, v92
	v_fmac_f32_e32 v89, v94, v94
	v_add_f32_e32 v88, v88, v89
	v_mul_f32_e32 v89, v91, v91
	v_fmac_f32_e32 v89, v90, v90
	v_add_f32_e32 v88, v89, v88
	v_mul_f32_e32 v89, v103, v103
	v_fmac_f32_e32 v89, v102, v102
	v_add_f32_e32 v100, v89, v88
	v_cvt_pk_bf16_f32 v88, v92, v93
	v_cvt_pk_bf16_f32 v89, v94, v95
	v_lshlrev_b32_e32 v92, 16, v168
	v_and_b32_e32 v93, 0xffff0000, v168
	v_lshlrev_b32_e32 v94, 16, v169
	v_and_b32_e32 v95, 0xffff0000, v169
	v_pk_fma_f32 v[86:87], v[86:87], 0.5, v[94:95] op_sel_hi:[1,0,1]
	v_pk_fma_f32 v[84:85], v[84:85], 0.5, v[92:93] op_sel_hi:[1,0,1]
	v_lshlrev_b32_e32 v92, 16, v170
	v_and_b32_e32 v93, 0xffff0000, v170
	v_pk_fma_f32 v[92:93], v[80:81], 0.5, v[92:93] op_sel_hi:[1,0,1]
	v_mul_f32_e32 v80, v85, v85
	v_mul_f32_e32 v81, v87, v87
	v_fmac_f32_e32 v80, v84, v84
	v_fmac_f32_e32 v81, v86, v86
	v_lshlrev_b32_e32 v94, 16, v171
	v_and_b32_e32 v95, 0xffff0000, v171
	v_add_f32_e32 v80, v80, v81
	v_mul_f32_e32 v81, v93, v93
	v_pk_fma_f32 v[94:95], v[82:83], 0.5, v[94:95] op_sel_hi:[1,0,1]
	v_fmac_f32_e32 v81, v92, v92
	v_add_f32_e32 v80, v81, v80
	v_mul_f32_e32 v81, v95, v95
	v_fmac_f32_e32 v81, v94, v94
	v_add_f32_e32 v80, v81, v80
	v_add_f32_e32 v83, v100, v80
	v_cvt_pk_bf16_f32 v90, v90, v91
	v_cvt_pk_bf16_f32 v91, v102, v103
	v_mov_b32_e32 v102, v83
	s_nop 1
	v_permlane16_swap_b32_e32 v102, v83
	v_lshl_add_u64 v[80:81], s[36:37], 0, v[216:217]
	v_lshl_add_u64 v[100:101], v[204:205], 1, v[80:81]
	global_store_dwordx4 v[100:101], v[88:91], off sc1
	v_cvt_pk_bf16_f32 v82, v84, v85
	s_waitcnt lgkmcnt(0)
	v_add_f32_e32 v80, v83, v102
	v_mov_b32_e32 v81, v80
	s_nop 1
	v_permlane32_swap_b32_e32 v81, v80
	v_cvt_pk_bf16_f32 v83, v86, v87
	v_cvt_pk_bf16_f32 v84, v92, v93
	v_cvt_pk_bf16_f32 v85, v94, v95
	global_store_dwordx4 v[100:101], v[82:85], off offset:256 sc1
	s_and_saveexec_b64 s[34:35], s[4:5]
	s_cbranch_execz .LBB0_1834
	s_add_u32 s46, s54, s20
	s_addc_u32 s47, s55, s21
	v_lshl_add_u64 v[82:83], v[202:203], 2, s[46:47]
	s_waitcnt lgkmcnt(0)
	v_add_f32_e32 v80, v80, v81
	global_store_dword v[82:83], v80, off offset:128
; __device__ __forceinline__ unsigned cvt_pk_bf16(float lo, float hi) { unsigned r; asm volatile("v_cvt_pk_bf16_f32 %0, %1, %2" : "=v"(r) : "v"(lo), "v"(hi)); return r; }
;     __device__ __forceinline__ void operator()(const f32x4 (&acc)[2][2][4][2], const pg8::Unit& u, int wr, int wc, int fr, int fq) const {
;     ...
;             for (int m = 0; m < 4; ++m) { const size_t ro = (size_t)(row0 + ai * 128 + m * 16) * D + col0; float sq = 0.f;
; #pragma unroll
;                 for (int bj = 0; bj < 2; ++bj) { const u32x4 xb = xin[ai][m][bj];
;                     const f32x4 x0 = (f32x4){bf_lo(xb.x), bf_hi(xb.x), bf_lo(xb.y), bf_hi(xb.y)} + acc[ai][bj][m][0] * s, x1 = (f32x4){bf_lo(xb.z), bf_hi(xb.z), bf_lo(xb.w), bf_hi(xb.w)} + acc[ai][bj][m][1] * s;
;                     sq += (x0[0] * x0[0] + x0[1] * x0[1]) + (x0[2] * x0[2] + x0[3] * x0[3]) + (x1[0] * x1[0] + x1[1] * x1[1]) + (x1[2] * x1[2] + x1[3] * x1[3]);
;                     u32x4 w; w.x = cvt_pk_bf16(x0[0], x0[1]); w.y = cvt_pk_bf16(x0[2], x0[3]); w.z = cvt_pk_bf16(x1[0], x1[1]); w.w = cvt_pk_bf16(x1[2], x1[3]);
;                     *(u32x4*)(XB + ro + bj * 128) = w; }
;                 sq += __shfl_xor(sq, 16); sq += __shfl_xor(sq, 32);
;                 if (fq == 0) SSo[(size_t)(u.pn * 4 + wc) * T + row0 + ai * 128 + m * 16] = sq; }
.LBB0_1834:
	s_or_b64 exec, exec, s[34:35]
	v_lshlrev_b32_e32 v80, 16, v164
	s_waitcnt lgkmcnt(0)
	v_and_b32_e32 v81, 0xffff0000, v164
	v_lshlrev_b32_e32 v82, 16, v165
	v_and_b32_e32 v83, 0xffff0000, v165
	v_pk_fma_f32 v[78:79], v[78:79], 0.5, v[82:83] op_sel_hi:[1,0,1]
	v_pk_fma_f32 v[76:77], v[76:77], 0.5, v[80:81] op_sel_hi:[1,0,1]
	v_lshlrev_b32_e32 v80, 16, v166
	v_and_b32_e32 v81, 0xffff0000, v166
	v_lshlrev_b32_e32 v82, 16, v167
	v_and_b32_e32 v83, 0xffff0000, v167
	v_pk_fma_f32 v[82:83], v[74:75], 0.5, v[82:83] op_sel_hi:[1,0,1]
	v_pk_fma_f32 v[74:75], v[72:73], 0.5, v[80:81] op_sel_hi:[1,0,1]
	v_mul_f32_e32 v72, v77, v77
	v_mul_f32_e32 v73, v79, v79
	v_fmac_f32_e32 v72, v76, v76
	v_fmac_f32_e32 v73, v78, v78
	v_add_f32_e32 v72, v72, v73
	v_mul_f32_e32 v73, v75, v75
	v_fmac_f32_e32 v73, v74, v74
	v_add_f32_e32 v72, v73, v72
	v_mul_f32_e32 v73, v83, v83
	v_fmac_f32_e32 v73, v82, v82
	v_add_f32_e32 v80, v73, v72
	v_cvt_pk_bf16_f32 v72, v76, v77
	v_cvt_pk_bf16_f32 v73, v78, v79
	v_lshlrev_b32_e32 v76, 16, v160
	v_and_b32_e32 v77, 0xffff0000, v160
	v_lshlrev_b32_e32 v78, 16, v161
	v_and_b32_e32 v79, 0xffff0000, v161
	v_pk_fma_f32 v[70:71], v[70:71], 0.5, v[78:79] op_sel_hi:[1,0,1]
	v_pk_fma_f32 v[68:69], v[68:69], 0.5, v[76:77] op_sel_hi:[1,0,1]
	v_lshlrev_b32_e32 v76, 16, v162
	v_and_b32_e32 v77, 0xffff0000, v162
	v_pk_fma_f32 v[76:77], v[64:65], 0.5, v[76:77] op_sel_hi:[1,0,1]
	v_mul_f32_e32 v64, v69, v69
	v_mul_f32_e32 v65, v71, v71
	v_fmac_f32_e32 v64, v68, v68
	v_fmac_f32_e32 v65, v70, v70
	v_lshlrev_b32_e32 v78, 16, v163
	v_and_b32_e32 v79, 0xffff0000, v163
	v_add_f32_e32 v64, v64, v65
	v_mul_f32_e32 v65, v77, v77
	v_pk_fma_f32 v[78:79], v[66:67], 0.5, v[78:79] op_sel_hi:[1,0,1]
	v_fmac_f32_e32 v65, v76, v76
	v_add_f32_e32 v64, v65, v64
	v_mul_f32_e32 v65, v79, v79
	v_fmac_f32_e32 v65, v78, v78
	v_add_f32_e32 v64, v65, v64
	v_add_f32_e32 v67, v80, v64
	v_cvt_pk_bf16_f32 v74, v74, v75
	v_cvt_pk_bf16_f32 v75, v82, v83
	v_mov_b32_e32 v82, v67
	s_nop 1
	v_permlane16_swap_b32_e32 v82, v67
	v_lshl_add_u64 v[64:65], s[36:37], 0, v[214:215]
	v_lshl_add_u64 v[80:81], v[204:205], 1, v[64:65]
	global_store_dwordx4 v[80:81], v[72:75], off sc1
	v_cvt_pk_bf16_f32 v66, v68, v69
	s_waitcnt lgkmcnt(0)
	v_add_f32_e32 v64, v67, v82
	v_mov_b32_e32 v65, v64
	s_nop 1
	v_permlane32_swap_b32_e32 v65, v64
	v_cvt_pk_bf16_f32 v67, v70, v71
	v_cvt_pk_bf16_f32 v68, v76, v77
	v_cvt_pk_bf16_f32 v69, v78, v79
	global_store_dwordx4 v[80:81], v[66:69], off offset:256 sc1
	s_and_saveexec_b64 s[34:35], s[4:5]
	s_cbranch_execz .LBB0_1836
	s_add_u32 s46, s54, s20
	s_addc_u32 s47, s55, s21
	v_lshl_add_u64 v[66:67], v[202:203], 2, s[46:47]
	s_waitcnt lgkmcnt(0)
	v_add_f32_e32 v64, v64, v65
	global_store_dword v[66:67], v64, off offset:192
.LBB0_1836:
	s_or_b64 exec, exec, s[34:35]
	v_lshlrev_b32_e32 v64, 16, v156
	s_waitcnt lgkmcnt(0)
	v_and_b32_e32 v65, 0xffff0000, v156
	v_lshlrev_b32_e32 v66, 16, v157
	v_and_b32_e32 v67, 0xffff0000, v157
	v_pk_fma_f32 v[62:63], v[62:63], 0.5, v[66:67] op_sel_hi:[1,0,1]
	v_pk_fma_f32 v[60:61], v[60:61], 0.5, v[64:65] op_sel_hi:[1,0,1]
	v_lshlrev_b32_e32 v64, 16, v158
	v_and_b32_e32 v65, 0xffff0000, v158
	v_lshlrev_b32_e32 v66, 16, v159
	v_and_b32_e32 v67, 0xffff0000, v159
	v_pk_fma_f32 v[66:67], v[58:59], 0.5, v[66:67] op_sel_hi:[1,0,1]
	v_pk_fma_f32 v[58:59], v[56:57], 0.5, v[64:65] op_sel_hi:[1,0,1]
	v_mul_f32_e32 v56, v61, v61
	v_mul_f32_e32 v57, v63, v63
	v_fmac_f32_e32 v56, v60, v60
	v_fmac_f32_e32 v57, v62, v62
	v_add_f32_e32 v56, v56, v57
	v_mul_f32_e32 v57, v59, v59
	v_fmac_f32_e32 v57, v58, v58
	v_add_f32_e32 v56, v57, v56
	v_mul_f32_e32 v57, v67, v67
	v_fmac_f32_e32 v57, v66, v66
	v_add_f32_e32 v64, v57, v56
	v_cvt_pk_bf16_f32 v56, v60, v61
	v_cvt_pk_bf16_f32 v57, v62, v63
	v_lshlrev_b32_e32 v60, 16, v152
	v_and_b32_e32 v61, 0xffff0000, v152
	v_lshlrev_b32_e32 v62, 16, v153
	v_and_b32_e32 v63, 0xffff0000, v153
	v_pk_fma_f32 v[54:55], v[54:55], 0.5, v[62:63] op_sel_hi:[1,0,1]
	v_pk_fma_f32 v[52:53], v[52:53], 0.5, v[60:61] op_sel_hi:[1,0,1]
	v_lshlrev_b32_e32 v60, 16, v154
	v_and_b32_e32 v61, 0xffff0000, v154
	v_pk_fma_f32 v[60:61], v[48:49], 0.5, v[60:61] op_sel_hi:[1,0,1]
	v_mul_f32_e32 v48, v53, v53
	v_mul_f32_e32 v49, v55, v55
	v_fmac_f32_e32 v48, v52, v52
	v_fmac_f32_e32 v49, v54, v54
	v_lshlrev_b32_e32 v62, 16, v155
	v_and_b32_e32 v63, 0xffff0000, v155
	v_add_f32_e32 v48, v48, v49
	v_mul_f32_e32 v49, v61, v61
	v_pk_fma_f32 v[62:63], v[50:51], 0.5, v[62:63] op_sel_hi:[1,0,1]
	v_fmac_f32_e32 v49, v60, v60
	v_add_f32_e32 v48, v49, v48
	v_mul_f32_e32 v49, v63, v63
	v_fmac_f32_e32 v49, v62, v62
	v_add_f32_e32 v48, v49, v48
	v_add_f32_e32 v51, v64, v48
	v_cvt_pk_bf16_f32 v58, v58, v59
	v_cvt_pk_bf16_f32 v59, v66, v67
	v_mov_b32_e32 v66, v51
	s_nop 1
	v_permlane16_swap_b32_e32 v66, v51
	v_lshl_add_u64 v[48:49], s[36:37], 0, v[212:213]
	v_lshl_add_u64 v[64:65], v[204:205], 1, v[48:49]
	global_store_dwordx4 v[64:65], v[56:59], off sc1
	v_cvt_pk_bf16_f32 v50, v52, v53
	s_waitcnt lgkmcnt(0)
	v_add_f32_e32 v48, v51, v66
	v_mov_b32_e32 v49, v48
	s_nop 1
	v_permlane32_swap_b32_e32 v49, v48
	v_cvt_pk_bf16_f32 v51, v54, v55
	v_cvt_pk_bf16_f32 v52, v60, v61
	v_cvt_pk_bf16_f32 v53, v62, v63
	global_store_dwordx4 v[64:65], v[50:53], off offset:256 sc1
	s_and_saveexec_b64 s[34:35], s[4:5]
	s_cbranch_execz .LBB0_1838
	s_add_u32 s46, s54, s20
	s_addc_u32 s47, s55, s21
	v_lshl_add_u64 v[50:51], v[202:203], 2, s[46:47]
	s_waitcnt lgkmcnt(0)
	v_add_f32_e32 v48, v48, v49
	global_store_dword v[50:51], v48, off offset:512
; __device__ __forceinline__ unsigned cvt_pk_bf16(float lo, float hi) { unsigned r; asm volatile("v_cvt_pk_bf16_f32 %0, %1, %2" : "=v"(r) : "v"(lo), "v"(hi)); return r; }
;     __device__ __forceinline__ void operator()(const f32x4 (&acc)[2][2][4][2], const pg8::Unit& u, int wr, int wc, int fr, int fq) const {
;     ...
;             for (int m = 0; m < 4; ++m) { const size_t ro = (size_t)(row0 + ai * 128 + m * 16) * D + col0; float sq = 0.f;
; #pragma unroll
;                 for (int bj = 0; bj < 2; ++bj) { const u32x4 xb = xin[ai][m][bj];
;                     const f32x4 x0 = (f32x4){bf_lo(xb.x), bf_hi(xb.x), bf_lo(xb.y), bf_hi(xb.y)} + acc[ai][bj][m][0] * s, x1 = (f32x4){bf_lo(xb.z), bf_hi(xb.z), bf_lo(xb.w), bf_hi(xb.w)} + acc[ai][bj][m][1] * s;
;                     sq += (x0[0] * x0[0] + x0[1] * x0[1]) + (x0[2] * x0[2] + x0[3] * x0[3]) + (x1[0] * x1[0] + x1[1] * x1[1]) + (x1[2] * x1[2] + x1[3] * x1[3]);
;                     u32x4 w; w.x = cvt_pk_bf16(x0[0], x0[1]); w.y = cvt_pk_bf16(x0[2], x0[3]); w.z = cvt_pk_bf16(x1[0], x1[1]); w.w = cvt_pk_bf16(x1[2], x1[3]);
;                     *(u32x4*)(XB + ro + bj * 128) = w; }
;                 sq += __shfl_xor(sq, 16); sq += __shfl_xor(sq, 32);
;                 if (fq == 0) SSo[(size_t)(u.pn * 4 + wc) * T + row0 + ai * 128 + m * 16] = sq; }
.LBB0_1838:
	s_or_b64 exec, exec, s[34:35]
	v_lshlrev_b32_e32 v48, 16, v148
	s_waitcnt lgkmcnt(0)
	v_and_b32_e32 v49, 0xffff0000, v148
	v_lshlrev_b32_e32 v50, 16, v149
	v_and_b32_e32 v51, 0xffff0000, v149
	v_pk_fma_f32 v[46:47], v[46:47], 0.5, v[50:51] op_sel_hi:[1,0,1]
	v_pk_fma_f32 v[44:45], v[44:45], 0.5, v[48:49] op_sel_hi:[1,0,1]
	v_lshlrev_b32_e32 v48, 16, v150
	v_and_b32_e32 v49, 0xffff0000, v150
	v_lshlrev_b32_e32 v50, 16, v151
	v_and_b32_e32 v51, 0xffff0000, v151
	v_pk_fma_f32 v[50:51], v[42:43], 0.5, v[50:51] op_sel_hi:[1,0,1]
	v_pk_fma_f32 v[42:43], v[40:41], 0.5, v[48:49] op_sel_hi:[1,0,1]
	v_mul_f32_e32 v40, v45, v45
	v_mul_f32_e32 v41, v47, v47
	v_fmac_f32_e32 v40, v44, v44
	v_fmac_f32_e32 v41, v46, v46
	v_add_f32_e32 v40, v40, v41
	v_mul_f32_e32 v41, v43, v43
	v_fmac_f32_e32 v41, v42, v42
	v_add_f32_e32 v40, v41, v40
	v_mul_f32_e32 v41, v51, v51
	v_fmac_f32_e32 v41, v50, v50
	v_add_f32_e32 v48, v41, v40
	v_cvt_pk_bf16_f32 v40, v44, v45
	v_cvt_pk_bf16_f32 v41, v46, v47
	v_lshlrev_b32_e32 v44, 16, v144
	v_and_b32_e32 v45, 0xffff0000, v144
	v_lshlrev_b32_e32 v46, 16, v145
	v_and_b32_e32 v47, 0xffff0000, v145
	v_pk_fma_f32 v[38:39], v[38:39], 0.5, v[46:47] op_sel_hi:[1,0,1]
	v_pk_fma_f32 v[36:37], v[36:37], 0.5, v[44:45] op_sel_hi:[1,0,1]
	v_lshlrev_b32_e32 v44, 16, v146
	v_and_b32_e32 v45, 0xffff0000, v146
	v_pk_fma_f32 v[44:45], v[32:33], 0.5, v[44:45] op_sel_hi:[1,0,1]
	v_mul_f32_e32 v32, v37, v37
	v_mul_f32_e32 v33, v39, v39
	v_fmac_f32_e32 v32, v36, v36
	v_fmac_f32_e32 v33, v38, v38
	v_lshlrev_b32_e32 v46, 16, v147
	v_and_b32_e32 v47, 0xffff0000, v147
	v_add_f32_e32 v32, v32, v33
	v_mul_f32_e32 v33, v45, v45
	v_pk_fma_f32 v[46:47], v[34:35], 0.5, v[46:47] op_sel_hi:[1,0,1]
	v_fmac_f32_e32 v33, v44, v44
	v_add_f32_e32 v32, v33, v32
	v_mul_f32_e32 v33, v47, v47
	v_fmac_f32_e32 v33, v46, v46
	v_add_f32_e32 v32, v33, v32
	v_add_f32_e32 v35, v48, v32
	v_cvt_pk_bf16_f32 v42, v42, v43
	v_cvt_pk_bf16_f32 v43, v50, v51
	v_mov_b32_e32 v50, v35
	s_nop 1
	v_permlane16_swap_b32_e32 v50, v35
	v_lshl_add_u64 v[32:33], s[36:37], 0, v[210:211]
	v_lshl_add_u64 v[48:49], v[204:205], 1, v[32:33]
	global_store_dwordx4 v[48:49], v[40:43], off sc1
	v_cvt_pk_bf16_f32 v34, v36, v37
	s_waitcnt lgkmcnt(0)
	v_add_f32_e32 v32, v35, v50
	v_mov_b32_e32 v33, v32
	s_nop 1
	v_permlane32_swap_b32_e32 v33, v32
	v_cvt_pk_bf16_f32 v35, v38, v39
	v_cvt_pk_bf16_f32 v36, v44, v45
	v_cvt_pk_bf16_f32 v37, v46, v47
	global_store_dwordx4 v[48:49], v[34:37], off offset:256 sc1
	s_and_saveexec_b64 s[34:35], s[4:5]
	s_cbranch_execz .LBB0_1840
	s_add_u32 s46, s54, s20
	s_addc_u32 s47, s55, s21
	v_lshl_add_u64 v[34:35], v[202:203], 2, s[46:47]
	s_waitcnt lgkmcnt(0)
	v_add_f32_e32 v32, v32, v33
	global_store_dword v[34:35], v32, off offset:576
; __device__ __forceinline__ unsigned cvt_pk_bf16(float lo, float hi) { unsigned r; asm volatile("v_cvt_pk_bf16_f32 %0, %1, %2" : "=v"(r) : "v"(lo), "v"(hi)); return r; }
;     __device__ __forceinline__ void operator()(const f32x4 (&acc)[2][2][4][2], const pg8::Unit& u, int wr, int wc, int fr, int fq) const {
;     ...
;             for (int m = 0; m < 4; ++m) { const size_t ro = (size_t)(row0 + ai * 128 + m * 16) * D + col0; float sq = 0.f;
; #pragma unroll
;                 for (int bj = 0; bj < 2; ++bj) { const u32x4 xb = xin[ai][m][bj];
;                     const f32x4 x0 = (f32x4){bf_lo(xb.x), bf_hi(xb.x), bf_lo(xb.y), bf_hi(xb.y)} + acc[ai][bj][m][0] * s, x1 = (f32x4){bf_lo(xb.z), bf_hi(xb.z), bf_lo(xb.w), bf_hi(xb.w)} + acc[ai][bj][m][1] * s;
;                     sq += (x0[0] * x0[0] + x0[1] * x0[1]) + (x0[2] * x0[2] + x0[3] * x0[3]) + (x1[0] * x1[0] + x1[1] * x1[1]) + (x1[2] * x1[2] + x1[3] * x1[3]);
;                     u32x4 w; w.x = cvt_pk_bf16(x0[0], x0[1]); w.y = cvt_pk_bf16(x0[2], x0[3]); w.z = cvt_pk_bf16(x1[0], x1[1]); w.w = cvt_pk_bf16(x1[2], x1[3]);
;                     *(u32x4*)(XB + ro + bj * 128) = w; }
;                 sq += __shfl_xor(sq, 16); sq += __shfl_xor(sq, 32);
;                 if (fq == 0) SSo[(size_t)(u.pn * 4 + wc) * T + row0 + ai * 128 + m * 16] = sq; }
.LBB0_1840:
	s_or_b64 exec, exec, s[34:35]
	v_lshlrev_b32_e32 v32, 16, v128
	s_waitcnt lgkmcnt(0)
	v_and_b32_e32 v33, 0xffff0000, v128
	v_lshlrev_b32_e32 v34, 16, v129
	v_and_b32_e32 v35, 0xffff0000, v129
	v_pk_fma_f32 v[30:31], v[30:31], 0.5, v[34:35] op_sel_hi:[1,0,1]
	v_pk_fma_f32 v[28:29], v[28:29], 0.5, v[32:33] op_sel_hi:[1,0,1]
	v_lshlrev_b32_e32 v32, 16, v130
	v_and_b32_e32 v33, 0xffff0000, v130
	v_lshlrev_b32_e32 v34, 16, v131
	v_and_b32_e32 v35, 0xffff0000, v131
	v_pk_fma_f32 v[34:35], v[26:27], 0.5, v[34:35] op_sel_hi:[1,0,1]
	v_pk_fma_f32 v[26:27], v[24:25], 0.5, v[32:33] op_sel_hi:[1,0,1]
	v_mul_f32_e32 v24, v29, v29
	v_mul_f32_e32 v25, v31, v31
	v_fmac_f32_e32 v24, v28, v28
	v_fmac_f32_e32 v25, v30, v30
	v_add_f32_e32 v24, v24, v25
	v_mul_f32_e32 v25, v27, v27
	v_fmac_f32_e32 v25, v26, v26
	v_add_f32_e32 v24, v25, v24
	v_mul_f32_e32 v25, v35, v35
	v_fmac_f32_e32 v25, v34, v34
	v_add_f32_e32 v32, v25, v24
	v_cvt_pk_bf16_f32 v24, v28, v29
	v_cvt_pk_bf16_f32 v25, v30, v31
	v_lshlrev_b32_e32 v28, 16, v120
	v_and_b32_e32 v29, 0xffff0000, v120
	v_lshlrev_b32_e32 v30, 16, v121
	v_and_b32_e32 v31, 0xffff0000, v121
	v_pk_fma_f32 v[22:23], v[22:23], 0.5, v[30:31] op_sel_hi:[1,0,1]
	v_pk_fma_f32 v[20:21], v[20:21], 0.5, v[28:29] op_sel_hi:[1,0,1]
	v_lshlrev_b32_e32 v28, 16, v122
	v_and_b32_e32 v29, 0xffff0000, v122
	v_pk_fma_f32 v[28:29], v[16:17], 0.5, v[28:29] op_sel_hi:[1,0,1]
	v_mul_f32_e32 v16, v21, v21
	v_mul_f32_e32 v17, v23, v23
	v_fmac_f32_e32 v16, v20, v20
	v_fmac_f32_e32 v17, v22, v22
	v_lshlrev_b32_e32 v30, 16, v123
	v_and_b32_e32 v31, 0xffff0000, v123
	v_add_f32_e32 v16, v16, v17
	v_mul_f32_e32 v17, v29, v29
	v_pk_fma_f32 v[30:31], v[18:19], 0.5, v[30:31] op_sel_hi:[1,0,1]
	v_fmac_f32_e32 v17, v28, v28
	v_add_f32_e32 v16, v17, v16
	v_mul_f32_e32 v17, v31, v31
	v_fmac_f32_e32 v17, v30, v30
	v_add_f32_e32 v16, v17, v16
	v_add_f32_e32 v19, v32, v16
	v_cvt_pk_bf16_f32 v26, v26, v27
	v_cvt_pk_bf16_f32 v27, v34, v35
	v_mov_b32_e32 v34, v19
	s_nop 1
	v_permlane16_swap_b32_e32 v34, v19
	v_lshl_add_u64 v[16:17], s[36:37], 0, v[208:209]
	v_lshl_add_u64 v[32:33], v[204:205], 1, v[16:17]
	global_store_dwordx4 v[32:33], v[24:27], off sc1
	v_cvt_pk_bf16_f32 v18, v20, v21
	s_waitcnt lgkmcnt(0)
	v_add_f32_e32 v16, v19, v34
	v_mov_b32_e32 v17, v16
	s_nop 1
	v_permlane32_swap_b32_e32 v17, v16
	v_cvt_pk_bf16_f32 v19, v22, v23
	v_cvt_pk_bf16_f32 v20, v28, v29
	v_cvt_pk_bf16_f32 v21, v30, v31
	global_store_dwordx4 v[32:33], v[18:21], off offset:256 sc1
	s_and_saveexec_b64 s[34:35], s[4:5]
	s_cbranch_execz .LBB0_1842
	s_add_u32 s46, s54, s20
	s_addc_u32 s47, s55, s21
	v_lshl_add_u64 v[18:19], v[202:203], 2, s[46:47]
	s_waitcnt lgkmcnt(0)
	v_add_f32_e32 v16, v16, v17
	global_store_dword v[18:19], v16, off offset:640
.LBB0_1842:
	s_or_b64 exec, exec, s[34:35]
	v_lshlrev_b32_e32 v16, 16, v108
	s_waitcnt lgkmcnt(0)
	v_and_b32_e32 v17, 0xffff0000, v108
	v_lshlrev_b32_e32 v18, 16, v109
	v_and_b32_e32 v19, 0xffff0000, v109
	v_pk_fma_f32 v[14:15], v[14:15], 0.5, v[18:19] op_sel_hi:[1,0,1]
	v_pk_fma_f32 v[12:13], v[12:13], 0.5, v[16:17] op_sel_hi:[1,0,1]
	v_lshlrev_b32_e32 v16, 16, v110
	v_and_b32_e32 v17, 0xffff0000, v110
	v_lshlrev_b32_e32 v18, 16, v111
	v_and_b32_e32 v19, 0xffff0000, v111
	v_pk_fma_f32 v[18:19], v[10:11], 0.5, v[18:19] op_sel_hi:[1,0,1]
	v_pk_fma_f32 v[10:11], v[8:9], 0.5, v[16:17] op_sel_hi:[1,0,1]
	v_mul_f32_e32 v8, v13, v13
	v_mul_f32_e32 v9, v15, v15
	v_fmac_f32_e32 v8, v12, v12
	v_fmac_f32_e32 v9, v14, v14
	v_add_f32_e32 v8, v8, v9
	v_mul_f32_e32 v9, v11, v11
	v_fmac_f32_e32 v9, v10, v10
	v_add_f32_e32 v8, v9, v8
	v_mul_f32_e32 v9, v19, v19
	v_fmac_f32_e32 v9, v18, v18
	v_add_f32_e32 v16, v9, v8
	v_cvt_pk_bf16_f32 v8, v12, v13
	v_cvt_pk_bf16_f32 v9, v14, v15
	v_lshlrev_b32_e32 v12, 16, v96
	v_and_b32_e32 v13, 0xffff0000, v96
	v_lshlrev_b32_e32 v14, 16, v97
	v_and_b32_e32 v15, 0xffff0000, v97
	v_pk_fma_f32 v[6:7], v[6:7], 0.5, v[14:15] op_sel_hi:[1,0,1]
	v_pk_fma_f32 v[4:5], v[4:5], 0.5, v[12:13] op_sel_hi:[1,0,1]
	v_lshlrev_b32_e32 v12, 16, v98
	v_and_b32_e32 v13, 0xffff0000, v98
	v_pk_fma_f32 v[12:13], v[0:1], 0.5, v[12:13] op_sel_hi:[1,0,1]
	v_mul_f32_e32 v0, v5, v5
	v_mul_f32_e32 v1, v7, v7
	v_fmac_f32_e32 v0, v4, v4
	v_fmac_f32_e32 v1, v6, v6
	v_lshlrev_b32_e32 v14, 16, v99
	v_and_b32_e32 v15, 0xffff0000, v99
	v_add_f32_e32 v0, v0, v1
	v_mul_f32_e32 v1, v13, v13
	v_pk_fma_f32 v[14:15], v[2:3], 0.5, v[14:15] op_sel_hi:[1,0,1]
	v_fmac_f32_e32 v1, v12, v12
	v_add_f32_e32 v0, v1, v0
	v_mul_f32_e32 v1, v15, v15
	v_fmac_f32_e32 v1, v14, v14
	v_add_f32_e32 v0, v1, v0
	v_add_f32_e32 v3, v16, v0
	v_cvt_pk_bf16_f32 v10, v10, v11
	v_cvt_pk_bf16_f32 v11, v18, v19
	v_mov_b32_e32 v18, v3
	s_nop 1
	v_permlane16_swap_b32_e32 v18, v3
	v_lshl_add_u64 v[0:1], s[36:37], 0, v[206:207]
	v_lshl_add_u64 v[16:17], v[204:205], 1, v[0:1]
	global_store_dwordx4 v[16:17], v[8:11], off sc1
	v_cvt_pk_bf16_f32 v2, v4, v5
	s_waitcnt lgkmcnt(0)
	v_add_f32_e32 v0, v3, v18
	v_mov_b32_e32 v1, v0
	s_nop 1
	v_permlane32_swap_b32_e32 v1, v0
	v_cvt_pk_bf16_f32 v3, v6, v7
	v_cvt_pk_bf16_f32 v4, v12, v13
	v_cvt_pk_bf16_f32 v5, v14, v15
	global_store_dwordx4 v[16:17], v[2:5], off offset:256 sc1
	s_and_saveexec_b64 s[34:35], s[4:5]
	s_cbranch_execz .LBB0_1844
	s_add_u32 s20, s54, s20
	s_addc_u32 s21, s55, s21
	v_lshl_add_u64 v[2:3], v[202:203], 2, s[20:21]
	s_waitcnt lgkmcnt(0)
	v_add_f32_e32 v0, v0, v1
	global_store_dword v[2:3], v0, off offset:704

; __device__ __forceinline__ float rs_of(float ss) { return 1.0f / sqrtf(ss * (1.f / 1024.f) + 1e-6f); }
; __device__ __forceinline__ void final_rows(const bf16_t* XB, float* out, const float* g, const float* SS, int gw, int NGW, int lane) {
;     ...
;     for (int m0 = 4 * gw; m0 < T; m0 += 4 * NGW) {
;         u32x2 w[4][4]; float tp[4];
; #pragma unroll
;         for (int q = 0; q < 4; ++q) { const u32x2* xr = (const u32x2*)(XB + (size_t)(m0 + q) * D) + lane;
; #pragma unroll
;             for (int j = 0; j < 4; ++j) w[q][j] = xr[64 * j];
;             tp[q] = (lane < 16) ? SS[(size_t)lane * T + m0 + q] : 0.f; }
; #pragma unroll
;         for (int q = 0; q < 4; ++q) { float t = tp[q]; t += __shfl_xor(t, 1); t += __shfl_xor(t, 2); t += __shfl_xor(t, 4); t += __shfl_xor(t, 8); const float r = rs_of(__shfl(t, 0));
;             f32x4* o = (f32x4*)(out + (size_t)(m0 + q) * D) + lane;
; #pragma unroll
;             for (int j = 0; j < 4; ++j) o[64 * j] = (f32x4){bf_lo(w[q][j].x), bf_hi(w[q][j].x), bf_lo(w[q][j].y), bf_hi(w[q][j].y)} * r * gv[j]; } }
.LBB0_1905:
	s_or_b64 exec, exec, s[2:3]
	s_waitcnt vmcnt(0)
	ds_bpermute_b32 v54, v56, v66
	v_lshlrev_b32_e32 v68, 16, v50
	v_and_b32_e32 v71, 0xffff0000, v51
	s_add_i32 s4, s4, s6
	v_lshl_add_u64 v[18:19], v[18:19], 0, s[10:11]
	s_waitcnt lgkmcnt(0)
	v_add_f32_e32 v54, v66, v54
	ds_bpermute_b32 v55, v57, v54
	s_cmp_lt_i32 s4, 0x8000
	v_lshl_add_u64 v[20:21], v[20:21], 0, s[12:13]
	s_waitcnt lgkmcnt(0)
	v_add_f32_e32 v54, v54, v55
	ds_bpermute_b32 v55, v58, v54
	s_waitcnt lgkmcnt(0)
	v_add_f32_e32 v66, v54, v55
	ds_bpermute_b32 v67, v59, v66
	v_lshlrev_b32_e32 v54, 16, v52
	v_and_b32_e32 v55, 0xffff0000, v52
	v_lshlrev_b32_e32 v52, 16, v53
	v_and_b32_e32 v53, 0xffff0000, v53
	s_waitcnt lgkmcnt(0)
	v_add_f32_e32 v66, v66, v67
	ds_bpermute_b32 v69, v60, v66
	v_add_co_u32_e32 v66, vcc, s7, v16
	s_waitcnt lgkmcnt(0)
	v_fmamk_f32 v69, v69, 0x3a800000, v61
	v_addc_co_u32_e32 v67, vcc, -1, v17, vcc
	v_mul_f32_e32 v70, 0x4f800000, v69
	v_cmp_gt_f32_e32 vcc, s5, v69
	s_nop 1
	v_cndmask_b32_e32 v72, v69, v70, vcc
	v_sqrt_f32_e32 v73, v72
	v_and_b32_e32 v69, 0xffff0000, v50
	v_lshlrev_b32_e32 v70, 16, v51
	v_add_u32_e32 v50, -1, v73
	v_add_u32_e32 v51, 1, v73
	v_fma_f32 v74, -v50, v73, v72
	v_fma_f32 v75, -v51, v73, v72
	v_cmp_ge_f32_e64 s[2:3], 0, v74
	s_nop 1
	v_cndmask_b32_e64 v50, v73, v50, s[2:3]
	v_cmp_lt_f32_e64 s[2:3], 0, v75
	ds_bpermute_b32 v73, v56, v65
	s_waitcnt lgkmcnt(0)
	v_add_f32_e32 v65, v65, v73
	v_cndmask_b32_e64 v50, v50, v51, s[2:3]
	v_mul_f32_e32 v51, 0x37800000, v50
	v_cndmask_b32_e32 v50, v50, v51, vcc
	v_cmp_class_f32_e32 vcc, v72, v62
	s_nop 1
	v_cndmask_b32_e32 v50, v50, v72, vcc
	v_div_scale_f32 v51, s[2:3], v50, v50, 1.0
	v_rcp_f32_e32 v72, v51
	v_div_scale_f32 v74, vcc, 1.0, v50, 1.0
	v_fma_f32 v75, -v51, v72, 1.0
	v_fmac_f32_e32 v72, v75, v72
	v_mul_f32_e32 v75, v74, v72
	v_fma_f32 v76, -v51, v75, v74
	v_fmac_f32_e32 v75, v76, v72
	v_fma_f32 v51, -v51, v75, v74
	v_div_fmas_f32 v51, v51, v72, v75
	v_div_fixup_f32 v72, v51, v50, 1.0
	v_pk_mul_f32 v[50:51], v[72:73], v[54:55] op_sel_hi:[0,1]
	v_pk_mul_f32 v[54:55], v[72:73], v[68:69] op_sel_hi:[0,1]
	ds_bpermute_b32 v68, v57, v65
	v_pk_mul_f32 v[52:53], v[72:73], v[52:53] op_sel_hi:[0,1]
	v_pk_mul_f32 v[52:53], v[2:3], v[52:53]
	v_pk_mul_f32 v[50:51], v[0:1], v[50:51]
	global_store_dwordx4 v[66:67], v[50:53], off offset:-3072 sc1
	s_nop 1
	v_pk_mul_f32 v[50:51], v[72:73], v[70:71] op_sel_hi:[0,1]
	v_pk_mul_f32 v[52:53], v[6:7], v[50:51]
	v_pk_mul_f32 v[50:51], v[4:5], v[54:55]
	s_waitcnt lgkmcnt(0)
	v_add_f32_e32 v54, v65, v68
	ds_bpermute_b32 v55, v58, v54
	global_store_dwordx4 v[66:67], v[50:53], off offset:-2048 sc1
	s_waitcnt lgkmcnt(0)
	v_add_f32_e32 v54, v54, v55
	ds_bpermute_b32 v55, v59, v54
	v_lshlrev_b32_e32 v50, 16, v48
	v_and_b32_e32 v51, 0xffff0000, v48
	v_lshlrev_b32_e32 v48, 16, v49
	v_and_b32_e32 v49, 0xffff0000, v49
	v_pk_mul_f32 v[52:53], v[72:73], v[50:51] op_sel_hi:[0,1]
	v_pk_mul_f32 v[48:49], v[72:73], v[48:49] op_sel_hi:[0,1]
	v_pk_mul_f32 v[50:51], v[10:11], v[48:49]
	v_pk_mul_f32 v[48:49], v[8:9], v[52:53]
	global_store_dwordx4 v[66:67], v[48:51], off offset:-1024 sc1
	s_waitcnt lgkmcnt(0)
	s_nop 0
	v_add_f32_e32 v49, v54, v55
	ds_bpermute_b32 v52, v60, v49
	v_lshlrev_b32_e32 v48, 16, v46
	v_and_b32_e32 v49, 0xffff0000, v46
	v_pk_mul_f32 v[50:51], v[72:73], v[48:49] op_sel_hi:[0,1]
	v_lshlrev_b32_e32 v46, 16, v47
	s_waitcnt lgkmcnt(0)
	v_fmamk_f32 v48, v52, 0x3a800000, v61
	v_mul_f32_e32 v49, 0x4f800000, v48
	v_cmp_gt_f32_e32 vcc, s5, v48
	v_and_b32_e32 v47, 0xffff0000, v47
	v_pk_mul_f32 v[46:47], v[72:73], v[46:47] op_sel_hi:[0,1]
	v_cndmask_b32_e32 v52, v48, v49, vcc
	v_sqrt_f32_e32 v53, v52
	v_pk_mul_f32 v[48:49], v[14:15], v[46:47]
	v_pk_mul_f32 v[46:47], v[12:13], v[50:51]
	v_add_u32_e32 v50, -1, v53
	v_fma_f32 v51, -v50, v53, v52
	v_cmp_ge_f32_e64 s[2:3], 0, v51
	v_add_u32_e32 v51, 1, v53
	s_nop 0
	v_cndmask_b32_e64 v50, v53, v50, s[2:3]
	v_fma_f32 v53, -v51, v53, v52
	v_cmp_lt_f32_e64 s[2:3], 0, v53
	s_nop 1
	v_cndmask_b32_e64 v50, v50, v51, s[2:3]
	v_mul_f32_e32 v51, 0x37800000, v50
	v_cndmask_b32_e32 v50, v50, v51, vcc
	v_cmp_class_f32_e32 vcc, v52, v62
	s_nop 1
	v_cndmask_b32_e32 v52, v50, v52, vcc
	v_div_scale_f32 v53, s[2:3], v52, v52, 1.0
	v_rcp_f32_e32 v54, v53
	v_add_co_u32_e32 v50, vcc, s14, v16
	s_nop 1
	v_addc_co_u32_e32 v51, vcc, -1, v17, vcc
	global_store_dwordx4 v[50:51], v[46:49], off offset:-4096 sc1
	s_nop 1
	v_fma_f32 v46, -v53, v54, 1.0
	v_fmac_f32_e32 v54, v46, v54
	v_div_scale_f32 v46, vcc, 1.0, v52, 1.0
	v_mul_f32_e32 v47, v46, v54
	v_fma_f32 v48, -v53, v47, v46
	v_fmac_f32_e32 v47, v48, v54
	v_fma_f32 v46, -v53, v47, v46
	v_div_fmas_f32 v46, v46, v54, v47
	v_div_fixup_f32 v48, v46, v52, 1.0
	v_lshlrev_b32_e32 v46, 16, v44
	v_and_b32_e32 v47, 0xffff0000, v44
	v_lshlrev_b32_e32 v44, 16, v45
	v_and_b32_e32 v45, 0xffff0000, v45
	v_pk_mul_f32 v[52:53], v[48:49], v[46:47] op_sel_hi:[0,1]
	v_pk_mul_f32 v[44:45], v[48:49], v[44:45] op_sel_hi:[0,1]
	ds_bpermute_b32 v49, v56, v64
	v_pk_mul_f32 v[46:47], v[2:3], v[44:45]
	v_pk_mul_f32 v[44:45], v[0:1], v[52:53]
	global_store_dwordx4 v[50:51], v[44:47], off offset:-3072 sc1
	s_nop 1
	v_lshlrev_b32_e32 v44, 16, v42
	v_and_b32_e32 v45, 0xffff0000, v42
	s_waitcnt lgkmcnt(0)
	v_pk_mul_f32 v[46:47], v[48:49], v[44:45] op_sel_hi:[0,1]
	v_add_f32_e32 v49, v64, v49
	ds_bpermute_b32 v52, v57, v49
	v_lshlrev_b32_e32 v42, 16, v43
	v_and_b32_e32 v43, 0xffff0000, v43
	v_pk_mul_f32 v[42:43], v[48:49], v[42:43] op_sel_hi:[0,1]
	v_pk_mul_f32 v[44:45], v[6:7], v[42:43]
	v_pk_mul_f32 v[42:43], v[4:5], v[46:47]
	global_store_dwordx4 v[50:51], v[42:45], off offset:-2048 sc1
	s_waitcnt lgkmcnt(0)
; __device__ __forceinline__ float rs_of(float ss) { return 1.0f / sqrtf(ss * (1.f / 1024.f) + 1e-6f); }
; __device__ __forceinline__ void final_rows(const bf16_t* XB, float* out, const float* g, const float* SS, int gw, int NGW, int lane) {
;     ...
;         for (int q = 0; q < 4; ++q) { const u32x2* xr = (const u32x2*)(XB + (size_t)(m0 + q) * D) + lane;
; #pragma unroll
;             for (int j = 0; j < 4; ++j) w[q][j] = xr[64 * j];
;             tp[q] = (lane < 16) ? SS[(size_t)lane * T + m0 + q] : 0.f; }
; #pragma unroll
;         for (int q = 0; q < 4; ++q) { float t = tp[q]; t += __shfl_xor(t, 1); t += __shfl_xor(t, 2); t += __shfl_xor(t, 4); t += __shfl_xor(t, 8); const float r = rs_of(__shfl(t, 0));
;             f32x4* o = (f32x4*)(out + (size_t)(m0 + q) * D) + lane;
; #pragma unroll
;             for (int j = 0; j < 4; ++j) o[64 * j] = (f32x4){bf_lo(w[q][j].x), bf_hi(w[q][j].x), bf_lo(w[q][j].y), bf_hi(w[q][j].y)} * r * gv[j]; } }
	s_nop 0
	v_add_f32_e32 v44, v49, v52
	ds_bpermute_b32 v45, v58, v44
	v_lshlrev_b32_e32 v42, 16, v40
	v_and_b32_e32 v43, 0xffff0000, v40
	v_lshlrev_b32_e32 v40, 16, v41
	v_and_b32_e32 v41, 0xffff0000, v41
	s_waitcnt lgkmcnt(0)
	v_add_f32_e32 v46, v44, v45
	ds_bpermute_b32 v47, v59, v46
	v_pk_mul_f32 v[44:45], v[48:49], v[42:43] op_sel_hi:[0,1]
	v_pk_mul_f32 v[40:41], v[48:49], v[40:41] op_sel_hi:[0,1]
	v_pk_mul_f32 v[42:43], v[10:11], v[40:41]
	v_pk_mul_f32 v[40:41], v[8:9], v[44:45]
	s_waitcnt lgkmcnt(0)
	v_add_f32_e32 v44, v46, v47
	ds_bpermute_b32 v44, v60, v44
	global_store_dwordx4 v[50:51], v[40:43], off offset:-1024 sc1
	s_nop 1
	v_lshlrev_b32_e32 v40, 16, v38
	s_waitcnt lgkmcnt(0)
	v_fmamk_f32 v42, v44, 0x3a800000, v61
	v_mul_f32_e32 v43, 0x4f800000, v42
	v_cmp_gt_f32_e32 vcc, s5, v42
	v_and_b32_e32 v41, 0xffff0000, v38
	v_lshlrev_b32_e32 v38, 16, v39
	v_cndmask_b32_e32 v44, v42, v43, vcc
	v_sqrt_f32_e32 v45, v44
	v_pk_mul_f32 v[42:43], v[48:49], v[40:41] op_sel_hi:[0,1]
	v_and_b32_e32 v39, 0xffff0000, v39
	v_pk_mul_f32 v[38:39], v[48:49], v[38:39] op_sel_hi:[0,1]
	v_add_u32_e32 v40, -1, v45
	v_fma_f32 v41, -v40, v45, v44
	v_cmp_ge_f32_e64 s[2:3], 0, v41
	v_add_u32_e32 v41, 1, v45
	s_nop 0
	v_cndmask_b32_e64 v40, v45, v40, s[2:3]
	v_fma_f32 v45, -v41, v45, v44
	v_cmp_lt_f32_e64 s[2:3], 0, v45
	s_nop 1
	v_cndmask_b32_e64 v40, v40, v41, s[2:3]
	v_mul_f32_e32 v41, 0x37800000, v40
	v_cndmask_b32_e32 v40, v40, v41, vcc
	v_cmp_class_f32_e32 vcc, v44, v62
	s_nop 1
	v_cndmask_b32_e32 v44, v40, v44, vcc
	v_div_scale_f32 v45, s[2:3], v44, v44, 1.0
	v_rcp_f32_e32 v46, v45
	v_pk_mul_f32 v[40:41], v[14:15], v[38:39]
	v_pk_mul_f32 v[38:39], v[12:13], v[42:43]
	global_store_dwordx4 v[50:51], v[38:41], off sc1
	s_nop 1
	v_fma_f32 v38, -v45, v46, 1.0
	v_fmac_f32_e32 v46, v38, v46
	v_div_scale_f32 v38, vcc, 1.0, v44, 1.0
	v_mul_f32_e32 v39, v38, v46
	v_fma_f32 v40, -v45, v39, v38
	v_fmac_f32_e32 v39, v40, v46
	v_fma_f32 v38, -v45, v39, v38
	v_div_fmas_f32 v38, v38, v46, v39
	v_div_fixup_f32 v40, v38, v44, 1.0
	v_lshlrev_b32_e32 v38, 16, v36
	v_and_b32_e32 v39, 0xffff0000, v36
	v_lshlrev_b32_e32 v36, 16, v37
	v_and_b32_e32 v37, 0xffff0000, v37
	v_pk_mul_f32 v[42:43], v[40:41], v[38:39] op_sel_hi:[0,1]
	v_pk_mul_f32 v[36:37], v[40:41], v[36:37] op_sel_hi:[0,1]
	ds_bpermute_b32 v41, v56, v63
	v_pk_mul_f32 v[38:39], v[2:3], v[36:37]
	v_pk_mul_f32 v[36:37], v[0:1], v[42:43]
	v_add_co_u32_e32 v42, vcc, s15, v16
	s_nop 1
	v_addc_co_u32_e32 v43, vcc, -1, v17, vcc
	global_store_dwordx4 v[42:43], v[36:39], off offset:-3072 sc1
	s_nop 1
	v_lshlrev_b32_e32 v36, 16, v34
	v_and_b32_e32 v37, 0xffff0000, v34
	s_waitcnt lgkmcnt(0)
	v_pk_mul_f32 v[38:39], v[40:41], v[36:37] op_sel_hi:[0,1]
	v_add_f32_e32 v41, v63, v41
	ds_bpermute_b32 v44, v57, v41
	v_lshlrev_b32_e32 v34, 16, v35
	v_and_b32_e32 v35, 0xffff0000, v35
	v_pk_mul_f32 v[34:35], v[40:41], v[34:35] op_sel_hi:[0,1]
	v_pk_mul_f32 v[36:37], v[6:7], v[34:35]
	v_pk_mul_f32 v[34:35], v[4:5], v[38:39]
	global_store_dwordx4 v[42:43], v[34:37], off offset:-2048 sc1
	s_waitcnt lgkmcnt(0)
	s_nop 0
	v_add_f32_e32 v36, v41, v44
	ds_bpermute_b32 v37, v58, v36
	v_lshlrev_b32_e32 v34, 16, v32
	v_and_b32_e32 v35, 0xffff0000, v32
	v_lshlrev_b32_e32 v32, 16, v33
	v_and_b32_e32 v33, 0xffff0000, v33
	s_waitcnt lgkmcnt(0)
	v_add_f32_e32 v38, v36, v37
	ds_bpermute_b32 v39, v59, v38
	v_pk_mul_f32 v[36:37], v[40:41], v[34:35] op_sel_hi:[0,1]
	v_pk_mul_f32 v[32:33], v[40:41], v[32:33] op_sel_hi:[0,1]
	v_pk_mul_f32 v[34:35], v[10:11], v[32:33]
	v_pk_mul_f32 v[32:33], v[8:9], v[36:37]
	s_waitcnt lgkmcnt(0)
	v_add_f32_e32 v36, v38, v39
	ds_bpermute_b32 v36, v60, v36
	global_store_dwordx4 v[42:43], v[32:35], off offset:-1024 sc1
	s_nop 1
	v_lshlrev_b32_e32 v32, 16, v30
	s_waitcnt lgkmcnt(0)
	v_fmamk_f32 v34, v36, 0x3a800000, v61
	v_mul_f32_e32 v35, 0x4f800000, v34
	v_cmp_gt_f32_e32 vcc, s5, v34
	v_and_b32_e32 v33, 0xffff0000, v30
	v_lshlrev_b32_e32 v30, 16, v31
	v_cndmask_b32_e32 v36, v34, v35, vcc
	v_sqrt_f32_e32 v37, v36
	v_pk_mul_f32 v[34:35], v[40:41], v[32:33] op_sel_hi:[0,1]
	v_and_b32_e32 v31, 0xffff0000, v31
	v_pk_mul_f32 v[30:31], v[40:41], v[30:31] op_sel_hi:[0,1]
	v_add_u32_e32 v32, -1, v37
	v_fma_f32 v33, -v32, v37, v36
	v_cmp_ge_f32_e64 s[2:3], 0, v33
	v_add_u32_e32 v33, 1, v37
	s_nop 0
	v_cndmask_b32_e64 v32, v37, v32, s[2:3]
	v_fma_f32 v37, -v33, v37, v36
	v_cmp_lt_f32_e64 s[2:3], 0, v37
	s_nop 1
	v_cndmask_b32_e64 v32, v32, v33, s[2:3]
	v_mul_f32_e32 v33, 0x37800000, v32
	v_cndmask_b32_e32 v32, v32, v33, vcc
	v_cmp_class_f32_e32 vcc, v36, v62
	s_nop 1
	v_cndmask_b32_e32 v36, v32, v36, vcc
	v_div_scale_f32 v37, s[2:3], v36, v36, 1.0
	v_rcp_f32_e32 v38, v37
	v_pk_mul_f32 v[32:33], v[14:15], v[30:31]
	v_pk_mul_f32 v[30:31], v[12:13], v[34:35]
	global_store_dwordx4 v[16:17], v[30:33], off offset:-4096 sc1
	s_nop 1
	v_fma_f32 v30, -v37, v38, 1.0
	v_fmac_f32_e32 v38, v30, v38
	v_div_scale_f32 v30, vcc, 1.0, v36, 1.0
	v_mul_f32_e32 v31, v30, v38
	v_fma_f32 v32, -v37, v31, v30
	v_fmac_f32_e32 v31, v32, v38
	v_fma_f32 v30, -v37, v31, v30
	v_div_fmas_f32 v30, v30, v38, v31
	v_div_fixup_f32 v32, v30, v36, 1.0
	v_lshlrev_b32_e32 v30, 16, v28
	v_and_b32_e32 v31, 0xffff0000, v28
	v_lshlrev_b32_e32 v28, 16, v29
	v_and_b32_e32 v29, 0xffff0000, v29
	v_pk_mul_f32 v[34:35], v[32:33], v[30:31] op_sel_hi:[0,1]
	v_pk_mul_f32 v[28:29], v[32:33], v[28:29] op_sel_hi:[0,1]
	v_pk_mul_f32 v[30:31], v[2:3], v[28:29]
	v_pk_mul_f32 v[28:29], v[0:1], v[34:35]
	global_store_dwordx4 v[16:17], v[28:31], off offset:-3072 sc1
	s_nop 1
	v_lshlrev_b32_e32 v28, 16, v26
	v_and_b32_e32 v29, 0xffff0000, v26
	v_lshlrev_b32_e32 v26, 16, v27
	v_and_b32_e32 v27, 0xffff0000, v27
	v_pk_mul_f32 v[30:31], v[32:33], v[28:29] op_sel_hi:[0,1]
	v_pk_mul_f32 v[26:27], v[32:33], v[26:27] op_sel_hi:[0,1]
	v_pk_mul_f32 v[28:29], v[6:7], v[26:27]
	v_pk_mul_f32 v[26:27], v[4:5], v[30:31]
	global_store_dwordx4 v[16:17], v[26:29], off offset:-2048 sc1
	s_nop 1
	v_lshlrev_b32_e32 v26, 16, v24
	v_and_b32_e32 v27, 0xffff0000, v24
	v_lshlrev_b32_e32 v24, 16, v25
	v_and_b32_e32 v25, 0xffff0000, v25
	v_pk_mul_f32 v[28:29], v[32:33], v[26:27] op_sel_hi:[0,1]
	v_pk_mul_f32 v[24:25], v[32:33], v[24:25] op_sel_hi:[0,1]
	v_pk_mul_f32 v[26:27], v[10:11], v[24:25]
	v_pk_mul_f32 v[24:25], v[8:9], v[28:29]
	global_store_dwordx4 v[16:17], v[24:27], off offset:-1024 sc1
	s_nop 1
	v_lshlrev_b32_e32 v24, 16, v22
	v_and_b32_e32 v25, 0xffff0000, v22
	v_lshlrev_b32_e32 v22, 16, v23
	v_and_b32_e32 v23, 0xffff0000, v23
	v_pk_mul_f32 v[26:27], v[32:33], v[24:25] op_sel_hi:[0,1]
	v_pk_mul_f32 v[22:23], v[32:33], v[22:23] op_sel_hi:[0,1]
	v_pk_mul_f32 v[24:25], v[14:15], v[22:23]
	v_pk_mul_f32 v[22:23], v[12:13], v[26:27]
	global_store_dwordx4 v[16:17], v[22:25], off sc1
	v_lshl_add_u64 v[16:17], v[16:17], 0, s[8:9]
	s_cbranch_scc0 .LBB0_1914
